# v67 + code placement: every K-loop MMA segment's first MFMA at address 4 mod 8 (33 s_nop 0 pads in LOAD-segment slack)
# baseline (speedup 1.0000x reference)
.LBB0_297:
	s_add_u32 s47, s38, s46
	s_addc_u32 s66, s39, 0
	s_add_u32 s64, s47, 0x100
	s_addc_u32 s65, s66, 0
	s_and_b64 s[48:49], s[44:45], exec
	s_cselect_b32 s49, s70, s65
	s_cselect_b32 s48, s71, s64
	s_add_u32 s46, s36, s46
	s_addc_u32 s64, s37, 0
	s_add_u32 s46, s46, 0x100
	s_addc_u32 s64, s64, 0
	s_and_b64 s[44:45], s[44:45], exec
	s_cselect_b32 s65, s72, s64
	s_cselect_b32 s64, s73, s46
	s_add_u32 s68, s47, 0x10080
	ds_read_b128 v[150:153], v146
	ds_read_b128 v[154:157], v146 offset:1024
	ds_read_b128 v[158:161], v146 offset:2048
	ds_read_b128 v[162:165], v146 offset:3072
	ds_read_b128 v[166:169], v147
	ds_read_b128 v[170:173], v147 offset:1024
	ds_read_b128 v[174:177], v147 offset:2048
	ds_read_b128 v[178:181], v147 offset:3072
	s_addc_u32 s69, s66, 0
	s_add_i32 s83, s30, s2
	s_add_i32 m0, s16, 0xc000
	s_add_i32 s84, s16, 0xe000
	s_add_i32 s80, s83, 0x2000
	s_add_u32 s66, s64, 0x40000
	s_addc_u32 s67, s65, 0
	s_add_i32 s82, s31, s2
	s_add_i32 s81, s82, 0x2000
	s_add_i32 s79, 0, 0x18000
	s_add_i32 s78, 0, 0x1c000
	s_add_u32 s46, s48, 0x10000
	s_addc_u32 s47, s49, 0
	s_add_i32 s77, s79, s2
	s_add_i32 s75, s77, 0x2000
	s_add_u32 s44, s64, 0x40080
	s_addc_u32 s45, s65, 0
	s_add_i32 s76, s78, s2
	s_add_i32 s74, s76, 0x2000
	v_lshl_add_u64 v[202:203], s[68:69], 0, v[130:131]
	ds_read_b128 v[182:185], v148
	ds_read_b128 v[186:189], v148 offset:1024
	ds_read_b128 v[190:193], v148 offset:2048
	ds_read_b128 v[194:197], v148 offset:3072
	ds_read_b128 v[198:201], v148 offset:4096
	ds_read_b128 v[206:209], v148 offset:5120
	ds_read_b128 v[210:213], v148 offset:6144
	ds_read_b128 v[214:217], v148 offset:7168
	global_load_lds_dwordx4 v[202:203], off
	s_mov_b32 m0, s84
	v_lshl_add_u64 v[202:203], s[68:69], 0, v[132:133]
	global_load_lds_dwordx4 v[202:203], off
	s_nop 0
	s_waitcnt vmcnt(8) lgkmcnt(0)
	s_setprio 1
	s_barrier
	v_mfma_f32_16x16x32_bf16 v[126:129], v[150:153], v[182:185], v[126:129]
	v_mfma_f32_16x16x32_bf16 v[122:125], v[158:161], v[182:185], v[122:125]
	v_mfma_f32_16x16x32_bf16 v[118:121], v[150:153], v[190:193], v[118:121]
	v_mfma_f32_16x16x32_bf16 v[114:117], v[158:161], v[190:193], v[114:117]
	v_mfma_f32_16x16x32_bf16 v[102:105], v[150:153], v[198:201], v[102:105]
	v_mfma_f32_16x16x32_bf16 v[98:101], v[158:161], v[198:201], v[98:101]
	v_mfma_f32_16x16x32_bf16 v[86:89], v[150:153], v[210:213], v[86:89]
	v_mfma_f32_16x16x32_bf16 v[82:85], v[158:161], v[210:213], v[82:85]
	v_mfma_f32_16x16x32_bf16 v[126:129], v[154:157], v[186:189], v[126:129]
	v_mfma_f32_16x16x32_bf16 v[122:125], v[162:165], v[186:189], v[122:125]
	v_mfma_f32_16x16x32_bf16 v[118:121], v[154:157], v[194:197], v[118:121]
	v_mfma_f32_16x16x32_bf16 v[114:117], v[162:165], v[194:197], v[114:117]
	v_mfma_f32_16x16x32_bf16 v[102:105], v[154:157], v[206:209], v[102:105]
	v_mfma_f32_16x16x32_bf16 v[98:101], v[162:165], v[206:209], v[98:101]
	v_mfma_f32_16x16x32_bf16 v[86:89], v[154:157], v[214:217], v[86:89]
	v_mfma_f32_16x16x32_bf16 v[82:85], v[162:165], v[214:217], v[82:85]
	v_mfma_f32_16x16x32_bf16 v[110:113], v[166:169], v[182:185], v[110:113]
	v_mfma_f32_16x16x32_bf16 v[106:109], v[174:177], v[182:185], v[106:109]
	v_mfma_f32_16x16x32_bf16 v[94:97], v[166:169], v[190:193], v[94:97]
	v_mfma_f32_16x16x32_bf16 v[90:93], v[174:177], v[190:193], v[90:93]
	v_mfma_f32_16x16x32_bf16 v[78:81], v[166:169], v[198:201], v[78:81]
	v_mfma_f32_16x16x32_bf16 v[74:77], v[174:177], v[198:201], v[74:77]
	v_mfma_f32_16x16x32_bf16 v[70:73], v[166:169], v[210:213], v[70:73]
	v_mfma_f32_16x16x32_bf16 v[66:69], v[174:177], v[210:213], v[66:69]
	v_mfma_f32_16x16x32_bf16 v[110:113], v[170:173], v[186:189], v[110:113]
	v_mfma_f32_16x16x32_bf16 v[106:109], v[178:181], v[186:189], v[106:109]
	v_mfma_f32_16x16x32_bf16 v[94:97], v[170:173], v[194:197], v[94:97]
	v_mfma_f32_16x16x32_bf16 v[90:93], v[178:181], v[194:197], v[90:93]
	v_mfma_f32_16x16x32_bf16 v[78:81], v[170:173], v[206:209], v[78:81]
	v_mfma_f32_16x16x32_bf16 v[74:77], v[178:181], v[206:209], v[74:77]
	v_mfma_f32_16x16x32_bf16 v[70:73], v[170:173], v[214:217], v[70:73]
	v_mfma_f32_16x16x32_bf16 v[66:69], v[178:181], v[214:217], v[66:69]
	s_setprio 0
	s_barrier
	s_mov_b32 m0, s83
	v_lshl_add_u64 v[202:203], s[64:65], 0, v[136:137]
	ds_read_b128 v[182:185], v148 offset:16384
	ds_read_b128 v[186:189], v148 offset:17408
	ds_read_b128 v[190:193], v148 offset:18432
	ds_read_b128 v[194:197], v148 offset:19456
	ds_read_b128 v[198:201], v148 offset:20480
	ds_read_b128 v[206:209], v148 offset:21504
	ds_read_b128 v[210:213], v148 offset:22528
	ds_read_b128 v[214:217], v148 offset:23552
	global_load_lds_dwordx4 v[202:203], off
	v_lshl_add_u64 v[218:219], s[64:65], 0, v[134:135]
	s_mov_b32 m0, s80
	v_lshl_add_u64 v[220:221], s[66:67], 0, v[136:137]
	global_load_lds_dwordx4 v[218:219], off
	s_mov_b32 m0, s82
	v_lshl_add_u64 v[222:223], s[48:49], 0, v[132:133]
	global_load_lds_dwordx4 v[220:221], off
	s_mov_b32 m0, s81
	v_lshl_add_u64 v[220:221], s[66:67], 0, v[134:135]
	global_load_lds_dwordx4 v[220:221], off
	s_mov_b32 m0, s16
	v_lshl_add_u64 v[220:221], s[48:49], 0, v[130:131]
	global_load_lds_dwordx4 v[220:221], off
	s_mov_b32 m0, s17
	s_nop 0
	global_load_lds_dwordx4 v[222:223], off
	s_waitcnt vmcnt(8) lgkmcnt(0)
	s_setprio 1
	s_barrier
	v_mfma_f32_16x16x32_bf16 v[62:65], v[150:153], v[182:185], v[62:65]
	v_mfma_f32_16x16x32_bf16 v[58:61], v[158:161], v[182:185], v[58:61]
	v_mfma_f32_16x16x32_bf16 v[54:57], v[150:153], v[190:193], v[54:57]
	v_mfma_f32_16x16x32_bf16 v[50:53], v[158:161], v[190:193], v[50:53]
	v_mfma_f32_16x16x32_bf16 v[38:41], v[150:153], v[198:201], v[38:41]
	v_mfma_f32_16x16x32_bf16 v[34:37], v[158:161], v[198:201], v[34:37]
	v_mfma_f32_16x16x32_bf16 v[22:25], v[150:153], v[210:213], v[22:25]
	v_mfma_f32_16x16x32_bf16 v[18:21], v[158:161], v[210:213], v[18:21]
	v_mfma_f32_16x16x32_bf16 v[62:65], v[154:157], v[186:189], v[62:65]
	v_mfma_f32_16x16x32_bf16 v[58:61], v[162:165], v[186:189], v[58:61]
	v_mfma_f32_16x16x32_bf16 v[54:57], v[154:157], v[194:197], v[54:57]
	v_mfma_f32_16x16x32_bf16 v[50:53], v[162:165], v[194:197], v[50:53]
	v_mfma_f32_16x16x32_bf16 v[38:41], v[154:157], v[206:209], v[38:41]
	v_mfma_f32_16x16x32_bf16 v[34:37], v[162:165], v[206:209], v[34:37]
	v_mfma_f32_16x16x32_bf16 v[22:25], v[154:157], v[214:217], v[22:25]
	v_mfma_f32_16x16x32_bf16 v[18:21], v[162:165], v[214:217], v[18:21]
	v_mfma_f32_16x16x32_bf16 v[46:49], v[166:169], v[182:185], v[46:49]
	v_mfma_f32_16x16x32_bf16 v[42:45], v[174:177], v[182:185], v[42:45]
	v_mfma_f32_16x16x32_bf16 v[30:33], v[166:169], v[190:193], v[30:33]
	v_mfma_f32_16x16x32_bf16 v[26:29], v[174:177], v[190:193], v[26:29]
	v_mfma_f32_16x16x32_bf16 v[14:17], v[166:169], v[198:201], v[14:17]
	v_mfma_f32_16x16x32_bf16 v[10:13], v[174:177], v[198:201], v[10:13]
	v_mfma_f32_16x16x32_bf16 v[6:9], v[166:169], v[210:213], v[6:9]
	v_mfma_f32_16x16x32_bf16 v[2:5], v[174:177], v[210:213], v[2:5]
	v_mfma_f32_16x16x32_bf16 v[46:49], v[170:173], v[186:189], v[46:49]
	v_mfma_f32_16x16x32_bf16 v[42:45], v[178:181], v[186:189], v[42:45]
	v_mfma_f32_16x16x32_bf16 v[30:33], v[170:173], v[194:197], v[30:33]
	v_mfma_f32_16x16x32_bf16 v[26:29], v[178:181], v[194:197], v[26:29]
	v_mfma_f32_16x16x32_bf16 v[14:17], v[170:173], v[206:209], v[14:17]
	v_mfma_f32_16x16x32_bf16 v[10:13], v[178:181], v[206:209], v[10:13]
	v_mfma_f32_16x16x32_bf16 v[6:9], v[170:173], v[214:217], v[6:9]
	v_mfma_f32_16x16x32_bf16 v[2:5], v[178:181], v[214:217], v[2:5]
	s_setprio 0
	s_barrier
	v_add_u32_e32 v149, s79, v145
	ds_read_b128 v[150:153], v149
	ds_read_b128 v[154:157], v149 offset:1024
	ds_read_b128 v[158:161], v149 offset:2048
	ds_read_b128 v[162:165], v149 offset:3072
	v_add_u32_e32 v149, s78, v145
	ds_read_b128 v[166:169], v149
	ds_read_b128 v[170:173], v149 offset:1024
	ds_read_b128 v[174:177], v149 offset:2048
	ds_read_b128 v[178:181], v149 offset:3072
	s_mov_b32 m0, s18
	v_lshl_add_u64 v[224:225], s[46:47], 0, v[130:131]
	ds_read_b128 v[182:185], v148 offset:32768
	ds_read_b128 v[186:189], v148 offset:33792
	ds_read_b128 v[190:193], v148 offset:34816
	ds_read_b128 v[194:197], v148 offset:35840
	ds_read_b128 v[198:201], v148 offset:36864
	ds_read_b128 v[206:209], v148 offset:37888
	ds_read_b128 v[210:213], v148 offset:38912
	ds_read_b128 v[214:217], v148 offset:39936
	global_load_lds_dwordx4 v[224:225], off
	s_mov_b32 m0, s19
	v_lshl_add_u64 v[224:225], s[46:47], 0, v[132:133]
	global_load_lds_dwordx4 v[224:225], off
	s_nop 0
	s_waitcnt vmcnt(8) lgkmcnt(0)
	s_setprio 1
	s_barrier
	v_mfma_f32_16x16x32_bf16 v[126:129], v[150:153], v[182:185], v[126:129]
	v_mfma_f32_16x16x32_bf16 v[122:125], v[158:161], v[182:185], v[122:125]
	v_mfma_f32_16x16x32_bf16 v[118:121], v[150:153], v[190:193], v[118:121]
	v_mfma_f32_16x16x32_bf16 v[114:117], v[158:161], v[190:193], v[114:117]
	v_mfma_f32_16x16x32_bf16 v[102:105], v[150:153], v[198:201], v[102:105]
	v_mfma_f32_16x16x32_bf16 v[98:101], v[158:161], v[198:201], v[98:101]
	v_mfma_f32_16x16x32_bf16 v[86:89], v[150:153], v[210:213], v[86:89]
	v_mfma_f32_16x16x32_bf16 v[82:85], v[158:161], v[210:213], v[82:85]
	v_mfma_f32_16x16x32_bf16 v[126:129], v[154:157], v[186:189], v[126:129]
	v_mfma_f32_16x16x32_bf16 v[122:125], v[162:165], v[186:189], v[122:125]
	v_mfma_f32_16x16x32_bf16 v[118:121], v[154:157], v[194:197], v[118:121]
	v_mfma_f32_16x16x32_bf16 v[114:117], v[162:165], v[194:197], v[114:117]
	v_mfma_f32_16x16x32_bf16 v[102:105], v[154:157], v[206:209], v[102:105]
	v_mfma_f32_16x16x32_bf16 v[98:101], v[162:165], v[206:209], v[98:101]
	v_mfma_f32_16x16x32_bf16 v[86:89], v[154:157], v[214:217], v[86:89]
	v_mfma_f32_16x16x32_bf16 v[82:85], v[162:165], v[214:217], v[82:85]
	v_mfma_f32_16x16x32_bf16 v[110:113], v[166:169], v[182:185], v[110:113]
	v_mfma_f32_16x16x32_bf16 v[106:109], v[174:177], v[182:185], v[106:109]
	v_mfma_f32_16x16x32_bf16 v[94:97], v[166:169], v[190:193], v[94:97]
	v_mfma_f32_16x16x32_bf16 v[90:93], v[174:177], v[190:193], v[90:93]
	v_mfma_f32_16x16x32_bf16 v[78:81], v[166:169], v[198:201], v[78:81]
	v_mfma_f32_16x16x32_bf16 v[74:77], v[174:177], v[198:201], v[74:77]
	v_mfma_f32_16x16x32_bf16 v[70:73], v[166:169], v[210:213], v[70:73]
	v_mfma_f32_16x16x32_bf16 v[66:69], v[174:177], v[210:213], v[66:69]
	v_mfma_f32_16x16x32_bf16 v[110:113], v[170:173], v[186:189], v[110:113]
	v_mfma_f32_16x16x32_bf16 v[106:109], v[178:181], v[186:189], v[106:109]
	v_mfma_f32_16x16x32_bf16 v[94:97], v[170:173], v[194:197], v[94:97]
	v_mfma_f32_16x16x32_bf16 v[90:93], v[178:181], v[194:197], v[90:93]
	v_mfma_f32_16x16x32_bf16 v[78:81], v[170:173], v[206:209], v[78:81]
	v_mfma_f32_16x16x32_bf16 v[74:77], v[178:181], v[206:209], v[74:77]
	v_mfma_f32_16x16x32_bf16 v[70:73], v[170:173], v[214:217], v[70:73]
	v_mfma_f32_16x16x32_bf16 v[66:69], v[178:181], v[214:217], v[66:69]
	s_setprio 0
	s_barrier
	s_mov_b32 m0, s77
	v_lshl_add_u64 v[202:203], v[202:203], 0, s[8:9]
	ds_read_b128 v[182:185], v148 offset:49152
	ds_read_b128 v[186:189], v148 offset:50176
	ds_read_b128 v[190:193], v148 offset:51200
	ds_read_b128 v[194:197], v148 offset:52224
	ds_read_b128 v[198:201], v148 offset:53248
	ds_read_b128 v[206:209], v148 offset:54272
	ds_read_b128 v[210:213], v148 offset:55296
	ds_read_b128 v[214:217], v148 offset:56320
	global_load_lds_dwordx4 v[202:203], off
	s_mov_b32 m0, s75
	v_lshl_add_u64 v[202:203], v[218:219], 0, s[8:9]
	global_load_lds_dwordx4 v[202:203], off
	s_mov_b32 m0, s76
	v_lshl_add_u64 v[202:203], s[44:45], 0, v[136:137]
	global_load_lds_dwordx4 v[202:203], off
	s_mov_b32 m0, s74
	v_lshl_add_u64 v[202:203], s[44:45], 0, v[134:135]
	global_load_lds_dwordx4 v[202:203], off
	s_mov_b32 m0, s28
	v_lshl_add_u64 v[202:203], v[220:221], 0, s[8:9]
	global_load_lds_dwordx4 v[202:203], off
	s_mov_b32 m0, s29
	v_lshl_add_u64 v[202:203], v[222:223], 0, s[8:9]
	global_load_lds_dwordx4 v[202:203], off
	s_nop 0
	s_waitcnt vmcnt(8) lgkmcnt(0)
	s_setprio 1
	s_barrier
	v_mfma_f32_16x16x32_bf16 v[62:65], v[150:153], v[182:185], v[62:65]
	v_mfma_f32_16x16x32_bf16 v[58:61], v[158:161], v[182:185], v[58:61]
	v_mfma_f32_16x16x32_bf16 v[54:57], v[150:153], v[190:193], v[54:57]
	v_mfma_f32_16x16x32_bf16 v[50:53], v[158:161], v[190:193], v[50:53]
	v_mfma_f32_16x16x32_bf16 v[38:41], v[150:153], v[198:201], v[38:41]
	v_mfma_f32_16x16x32_bf16 v[34:37], v[158:161], v[198:201], v[34:37]
	v_mfma_f32_16x16x32_bf16 v[22:25], v[150:153], v[210:213], v[22:25]
	v_mfma_f32_16x16x32_bf16 v[18:21], v[158:161], v[210:213], v[18:21]
	v_mfma_f32_16x16x32_bf16 v[62:65], v[154:157], v[186:189], v[62:65]
	v_mfma_f32_16x16x32_bf16 v[58:61], v[162:165], v[186:189], v[58:61]
	v_mfma_f32_16x16x32_bf16 v[54:57], v[154:157], v[194:197], v[54:57]
	v_mfma_f32_16x16x32_bf16 v[50:53], v[162:165], v[194:197], v[50:53]
	v_mfma_f32_16x16x32_bf16 v[38:41], v[154:157], v[206:209], v[38:41]
	v_mfma_f32_16x16x32_bf16 v[34:37], v[162:165], v[206:209], v[34:37]
	v_mfma_f32_16x16x32_bf16 v[22:25], v[154:157], v[214:217], v[22:25]
	v_mfma_f32_16x16x32_bf16 v[18:21], v[162:165], v[214:217], v[18:21]
	v_mfma_f32_16x16x32_bf16 v[46:49], v[166:169], v[182:185], v[46:49]
	v_mfma_f32_16x16x32_bf16 v[42:45], v[174:177], v[182:185], v[42:45]
	v_mfma_f32_16x16x32_bf16 v[30:33], v[166:169], v[190:193], v[30:33]
	v_mfma_f32_16x16x32_bf16 v[26:29], v[174:177], v[190:193], v[26:29]
	v_mfma_f32_16x16x32_bf16 v[14:17], v[166:169], v[198:201], v[14:17]
	v_mfma_f32_16x16x32_bf16 v[10:13], v[174:177], v[198:201], v[10:13]
	v_mfma_f32_16x16x32_bf16 v[6:9], v[166:169], v[210:213], v[6:9]
	v_mfma_f32_16x16x32_bf16 v[2:5], v[174:177], v[210:213], v[2:5]
	v_mfma_f32_16x16x32_bf16 v[46:49], v[170:173], v[186:189], v[46:49]
	v_mfma_f32_16x16x32_bf16 v[42:45], v[178:181], v[186:189], v[42:45]
	v_mfma_f32_16x16x32_bf16 v[30:33], v[170:173], v[194:197], v[30:33]
	v_mfma_f32_16x16x32_bf16 v[26:29], v[178:181], v[194:197], v[26:29]
	v_mfma_f32_16x16x32_bf16 v[14:17], v[170:173], v[206:209], v[14:17]
	v_mfma_f32_16x16x32_bf16 v[10:13], v[178:181], v[206:209], v[10:13]
	v_mfma_f32_16x16x32_bf16 v[6:9], v[170:173], v[214:217], v[6:9]
	v_mfma_f32_16x16x32_bf16 v[2:5], v[178:181], v[214:217], v[2:5]
	s_setprio 0
	s_barrier
	s_movk_i32 s46, 0x100
	s_andn2_b64 vcc, exec, s[42:43]
	s_mov_b64 s[44:45], -1
	s_mov_b64 s[42:43], 0
	s_cbranch_vccz .LBB0_297
	s_and_b64 vcc, exec, s[10:11]
	s_cbranch_vccz .LBB0_300
	s_barrier

.LBB0_313:
	s_add_u32 s49, s38, s48
	s_addc_u32 s68, s39, 0
	s_add_u32 s66, s49, 0x100
	s_addc_u32 s67, s68, 0
	s_and_b64 s[64:65], s[46:47], exec
	s_cselect_b32 s65, s43, s67
	s_cselect_b32 s64, s75, s66
	s_add_u32 s48, s36, s48
	s_addc_u32 s66, s37, 0
	s_add_u32 s48, s48, 0x100
	s_addc_u32 s66, s66, 0
	s_and_b64 s[46:47], s[46:47], exec
	s_cselect_b32 s67, s76, s66
	s_cselect_b32 s66, s77, s48
	s_add_u32 s70, s49, 0x10080
	ds_read_b128 v[144:147], v140
	ds_read_b128 v[148:151], v140 offset:1024
	ds_read_b128 v[152:155], v140 offset:2048
	ds_read_b128 v[156:159], v140 offset:3072
	ds_read_b128 v[160:163], v141
	ds_read_b128 v[164:167], v141 offset:1024
	ds_read_b128 v[168:171], v141 offset:2048
	ds_read_b128 v[172:175], v141 offset:3072
	s_addc_u32 s71, s68, 0
	s_add_i32 s87, s33, s2
	s_add_i32 m0, s16, 0xc000
	s_add_i32 s88, s16, 0xe000
	s_add_i32 s84, s87, 0x2000
	s_add_u32 s68, s66, 0x1000
	s_addc_u32 s69, s67, 0
	s_add_i32 s86, s34, s2
	s_add_i32 s85, s86, 0x2000
	s_add_i32 s83, 0, 0x18000
	s_add_i32 s82, 0, 0x1c000
	s_add_u32 s48, s64, 0x10000
	s_addc_u32 s49, s65, 0
	s_add_i32 s81, s83, s2
	s_add_i32 s79, s81, 0x2000
	s_add_u32 s46, s66, 0x1080
	s_addc_u32 s47, s67, 0
	s_add_i32 s80, s82, s2
	s_add_i32 s78, s80, 0x2000
	v_lshl_add_u64 v[210:211], s[70:71], 0, v[130:131]
	ds_read_b128 v[176:179], v142
	ds_read_b128 v[180:183], v142 offset:1024
	ds_read_b128 v[184:187], v142 offset:2048
	ds_read_b128 v[188:191], v142 offset:3072
	ds_read_b128 v[192:195], v142 offset:4096
	ds_read_b128 v[196:199], v142 offset:5120
	ds_read_b128 v[200:203], v142 offset:6144
	ds_read_b128 v[206:209], v142 offset:7168
	global_load_lds_dwordx4 v[210:211], off
	s_mov_b32 m0, s88
	v_lshl_add_u64 v[210:211], s[70:71], 0, v[132:133]
	global_load_lds_dwordx4 v[210:211], off
	s_waitcnt vmcnt(8) lgkmcnt(0)
	s_setprio 1
	s_barrier
	v_mfma_f32_16x16x32_bf16 v[126:129], v[144:147], v[176:179], v[126:129]
	v_mfma_f32_16x16x32_bf16 v[122:125], v[152:155], v[176:179], v[122:125]
	v_mfma_f32_16x16x32_bf16 v[118:121], v[144:147], v[184:187], v[118:121]
	v_mfma_f32_16x16x32_bf16 v[114:117], v[152:155], v[184:187], v[114:117]
	v_mfma_f32_16x16x32_bf16 v[102:105], v[144:147], v[192:195], v[102:105]
	v_mfma_f32_16x16x32_bf16 v[98:101], v[152:155], v[192:195], v[98:101]
	v_mfma_f32_16x16x32_bf16 v[86:89], v[144:147], v[200:203], v[86:89]
	v_mfma_f32_16x16x32_bf16 v[82:85], v[152:155], v[200:203], v[82:85]
	v_mfma_f32_16x16x32_bf16 v[126:129], v[148:151], v[180:183], v[126:129]
	v_mfma_f32_16x16x32_bf16 v[122:125], v[156:159], v[180:183], v[122:125]
	v_mfma_f32_16x16x32_bf16 v[118:121], v[148:151], v[188:191], v[118:121]
	v_mfma_f32_16x16x32_bf16 v[114:117], v[156:159], v[188:191], v[114:117]
	v_mfma_f32_16x16x32_bf16 v[102:105], v[148:151], v[196:199], v[102:105]
	v_mfma_f32_16x16x32_bf16 v[98:101], v[156:159], v[196:199], v[98:101]
	v_mfma_f32_16x16x32_bf16 v[86:89], v[148:151], v[206:209], v[86:89]
	v_mfma_f32_16x16x32_bf16 v[82:85], v[156:159], v[206:209], v[82:85]
	v_mfma_f32_16x16x32_bf16 v[110:113], v[160:163], v[176:179], v[110:113]
	v_mfma_f32_16x16x32_bf16 v[106:109], v[168:171], v[176:179], v[106:109]
	v_mfma_f32_16x16x32_bf16 v[94:97], v[160:163], v[184:187], v[94:97]
	v_mfma_f32_16x16x32_bf16 v[90:93], v[168:171], v[184:187], v[90:93]
	v_mfma_f32_16x16x32_bf16 v[78:81], v[160:163], v[192:195], v[78:81]
	v_mfma_f32_16x16x32_bf16 v[74:77], v[168:171], v[192:195], v[74:77]
	v_mfma_f32_16x16x32_bf16 v[70:73], v[160:163], v[200:203], v[70:73]
	v_mfma_f32_16x16x32_bf16 v[66:69], v[168:171], v[200:203], v[66:69]
	v_mfma_f32_16x16x32_bf16 v[110:113], v[164:167], v[180:183], v[110:113]
	v_mfma_f32_16x16x32_bf16 v[106:109], v[172:175], v[180:183], v[106:109]
	v_mfma_f32_16x16x32_bf16 v[94:97], v[164:167], v[188:191], v[94:97]
	v_mfma_f32_16x16x32_bf16 v[90:93], v[172:175], v[188:191], v[90:93]
	v_mfma_f32_16x16x32_bf16 v[78:81], v[164:167], v[196:199], v[78:81]
	v_mfma_f32_16x16x32_bf16 v[74:77], v[172:175], v[196:199], v[74:77]
	v_mfma_f32_16x16x32_bf16 v[70:73], v[164:167], v[206:209], v[70:73]
	v_mfma_f32_16x16x32_bf16 v[66:69], v[172:175], v[206:209], v[66:69]
	s_setprio 0
	s_barrier
	s_mov_b32 m0, s87
	v_lshl_add_u64 v[210:211], s[66:67], 0, v[136:137]
	ds_read_b128 v[176:179], v142 offset:16384
	ds_read_b128 v[180:183], v142 offset:17408
	ds_read_b128 v[184:187], v142 offset:18432
	ds_read_b128 v[188:191], v142 offset:19456
	ds_read_b128 v[192:195], v142 offset:20480
	ds_read_b128 v[196:199], v142 offset:21504
	ds_read_b128 v[200:203], v142 offset:22528
	ds_read_b128 v[206:209], v142 offset:23552
	global_load_lds_dwordx4 v[210:211], off
	v_lshl_add_u64 v[212:213], s[66:67], 0, v[134:135]
	s_mov_b32 m0, s84
	v_lshl_add_u64 v[214:215], s[68:69], 0, v[136:137]
	global_load_lds_dwordx4 v[212:213], off
	s_mov_b32 m0, s86
	v_lshl_add_u64 v[216:217], s[64:65], 0, v[132:133]
	global_load_lds_dwordx4 v[214:215], off
	s_mov_b32 m0, s85
	v_lshl_add_u64 v[214:215], s[68:69], 0, v[134:135]
	global_load_lds_dwordx4 v[214:215], off
	s_mov_b32 m0, s16
	v_lshl_add_u64 v[214:215], s[64:65], 0, v[130:131]
	global_load_lds_dwordx4 v[214:215], off
	s_mov_b32 m0, s17
	s_nop 0
	global_load_lds_dwordx4 v[216:217], off
	s_waitcnt vmcnt(8) lgkmcnt(0)
	s_setprio 1
	s_barrier
	v_mfma_f32_16x16x32_bf16 v[62:65], v[144:147], v[176:179], v[62:65]
	v_mfma_f32_16x16x32_bf16 v[58:61], v[152:155], v[176:179], v[58:61]
	v_mfma_f32_16x16x32_bf16 v[54:57], v[144:147], v[184:187], v[54:57]
	v_mfma_f32_16x16x32_bf16 v[50:53], v[152:155], v[184:187], v[50:53]
	v_mfma_f32_16x16x32_bf16 v[38:41], v[144:147], v[192:195], v[38:41]
	v_mfma_f32_16x16x32_bf16 v[34:37], v[152:155], v[192:195], v[34:37]
	v_mfma_f32_16x16x32_bf16 v[22:25], v[144:147], v[200:203], v[22:25]
	v_mfma_f32_16x16x32_bf16 v[18:21], v[152:155], v[200:203], v[18:21]
	v_mfma_f32_16x16x32_bf16 v[62:65], v[148:151], v[180:183], v[62:65]
	v_mfma_f32_16x16x32_bf16 v[58:61], v[156:159], v[180:183], v[58:61]
	v_mfma_f32_16x16x32_bf16 v[54:57], v[148:151], v[188:191], v[54:57]
	v_mfma_f32_16x16x32_bf16 v[50:53], v[156:159], v[188:191], v[50:53]
	v_mfma_f32_16x16x32_bf16 v[38:41], v[148:151], v[196:199], v[38:41]
	v_mfma_f32_16x16x32_bf16 v[34:37], v[156:159], v[196:199], v[34:37]
	v_mfma_f32_16x16x32_bf16 v[22:25], v[148:151], v[206:209], v[22:25]
	v_mfma_f32_16x16x32_bf16 v[18:21], v[156:159], v[206:209], v[18:21]
	v_mfma_f32_16x16x32_bf16 v[46:49], v[160:163], v[176:179], v[46:49]
	v_mfma_f32_16x16x32_bf16 v[42:45], v[168:171], v[176:179], v[42:45]
	v_mfma_f32_16x16x32_bf16 v[30:33], v[160:163], v[184:187], v[30:33]
	v_mfma_f32_16x16x32_bf16 v[26:29], v[168:171], v[184:187], v[26:29]
	v_mfma_f32_16x16x32_bf16 v[14:17], v[160:163], v[192:195], v[14:17]
	v_mfma_f32_16x16x32_bf16 v[10:13], v[168:171], v[192:195], v[10:13]
	v_mfma_f32_16x16x32_bf16 v[6:9], v[160:163], v[200:203], v[6:9]
	v_mfma_f32_16x16x32_bf16 v[2:5], v[168:171], v[200:203], v[2:5]
	v_mfma_f32_16x16x32_bf16 v[46:49], v[164:167], v[180:183], v[46:49]
	v_mfma_f32_16x16x32_bf16 v[42:45], v[172:175], v[180:183], v[42:45]
	v_mfma_f32_16x16x32_bf16 v[30:33], v[164:167], v[188:191], v[30:33]
	v_mfma_f32_16x16x32_bf16 v[26:29], v[172:175], v[188:191], v[26:29]
	v_mfma_f32_16x16x32_bf16 v[14:17], v[164:167], v[196:199], v[14:17]
	v_mfma_f32_16x16x32_bf16 v[10:13], v[172:175], v[196:199], v[10:13]
	v_mfma_f32_16x16x32_bf16 v[6:9], v[164:167], v[206:209], v[6:9]
	v_mfma_f32_16x16x32_bf16 v[2:5], v[172:175], v[206:209], v[2:5]
	s_setprio 0
	s_barrier
	v_add_u32_e32 v143, s83, v139
	ds_read_b128 v[144:147], v143
	ds_read_b128 v[148:151], v143 offset:1024
	ds_read_b128 v[152:155], v143 offset:2048
	ds_read_b128 v[156:159], v143 offset:3072
	v_add_u32_e32 v143, s82, v139
	ds_read_b128 v[160:163], v143
	ds_read_b128 v[164:167], v143 offset:1024
	ds_read_b128 v[168:171], v143 offset:2048
	ds_read_b128 v[172:175], v143 offset:3072
	s_mov_b32 m0, s18
	v_lshl_add_u64 v[218:219], s[48:49], 0, v[130:131]
	ds_read_b128 v[176:179], v142 offset:32768
	ds_read_b128 v[180:183], v142 offset:33792
	ds_read_b128 v[184:187], v142 offset:34816
	ds_read_b128 v[188:191], v142 offset:35840
	ds_read_b128 v[192:195], v142 offset:36864
	ds_read_b128 v[196:199], v142 offset:37888
	ds_read_b128 v[200:203], v142 offset:38912
	ds_read_b128 v[206:209], v142 offset:39936
	global_load_lds_dwordx4 v[218:219], off
	s_mov_b32 m0, s19
	v_lshl_add_u64 v[218:219], s[48:49], 0, v[132:133]
	global_load_lds_dwordx4 v[218:219], off
	s_nop 0
	s_waitcnt vmcnt(8) lgkmcnt(0)
	s_setprio 1
	s_barrier
	v_mfma_f32_16x16x32_bf16 v[126:129], v[144:147], v[176:179], v[126:129]
	v_mfma_f32_16x16x32_bf16 v[122:125], v[152:155], v[176:179], v[122:125]
	v_mfma_f32_16x16x32_bf16 v[118:121], v[144:147], v[184:187], v[118:121]
	v_mfma_f32_16x16x32_bf16 v[114:117], v[152:155], v[184:187], v[114:117]
	v_mfma_f32_16x16x32_bf16 v[102:105], v[144:147], v[192:195], v[102:105]
	v_mfma_f32_16x16x32_bf16 v[98:101], v[152:155], v[192:195], v[98:101]
	v_mfma_f32_16x16x32_bf16 v[86:89], v[144:147], v[200:203], v[86:89]
	v_mfma_f32_16x16x32_bf16 v[82:85], v[152:155], v[200:203], v[82:85]
	v_mfma_f32_16x16x32_bf16 v[126:129], v[148:151], v[180:183], v[126:129]
	v_mfma_f32_16x16x32_bf16 v[122:125], v[156:159], v[180:183], v[122:125]
	v_mfma_f32_16x16x32_bf16 v[118:121], v[148:151], v[188:191], v[118:121]
	v_mfma_f32_16x16x32_bf16 v[114:117], v[156:159], v[188:191], v[114:117]
	v_mfma_f32_16x16x32_bf16 v[102:105], v[148:151], v[196:199], v[102:105]
	v_mfma_f32_16x16x32_bf16 v[98:101], v[156:159], v[196:199], v[98:101]
	v_mfma_f32_16x16x32_bf16 v[86:89], v[148:151], v[206:209], v[86:89]
	v_mfma_f32_16x16x32_bf16 v[82:85], v[156:159], v[206:209], v[82:85]
	v_mfma_f32_16x16x32_bf16 v[110:113], v[160:163], v[176:179], v[110:113]
	v_mfma_f32_16x16x32_bf16 v[106:109], v[168:171], v[176:179], v[106:109]
	v_mfma_f32_16x16x32_bf16 v[94:97], v[160:163], v[184:187], v[94:97]
	v_mfma_f32_16x16x32_bf16 v[90:93], v[168:171], v[184:187], v[90:93]
	v_mfma_f32_16x16x32_bf16 v[78:81], v[160:163], v[192:195], v[78:81]
	v_mfma_f32_16x16x32_bf16 v[74:77], v[168:171], v[192:195], v[74:77]
	v_mfma_f32_16x16x32_bf16 v[70:73], v[160:163], v[200:203], v[70:73]
	v_mfma_f32_16x16x32_bf16 v[66:69], v[168:171], v[200:203], v[66:69]
	v_mfma_f32_16x16x32_bf16 v[110:113], v[164:167], v[180:183], v[110:113]
	v_mfma_f32_16x16x32_bf16 v[106:109], v[172:175], v[180:183], v[106:109]
	v_mfma_f32_16x16x32_bf16 v[94:97], v[164:167], v[188:191], v[94:97]
	v_mfma_f32_16x16x32_bf16 v[90:93], v[172:175], v[188:191], v[90:93]
	v_mfma_f32_16x16x32_bf16 v[78:81], v[164:167], v[196:199], v[78:81]
	v_mfma_f32_16x16x32_bf16 v[74:77], v[172:175], v[196:199], v[74:77]
	v_mfma_f32_16x16x32_bf16 v[70:73], v[164:167], v[206:209], v[70:73]
	v_mfma_f32_16x16x32_bf16 v[66:69], v[172:175], v[206:209], v[66:69]
	s_setprio 0
	s_barrier
	s_mov_b32 m0, s81
	v_lshl_add_u64 v[210:211], v[210:211], 0, s[8:9]
	ds_read_b128 v[176:179], v142 offset:49152
	ds_read_b128 v[180:183], v142 offset:50176
	ds_read_b128 v[184:187], v142 offset:51200
	ds_read_b128 v[188:191], v142 offset:52224
	ds_read_b128 v[192:195], v142 offset:53248
	ds_read_b128 v[196:199], v142 offset:54272
	ds_read_b128 v[200:203], v142 offset:55296
	ds_read_b128 v[206:209], v142 offset:56320
	global_load_lds_dwordx4 v[210:211], off
	s_mov_b32 m0, s79
	v_lshl_add_u64 v[210:211], v[212:213], 0, s[8:9]
	global_load_lds_dwordx4 v[210:211], off
	s_mov_b32 m0, s80
	v_lshl_add_u64 v[210:211], s[46:47], 0, v[136:137]
	global_load_lds_dwordx4 v[210:211], off
	s_mov_b32 m0, s78
	v_lshl_add_u64 v[210:211], s[46:47], 0, v[134:135]
	global_load_lds_dwordx4 v[210:211], off
	s_mov_b32 m0, s30
	v_lshl_add_u64 v[210:211], v[214:215], 0, s[8:9]
	global_load_lds_dwordx4 v[210:211], off
	s_mov_b32 m0, s31
	v_lshl_add_u64 v[210:211], v[216:217], 0, s[8:9]
	global_load_lds_dwordx4 v[210:211], off
	s_nop 0
	s_waitcnt vmcnt(8) lgkmcnt(0)
	s_setprio 1
	s_barrier
	v_mfma_f32_16x16x32_bf16 v[62:65], v[144:147], v[176:179], v[62:65]
	v_mfma_f32_16x16x32_bf16 v[58:61], v[152:155], v[176:179], v[58:61]
	v_mfma_f32_16x16x32_bf16 v[54:57], v[144:147], v[184:187], v[54:57]
	v_mfma_f32_16x16x32_bf16 v[50:53], v[152:155], v[184:187], v[50:53]
	v_mfma_f32_16x16x32_bf16 v[38:41], v[144:147], v[192:195], v[38:41]
	v_mfma_f32_16x16x32_bf16 v[34:37], v[152:155], v[192:195], v[34:37]
	v_mfma_f32_16x16x32_bf16 v[22:25], v[144:147], v[200:203], v[22:25]
	v_mfma_f32_16x16x32_bf16 v[18:21], v[152:155], v[200:203], v[18:21]
	v_mfma_f32_16x16x32_bf16 v[62:65], v[148:151], v[180:183], v[62:65]
	v_mfma_f32_16x16x32_bf16 v[58:61], v[156:159], v[180:183], v[58:61]
	v_mfma_f32_16x16x32_bf16 v[54:57], v[148:151], v[188:191], v[54:57]
	v_mfma_f32_16x16x32_bf16 v[50:53], v[156:159], v[188:191], v[50:53]
	v_mfma_f32_16x16x32_bf16 v[38:41], v[148:151], v[196:199], v[38:41]
	v_mfma_f32_16x16x32_bf16 v[34:37], v[156:159], v[196:199], v[34:37]
	v_mfma_f32_16x16x32_bf16 v[22:25], v[148:151], v[206:209], v[22:25]
	v_mfma_f32_16x16x32_bf16 v[18:21], v[156:159], v[206:209], v[18:21]
	v_mfma_f32_16x16x32_bf16 v[46:49], v[160:163], v[176:179], v[46:49]
	v_mfma_f32_16x16x32_bf16 v[42:45], v[168:171], v[176:179], v[42:45]
	v_mfma_f32_16x16x32_bf16 v[30:33], v[160:163], v[184:187], v[30:33]
	v_mfma_f32_16x16x32_bf16 v[26:29], v[168:171], v[184:187], v[26:29]
	v_mfma_f32_16x16x32_bf16 v[14:17], v[160:163], v[192:195], v[14:17]
	v_mfma_f32_16x16x32_bf16 v[10:13], v[168:171], v[192:195], v[10:13]
	v_mfma_f32_16x16x32_bf16 v[6:9], v[160:163], v[200:203], v[6:9]
	v_mfma_f32_16x16x32_bf16 v[2:5], v[168:171], v[200:203], v[2:5]
	v_mfma_f32_16x16x32_bf16 v[46:49], v[164:167], v[180:183], v[46:49]
	v_mfma_f32_16x16x32_bf16 v[42:45], v[172:175], v[180:183], v[42:45]
	v_mfma_f32_16x16x32_bf16 v[30:33], v[164:167], v[188:191], v[30:33]
	v_mfma_f32_16x16x32_bf16 v[26:29], v[172:175], v[188:191], v[26:29]
	v_mfma_f32_16x16x32_bf16 v[14:17], v[164:167], v[196:199], v[14:17]
	v_mfma_f32_16x16x32_bf16 v[10:13], v[172:175], v[196:199], v[10:13]
	v_mfma_f32_16x16x32_bf16 v[6:9], v[164:167], v[206:209], v[6:9]
	v_mfma_f32_16x16x32_bf16 v[2:5], v[172:175], v[206:209], v[2:5]
	s_setprio 0
	s_barrier
	s_movk_i32 s48, 0x100
	s_andn2_b64 vcc, exec, s[44:45]
	s_mov_b64 s[46:47], -1
	s_mov_b64 s[44:45], 0
	s_cbranch_vccz .LBB0_313
	s_and_b64 vcc, exec, s[10:11]
	s_cbranch_vccz .LBB0_316
	s_barrier

.LBB0_383:
	s_add_u32 s26, s0, s22
	s_addc_u32 s27, s1, s23
	s_and_b64 s[44:45], s[36:37], exec
	s_cselect_b32 s15, s27, s43
	s_cselect_b32 s39, s26, s42
	s_add_u32 s66, s42, 0x100
	s_addc_u32 s67, s43, 0
	s_mov_b32 s68, -2
	s_mov_b64 s[42:43], 0
	ds_read_b128 v[152:155], v146
	ds_read_b128 v[156:159], v146 offset:1024
	ds_read_b128 v[160:163], v146 offset:2048
	ds_read_b128 v[164:167], v146 offset:3072
	ds_read_b128 v[168:171], v147
	ds_read_b128 v[172:175], v147 offset:1024
	ds_read_b128 v[176:179], v147 offset:2048
	ds_read_b128 v[180:183], v147 offset:3072
	s_add_u32 s44, s42, 0x100
	s_addc_u32 s45, s43, 0
	s_add_u32 s46, s66, s42
	s_addc_u32 s47, s67, s43
	s_cmp_eq_u32 s68, 4
	s_cselect_b32 s48, 0, s44
	s_cselect_b32 s49, 0, s45
	s_cselect_b32 s46, s39, s46
	s_cselect_b32 s47, s15, s47
	s_add_u32 s48, s6, s48
	s_addc_u32 s49, s7, s49
	s_mov_b32 m0, s29
	v_lshl_add_u64 v[218:219], v[138:139], 0, s[42:43]
	ds_read_b128 v[184:187], v148
	ds_read_b128 v[188:191], v148 offset:1024
	ds_read_b128 v[192:195], v148 offset:2048
	ds_read_b128 v[196:199], v148 offset:3072
	ds_read_b128 v[200:203], v148 offset:4096
	ds_read_b128 v[206:209], v148 offset:5120
	ds_read_b128 v[210:213], v148 offset:6144
	ds_read_b128 v[214:217], v148 offset:7168
	global_load_lds_dwordx4 v[218:219], off
	s_mov_b32 m0, s30
	v_lshl_add_u64 v[218:219], v[140:141], 0, s[42:43]
	global_load_lds_dwordx4 v[218:219], off
	s_waitcnt vmcnt(8) lgkmcnt(0)
	s_setprio 1
	s_barrier
	v_mfma_f32_16x16x32_bf16 v[126:129], v[152:155], v[184:187], 0
	v_mfma_f32_16x16x32_bf16 v[122:125], v[160:163], v[184:187], 0
	v_mfma_f32_16x16x32_bf16 v[118:121], v[152:155], v[192:195], 0
	v_mfma_f32_16x16x32_bf16 v[114:117], v[160:163], v[192:195], 0
	v_mfma_f32_16x16x32_bf16 v[102:105], v[152:155], v[200:203], 0
	v_mfma_f32_16x16x32_bf16 v[98:101], v[160:163], v[200:203], 0
	v_mfma_f32_16x16x32_bf16 v[86:89], v[152:155], v[210:213], 0
	v_mfma_f32_16x16x32_bf16 v[82:85], v[160:163], v[210:213], 0
	v_mfma_f32_16x16x32_bf16 v[126:129], v[156:159], v[188:191], v[126:129]
	v_mfma_f32_16x16x32_bf16 v[122:125], v[164:167], v[188:191], v[122:125]
	v_mfma_f32_16x16x32_bf16 v[118:121], v[156:159], v[196:199], v[118:121]
	v_mfma_f32_16x16x32_bf16 v[114:117], v[164:167], v[196:199], v[114:117]
	v_mfma_f32_16x16x32_bf16 v[102:105], v[156:159], v[206:209], v[102:105]
	v_mfma_f32_16x16x32_bf16 v[98:101], v[164:167], v[206:209], v[98:101]
	v_mfma_f32_16x16x32_bf16 v[86:89], v[156:159], v[214:217], v[86:89]
	v_mfma_f32_16x16x32_bf16 v[82:85], v[164:167], v[214:217], v[82:85]
	v_mfma_f32_16x16x32_bf16 v[110:113], v[168:171], v[184:187], 0
	v_mfma_f32_16x16x32_bf16 v[106:109], v[176:179], v[184:187], 0
	v_mfma_f32_16x16x32_bf16 v[94:97], v[168:171], v[192:195], 0
	v_mfma_f32_16x16x32_bf16 v[90:93], v[176:179], v[192:195], 0
	v_mfma_f32_16x16x32_bf16 v[78:81], v[168:171], v[200:203], 0
	v_mfma_f32_16x16x32_bf16 v[74:77], v[176:179], v[200:203], 0
	v_mfma_f32_16x16x32_bf16 v[70:73], v[168:171], v[210:213], 0
	v_mfma_f32_16x16x32_bf16 v[66:69], v[176:179], v[210:213], 0
	v_mfma_f32_16x16x32_bf16 v[110:113], v[172:175], v[188:191], v[110:113]
	v_mfma_f32_16x16x32_bf16 v[106:109], v[180:183], v[188:191], v[106:109]
	v_mfma_f32_16x16x32_bf16 v[94:97], v[172:175], v[196:199], v[94:97]
	v_mfma_f32_16x16x32_bf16 v[90:93], v[180:183], v[196:199], v[90:93]
	v_mfma_f32_16x16x32_bf16 v[78:81], v[172:175], v[206:209], v[78:81]
	v_mfma_f32_16x16x32_bf16 v[74:77], v[180:183], v[206:209], v[74:77]
	v_mfma_f32_16x16x32_bf16 v[70:73], v[172:175], v[214:217], v[70:73]
	v_mfma_f32_16x16x32_bf16 v[66:69], v[180:183], v[214:217], v[66:69]
	s_setprio 0
	s_barrier
	s_mov_b32 m0, s31
	v_lshl_add_u64 v[218:219], s[46:47], 0, v[134:135]
	s_add_u32 s42, s46, 0x20000
	ds_read_b128 v[184:187], v148 offset:16384
	ds_read_b128 v[188:191], v148 offset:17408
	ds_read_b128 v[192:195], v148 offset:18432
	ds_read_b128 v[196:199], v148 offset:19456
	ds_read_b128 v[200:203], v148 offset:20480
	ds_read_b128 v[206:209], v148 offset:21504
	ds_read_b128 v[210:213], v148 offset:22528
	ds_read_b128 v[214:217], v148 offset:23552
	global_load_lds_dwordx4 v[218:219], off
	v_lshl_add_u64 v[220:221], s[46:47], 0, v[130:131]
	s_mov_b32 m0, s33
	s_addc_u32 s43, s47, 0
	global_load_lds_dwordx4 v[220:221], off
	v_lshl_add_u64 v[222:223], s[42:43], 0, v[134:135]
	s_mov_b32 m0, s34
	v_lshl_add_u64 v[224:225], s[48:49], 0, v[132:133]
	global_load_lds_dwordx4 v[222:223], off
	s_mov_b32 m0, s35
	v_lshl_add_u64 v[222:223], s[42:43], 0, v[130:131]
	global_load_lds_dwordx4 v[222:223], off
	s_mov_b32 m0, s2
	v_lshl_add_u64 v[222:223], s[48:49], 0, v[136:137]
	global_load_lds_dwordx4 v[222:223], off
	s_mov_b32 m0, s3
	s_nop 0
	global_load_lds_dwordx4 v[224:225], off
	s_nop 0
	s_waitcnt vmcnt(8) lgkmcnt(0)
	s_setprio 1
	s_barrier
	v_mfma_f32_16x16x32_bf16 v[62:65], v[152:155], v[184:187], 0
	v_mfma_f32_16x16x32_bf16 v[58:61], v[160:163], v[184:187], 0
	v_mfma_f32_16x16x32_bf16 v[54:57], v[152:155], v[192:195], 0
	v_mfma_f32_16x16x32_bf16 v[50:53], v[160:163], v[192:195], 0
	v_mfma_f32_16x16x32_bf16 v[38:41], v[152:155], v[200:203], 0
	v_mfma_f32_16x16x32_bf16 v[34:37], v[160:163], v[200:203], 0
	v_mfma_f32_16x16x32_bf16 v[22:25], v[152:155], v[210:213], 0
	v_mfma_f32_16x16x32_bf16 v[18:21], v[160:163], v[210:213], 0
	v_mfma_f32_16x16x32_bf16 v[62:65], v[156:159], v[188:191], v[62:65]
	v_mfma_f32_16x16x32_bf16 v[58:61], v[164:167], v[188:191], v[58:61]
	v_mfma_f32_16x16x32_bf16 v[54:57], v[156:159], v[196:199], v[54:57]
	v_mfma_f32_16x16x32_bf16 v[50:53], v[164:167], v[196:199], v[50:53]
	v_mfma_f32_16x16x32_bf16 v[38:41], v[156:159], v[206:209], v[38:41]
	v_mfma_f32_16x16x32_bf16 v[34:37], v[164:167], v[206:209], v[34:37]
	v_mfma_f32_16x16x32_bf16 v[22:25], v[156:159], v[214:217], v[22:25]
	v_mfma_f32_16x16x32_bf16 v[18:21], v[164:167], v[214:217], v[18:21]
	v_mfma_f32_16x16x32_bf16 v[46:49], v[168:171], v[184:187], 0
	v_mfma_f32_16x16x32_bf16 v[42:45], v[176:179], v[184:187], 0
	v_mfma_f32_16x16x32_bf16 v[30:33], v[168:171], v[192:195], 0
	v_mfma_f32_16x16x32_bf16 v[26:29], v[176:179], v[192:195], 0
	v_mfma_f32_16x16x32_bf16 v[14:17], v[168:171], v[200:203], 0
	v_mfma_f32_16x16x32_bf16 v[10:13], v[176:179], v[200:203], 0
	v_mfma_f32_16x16x32_bf16 v[6:9], v[168:171], v[210:213], 0
	v_mfma_f32_16x16x32_bf16 v[2:5], v[176:179], v[210:213], 0
	v_mfma_f32_16x16x32_bf16 v[46:49], v[172:175], v[188:191], v[46:49]
	v_mfma_f32_16x16x32_bf16 v[42:45], v[180:183], v[188:191], v[42:45]
	v_mfma_f32_16x16x32_bf16 v[30:33], v[172:175], v[196:199], v[30:33]
	v_mfma_f32_16x16x32_bf16 v[26:29], v[180:183], v[196:199], v[26:29]
	v_mfma_f32_16x16x32_bf16 v[14:17], v[172:175], v[206:209], v[14:17]
	v_mfma_f32_16x16x32_bf16 v[10:13], v[180:183], v[206:209], v[10:13]
	v_mfma_f32_16x16x32_bf16 v[6:9], v[172:175], v[214:217], v[6:9]
	v_mfma_f32_16x16x32_bf16 v[2:5], v[180:183], v[214:217], v[2:5]
	s_setprio 0
	s_barrier
	ds_read_b128 v[152:155], v149
	ds_read_b128 v[156:159], v149 offset:1024
	ds_read_b128 v[160:163], v149 offset:2048
	ds_read_b128 v[164:167], v149 offset:3072
	ds_read_b128 v[168:171], v150
	ds_read_b128 v[172:175], v150 offset:1024
	ds_read_b128 v[176:179], v150 offset:2048
	ds_read_b128 v[180:183], v150 offset:3072
	s_add_u32 s42, s48, 0x20000
	s_addc_u32 s43, s49, 0
	s_mov_b32 m0, s16
	v_lshl_add_u64 v[226:227], s[42:43], 0, v[136:137]
	ds_read_b128 v[184:187], v148 offset:32768
	ds_read_b128 v[188:191], v148 offset:33792
	ds_read_b128 v[192:195], v148 offset:34816
	ds_read_b128 v[196:199], v148 offset:35840
	ds_read_b128 v[200:203], v148 offset:36864
	ds_read_b128 v[206:209], v148 offset:37888
	ds_read_b128 v[210:213], v148 offset:38912
	ds_read_b128 v[214:217], v148 offset:39936
	global_load_lds_dwordx4 v[226:227], off
	s_mov_b32 m0, s17
	v_lshl_add_u64 v[226:227], s[42:43], 0, v[132:133]
	global_load_lds_dwordx4 v[226:227], off
	s_waitcnt vmcnt(8) lgkmcnt(0)
	s_setprio 1
	s_barrier
	v_mfma_f32_16x16x32_bf16 v[126:129], v[152:155], v[184:187], v[126:129]
	v_mfma_f32_16x16x32_bf16 v[122:125], v[160:163], v[184:187], v[122:125]
	v_mfma_f32_16x16x32_bf16 v[118:121], v[152:155], v[192:195], v[118:121]
	v_mfma_f32_16x16x32_bf16 v[114:117], v[160:163], v[192:195], v[114:117]
	v_mfma_f32_16x16x32_bf16 v[102:105], v[152:155], v[200:203], v[102:105]
	v_mfma_f32_16x16x32_bf16 v[98:101], v[160:163], v[200:203], v[98:101]
	v_mfma_f32_16x16x32_bf16 v[86:89], v[152:155], v[210:213], v[86:89]
	v_mfma_f32_16x16x32_bf16 v[82:85], v[160:163], v[210:213], v[82:85]
	v_mfma_f32_16x16x32_bf16 v[126:129], v[156:159], v[188:191], v[126:129]
	v_mfma_f32_16x16x32_bf16 v[122:125], v[164:167], v[188:191], v[122:125]
	v_mfma_f32_16x16x32_bf16 v[118:121], v[156:159], v[196:199], v[118:121]
	v_mfma_f32_16x16x32_bf16 v[114:117], v[164:167], v[196:199], v[114:117]
	v_mfma_f32_16x16x32_bf16 v[102:105], v[156:159], v[206:209], v[102:105]
	v_mfma_f32_16x16x32_bf16 v[98:101], v[164:167], v[206:209], v[98:101]
	v_mfma_f32_16x16x32_bf16 v[86:89], v[156:159], v[214:217], v[86:89]
	v_mfma_f32_16x16x32_bf16 v[82:85], v[164:167], v[214:217], v[82:85]
	v_mfma_f32_16x16x32_bf16 v[110:113], v[168:171], v[184:187], v[110:113]
	v_mfma_f32_16x16x32_bf16 v[106:109], v[176:179], v[184:187], v[106:109]
	v_mfma_f32_16x16x32_bf16 v[94:97], v[168:171], v[192:195], v[94:97]
	v_mfma_f32_16x16x32_bf16 v[90:93], v[176:179], v[192:195], v[90:93]
	v_mfma_f32_16x16x32_bf16 v[78:81], v[168:171], v[200:203], v[78:81]
	v_mfma_f32_16x16x32_bf16 v[74:77], v[176:179], v[200:203], v[74:77]
	v_mfma_f32_16x16x32_bf16 v[70:73], v[168:171], v[210:213], v[70:73]
	v_mfma_f32_16x16x32_bf16 v[66:69], v[176:179], v[210:213], v[66:69]
	v_mfma_f32_16x16x32_bf16 v[110:113], v[172:175], v[188:191], v[110:113]
	v_mfma_f32_16x16x32_bf16 v[106:109], v[180:183], v[188:191], v[106:109]
	v_mfma_f32_16x16x32_bf16 v[94:97], v[172:175], v[196:199], v[94:97]
	v_mfma_f32_16x16x32_bf16 v[90:93], v[180:183], v[196:199], v[90:93]
	v_mfma_f32_16x16x32_bf16 v[78:81], v[172:175], v[206:209], v[78:81]
	v_mfma_f32_16x16x32_bf16 v[74:77], v[180:183], v[206:209], v[74:77]
	v_mfma_f32_16x16x32_bf16 v[70:73], v[172:175], v[214:217], v[70:73]
	v_mfma_f32_16x16x32_bf16 v[66:69], v[180:183], v[214:217], v[66:69]
	s_setprio 0
	s_barrier
	s_mov_b32 m0, s62
	v_lshl_add_u64 v[218:219], v[218:219], 0, s[10:11]
	s_add_u32 s42, s46, 0x20080
	ds_read_b128 v[184:187], v148 offset:49152
	ds_read_b128 v[188:191], v148 offset:50176
	ds_read_b128 v[192:195], v148 offset:51200
	ds_read_b128 v[196:199], v148 offset:52224
	ds_read_b128 v[200:203], v148 offset:53248
	ds_read_b128 v[206:209], v148 offset:54272
	ds_read_b128 v[210:213], v148 offset:55296
	ds_read_b128 v[214:217], v148 offset:56320
	global_load_lds_dwordx4 v[218:219], off
	v_lshl_add_u64 v[218:219], v[220:221], 0, s[10:11]
	s_mov_b32 m0, s63
	s_addc_u32 s43, s47, 0
	global_load_lds_dwordx4 v[218:219], off
	s_mov_b32 m0, s64
	v_lshl_add_u64 v[218:219], s[42:43], 0, v[134:135]
	global_load_lds_dwordx4 v[218:219], off
	s_mov_b32 m0, s65
	v_lshl_add_u64 v[218:219], s[42:43], 0, v[130:131]
	global_load_lds_dwordx4 v[218:219], off
	s_mov_b32 m0, s25
	v_lshl_add_u64 v[218:219], v[222:223], 0, s[10:11]
	global_load_lds_dwordx4 v[218:219], off
	s_mov_b32 m0, s28
	v_lshl_add_u64 v[218:219], v[224:225], 0, s[10:11]
	global_load_lds_dwordx4 v[218:219], off
	s_waitcnt vmcnt(8) lgkmcnt(0)
	s_setprio 1
	s_barrier
	v_mfma_f32_16x16x32_bf16 v[62:65], v[152:155], v[184:187], v[62:65]
	v_mfma_f32_16x16x32_bf16 v[58:61], v[160:163], v[184:187], v[58:61]
	v_mfma_f32_16x16x32_bf16 v[54:57], v[152:155], v[192:195], v[54:57]
	v_mfma_f32_16x16x32_bf16 v[50:53], v[160:163], v[192:195], v[50:53]
	v_mfma_f32_16x16x32_bf16 v[38:41], v[152:155], v[200:203], v[38:41]
	v_mfma_f32_16x16x32_bf16 v[34:37], v[160:163], v[200:203], v[34:37]
	v_mfma_f32_16x16x32_bf16 v[22:25], v[152:155], v[210:213], v[22:25]
	v_mfma_f32_16x16x32_bf16 v[18:21], v[160:163], v[210:213], v[18:21]
	v_mfma_f32_16x16x32_bf16 v[62:65], v[156:159], v[188:191], v[62:65]
	v_mfma_f32_16x16x32_bf16 v[58:61], v[164:167], v[188:191], v[58:61]
	v_mfma_f32_16x16x32_bf16 v[54:57], v[156:159], v[196:199], v[54:57]
	v_mfma_f32_16x16x32_bf16 v[50:53], v[164:167], v[196:199], v[50:53]
	v_mfma_f32_16x16x32_bf16 v[38:41], v[156:159], v[206:209], v[38:41]
	v_mfma_f32_16x16x32_bf16 v[34:37], v[164:167], v[206:209], v[34:37]
	v_mfma_f32_16x16x32_bf16 v[22:25], v[156:159], v[214:217], v[22:25]
	v_mfma_f32_16x16x32_bf16 v[18:21], v[164:167], v[214:217], v[18:21]
	v_mfma_f32_16x16x32_bf16 v[46:49], v[168:171], v[184:187], v[46:49]
	v_mfma_f32_16x16x32_bf16 v[42:45], v[176:179], v[184:187], v[42:45]
	v_mfma_f32_16x16x32_bf16 v[30:33], v[168:171], v[192:195], v[30:33]
	v_mfma_f32_16x16x32_bf16 v[26:29], v[176:179], v[192:195], v[26:29]
	v_mfma_f32_16x16x32_bf16 v[14:17], v[168:171], v[200:203], v[14:17]
	v_mfma_f32_16x16x32_bf16 v[10:13], v[176:179], v[200:203], v[10:13]
	v_mfma_f32_16x16x32_bf16 v[6:9], v[168:171], v[210:213], v[6:9]
	v_mfma_f32_16x16x32_bf16 v[2:5], v[176:179], v[210:213], v[2:5]
	v_mfma_f32_16x16x32_bf16 v[46:49], v[172:175], v[188:191], v[46:49]
	v_mfma_f32_16x16x32_bf16 v[42:45], v[180:183], v[188:191], v[42:45]
	v_mfma_f32_16x16x32_bf16 v[30:33], v[172:175], v[196:199], v[30:33]
	v_mfma_f32_16x16x32_bf16 v[26:29], v[180:183], v[196:199], v[26:29]
	v_mfma_f32_16x16x32_bf16 v[14:17], v[172:175], v[206:209], v[14:17]
	v_mfma_f32_16x16x32_bf16 v[10:13], v[180:183], v[206:209], v[10:13]
	v_mfma_f32_16x16x32_bf16 v[6:9], v[172:175], v[214:217], v[6:9]
	v_mfma_f32_16x16x32_bf16 v[2:5], v[180:183], v[214:217], v[2:5]
	s_setprio 0
	s_barrier
	s_add_i32 s68, s68, 2
	s_cmp_gt_u32 s68, 5
	s_mov_b64 s[42:43], s[44:45]
.LBB0_384:
	ds_read_b128 v[152:155], v146
	ds_read_b128 v[156:159], v146 offset:1024
	ds_read_b128 v[160:163], v146 offset:2048
	ds_read_b128 v[164:167], v146 offset:3072
	ds_read_b128 v[168:171], v147
	ds_read_b128 v[172:175], v147 offset:1024
	ds_read_b128 v[176:179], v147 offset:2048
	ds_read_b128 v[180:183], v147 offset:3072
	s_add_u32 s44, s42, 0x100
	s_addc_u32 s45, s43, 0
	s_add_u32 s46, s66, s42
	s_addc_u32 s47, s67, s43
	s_cmp_eq_u32 s68, 4
	s_cselect_b32 s48, 0, s44
	s_cselect_b32 s49, 0, s45
	s_cselect_b32 s46, s39, s46
	s_cselect_b32 s47, s15, s47
	s_add_u32 s48, s6, s48
	s_addc_u32 s49, s7, s49
	s_mov_b32 m0, s29
	v_lshl_add_u64 v[218:219], v[138:139], 0, s[42:43]
	ds_read_b128 v[184:187], v148
	ds_read_b128 v[188:191], v148 offset:1024
	ds_read_b128 v[192:195], v148 offset:2048
	ds_read_b128 v[196:199], v148 offset:3072
	ds_read_b128 v[200:203], v148 offset:4096
	ds_read_b128 v[206:209], v148 offset:5120
	ds_read_b128 v[210:213], v148 offset:6144
	ds_read_b128 v[214:217], v148 offset:7168
	global_load_lds_dwordx4 v[218:219], off
	s_mov_b32 m0, s30
	v_lshl_add_u64 v[218:219], v[140:141], 0, s[42:43]
	global_load_lds_dwordx4 v[218:219], off
	s_waitcnt vmcnt(8) lgkmcnt(0)
	s_setprio 1
	s_barrier
	v_mfma_f32_16x16x32_bf16 v[126:129], v[152:155], v[184:187], v[126:129]
	v_mfma_f32_16x16x32_bf16 v[122:125], v[160:163], v[184:187], v[122:125]
	v_mfma_f32_16x16x32_bf16 v[118:121], v[152:155], v[192:195], v[118:121]
	v_mfma_f32_16x16x32_bf16 v[114:117], v[160:163], v[192:195], v[114:117]
	v_mfma_f32_16x16x32_bf16 v[102:105], v[152:155], v[200:203], v[102:105]
	v_mfma_f32_16x16x32_bf16 v[98:101], v[160:163], v[200:203], v[98:101]
	v_mfma_f32_16x16x32_bf16 v[86:89], v[152:155], v[210:213], v[86:89]
	v_mfma_f32_16x16x32_bf16 v[82:85], v[160:163], v[210:213], v[82:85]
	v_mfma_f32_16x16x32_bf16 v[126:129], v[156:159], v[188:191], v[126:129]
	v_mfma_f32_16x16x32_bf16 v[122:125], v[164:167], v[188:191], v[122:125]
	v_mfma_f32_16x16x32_bf16 v[118:121], v[156:159], v[196:199], v[118:121]
	v_mfma_f32_16x16x32_bf16 v[114:117], v[164:167], v[196:199], v[114:117]
	v_mfma_f32_16x16x32_bf16 v[102:105], v[156:159], v[206:209], v[102:105]
	v_mfma_f32_16x16x32_bf16 v[98:101], v[164:167], v[206:209], v[98:101]
	v_mfma_f32_16x16x32_bf16 v[86:89], v[156:159], v[214:217], v[86:89]
	v_mfma_f32_16x16x32_bf16 v[82:85], v[164:167], v[214:217], v[82:85]
	v_mfma_f32_16x16x32_bf16 v[110:113], v[168:171], v[184:187], v[110:113]
	v_mfma_f32_16x16x32_bf16 v[106:109], v[176:179], v[184:187], v[106:109]
	v_mfma_f32_16x16x32_bf16 v[94:97], v[168:171], v[192:195], v[94:97]
	v_mfma_f32_16x16x32_bf16 v[90:93], v[176:179], v[192:195], v[90:93]
	v_mfma_f32_16x16x32_bf16 v[78:81], v[168:171], v[200:203], v[78:81]
	v_mfma_f32_16x16x32_bf16 v[74:77], v[176:179], v[200:203], v[74:77]
	v_mfma_f32_16x16x32_bf16 v[70:73], v[168:171], v[210:213], v[70:73]
	v_mfma_f32_16x16x32_bf16 v[66:69], v[176:179], v[210:213], v[66:69]
	v_mfma_f32_16x16x32_bf16 v[110:113], v[172:175], v[188:191], v[110:113]
	v_mfma_f32_16x16x32_bf16 v[106:109], v[180:183], v[188:191], v[106:109]
	v_mfma_f32_16x16x32_bf16 v[94:97], v[172:175], v[196:199], v[94:97]
	v_mfma_f32_16x16x32_bf16 v[90:93], v[180:183], v[196:199], v[90:93]
	v_mfma_f32_16x16x32_bf16 v[78:81], v[172:175], v[206:209], v[78:81]
	v_mfma_f32_16x16x32_bf16 v[74:77], v[180:183], v[206:209], v[74:77]
	v_mfma_f32_16x16x32_bf16 v[70:73], v[172:175], v[214:217], v[70:73]
	v_mfma_f32_16x16x32_bf16 v[66:69], v[180:183], v[214:217], v[66:69]
	s_setprio 0
	s_barrier
	s_mov_b32 m0, s31
	v_lshl_add_u64 v[218:219], s[46:47], 0, v[134:135]
	s_add_u32 s42, s46, 0x20000
	ds_read_b128 v[184:187], v148 offset:16384
	ds_read_b128 v[188:191], v148 offset:17408
	ds_read_b128 v[192:195], v148 offset:18432
	ds_read_b128 v[196:199], v148 offset:19456
	ds_read_b128 v[200:203], v148 offset:20480
	ds_read_b128 v[206:209], v148 offset:21504
	ds_read_b128 v[210:213], v148 offset:22528
	ds_read_b128 v[214:217], v148 offset:23552
	global_load_lds_dwordx4 v[218:219], off
	v_lshl_add_u64 v[220:221], s[46:47], 0, v[130:131]
	s_mov_b32 m0, s33
	s_addc_u32 s43, s47, 0
	global_load_lds_dwordx4 v[220:221], off
	v_lshl_add_u64 v[222:223], s[42:43], 0, v[134:135]
	s_mov_b32 m0, s34
	v_lshl_add_u64 v[224:225], s[48:49], 0, v[132:133]
	global_load_lds_dwordx4 v[222:223], off
	s_mov_b32 m0, s35
	v_lshl_add_u64 v[222:223], s[42:43], 0, v[130:131]
	global_load_lds_dwordx4 v[222:223], off
	s_mov_b32 m0, s2
	v_lshl_add_u64 v[222:223], s[48:49], 0, v[136:137]
	global_load_lds_dwordx4 v[222:223], off
	s_mov_b32 m0, s3
	s_nop 0
	global_load_lds_dwordx4 v[224:225], off
	s_nop 0
	s_waitcnt vmcnt(8) lgkmcnt(0)
	s_setprio 1
	s_barrier
	v_mfma_f32_16x16x32_bf16 v[62:65], v[152:155], v[184:187], v[62:65]
	v_mfma_f32_16x16x32_bf16 v[58:61], v[160:163], v[184:187], v[58:61]
	v_mfma_f32_16x16x32_bf16 v[54:57], v[152:155], v[192:195], v[54:57]
	v_mfma_f32_16x16x32_bf16 v[50:53], v[160:163], v[192:195], v[50:53]
	v_mfma_f32_16x16x32_bf16 v[38:41], v[152:155], v[200:203], v[38:41]
	v_mfma_f32_16x16x32_bf16 v[34:37], v[160:163], v[200:203], v[34:37]
	v_mfma_f32_16x16x32_bf16 v[22:25], v[152:155], v[210:213], v[22:25]
	v_mfma_f32_16x16x32_bf16 v[18:21], v[160:163], v[210:213], v[18:21]
	v_mfma_f32_16x16x32_bf16 v[62:65], v[156:159], v[188:191], v[62:65]
	v_mfma_f32_16x16x32_bf16 v[58:61], v[164:167], v[188:191], v[58:61]
	v_mfma_f32_16x16x32_bf16 v[54:57], v[156:159], v[196:199], v[54:57]
	v_mfma_f32_16x16x32_bf16 v[50:53], v[164:167], v[196:199], v[50:53]
	v_mfma_f32_16x16x32_bf16 v[38:41], v[156:159], v[206:209], v[38:41]
	v_mfma_f32_16x16x32_bf16 v[34:37], v[164:167], v[206:209], v[34:37]
	v_mfma_f32_16x16x32_bf16 v[22:25], v[156:159], v[214:217], v[22:25]
	v_mfma_f32_16x16x32_bf16 v[18:21], v[164:167], v[214:217], v[18:21]
	v_mfma_f32_16x16x32_bf16 v[46:49], v[168:171], v[184:187], v[46:49]
	v_mfma_f32_16x16x32_bf16 v[42:45], v[176:179], v[184:187], v[42:45]
	v_mfma_f32_16x16x32_bf16 v[30:33], v[168:171], v[192:195], v[30:33]
	v_mfma_f32_16x16x32_bf16 v[26:29], v[176:179], v[192:195], v[26:29]
	v_mfma_f32_16x16x32_bf16 v[14:17], v[168:171], v[200:203], v[14:17]
	v_mfma_f32_16x16x32_bf16 v[10:13], v[176:179], v[200:203], v[10:13]
	v_mfma_f32_16x16x32_bf16 v[6:9], v[168:171], v[210:213], v[6:9]
	v_mfma_f32_16x16x32_bf16 v[2:5], v[176:179], v[210:213], v[2:5]
	v_mfma_f32_16x16x32_bf16 v[46:49], v[172:175], v[188:191], v[46:49]
	v_mfma_f32_16x16x32_bf16 v[42:45], v[180:183], v[188:191], v[42:45]
	v_mfma_f32_16x16x32_bf16 v[30:33], v[172:175], v[196:199], v[30:33]
	v_mfma_f32_16x16x32_bf16 v[26:29], v[180:183], v[196:199], v[26:29]
	v_mfma_f32_16x16x32_bf16 v[14:17], v[172:175], v[206:209], v[14:17]
	v_mfma_f32_16x16x32_bf16 v[10:13], v[180:183], v[206:209], v[10:13]
	v_mfma_f32_16x16x32_bf16 v[6:9], v[172:175], v[214:217], v[6:9]
	v_mfma_f32_16x16x32_bf16 v[2:5], v[180:183], v[214:217], v[2:5]
	s_setprio 0
	s_barrier
	ds_read_b128 v[152:155], v149
	ds_read_b128 v[156:159], v149 offset:1024
	ds_read_b128 v[160:163], v149 offset:2048
	ds_read_b128 v[164:167], v149 offset:3072
	ds_read_b128 v[168:171], v150
	ds_read_b128 v[172:175], v150 offset:1024
	ds_read_b128 v[176:179], v150 offset:2048
	ds_read_b128 v[180:183], v150 offset:3072
	s_add_u32 s42, s48, 0x20000
	s_addc_u32 s43, s49, 0
	s_mov_b32 m0, s16
	v_lshl_add_u64 v[226:227], s[42:43], 0, v[136:137]
	ds_read_b128 v[184:187], v148 offset:32768
	ds_read_b128 v[188:191], v148 offset:33792
	ds_read_b128 v[192:195], v148 offset:34816
	ds_read_b128 v[196:199], v148 offset:35840
	ds_read_b128 v[200:203], v148 offset:36864
	ds_read_b128 v[206:209], v148 offset:37888
	ds_read_b128 v[210:213], v148 offset:38912
	ds_read_b128 v[214:217], v148 offset:39936
	global_load_lds_dwordx4 v[226:227], off
	s_mov_b32 m0, s17
	v_lshl_add_u64 v[226:227], s[42:43], 0, v[132:133]
	global_load_lds_dwordx4 v[226:227], off
	s_waitcnt vmcnt(8) lgkmcnt(0)
	s_setprio 1
	s_barrier
	v_mfma_f32_16x16x32_bf16 v[126:129], v[152:155], v[184:187], v[126:129]
	v_mfma_f32_16x16x32_bf16 v[122:125], v[160:163], v[184:187], v[122:125]
	v_mfma_f32_16x16x32_bf16 v[118:121], v[152:155], v[192:195], v[118:121]
	v_mfma_f32_16x16x32_bf16 v[114:117], v[160:163], v[192:195], v[114:117]
	v_mfma_f32_16x16x32_bf16 v[102:105], v[152:155], v[200:203], v[102:105]
	v_mfma_f32_16x16x32_bf16 v[98:101], v[160:163], v[200:203], v[98:101]
	v_mfma_f32_16x16x32_bf16 v[86:89], v[152:155], v[210:213], v[86:89]
	v_mfma_f32_16x16x32_bf16 v[82:85], v[160:163], v[210:213], v[82:85]
	v_mfma_f32_16x16x32_bf16 v[126:129], v[156:159], v[188:191], v[126:129]
	v_mfma_f32_16x16x32_bf16 v[122:125], v[164:167], v[188:191], v[122:125]
	v_mfma_f32_16x16x32_bf16 v[118:121], v[156:159], v[196:199], v[118:121]
	v_mfma_f32_16x16x32_bf16 v[114:117], v[164:167], v[196:199], v[114:117]
	v_mfma_f32_16x16x32_bf16 v[102:105], v[156:159], v[206:209], v[102:105]
	v_mfma_f32_16x16x32_bf16 v[98:101], v[164:167], v[206:209], v[98:101]
	v_mfma_f32_16x16x32_bf16 v[86:89], v[156:159], v[214:217], v[86:89]
	v_mfma_f32_16x16x32_bf16 v[82:85], v[164:167], v[214:217], v[82:85]
	v_mfma_f32_16x16x32_bf16 v[110:113], v[168:171], v[184:187], v[110:113]
	v_mfma_f32_16x16x32_bf16 v[106:109], v[176:179], v[184:187], v[106:109]
	v_mfma_f32_16x16x32_bf16 v[94:97], v[168:171], v[192:195], v[94:97]
	v_mfma_f32_16x16x32_bf16 v[90:93], v[176:179], v[192:195], v[90:93]
	v_mfma_f32_16x16x32_bf16 v[78:81], v[168:171], v[200:203], v[78:81]
	v_mfma_f32_16x16x32_bf16 v[74:77], v[176:179], v[200:203], v[74:77]
	v_mfma_f32_16x16x32_bf16 v[70:73], v[168:171], v[210:213], v[70:73]
	v_mfma_f32_16x16x32_bf16 v[66:69], v[176:179], v[210:213], v[66:69]
	v_mfma_f32_16x16x32_bf16 v[110:113], v[172:175], v[188:191], v[110:113]
	v_mfma_f32_16x16x32_bf16 v[106:109], v[180:183], v[188:191], v[106:109]
	v_mfma_f32_16x16x32_bf16 v[94:97], v[172:175], v[196:199], v[94:97]
	v_mfma_f32_16x16x32_bf16 v[90:93], v[180:183], v[196:199], v[90:93]
	v_mfma_f32_16x16x32_bf16 v[78:81], v[172:175], v[206:209], v[78:81]
	v_mfma_f32_16x16x32_bf16 v[74:77], v[180:183], v[206:209], v[74:77]
	v_mfma_f32_16x16x32_bf16 v[70:73], v[172:175], v[214:217], v[70:73]
	v_mfma_f32_16x16x32_bf16 v[66:69], v[180:183], v[214:217], v[66:69]
	s_setprio 0
	s_barrier
	s_mov_b32 m0, s62
	v_lshl_add_u64 v[218:219], v[218:219], 0, s[10:11]
	s_add_u32 s42, s46, 0x20080
	ds_read_b128 v[184:187], v148 offset:49152
	ds_read_b128 v[188:191], v148 offset:50176
	ds_read_b128 v[192:195], v148 offset:51200
	ds_read_b128 v[196:199], v148 offset:52224
	ds_read_b128 v[200:203], v148 offset:53248
	ds_read_b128 v[206:209], v148 offset:54272
	ds_read_b128 v[210:213], v148 offset:55296
	ds_read_b128 v[214:217], v148 offset:56320
	global_load_lds_dwordx4 v[218:219], off
	v_lshl_add_u64 v[218:219], v[220:221], 0, s[10:11]
	s_mov_b32 m0, s63
	s_addc_u32 s43, s47, 0
	global_load_lds_dwordx4 v[218:219], off
	s_mov_b32 m0, s64
	v_lshl_add_u64 v[218:219], s[42:43], 0, v[134:135]
	global_load_lds_dwordx4 v[218:219], off
	s_mov_b32 m0, s65
	v_lshl_add_u64 v[218:219], s[42:43], 0, v[130:131]
	global_load_lds_dwordx4 v[218:219], off
	s_mov_b32 m0, s25
	v_lshl_add_u64 v[218:219], v[222:223], 0, s[10:11]
	global_load_lds_dwordx4 v[218:219], off
	s_mov_b32 m0, s28
	v_lshl_add_u64 v[218:219], v[224:225], 0, s[10:11]
	global_load_lds_dwordx4 v[218:219], off
	s_waitcnt vmcnt(8) lgkmcnt(0)
	s_setprio 1
	s_barrier
	v_mfma_f32_16x16x32_bf16 v[62:65], v[152:155], v[184:187], v[62:65]
	v_mfma_f32_16x16x32_bf16 v[58:61], v[160:163], v[184:187], v[58:61]
	v_mfma_f32_16x16x32_bf16 v[54:57], v[152:155], v[192:195], v[54:57]
	v_mfma_f32_16x16x32_bf16 v[50:53], v[160:163], v[192:195], v[50:53]
	v_mfma_f32_16x16x32_bf16 v[38:41], v[152:155], v[200:203], v[38:41]
	v_mfma_f32_16x16x32_bf16 v[34:37], v[160:163], v[200:203], v[34:37]
	v_mfma_f32_16x16x32_bf16 v[22:25], v[152:155], v[210:213], v[22:25]
	v_mfma_f32_16x16x32_bf16 v[18:21], v[160:163], v[210:213], v[18:21]
	v_mfma_f32_16x16x32_bf16 v[62:65], v[156:159], v[188:191], v[62:65]
	v_mfma_f32_16x16x32_bf16 v[58:61], v[164:167], v[188:191], v[58:61]
	v_mfma_f32_16x16x32_bf16 v[54:57], v[156:159], v[196:199], v[54:57]
	v_mfma_f32_16x16x32_bf16 v[50:53], v[164:167], v[196:199], v[50:53]
	v_mfma_f32_16x16x32_bf16 v[38:41], v[156:159], v[206:209], v[38:41]
	v_mfma_f32_16x16x32_bf16 v[34:37], v[164:167], v[206:209], v[34:37]
	v_mfma_f32_16x16x32_bf16 v[22:25], v[156:159], v[214:217], v[22:25]
	v_mfma_f32_16x16x32_bf16 v[18:21], v[164:167], v[214:217], v[18:21]
	v_mfma_f32_16x16x32_bf16 v[46:49], v[168:171], v[184:187], v[46:49]
	v_mfma_f32_16x16x32_bf16 v[42:45], v[176:179], v[184:187], v[42:45]
	v_mfma_f32_16x16x32_bf16 v[30:33], v[168:171], v[192:195], v[30:33]
	v_mfma_f32_16x16x32_bf16 v[26:29], v[176:179], v[192:195], v[26:29]
	v_mfma_f32_16x16x32_bf16 v[14:17], v[168:171], v[200:203], v[14:17]
	v_mfma_f32_16x16x32_bf16 v[10:13], v[176:179], v[200:203], v[10:13]
	v_mfma_f32_16x16x32_bf16 v[6:9], v[168:171], v[210:213], v[6:9]
	v_mfma_f32_16x16x32_bf16 v[2:5], v[176:179], v[210:213], v[2:5]
	v_mfma_f32_16x16x32_bf16 v[46:49], v[172:175], v[188:191], v[46:49]
	v_mfma_f32_16x16x32_bf16 v[42:45], v[180:183], v[188:191], v[42:45]
	v_mfma_f32_16x16x32_bf16 v[30:33], v[172:175], v[196:199], v[30:33]
	v_mfma_f32_16x16x32_bf16 v[26:29], v[180:183], v[196:199], v[26:29]
	v_mfma_f32_16x16x32_bf16 v[14:17], v[172:175], v[206:209], v[14:17]
	v_mfma_f32_16x16x32_bf16 v[10:13], v[180:183], v[206:209], v[10:13]
	v_mfma_f32_16x16x32_bf16 v[6:9], v[172:175], v[214:217], v[6:9]
	v_mfma_f32_16x16x32_bf16 v[2:5], v[180:183], v[214:217], v[2:5]
	s_setprio 0
	s_barrier
	s_add_i32 s68, s68, 2
	s_cmp_gt_u32 s68, 5
	s_mov_b64 s[42:43], s[44:45]
	s_cbranch_scc0 .LBB0_384
	s_and_b64 vcc, exec, s[12:13]
	s_cbranch_vccz .LBB0_387
	s_barrier

.LBB0_406:
	s_lshl_b32 s74, s12, 7
	s_add_i32 s12, s12, 2
	v_cndmask_b32_e64 v138, 0, 1, s[66:67]
	s_lshl_b64 s[66:67], s[12:13], 7
	s_and_b64 s[68:69], s[64:65], exec
	s_cselect_b32 s66, 0, s66
	s_cselect_b32 s67, 0, s67
	s_add_u32 s70, s8, s66
	s_addc_u32 s71, s9, s67
	s_lshl_b64 s[66:67], s[12:13], 12
	s_add_u32 s12, s48, s66
	s_addc_u32 s66, s49, s67
	s_and_b64 s[64:65], s[64:65], exec
	s_cselect_b32 s73, s14, s66
	s_cselect_b32 s72, s15, s12
	s_add_u32 s76, s10, s74
	s_addc_u32 s77, s11, 0
	s_add_i32 s91, s62, s16
	s_add_i32 m0, s17, 0xc000
	s_add_i32 s92, s17, 0xe000
	s_add_i32 s88, s91, 0x2000
	s_add_u32 s74, s72, 0x10000
	ds_read_b128 v[146:149], v141
	ds_read_b128 v[150:153], v141 offset:1024
	ds_read_b128 v[154:157], v141 offset:2048
	ds_read_b128 v[158:161], v141 offset:3072
	ds_read_b128 v[162:165], v143
	ds_read_b128 v[166:169], v143 offset:1024
	ds_read_b128 v[170:173], v143 offset:2048
	ds_read_b128 v[174:177], v143 offset:3072
	s_addc_u32 s75, s73, 0
	s_add_i32 s90, s63, s16
	s_add_i32 s89, s90, 0x2000
	s_add_i32 s87, 0, 0x18000
	s_add_i32 s86, 0, 0x1c000
	s_add_u32 s68, s70, 0x10000
	s_addc_u32 s69, s71, 0
	s_add_u32 s64, s72, 0x1000
	s_addc_u32 s65, s73, 0
	s_add_i32 s85, s87, s16
	s_add_i32 s83, s85, 0x2000
	s_add_u32 s66, s72, 0x11000
	s_addc_u32 s67, s73, 0
	s_add_i32 s84, s86, s16
	s_add_i32 s12, s84, 0x2000
	v_cmp_ne_u32_e32 vcc, 1, v138
	v_lshl_add_u64 v[202:203], s[76:77], 0, v[136:137]
	v_lshl_add_u64 v[202:203], v[202:203], 0, s[36:37]
	ds_read_b128 v[178:181], v144
	ds_read_b128 v[182:185], v144 offset:1024
	ds_read_b128 v[186:189], v144 offset:2048
	ds_read_b128 v[190:193], v144 offset:3072
	ds_read_b128 v[194:197], v144 offset:4096
	ds_read_b128 v[198:201], v144 offset:5120
	ds_read_b128 v[206:209], v144 offset:6144
	ds_read_b128 v[210:213], v144 offset:7168
	global_load_lds_dwordx4 v[202:203], off
	v_lshl_add_u64 v[202:203], s[76:77], 0, v[132:133]
	s_mov_b32 m0, s92
	v_lshl_add_u64 v[202:203], v[202:203], 0, s[36:37]
	global_load_lds_dwordx4 v[202:203], off
	s_waitcnt vmcnt(8) lgkmcnt(0)
	s_setprio 1
	s_barrier
	v_mfma_f32_16x16x32_bf16 v[126:129], v[146:149], v[178:181], v[126:129]
	v_mfma_f32_16x16x32_bf16 v[122:125], v[154:157], v[178:181], v[122:125]
	v_mfma_f32_16x16x32_bf16 v[118:121], v[146:149], v[186:189], v[118:121]
	v_mfma_f32_16x16x32_bf16 v[110:113], v[154:157], v[186:189], v[110:113]
	v_mfma_f32_16x16x32_bf16 v[102:105], v[146:149], v[194:197], v[102:105]
	v_mfma_f32_16x16x32_bf16 v[98:101], v[154:157], v[194:197], v[98:101]
	v_mfma_f32_16x16x32_bf16 v[86:89], v[146:149], v[206:209], v[86:89]
	v_mfma_f32_16x16x32_bf16 v[82:85], v[154:157], v[206:209], v[82:85]
	v_mfma_f32_16x16x32_bf16 v[126:129], v[150:153], v[182:185], v[126:129]
	v_mfma_f32_16x16x32_bf16 v[122:125], v[158:161], v[182:185], v[122:125]
	v_mfma_f32_16x16x32_bf16 v[118:121], v[150:153], v[190:193], v[118:121]
	v_mfma_f32_16x16x32_bf16 v[110:113], v[158:161], v[190:193], v[110:113]
	v_mfma_f32_16x16x32_bf16 v[102:105], v[150:153], v[198:201], v[102:105]
	v_mfma_f32_16x16x32_bf16 v[98:101], v[158:161], v[198:201], v[98:101]
	v_mfma_f32_16x16x32_bf16 v[86:89], v[150:153], v[210:213], v[86:89]
	v_mfma_f32_16x16x32_bf16 v[82:85], v[158:161], v[210:213], v[82:85]
	v_mfma_f32_16x16x32_bf16 v[114:117], v[162:165], v[178:181], v[114:117]
	v_mfma_f32_16x16x32_bf16 v[106:109], v[170:173], v[178:181], v[106:109]
	v_mfma_f32_16x16x32_bf16 v[94:97], v[162:165], v[186:189], v[94:97]
	v_mfma_f32_16x16x32_bf16 v[90:93], v[170:173], v[186:189], v[90:93]
	v_mfma_f32_16x16x32_bf16 v[78:81], v[162:165], v[194:197], v[78:81]
	v_mfma_f32_16x16x32_bf16 v[74:77], v[170:173], v[194:197], v[74:77]
	v_mfma_f32_16x16x32_bf16 v[70:73], v[162:165], v[206:209], v[70:73]
	v_mfma_f32_16x16x32_bf16 v[66:69], v[170:173], v[206:209], v[66:69]
	v_mfma_f32_16x16x32_bf16 v[114:117], v[166:169], v[182:185], v[114:117]
	v_mfma_f32_16x16x32_bf16 v[106:109], v[174:177], v[182:185], v[106:109]
	v_mfma_f32_16x16x32_bf16 v[94:97], v[166:169], v[190:193], v[94:97]
	v_mfma_f32_16x16x32_bf16 v[90:93], v[174:177], v[190:193], v[90:93]
	v_mfma_f32_16x16x32_bf16 v[78:81], v[166:169], v[198:201], v[78:81]
	v_mfma_f32_16x16x32_bf16 v[74:77], v[174:177], v[198:201], v[74:77]
	v_mfma_f32_16x16x32_bf16 v[70:73], v[166:169], v[210:213], v[70:73]
	v_mfma_f32_16x16x32_bf16 v[66:69], v[174:177], v[210:213], v[66:69]
	s_setprio 0
	s_barrier
	s_mov_b32 m0, s91
	v_lshl_add_u64 v[202:203], s[72:73], 0, v[134:135]
	ds_read_b128 v[178:181], v144 offset:16384
	ds_read_b128 v[182:185], v144 offset:17408
	ds_read_b128 v[186:189], v144 offset:18432
	ds_read_b128 v[190:193], v144 offset:19456
	ds_read_b128 v[194:197], v144 offset:20480
	ds_read_b128 v[198:201], v144 offset:21504
	ds_read_b128 v[206:209], v144 offset:22528
	ds_read_b128 v[210:213], v144 offset:23552
	global_load_lds_dwordx4 v[202:203], off
	v_lshl_add_u64 v[202:203], s[72:73], 0, v[130:131]
	s_mov_b32 m0, s88
	v_lshl_add_u64 v[214:215], s[70:71], 0, v[132:133]
	global_load_lds_dwordx4 v[202:203], off
	s_mov_b32 m0, s90
	v_lshl_add_u64 v[202:203], s[74:75], 0, v[134:135]
	global_load_lds_dwordx4 v[202:203], off
	s_mov_b32 m0, s89
	v_lshl_add_u64 v[202:203], s[74:75], 0, v[130:131]
	global_load_lds_dwordx4 v[202:203], off
	s_mov_b32 m0, s17
	v_lshl_add_u64 v[202:203], s[70:71], 0, v[136:137]
	global_load_lds_dwordx4 v[202:203], off
	s_mov_b32 m0, s18
	s_nop 0
	global_load_lds_dwordx4 v[214:215], off
	s_waitcnt vmcnt(8) lgkmcnt(0)
	s_setprio 1
	s_barrier
	v_mfma_f32_16x16x32_bf16 v[62:65], v[146:149], v[178:181], v[62:65]
	v_mfma_f32_16x16x32_bf16 v[58:61], v[154:157], v[178:181], v[58:61]
	v_mfma_f32_16x16x32_bf16 v[54:57], v[146:149], v[186:189], v[54:57]
	v_mfma_f32_16x16x32_bf16 v[50:53], v[154:157], v[186:189], v[50:53]
	v_mfma_f32_16x16x32_bf16 v[38:41], v[146:149], v[194:197], v[38:41]
	v_mfma_f32_16x16x32_bf16 v[34:37], v[154:157], v[194:197], v[34:37]
	v_mfma_f32_16x16x32_bf16 v[22:25], v[146:149], v[206:209], v[22:25]
	v_mfma_f32_16x16x32_bf16 v[18:21], v[154:157], v[206:209], v[18:21]
	v_mfma_f32_16x16x32_bf16 v[62:65], v[150:153], v[182:185], v[62:65]
	v_mfma_f32_16x16x32_bf16 v[58:61], v[158:161], v[182:185], v[58:61]
	v_mfma_f32_16x16x32_bf16 v[54:57], v[150:153], v[190:193], v[54:57]
	v_mfma_f32_16x16x32_bf16 v[50:53], v[158:161], v[190:193], v[50:53]
	v_mfma_f32_16x16x32_bf16 v[38:41], v[150:153], v[198:201], v[38:41]
	v_mfma_f32_16x16x32_bf16 v[34:37], v[158:161], v[198:201], v[34:37]
	v_mfma_f32_16x16x32_bf16 v[22:25], v[150:153], v[210:213], v[22:25]
	v_mfma_f32_16x16x32_bf16 v[18:21], v[158:161], v[210:213], v[18:21]
	v_mfma_f32_16x16x32_bf16 v[46:49], v[162:165], v[178:181], v[46:49]
	v_mfma_f32_16x16x32_bf16 v[42:45], v[170:173], v[178:181], v[42:45]
	v_mfma_f32_16x16x32_bf16 v[30:33], v[162:165], v[186:189], v[30:33]
	v_mfma_f32_16x16x32_bf16 v[26:29], v[170:173], v[186:189], v[26:29]
	v_mfma_f32_16x16x32_bf16 v[14:17], v[162:165], v[194:197], v[14:17]
	v_mfma_f32_16x16x32_bf16 v[10:13], v[170:173], v[194:197], v[10:13]
	v_mfma_f32_16x16x32_bf16 v[6:9], v[162:165], v[206:209], v[6:9]
	v_mfma_f32_16x16x32_bf16 v[2:5], v[170:173], v[206:209], v[2:5]
	v_mfma_f32_16x16x32_bf16 v[46:49], v[166:169], v[182:185], v[46:49]
	v_mfma_f32_16x16x32_bf16 v[42:45], v[174:177], v[182:185], v[42:45]
	v_mfma_f32_16x16x32_bf16 v[30:33], v[166:169], v[190:193], v[30:33]
	v_mfma_f32_16x16x32_bf16 v[26:29], v[174:177], v[190:193], v[26:29]
	v_mfma_f32_16x16x32_bf16 v[14:17], v[166:169], v[198:201], v[14:17]
	v_mfma_f32_16x16x32_bf16 v[10:13], v[174:177], v[198:201], v[10:13]
	v_mfma_f32_16x16x32_bf16 v[6:9], v[166:169], v[210:213], v[6:9]
	v_mfma_f32_16x16x32_bf16 v[2:5], v[174:177], v[210:213], v[2:5]
	s_setprio 0
	s_barrier
	v_add_u32_e32 v138, s87, v140
	ds_read_b128 v[146:149], v138
	ds_read_b128 v[150:153], v138 offset:1024
	ds_read_b128 v[154:157], v138 offset:2048
	ds_read_b128 v[158:161], v138 offset:3072
	v_add_u32_e32 v138, s86, v140
	ds_read_b128 v[162:165], v138
	ds_read_b128 v[166:169], v138 offset:1024
	ds_read_b128 v[170:173], v138 offset:2048
	ds_read_b128 v[174:177], v138 offset:3072
	s_mov_b32 m0, s19
	v_lshl_add_u64 v[216:217], s[68:69], 0, v[136:137]
	ds_read_b128 v[178:181], v144 offset:32768
	ds_read_b128 v[182:185], v144 offset:33792
	ds_read_b128 v[186:189], v144 offset:34816
	ds_read_b128 v[190:193], v144 offset:35840
	ds_read_b128 v[194:197], v144 offset:36864
	ds_read_b128 v[198:201], v144 offset:37888
	ds_read_b128 v[206:209], v144 offset:38912
	ds_read_b128 v[210:213], v144 offset:39936
	global_load_lds_dwordx4 v[216:217], off
	s_mov_b32 m0, s24
	v_lshl_add_u64 v[216:217], s[68:69], 0, v[132:133]
	global_load_lds_dwordx4 v[216:217], off
	s_nop 0
	s_waitcnt vmcnt(8) lgkmcnt(0)
	s_setprio 1
	s_barrier
	v_mfma_f32_16x16x32_bf16 v[126:129], v[146:149], v[178:181], v[126:129]
	v_mfma_f32_16x16x32_bf16 v[122:125], v[154:157], v[178:181], v[122:125]
	v_mfma_f32_16x16x32_bf16 v[118:121], v[146:149], v[186:189], v[118:121]
	v_mfma_f32_16x16x32_bf16 v[110:113], v[154:157], v[186:189], v[110:113]
	v_mfma_f32_16x16x32_bf16 v[102:105], v[146:149], v[194:197], v[102:105]
	v_mfma_f32_16x16x32_bf16 v[98:101], v[154:157], v[194:197], v[98:101]
	v_mfma_f32_16x16x32_bf16 v[86:89], v[146:149], v[206:209], v[86:89]
	v_mfma_f32_16x16x32_bf16 v[82:85], v[154:157], v[206:209], v[82:85]
	v_mfma_f32_16x16x32_bf16 v[126:129], v[150:153], v[182:185], v[126:129]
	v_mfma_f32_16x16x32_bf16 v[122:125], v[158:161], v[182:185], v[122:125]
	v_mfma_f32_16x16x32_bf16 v[118:121], v[150:153], v[190:193], v[118:121]
	v_mfma_f32_16x16x32_bf16 v[110:113], v[158:161], v[190:193], v[110:113]
	v_mfma_f32_16x16x32_bf16 v[102:105], v[150:153], v[198:201], v[102:105]
	v_mfma_f32_16x16x32_bf16 v[98:101], v[158:161], v[198:201], v[98:101]
	v_mfma_f32_16x16x32_bf16 v[86:89], v[150:153], v[210:213], v[86:89]
	v_mfma_f32_16x16x32_bf16 v[82:85], v[158:161], v[210:213], v[82:85]
	v_mfma_f32_16x16x32_bf16 v[114:117], v[162:165], v[178:181], v[114:117]
	v_mfma_f32_16x16x32_bf16 v[106:109], v[170:173], v[178:181], v[106:109]
	v_mfma_f32_16x16x32_bf16 v[94:97], v[162:165], v[186:189], v[94:97]
	v_mfma_f32_16x16x32_bf16 v[90:93], v[170:173], v[186:189], v[90:93]
	v_mfma_f32_16x16x32_bf16 v[78:81], v[162:165], v[194:197], v[78:81]
	v_mfma_f32_16x16x32_bf16 v[74:77], v[170:173], v[194:197], v[74:77]
	v_mfma_f32_16x16x32_bf16 v[70:73], v[162:165], v[206:209], v[70:73]
	v_mfma_f32_16x16x32_bf16 v[66:69], v[170:173], v[206:209], v[66:69]
	v_mfma_f32_16x16x32_bf16 v[114:117], v[166:169], v[182:185], v[114:117]
	v_mfma_f32_16x16x32_bf16 v[106:109], v[174:177], v[182:185], v[106:109]
	v_mfma_f32_16x16x32_bf16 v[94:97], v[166:169], v[190:193], v[94:97]
	v_mfma_f32_16x16x32_bf16 v[90:93], v[174:177], v[190:193], v[90:93]
	v_mfma_f32_16x16x32_bf16 v[78:81], v[166:169], v[198:201], v[78:81]
	v_mfma_f32_16x16x32_bf16 v[74:77], v[174:177], v[198:201], v[74:77]
	v_mfma_f32_16x16x32_bf16 v[70:73], v[166:169], v[210:213], v[70:73]
	v_mfma_f32_16x16x32_bf16 v[66:69], v[174:177], v[210:213], v[66:69]
	s_setprio 0
	s_barrier
	s_mov_b32 m0, s85
	v_lshl_add_u64 v[216:217], s[64:65], 0, v[134:135]
	ds_read_b128 v[178:181], v144 offset:49152
	ds_read_b128 v[182:185], v144 offset:50176
	ds_read_b128 v[186:189], v144 offset:51200
	ds_read_b128 v[190:193], v144 offset:52224
	ds_read_b128 v[194:197], v144 offset:53248
	ds_read_b128 v[198:201], v144 offset:54272
	ds_read_b128 v[206:209], v144 offset:55296
	ds_read_b128 v[210:213], v144 offset:56320
	global_load_lds_dwordx4 v[216:217], off
	v_lshl_add_u64 v[216:217], s[64:65], 0, v[130:131]
	s_mov_b32 m0, s83
	v_lshl_add_u64 v[202:203], v[202:203], 0, s[36:37]
	global_load_lds_dwordx4 v[216:217], off
	s_mov_b32 m0, s84
	v_lshl_add_u64 v[216:217], s[66:67], 0, v[134:135]
	global_load_lds_dwordx4 v[216:217], off
	s_mov_b32 m0, s12
	v_lshl_add_u64 v[216:217], s[66:67], 0, v[130:131]
	global_load_lds_dwordx4 v[216:217], off
	s_mov_b32 m0, s31
	s_nop 0
	global_load_lds_dwordx4 v[202:203], off
	s_mov_b32 m0, s33
	v_lshl_add_u64 v[202:203], v[214:215], 0, s[36:37]
	global_load_lds_dwordx4 v[202:203], off
	s_waitcnt vmcnt(8) lgkmcnt(0)
	s_setprio 1
	s_barrier
	v_mfma_f32_16x16x32_bf16 v[62:65], v[146:149], v[178:181], v[62:65]
	v_mfma_f32_16x16x32_bf16 v[58:61], v[154:157], v[178:181], v[58:61]
	v_mfma_f32_16x16x32_bf16 v[54:57], v[146:149], v[186:189], v[54:57]
	v_mfma_f32_16x16x32_bf16 v[50:53], v[154:157], v[186:189], v[50:53]
	v_mfma_f32_16x16x32_bf16 v[38:41], v[146:149], v[194:197], v[38:41]
	v_mfma_f32_16x16x32_bf16 v[34:37], v[154:157], v[194:197], v[34:37]
	v_mfma_f32_16x16x32_bf16 v[22:25], v[146:149], v[206:209], v[22:25]
	v_mfma_f32_16x16x32_bf16 v[18:21], v[154:157], v[206:209], v[18:21]
	v_mfma_f32_16x16x32_bf16 v[62:65], v[150:153], v[182:185], v[62:65]
	v_mfma_f32_16x16x32_bf16 v[58:61], v[158:161], v[182:185], v[58:61]
	v_mfma_f32_16x16x32_bf16 v[54:57], v[150:153], v[190:193], v[54:57]
	v_mfma_f32_16x16x32_bf16 v[50:53], v[158:161], v[190:193], v[50:53]
	v_mfma_f32_16x16x32_bf16 v[38:41], v[150:153], v[198:201], v[38:41]
	v_mfma_f32_16x16x32_bf16 v[34:37], v[158:161], v[198:201], v[34:37]
	v_mfma_f32_16x16x32_bf16 v[22:25], v[150:153], v[210:213], v[22:25]
	v_mfma_f32_16x16x32_bf16 v[18:21], v[158:161], v[210:213], v[18:21]
	v_mfma_f32_16x16x32_bf16 v[46:49], v[162:165], v[178:181], v[46:49]
	v_mfma_f32_16x16x32_bf16 v[42:45], v[170:173], v[178:181], v[42:45]
	v_mfma_f32_16x16x32_bf16 v[30:33], v[162:165], v[186:189], v[30:33]
	v_mfma_f32_16x16x32_bf16 v[26:29], v[170:173], v[186:189], v[26:29]
	v_mfma_f32_16x16x32_bf16 v[14:17], v[162:165], v[194:197], v[14:17]
	v_mfma_f32_16x16x32_bf16 v[10:13], v[170:173], v[194:197], v[10:13]
	v_mfma_f32_16x16x32_bf16 v[6:9], v[162:165], v[206:209], v[6:9]
	v_mfma_f32_16x16x32_bf16 v[2:5], v[170:173], v[206:209], v[2:5]
	v_mfma_f32_16x16x32_bf16 v[46:49], v[166:169], v[182:185], v[46:49]
	v_mfma_f32_16x16x32_bf16 v[42:45], v[174:177], v[182:185], v[42:45]
	v_mfma_f32_16x16x32_bf16 v[30:33], v[166:169], v[190:193], v[30:33]
	v_mfma_f32_16x16x32_bf16 v[26:29], v[174:177], v[190:193], v[26:29]
	v_mfma_f32_16x16x32_bf16 v[14:17], v[166:169], v[198:201], v[14:17]
	v_mfma_f32_16x16x32_bf16 v[10:13], v[174:177], v[198:201], v[10:13]
	v_mfma_f32_16x16x32_bf16 v[6:9], v[166:169], v[210:213], v[6:9]
	v_mfma_f32_16x16x32_bf16 v[2:5], v[174:177], v[210:213], v[2:5]
	s_setprio 0
	s_barrier
	s_mov_b64 s[66:67], 0
	s_mov_b64 s[64:65], -1
	s_mov_b32 s12, 2
	s_cbranch_vccz .LBB0_406
	s_and_b64 vcc, exec, s[22:23]
	s_cbranch_vccz .LBB0_409
	s_barrier

.LBB0_476:
	s_add_u32 s22, s2, s49
	s_addc_u32 s23, s3, s29
	s_and_b64 s[26:27], s[20:21], exec
	s_cselect_b32 s63, s23, s37
	s_cselect_b32 s64, s22, s36
	s_add_u32 s26, s16, s12
	s_addc_u32 s27, s17, s13
	s_and_b64 s[42:43], s[20:21], exec
	s_cselect_b32 s65, s27, s39
	s_cselect_b32 s66, s26, s38
	s_add_u32 s36, s36, 0x20080
	s_addc_u32 s37, s37, 0
	s_add_u32 s67, s38, 0x100
	s_addc_u32 s68, s39, 0
	s_mov_b32 s69, -2
	ds_read_b128 v[148:151], v144
	ds_read_b128 v[152:155], v144 offset:1024
	ds_read_b128 v[156:159], v144 offset:2048
	ds_read_b128 v[160:163], v144 offset:3072
	ds_read_b128 v[164:167], v145
	ds_read_b128 v[168:171], v145 offset:1024
	ds_read_b128 v[172:175], v145 offset:2048
	ds_read_b128 v[176:179], v145 offset:3072
	s_add_u32 s38, s36, 0xfffe0080
	s_addc_u32 s39, s37, -1
	s_cmp_eq_u32 s69, 4
	s_cselect_b32 s43, s63, s39
	s_cselect_b32 s42, s64, s38
	s_cselect_b32 s39, s65, s68
	s_cselect_b32 s38, s66, s67
	v_lshl_add_u64 v[214:215], s[36:37], 0, v[138:139]
	s_add_i32 m0, s19, 0xc000
	ds_read_b128 v[180:183], v146
	ds_read_b128 v[184:187], v146 offset:1024
	ds_read_b128 v[188:191], v146 offset:2048
	ds_read_b128 v[192:195], v146 offset:3072
	ds_read_b128 v[196:199], v146 offset:4096
	ds_read_b128 v[200:203], v146 offset:5120
	ds_read_b128 v[206:209], v146 offset:6144
	ds_read_b128 v[210:213], v146 offset:7168
	global_load_lds_dwordx4 v[214:215], off
	s_add_i32 m0, s19, 0xe000
	v_lshl_add_u64 v[214:215], s[36:37], 0, v[140:141]
	global_load_lds_dwordx4 v[214:215], off
	s_waitcnt vmcnt(8) lgkmcnt(0)
	s_setprio 1
	s_barrier
	v_mfma_f32_16x16x32_bf16 v[126:129], v[148:151], v[180:183], 0
	v_mfma_f32_16x16x32_bf16 v[122:125], v[156:159], v[180:183], 0
	v_mfma_f32_16x16x32_bf16 v[118:121], v[148:151], v[188:191], 0
	v_mfma_f32_16x16x32_bf16 v[114:117], v[156:159], v[188:191], 0
	v_mfma_f32_16x16x32_bf16 v[102:105], v[148:151], v[196:199], 0
	v_mfma_f32_16x16x32_bf16 v[98:101], v[156:159], v[196:199], 0
	v_mfma_f32_16x16x32_bf16 v[86:89], v[148:151], v[206:209], 0
	v_mfma_f32_16x16x32_bf16 v[82:85], v[156:159], v[206:209], 0
	v_mfma_f32_16x16x32_bf16 v[126:129], v[152:155], v[184:187], v[126:129]
	v_mfma_f32_16x16x32_bf16 v[122:125], v[160:163], v[184:187], v[122:125]
	v_mfma_f32_16x16x32_bf16 v[118:121], v[152:155], v[192:195], v[118:121]
	v_mfma_f32_16x16x32_bf16 v[114:117], v[160:163], v[192:195], v[114:117]
	v_mfma_f32_16x16x32_bf16 v[102:105], v[152:155], v[200:203], v[102:105]
	v_mfma_f32_16x16x32_bf16 v[98:101], v[160:163], v[200:203], v[98:101]
	v_mfma_f32_16x16x32_bf16 v[86:89], v[152:155], v[210:213], v[86:89]
	v_mfma_f32_16x16x32_bf16 v[82:85], v[160:163], v[210:213], v[82:85]
	v_mfma_f32_16x16x32_bf16 v[110:113], v[164:167], v[180:183], 0
	v_mfma_f32_16x16x32_bf16 v[106:109], v[172:175], v[180:183], 0
	v_mfma_f32_16x16x32_bf16 v[94:97], v[164:167], v[188:191], 0
	v_mfma_f32_16x16x32_bf16 v[90:93], v[172:175], v[188:191], 0
	v_mfma_f32_16x16x32_bf16 v[78:81], v[164:167], v[196:199], 0
	v_mfma_f32_16x16x32_bf16 v[74:77], v[172:175], v[196:199], 0
	v_mfma_f32_16x16x32_bf16 v[70:73], v[164:167], v[206:209], 0
	v_mfma_f32_16x16x32_bf16 v[66:69], v[172:175], v[206:209], 0
	v_mfma_f32_16x16x32_bf16 v[110:113], v[168:171], v[184:187], v[110:113]
	v_mfma_f32_16x16x32_bf16 v[106:109], v[176:179], v[184:187], v[106:109]
	v_mfma_f32_16x16x32_bf16 v[94:97], v[168:171], v[192:195], v[94:97]
	v_mfma_f32_16x16x32_bf16 v[90:93], v[176:179], v[192:195], v[90:93]
	v_mfma_f32_16x16x32_bf16 v[78:81], v[168:171], v[200:203], v[78:81]
	v_mfma_f32_16x16x32_bf16 v[74:77], v[176:179], v[200:203], v[74:77]
	v_mfma_f32_16x16x32_bf16 v[70:73], v[168:171], v[210:213], v[70:73]
	v_mfma_f32_16x16x32_bf16 v[66:69], v[176:179], v[210:213], v[66:69]
	s_setprio 0
	s_barrier
	s_add_i32 s70, s35, s18
	v_lshl_add_u64 v[214:215], s[38:39], 0, v[134:135]
	s_mov_b32 m0, s70
	ds_read_b128 v[180:183], v146 offset:16384
	ds_read_b128 v[184:187], v146 offset:17408
	ds_read_b128 v[188:191], v146 offset:18432
	ds_read_b128 v[192:195], v146 offset:19456
	ds_read_b128 v[196:199], v146 offset:20480
	ds_read_b128 v[200:203], v146 offset:21504
	ds_read_b128 v[206:209], v146 offset:22528
	ds_read_b128 v[210:213], v146 offset:23552
	global_load_lds_dwordx4 v[214:215], off
	s_add_i32 m0, s70, 0x2000
	s_add_u32 s70, s38, 0x200000
	v_lshl_add_u64 v[216:217], s[38:39], 0, v[130:131]
	s_addc_u32 s71, s39, 0
	s_add_i32 s72, s44, s18
	global_load_lds_dwordx4 v[216:217], off
	v_lshl_add_u64 v[218:219], s[70:71], 0, v[134:135]
	s_mov_b32 m0, s72
	v_lshl_add_u64 v[220:221], s[42:43], 0, v[132:133]
	global_load_lds_dwordx4 v[218:219], off
	s_add_i32 m0, s72, 0x2000
	v_lshl_add_u64 v[218:219], s[70:71], 0, v[130:131]
	global_load_lds_dwordx4 v[218:219], off
	s_mov_b32 m0, s19
	v_lshl_add_u64 v[218:219], s[42:43], 0, v[136:137]
	global_load_lds_dwordx4 v[218:219], off
	s_mov_b32 m0, s24
	s_nop 0
	global_load_lds_dwordx4 v[220:221], off
	s_nop 0
	s_waitcnt vmcnt(8) lgkmcnt(0)
	s_setprio 1
	s_barrier
	v_mfma_f32_16x16x32_bf16 v[62:65], v[148:151], v[180:183], 0
	v_mfma_f32_16x16x32_bf16 v[58:61], v[156:159], v[180:183], 0
	v_mfma_f32_16x16x32_bf16 v[54:57], v[148:151], v[188:191], 0
	v_mfma_f32_16x16x32_bf16 v[50:53], v[156:159], v[188:191], 0
	v_mfma_f32_16x16x32_bf16 v[38:41], v[148:151], v[196:199], 0
	v_mfma_f32_16x16x32_bf16 v[34:37], v[156:159], v[196:199], 0
	v_mfma_f32_16x16x32_bf16 v[22:25], v[148:151], v[206:209], 0
	v_mfma_f32_16x16x32_bf16 v[18:21], v[156:159], v[206:209], 0
	v_mfma_f32_16x16x32_bf16 v[62:65], v[152:155], v[184:187], v[62:65]
	v_mfma_f32_16x16x32_bf16 v[58:61], v[160:163], v[184:187], v[58:61]
	v_mfma_f32_16x16x32_bf16 v[54:57], v[152:155], v[192:195], v[54:57]
	v_mfma_f32_16x16x32_bf16 v[50:53], v[160:163], v[192:195], v[50:53]
	v_mfma_f32_16x16x32_bf16 v[38:41], v[152:155], v[200:203], v[38:41]
	v_mfma_f32_16x16x32_bf16 v[34:37], v[160:163], v[200:203], v[34:37]
	v_mfma_f32_16x16x32_bf16 v[22:25], v[152:155], v[210:213], v[22:25]
	v_mfma_f32_16x16x32_bf16 v[18:21], v[160:163], v[210:213], v[18:21]
	v_mfma_f32_16x16x32_bf16 v[46:49], v[164:167], v[180:183], 0
	v_mfma_f32_16x16x32_bf16 v[42:45], v[172:175], v[180:183], 0
	v_mfma_f32_16x16x32_bf16 v[30:33], v[164:167], v[188:191], 0
	v_mfma_f32_16x16x32_bf16 v[26:29], v[172:175], v[188:191], 0
	v_mfma_f32_16x16x32_bf16 v[14:17], v[164:167], v[196:199], 0
	v_mfma_f32_16x16x32_bf16 v[10:13], v[172:175], v[196:199], 0
	v_mfma_f32_16x16x32_bf16 v[6:9], v[164:167], v[206:209], 0
	v_mfma_f32_16x16x32_bf16 v[2:5], v[172:175], v[206:209], 0
	v_mfma_f32_16x16x32_bf16 v[46:49], v[168:171], v[184:187], v[46:49]
	v_mfma_f32_16x16x32_bf16 v[42:45], v[176:179], v[184:187], v[42:45]
	v_mfma_f32_16x16x32_bf16 v[30:33], v[168:171], v[192:195], v[30:33]
	v_mfma_f32_16x16x32_bf16 v[26:29], v[176:179], v[192:195], v[26:29]
	v_mfma_f32_16x16x32_bf16 v[14:17], v[168:171], v[200:203], v[14:17]
	v_mfma_f32_16x16x32_bf16 v[10:13], v[176:179], v[200:203], v[10:13]
	v_mfma_f32_16x16x32_bf16 v[6:9], v[168:171], v[210:213], v[6:9]
	v_mfma_f32_16x16x32_bf16 v[2:5], v[176:179], v[210:213], v[2:5]
	s_setprio 0
	s_barrier
	s_add_i32 s70, 0, 0x18000
	v_add_u32_e32 v147, s70, v143
	s_add_i32 s71, 0, 0x1c000
	ds_read_b128 v[148:151], v147
	ds_read_b128 v[152:155], v147 offset:1024
	ds_read_b128 v[156:159], v147 offset:2048
	ds_read_b128 v[160:163], v147 offset:3072
	v_add_u32_e32 v147, s71, v143
	ds_read_b128 v[164:167], v147
	ds_read_b128 v[168:171], v147 offset:1024
	ds_read_b128 v[172:175], v147 offset:2048
	ds_read_b128 v[176:179], v147 offset:3072
	s_add_u32 s42, s42, 0x20000
	s_addc_u32 s43, s43, 0
	s_mov_b32 m0, s25
	v_lshl_add_u64 v[222:223], s[42:43], 0, v[136:137]
	ds_read_b128 v[180:183], v146 offset:32768
	ds_read_b128 v[184:187], v146 offset:33792
	ds_read_b128 v[188:191], v146 offset:34816
	ds_read_b128 v[192:195], v146 offset:35840
	ds_read_b128 v[196:199], v146 offset:36864
	ds_read_b128 v[200:203], v146 offset:37888
	ds_read_b128 v[206:209], v146 offset:38912
	ds_read_b128 v[210:213], v146 offset:39936
	global_load_lds_dwordx4 v[222:223], off
	s_mov_b32 m0, s28
	v_lshl_add_u64 v[222:223], s[42:43], 0, v[132:133]
	global_load_lds_dwordx4 v[222:223], off
	s_waitcnt vmcnt(8) lgkmcnt(0)
	s_setprio 1
	s_barrier
	v_mfma_f32_16x16x32_bf16 v[126:129], v[148:151], v[180:183], v[126:129]
	v_mfma_f32_16x16x32_bf16 v[122:125], v[156:159], v[180:183], v[122:125]
	v_mfma_f32_16x16x32_bf16 v[118:121], v[148:151], v[188:191], v[118:121]
	v_mfma_f32_16x16x32_bf16 v[114:117], v[156:159], v[188:191], v[114:117]
	v_mfma_f32_16x16x32_bf16 v[102:105], v[148:151], v[196:199], v[102:105]
	v_mfma_f32_16x16x32_bf16 v[98:101], v[156:159], v[196:199], v[98:101]
	v_mfma_f32_16x16x32_bf16 v[86:89], v[148:151], v[206:209], v[86:89]
	v_mfma_f32_16x16x32_bf16 v[82:85], v[156:159], v[206:209], v[82:85]
	v_mfma_f32_16x16x32_bf16 v[126:129], v[152:155], v[184:187], v[126:129]
	v_mfma_f32_16x16x32_bf16 v[122:125], v[160:163], v[184:187], v[122:125]
	v_mfma_f32_16x16x32_bf16 v[118:121], v[152:155], v[192:195], v[118:121]
	v_mfma_f32_16x16x32_bf16 v[114:117], v[160:163], v[192:195], v[114:117]
	v_mfma_f32_16x16x32_bf16 v[102:105], v[152:155], v[200:203], v[102:105]
	v_mfma_f32_16x16x32_bf16 v[98:101], v[160:163], v[200:203], v[98:101]
	v_mfma_f32_16x16x32_bf16 v[86:89], v[152:155], v[210:213], v[86:89]
	v_mfma_f32_16x16x32_bf16 v[82:85], v[160:163], v[210:213], v[82:85]
	v_mfma_f32_16x16x32_bf16 v[110:113], v[164:167], v[180:183], v[110:113]
	v_mfma_f32_16x16x32_bf16 v[106:109], v[172:175], v[180:183], v[106:109]
	v_mfma_f32_16x16x32_bf16 v[94:97], v[164:167], v[188:191], v[94:97]
	v_mfma_f32_16x16x32_bf16 v[90:93], v[172:175], v[188:191], v[90:93]
	v_mfma_f32_16x16x32_bf16 v[78:81], v[164:167], v[196:199], v[78:81]
	v_mfma_f32_16x16x32_bf16 v[74:77], v[172:175], v[196:199], v[74:77]
	v_mfma_f32_16x16x32_bf16 v[70:73], v[164:167], v[206:209], v[70:73]
	v_mfma_f32_16x16x32_bf16 v[66:69], v[172:175], v[206:209], v[66:69]
	v_mfma_f32_16x16x32_bf16 v[110:113], v[168:171], v[184:187], v[110:113]
	v_mfma_f32_16x16x32_bf16 v[106:109], v[176:179], v[184:187], v[106:109]
	v_mfma_f32_16x16x32_bf16 v[94:97], v[168:171], v[192:195], v[94:97]
	v_mfma_f32_16x16x32_bf16 v[90:93], v[176:179], v[192:195], v[90:93]
	v_mfma_f32_16x16x32_bf16 v[78:81], v[168:171], v[200:203], v[78:81]
	v_mfma_f32_16x16x32_bf16 v[74:77], v[176:179], v[200:203], v[74:77]
	v_mfma_f32_16x16x32_bf16 v[70:73], v[168:171], v[210:213], v[70:73]
	v_mfma_f32_16x16x32_bf16 v[66:69], v[176:179], v[210:213], v[66:69]
	s_setprio 0
	s_barrier
	s_add_i32 s42, s70, s18
	v_lshl_add_u64 v[214:215], v[214:215], 0, s[8:9]
	s_mov_b32 m0, s42
	ds_read_b128 v[180:183], v146 offset:49152
	ds_read_b128 v[184:187], v146 offset:50176
	ds_read_b128 v[188:191], v146 offset:51200
	ds_read_b128 v[192:195], v146 offset:52224
	ds_read_b128 v[196:199], v146 offset:53248
	ds_read_b128 v[200:203], v146 offset:54272
	ds_read_b128 v[206:209], v146 offset:55296
	ds_read_b128 v[210:213], v146 offset:56320
	global_load_lds_dwordx4 v[214:215], off
	s_add_i32 m0, s42, 0x2000
	s_add_u32 s38, s38, 0x200080
	v_lshl_add_u64 v[214:215], v[216:217], 0, s[8:9]
	s_addc_u32 s39, s39, 0
	s_add_i32 s42, s71, s18
	global_load_lds_dwordx4 v[214:215], off
	s_mov_b32 m0, s42
	v_lshl_add_u64 v[214:215], s[38:39], 0, v[134:135]
	global_load_lds_dwordx4 v[214:215], off
	s_add_i32 m0, s42, 0x2000
	v_lshl_add_u64 v[214:215], s[38:39], 0, v[130:131]
	global_load_lds_dwordx4 v[214:215], off
	s_mov_b32 m0, s33
	v_lshl_add_u64 v[214:215], v[218:219], 0, s[8:9]
	global_load_lds_dwordx4 v[214:215], off
	s_mov_b32 m0, s34
	v_lshl_add_u64 v[214:215], v[220:221], 0, s[8:9]
	global_load_lds_dwordx4 v[214:215], off
	s_waitcnt vmcnt(8) lgkmcnt(0)
	s_setprio 1
	s_barrier
	v_mfma_f32_16x16x32_bf16 v[62:65], v[148:151], v[180:183], v[62:65]
	v_mfma_f32_16x16x32_bf16 v[58:61], v[156:159], v[180:183], v[58:61]
	v_mfma_f32_16x16x32_bf16 v[54:57], v[148:151], v[188:191], v[54:57]
	v_mfma_f32_16x16x32_bf16 v[50:53], v[156:159], v[188:191], v[50:53]
	v_mfma_f32_16x16x32_bf16 v[38:41], v[148:151], v[196:199], v[38:41]
	v_mfma_f32_16x16x32_bf16 v[34:37], v[156:159], v[196:199], v[34:37]
	v_mfma_f32_16x16x32_bf16 v[22:25], v[148:151], v[206:209], v[22:25]
	v_mfma_f32_16x16x32_bf16 v[18:21], v[156:159], v[206:209], v[18:21]
	v_mfma_f32_16x16x32_bf16 v[62:65], v[152:155], v[184:187], v[62:65]
	v_mfma_f32_16x16x32_bf16 v[58:61], v[160:163], v[184:187], v[58:61]
	v_mfma_f32_16x16x32_bf16 v[54:57], v[152:155], v[192:195], v[54:57]
	v_mfma_f32_16x16x32_bf16 v[50:53], v[160:163], v[192:195], v[50:53]
	v_mfma_f32_16x16x32_bf16 v[38:41], v[152:155], v[200:203], v[38:41]
	v_mfma_f32_16x16x32_bf16 v[34:37], v[160:163], v[200:203], v[34:37]
	v_mfma_f32_16x16x32_bf16 v[22:25], v[152:155], v[210:213], v[22:25]
	v_mfma_f32_16x16x32_bf16 v[18:21], v[160:163], v[210:213], v[18:21]
	v_mfma_f32_16x16x32_bf16 v[46:49], v[164:167], v[180:183], v[46:49]
	v_mfma_f32_16x16x32_bf16 v[42:45], v[172:175], v[180:183], v[42:45]
	v_mfma_f32_16x16x32_bf16 v[30:33], v[164:167], v[188:191], v[30:33]
	v_mfma_f32_16x16x32_bf16 v[26:29], v[172:175], v[188:191], v[26:29]
	v_mfma_f32_16x16x32_bf16 v[14:17], v[164:167], v[196:199], v[14:17]
	v_mfma_f32_16x16x32_bf16 v[10:13], v[172:175], v[196:199], v[10:13]
	v_mfma_f32_16x16x32_bf16 v[6:9], v[164:167], v[206:209], v[6:9]
	v_mfma_f32_16x16x32_bf16 v[2:5], v[172:175], v[206:209], v[2:5]
	v_mfma_f32_16x16x32_bf16 v[46:49], v[168:171], v[184:187], v[46:49]
	v_mfma_f32_16x16x32_bf16 v[42:45], v[176:179], v[184:187], v[42:45]
	v_mfma_f32_16x16x32_bf16 v[30:33], v[168:171], v[192:195], v[30:33]
	v_mfma_f32_16x16x32_bf16 v[26:29], v[176:179], v[192:195], v[26:29]
	v_mfma_f32_16x16x32_bf16 v[14:17], v[168:171], v[200:203], v[14:17]
	v_mfma_f32_16x16x32_bf16 v[10:13], v[176:179], v[200:203], v[10:13]
	v_mfma_f32_16x16x32_bf16 v[6:9], v[168:171], v[210:213], v[6:9]
	v_mfma_f32_16x16x32_bf16 v[2:5], v[176:179], v[210:213], v[2:5]
	s_setprio 0
	s_barrier
	s_add_i32 s69, s69, 2
	s_add_u32 s36, s36, 0x100
	s_addc_u32 s37, s37, 0
	s_add_u32 s67, s67, 0x100
	s_addc_u32 s68, s68, 0
	s_cmp_gt_u32 s69, 5
.LBB0_477:
	ds_read_b128 v[148:151], v144
	ds_read_b128 v[152:155], v144 offset:1024
	ds_read_b128 v[156:159], v144 offset:2048
	ds_read_b128 v[160:163], v144 offset:3072
	ds_read_b128 v[164:167], v145
	ds_read_b128 v[168:171], v145 offset:1024
	ds_read_b128 v[172:175], v145 offset:2048
	ds_read_b128 v[176:179], v145 offset:3072
	s_add_u32 s38, s36, 0xfffe0080
	s_addc_u32 s39, s37, -1
	s_cmp_eq_u32 s69, 4
	s_cselect_b32 s43, s63, s39
	s_cselect_b32 s42, s64, s38
	s_cselect_b32 s39, s65, s68
	s_cselect_b32 s38, s66, s67
	v_lshl_add_u64 v[214:215], s[36:37], 0, v[138:139]
	s_add_i32 m0, s19, 0xc000
	ds_read_b128 v[180:183], v146
	ds_read_b128 v[184:187], v146 offset:1024
	ds_read_b128 v[188:191], v146 offset:2048
	ds_read_b128 v[192:195], v146 offset:3072
	ds_read_b128 v[196:199], v146 offset:4096
	ds_read_b128 v[200:203], v146 offset:5120
	ds_read_b128 v[206:209], v146 offset:6144
	ds_read_b128 v[210:213], v146 offset:7168
	global_load_lds_dwordx4 v[214:215], off
	s_add_i32 m0, s19, 0xe000
	v_lshl_add_u64 v[214:215], s[36:37], 0, v[140:141]
	global_load_lds_dwordx4 v[214:215], off
	s_nop 0
	s_waitcnt vmcnt(8) lgkmcnt(0)
	s_setprio 1
	s_barrier
	v_mfma_f32_16x16x32_bf16 v[126:129], v[148:151], v[180:183], v[126:129]
	v_mfma_f32_16x16x32_bf16 v[122:125], v[156:159], v[180:183], v[122:125]
	v_mfma_f32_16x16x32_bf16 v[118:121], v[148:151], v[188:191], v[118:121]
	v_mfma_f32_16x16x32_bf16 v[114:117], v[156:159], v[188:191], v[114:117]
	v_mfma_f32_16x16x32_bf16 v[102:105], v[148:151], v[196:199], v[102:105]
	v_mfma_f32_16x16x32_bf16 v[98:101], v[156:159], v[196:199], v[98:101]
	v_mfma_f32_16x16x32_bf16 v[86:89], v[148:151], v[206:209], v[86:89]
	v_mfma_f32_16x16x32_bf16 v[82:85], v[156:159], v[206:209], v[82:85]
	v_mfma_f32_16x16x32_bf16 v[126:129], v[152:155], v[184:187], v[126:129]
	v_mfma_f32_16x16x32_bf16 v[122:125], v[160:163], v[184:187], v[122:125]
	v_mfma_f32_16x16x32_bf16 v[118:121], v[152:155], v[192:195], v[118:121]
	v_mfma_f32_16x16x32_bf16 v[114:117], v[160:163], v[192:195], v[114:117]
	v_mfma_f32_16x16x32_bf16 v[102:105], v[152:155], v[200:203], v[102:105]
	v_mfma_f32_16x16x32_bf16 v[98:101], v[160:163], v[200:203], v[98:101]
	v_mfma_f32_16x16x32_bf16 v[86:89], v[152:155], v[210:213], v[86:89]
	v_mfma_f32_16x16x32_bf16 v[82:85], v[160:163], v[210:213], v[82:85]
	v_mfma_f32_16x16x32_bf16 v[110:113], v[164:167], v[180:183], v[110:113]
	v_mfma_f32_16x16x32_bf16 v[106:109], v[172:175], v[180:183], v[106:109]
	v_mfma_f32_16x16x32_bf16 v[94:97], v[164:167], v[188:191], v[94:97]
	v_mfma_f32_16x16x32_bf16 v[90:93], v[172:175], v[188:191], v[90:93]
	v_mfma_f32_16x16x32_bf16 v[78:81], v[164:167], v[196:199], v[78:81]
	v_mfma_f32_16x16x32_bf16 v[74:77], v[172:175], v[196:199], v[74:77]
	v_mfma_f32_16x16x32_bf16 v[70:73], v[164:167], v[206:209], v[70:73]
	v_mfma_f32_16x16x32_bf16 v[66:69], v[172:175], v[206:209], v[66:69]
	v_mfma_f32_16x16x32_bf16 v[110:113], v[168:171], v[184:187], v[110:113]
	v_mfma_f32_16x16x32_bf16 v[106:109], v[176:179], v[184:187], v[106:109]
	v_mfma_f32_16x16x32_bf16 v[94:97], v[168:171], v[192:195], v[94:97]
	v_mfma_f32_16x16x32_bf16 v[90:93], v[176:179], v[192:195], v[90:93]
	v_mfma_f32_16x16x32_bf16 v[78:81], v[168:171], v[200:203], v[78:81]
	v_mfma_f32_16x16x32_bf16 v[74:77], v[176:179], v[200:203], v[74:77]
	v_mfma_f32_16x16x32_bf16 v[70:73], v[168:171], v[210:213], v[70:73]
	v_mfma_f32_16x16x32_bf16 v[66:69], v[176:179], v[210:213], v[66:69]
	s_setprio 0
	s_barrier
	s_add_i32 s70, s35, s18
	v_lshl_add_u64 v[214:215], s[38:39], 0, v[134:135]
	s_mov_b32 m0, s70
	ds_read_b128 v[180:183], v146 offset:16384
	ds_read_b128 v[184:187], v146 offset:17408
	ds_read_b128 v[188:191], v146 offset:18432
	ds_read_b128 v[192:195], v146 offset:19456
	ds_read_b128 v[196:199], v146 offset:20480
	ds_read_b128 v[200:203], v146 offset:21504
	ds_read_b128 v[206:209], v146 offset:22528
	ds_read_b128 v[210:213], v146 offset:23552
	global_load_lds_dwordx4 v[214:215], off
	s_add_i32 m0, s70, 0x2000
	s_add_u32 s70, s38, 0x200000
	v_lshl_add_u64 v[216:217], s[38:39], 0, v[130:131]
	s_addc_u32 s71, s39, 0
	s_add_i32 s72, s44, s18
	global_load_lds_dwordx4 v[216:217], off
	v_lshl_add_u64 v[218:219], s[70:71], 0, v[134:135]
	s_mov_b32 m0, s72
	v_lshl_add_u64 v[220:221], s[42:43], 0, v[132:133]
	global_load_lds_dwordx4 v[218:219], off
	s_add_i32 m0, s72, 0x2000
	v_lshl_add_u64 v[218:219], s[70:71], 0, v[130:131]
	global_load_lds_dwordx4 v[218:219], off
	s_mov_b32 m0, s19
	v_lshl_add_u64 v[218:219], s[42:43], 0, v[136:137]
	global_load_lds_dwordx4 v[218:219], off
	s_mov_b32 m0, s24
	s_nop 0
	global_load_lds_dwordx4 v[220:221], off
	s_nop 0
	s_waitcnt vmcnt(8) lgkmcnt(0)
	s_setprio 1
	s_barrier
	v_mfma_f32_16x16x32_bf16 v[62:65], v[148:151], v[180:183], v[62:65]
	v_mfma_f32_16x16x32_bf16 v[58:61], v[156:159], v[180:183], v[58:61]
	v_mfma_f32_16x16x32_bf16 v[54:57], v[148:151], v[188:191], v[54:57]
	v_mfma_f32_16x16x32_bf16 v[50:53], v[156:159], v[188:191], v[50:53]
	v_mfma_f32_16x16x32_bf16 v[38:41], v[148:151], v[196:199], v[38:41]
	v_mfma_f32_16x16x32_bf16 v[34:37], v[156:159], v[196:199], v[34:37]
	v_mfma_f32_16x16x32_bf16 v[22:25], v[148:151], v[206:209], v[22:25]
	v_mfma_f32_16x16x32_bf16 v[18:21], v[156:159], v[206:209], v[18:21]
	v_mfma_f32_16x16x32_bf16 v[62:65], v[152:155], v[184:187], v[62:65]
	v_mfma_f32_16x16x32_bf16 v[58:61], v[160:163], v[184:187], v[58:61]
	v_mfma_f32_16x16x32_bf16 v[54:57], v[152:155], v[192:195], v[54:57]
	v_mfma_f32_16x16x32_bf16 v[50:53], v[160:163], v[192:195], v[50:53]
	v_mfma_f32_16x16x32_bf16 v[38:41], v[152:155], v[200:203], v[38:41]
	v_mfma_f32_16x16x32_bf16 v[34:37], v[160:163], v[200:203], v[34:37]
	v_mfma_f32_16x16x32_bf16 v[22:25], v[152:155], v[210:213], v[22:25]
	v_mfma_f32_16x16x32_bf16 v[18:21], v[160:163], v[210:213], v[18:21]
	v_mfma_f32_16x16x32_bf16 v[46:49], v[164:167], v[180:183], v[46:49]
	v_mfma_f32_16x16x32_bf16 v[42:45], v[172:175], v[180:183], v[42:45]
	v_mfma_f32_16x16x32_bf16 v[30:33], v[164:167], v[188:191], v[30:33]
	v_mfma_f32_16x16x32_bf16 v[26:29], v[172:175], v[188:191], v[26:29]
	v_mfma_f32_16x16x32_bf16 v[14:17], v[164:167], v[196:199], v[14:17]
	v_mfma_f32_16x16x32_bf16 v[10:13], v[172:175], v[196:199], v[10:13]
	v_mfma_f32_16x16x32_bf16 v[6:9], v[164:167], v[206:209], v[6:9]
	v_mfma_f32_16x16x32_bf16 v[2:5], v[172:175], v[206:209], v[2:5]
	v_mfma_f32_16x16x32_bf16 v[46:49], v[168:171], v[184:187], v[46:49]
	v_mfma_f32_16x16x32_bf16 v[42:45], v[176:179], v[184:187], v[42:45]
	v_mfma_f32_16x16x32_bf16 v[30:33], v[168:171], v[192:195], v[30:33]
	v_mfma_f32_16x16x32_bf16 v[26:29], v[176:179], v[192:195], v[26:29]
	v_mfma_f32_16x16x32_bf16 v[14:17], v[168:171], v[200:203], v[14:17]
	v_mfma_f32_16x16x32_bf16 v[10:13], v[176:179], v[200:203], v[10:13]
	v_mfma_f32_16x16x32_bf16 v[6:9], v[168:171], v[210:213], v[6:9]
	v_mfma_f32_16x16x32_bf16 v[2:5], v[176:179], v[210:213], v[2:5]
	s_setprio 0
	s_barrier
	s_add_i32 s70, 0, 0x18000
	v_add_u32_e32 v147, s70, v143
	s_add_i32 s71, 0, 0x1c000
	ds_read_b128 v[148:151], v147
	ds_read_b128 v[152:155], v147 offset:1024
	ds_read_b128 v[156:159], v147 offset:2048
	ds_read_b128 v[160:163], v147 offset:3072
	v_add_u32_e32 v147, s71, v143
	ds_read_b128 v[164:167], v147
	ds_read_b128 v[168:171], v147 offset:1024
	ds_read_b128 v[172:175], v147 offset:2048
	ds_read_b128 v[176:179], v147 offset:3072
	s_add_u32 s42, s42, 0x20000
	s_addc_u32 s43, s43, 0
	s_mov_b32 m0, s25
	v_lshl_add_u64 v[222:223], s[42:43], 0, v[136:137]
	ds_read_b128 v[180:183], v146 offset:32768
	ds_read_b128 v[184:187], v146 offset:33792
	ds_read_b128 v[188:191], v146 offset:34816
	ds_read_b128 v[192:195], v146 offset:35840
	ds_read_b128 v[196:199], v146 offset:36864
	ds_read_b128 v[200:203], v146 offset:37888
	ds_read_b128 v[206:209], v146 offset:38912
	ds_read_b128 v[210:213], v146 offset:39936
	global_load_lds_dwordx4 v[222:223], off
	s_mov_b32 m0, s28
	v_lshl_add_u64 v[222:223], s[42:43], 0, v[132:133]
	global_load_lds_dwordx4 v[222:223], off
	s_waitcnt vmcnt(8) lgkmcnt(0)
	s_setprio 1
	s_barrier
	v_mfma_f32_16x16x32_bf16 v[126:129], v[148:151], v[180:183], v[126:129]
	v_mfma_f32_16x16x32_bf16 v[122:125], v[156:159], v[180:183], v[122:125]
	v_mfma_f32_16x16x32_bf16 v[118:121], v[148:151], v[188:191], v[118:121]
	v_mfma_f32_16x16x32_bf16 v[114:117], v[156:159], v[188:191], v[114:117]
	v_mfma_f32_16x16x32_bf16 v[102:105], v[148:151], v[196:199], v[102:105]
	v_mfma_f32_16x16x32_bf16 v[98:101], v[156:159], v[196:199], v[98:101]
	v_mfma_f32_16x16x32_bf16 v[86:89], v[148:151], v[206:209], v[86:89]
	v_mfma_f32_16x16x32_bf16 v[82:85], v[156:159], v[206:209], v[82:85]
	v_mfma_f32_16x16x32_bf16 v[126:129], v[152:155], v[184:187], v[126:129]
	v_mfma_f32_16x16x32_bf16 v[122:125], v[160:163], v[184:187], v[122:125]
	v_mfma_f32_16x16x32_bf16 v[118:121], v[152:155], v[192:195], v[118:121]
	v_mfma_f32_16x16x32_bf16 v[114:117], v[160:163], v[192:195], v[114:117]
	v_mfma_f32_16x16x32_bf16 v[102:105], v[152:155], v[200:203], v[102:105]
	v_mfma_f32_16x16x32_bf16 v[98:101], v[160:163], v[200:203], v[98:101]
	v_mfma_f32_16x16x32_bf16 v[86:89], v[152:155], v[210:213], v[86:89]
	v_mfma_f32_16x16x32_bf16 v[82:85], v[160:163], v[210:213], v[82:85]
	v_mfma_f32_16x16x32_bf16 v[110:113], v[164:167], v[180:183], v[110:113]
	v_mfma_f32_16x16x32_bf16 v[106:109], v[172:175], v[180:183], v[106:109]
	v_mfma_f32_16x16x32_bf16 v[94:97], v[164:167], v[188:191], v[94:97]
	v_mfma_f32_16x16x32_bf16 v[90:93], v[172:175], v[188:191], v[90:93]
	v_mfma_f32_16x16x32_bf16 v[78:81], v[164:167], v[196:199], v[78:81]
	v_mfma_f32_16x16x32_bf16 v[74:77], v[172:175], v[196:199], v[74:77]
	v_mfma_f32_16x16x32_bf16 v[70:73], v[164:167], v[206:209], v[70:73]
	v_mfma_f32_16x16x32_bf16 v[66:69], v[172:175], v[206:209], v[66:69]
	v_mfma_f32_16x16x32_bf16 v[110:113], v[168:171], v[184:187], v[110:113]
	v_mfma_f32_16x16x32_bf16 v[106:109], v[176:179], v[184:187], v[106:109]
	v_mfma_f32_16x16x32_bf16 v[94:97], v[168:171], v[192:195], v[94:97]
	v_mfma_f32_16x16x32_bf16 v[90:93], v[176:179], v[192:195], v[90:93]
	v_mfma_f32_16x16x32_bf16 v[78:81], v[168:171], v[200:203], v[78:81]
	v_mfma_f32_16x16x32_bf16 v[74:77], v[176:179], v[200:203], v[74:77]
	v_mfma_f32_16x16x32_bf16 v[70:73], v[168:171], v[210:213], v[70:73]
	v_mfma_f32_16x16x32_bf16 v[66:69], v[176:179], v[210:213], v[66:69]
	s_setprio 0
	s_barrier
	s_add_i32 s42, s70, s18
	v_lshl_add_u64 v[214:215], v[214:215], 0, s[8:9]
	s_mov_b32 m0, s42
	ds_read_b128 v[180:183], v146 offset:49152
	ds_read_b128 v[184:187], v146 offset:50176
	ds_read_b128 v[188:191], v146 offset:51200
	ds_read_b128 v[192:195], v146 offset:52224
	ds_read_b128 v[196:199], v146 offset:53248
	ds_read_b128 v[200:203], v146 offset:54272
	ds_read_b128 v[206:209], v146 offset:55296
	ds_read_b128 v[210:213], v146 offset:56320
	global_load_lds_dwordx4 v[214:215], off
	s_add_i32 m0, s42, 0x2000
	s_add_u32 s38, s38, 0x200080
	v_lshl_add_u64 v[214:215], v[216:217], 0, s[8:9]
	s_addc_u32 s39, s39, 0
	s_add_i32 s42, s71, s18
	global_load_lds_dwordx4 v[214:215], off
	s_mov_b32 m0, s42
	v_lshl_add_u64 v[214:215], s[38:39], 0, v[134:135]
	global_load_lds_dwordx4 v[214:215], off
	s_add_i32 m0, s42, 0x2000
	v_lshl_add_u64 v[214:215], s[38:39], 0, v[130:131]
	global_load_lds_dwordx4 v[214:215], off
	s_mov_b32 m0, s33
	v_lshl_add_u64 v[214:215], v[218:219], 0, s[8:9]
	global_load_lds_dwordx4 v[214:215], off
	s_mov_b32 m0, s34
	v_lshl_add_u64 v[214:215], v[220:221], 0, s[8:9]
	global_load_lds_dwordx4 v[214:215], off
	s_waitcnt vmcnt(8) lgkmcnt(0)
	s_setprio 1
	s_barrier
	v_mfma_f32_16x16x32_bf16 v[62:65], v[148:151], v[180:183], v[62:65]
	v_mfma_f32_16x16x32_bf16 v[58:61], v[156:159], v[180:183], v[58:61]
	v_mfma_f32_16x16x32_bf16 v[54:57], v[148:151], v[188:191], v[54:57]
	v_mfma_f32_16x16x32_bf16 v[50:53], v[156:159], v[188:191], v[50:53]
	v_mfma_f32_16x16x32_bf16 v[38:41], v[148:151], v[196:199], v[38:41]
	v_mfma_f32_16x16x32_bf16 v[34:37], v[156:159], v[196:199], v[34:37]
	v_mfma_f32_16x16x32_bf16 v[22:25], v[148:151], v[206:209], v[22:25]
	v_mfma_f32_16x16x32_bf16 v[18:21], v[156:159], v[206:209], v[18:21]
	v_mfma_f32_16x16x32_bf16 v[62:65], v[152:155], v[184:187], v[62:65]
	v_mfma_f32_16x16x32_bf16 v[58:61], v[160:163], v[184:187], v[58:61]
	v_mfma_f32_16x16x32_bf16 v[54:57], v[152:155], v[192:195], v[54:57]
	v_mfma_f32_16x16x32_bf16 v[50:53], v[160:163], v[192:195], v[50:53]
	v_mfma_f32_16x16x32_bf16 v[38:41], v[152:155], v[200:203], v[38:41]
	v_mfma_f32_16x16x32_bf16 v[34:37], v[160:163], v[200:203], v[34:37]
	v_mfma_f32_16x16x32_bf16 v[22:25], v[152:155], v[210:213], v[22:25]
	v_mfma_f32_16x16x32_bf16 v[18:21], v[160:163], v[210:213], v[18:21]
	v_mfma_f32_16x16x32_bf16 v[46:49], v[164:167], v[180:183], v[46:49]
	v_mfma_f32_16x16x32_bf16 v[42:45], v[172:175], v[180:183], v[42:45]
	v_mfma_f32_16x16x32_bf16 v[30:33], v[164:167], v[188:191], v[30:33]
	v_mfma_f32_16x16x32_bf16 v[26:29], v[172:175], v[188:191], v[26:29]
	v_mfma_f32_16x16x32_bf16 v[14:17], v[164:167], v[196:199], v[14:17]
	v_mfma_f32_16x16x32_bf16 v[10:13], v[172:175], v[196:199], v[10:13]
	v_mfma_f32_16x16x32_bf16 v[6:9], v[164:167], v[206:209], v[6:9]
	v_mfma_f32_16x16x32_bf16 v[2:5], v[172:175], v[206:209], v[2:5]
	v_mfma_f32_16x16x32_bf16 v[46:49], v[168:171], v[184:187], v[46:49]
	v_mfma_f32_16x16x32_bf16 v[42:45], v[176:179], v[184:187], v[42:45]
	v_mfma_f32_16x16x32_bf16 v[30:33], v[168:171], v[192:195], v[30:33]
	v_mfma_f32_16x16x32_bf16 v[26:29], v[176:179], v[192:195], v[26:29]
	v_mfma_f32_16x16x32_bf16 v[14:17], v[168:171], v[200:203], v[14:17]
	v_mfma_f32_16x16x32_bf16 v[10:13], v[176:179], v[200:203], v[10:13]
	v_mfma_f32_16x16x32_bf16 v[6:9], v[168:171], v[210:213], v[6:9]
	v_mfma_f32_16x16x32_bf16 v[2:5], v[176:179], v[210:213], v[2:5]
	s_setprio 0
	s_barrier
	s_add_i32 s69, s69, 2
	s_add_u32 s36, s36, 0x100
	s_addc_u32 s37, s37, 0
	s_add_u32 s67, s67, 0x100
	s_addc_u32 s68, s68, 0
	s_cmp_gt_u32 s69, 5
	s_cbranch_scc0 .LBB0_477
	s_and_b64 vcc, exec, s[10:11]
	s_cbranch_vccz .LBB0_480
	s_barrier

.LBB0_565:
	v_readlane_b32 s62, v249, 27
	v_readlane_b32 s63, v249, 28
	s_add_u32 s72, s62, s68
	s_addc_u32 s73, s63, s69
	s_and_b64 s[62:63], s[70:71], exec
	s_cselect_b32 s31, s73, s77
	s_cselect_b32 s33, s72, s76
	s_add_u32 s74, s35, s66
	s_addc_u32 s75, s85, s67
	s_and_b64 s[62:63], s[70:71], exec
	s_cselect_b32 s34, s75, s79
	s_cselect_b32 s39, s74, s78
	s_add_i32 s45, s7, -2
	s_add_u32 s76, s76, 0x40080
	s_addc_u32 s77, s77, 0
	s_add_u32 s47, s78, 0x100
	s_addc_u32 s62, s79, 0
	s_mov_b32 s63, 0
	s_waitcnt vmcnt(0)
	ds_read_b128 v[114:117], v190
	ds_read_b128 v[118:121], v190 offset:1024
	ds_read_b128 v[122:125], v190 offset:2048
	ds_read_b128 v[126:129], v190 offset:3072
	ds_read_b128 v[146:149], v191
	ds_read_b128 v[150:153], v191 offset:1024
	ds_read_b128 v[154:157], v191 offset:2048
	ds_read_b128 v[158:161], v191 offset:3072
	s_add_i32 s82, s63, 2
	s_add_u32 s78, s76, 0xfffc0080
	s_addc_u32 s79, s77, -1
	s_cmp_eq_u32 s45, s63
	s_cselect_b32 s81, s31, s79
	s_cselect_b32 s80, s33, s78
	s_cselect_b32 s79, s34, s62
	s_cselect_b32 s78, s39, s47
	v_lshl_add_u64 v[186:187], s[76:77], 0, v[180:181]
	s_add_i32 m0, s87, 0xc000
	ds_read_b128 v[162:165], v192
	ds_read_b128 v[166:169], v192 offset:1024
	ds_read_b128 v[194:197], v192 offset:2048
	ds_read_b128 v[198:201], v192 offset:3072
	ds_read_b128 v[206:209], v192 offset:4096
	ds_read_b128 v[210:213], v192 offset:5120
	ds_read_b128 v[214:217], v192 offset:6144
	ds_read_b128 v[218:221], v192 offset:7168
	global_load_lds_dwordx4 v[186:187], off
	s_add_i32 m0, s87, 0xe000
	v_lshl_add_u64 v[186:187], s[76:77], 0, v[182:183]
	global_load_lds_dwordx4 v[186:187], off
	s_waitcnt vmcnt(8)
	s_waitcnt lgkmcnt(0)
	s_setprio 1
	s_barrier
	v_mfma_f32_16x16x32_bf16 v[142:145], v[114:117], v[162:165], 0
	v_mfma_f32_16x16x32_bf16 v[138:141], v[122:125], v[162:165], 0
	v_mfma_f32_16x16x32_bf16 v[110:113], v[114:117], v[194:197], 0
	v_mfma_f32_16x16x32_bf16 v[106:109], v[122:125], v[194:197], 0
	v_mfma_f32_16x16x32_bf16 v[98:101], v[114:117], v[206:209], 0
	v_mfma_f32_16x16x32_bf16 v[90:93], v[122:125], v[206:209], 0
	v_mfma_f32_16x16x32_bf16 v[82:85], v[114:117], v[214:217], 0
	v_mfma_f32_16x16x32_bf16 v[74:77], v[122:125], v[214:217], 0
	v_mfma_f32_16x16x32_bf16 v[142:145], v[118:121], v[166:169], v[142:145]
	v_mfma_f32_16x16x32_bf16 v[138:141], v[126:129], v[166:169], v[138:141]
	v_mfma_f32_16x16x32_bf16 v[110:113], v[118:121], v[198:201], v[110:113]
	v_mfma_f32_16x16x32_bf16 v[106:109], v[126:129], v[198:201], v[106:109]
	v_mfma_f32_16x16x32_bf16 v[98:101], v[118:121], v[210:213], v[98:101]
	v_mfma_f32_16x16x32_bf16 v[90:93], v[126:129], v[210:213], v[90:93]
	v_mfma_f32_16x16x32_bf16 v[82:85], v[118:121], v[218:221], v[82:85]
	v_mfma_f32_16x16x32_bf16 v[74:77], v[126:129], v[218:221], v[74:77]
	v_mfma_f32_16x16x32_bf16 v[134:137], v[146:149], v[162:165], 0
	v_mfma_f32_16x16x32_bf16 v[130:133], v[154:157], v[162:165], 0
	v_mfma_f32_16x16x32_bf16 v[102:105], v[146:149], v[194:197], 0
	v_mfma_f32_16x16x32_bf16 v[94:97], v[154:157], v[194:197], 0
	v_mfma_f32_16x16x32_bf16 v[86:89], v[146:149], v[206:209], 0
	v_mfma_f32_16x16x32_bf16 v[78:81], v[154:157], v[206:209], 0
	v_mfma_f32_16x16x32_bf16 v[70:73], v[146:149], v[214:217], 0
	v_mfma_f32_16x16x32_bf16 v[66:69], v[154:157], v[214:217], 0
	v_mfma_f32_16x16x32_bf16 v[134:137], v[150:153], v[166:169], v[134:137]
	v_mfma_f32_16x16x32_bf16 v[130:133], v[158:161], v[166:169], v[130:133]
	v_mfma_f32_16x16x32_bf16 v[102:105], v[150:153], v[198:201], v[102:105]
	v_mfma_f32_16x16x32_bf16 v[94:97], v[158:161], v[198:201], v[94:97]
	v_mfma_f32_16x16x32_bf16 v[86:89], v[150:153], v[210:213], v[86:89]
	v_mfma_f32_16x16x32_bf16 v[78:81], v[158:161], v[210:213], v[78:81]
	v_mfma_f32_16x16x32_bf16 v[70:73], v[150:153], v[218:221], v[70:73]
	v_mfma_f32_16x16x32_bf16 v[66:69], v[158:161], v[218:221], v[66:69]
	s_setprio 0
	s_barrier
	s_add_i32 s63, s24, s86
	v_lshl_add_u64 v[186:187], s[78:79], 0, v[172:173]
	s_mov_b32 m0, s63
	ds_read_b128 v[162:165], v192 offset:16384
	ds_read_b128 v[166:169], v192 offset:17408
	ds_read_b128 v[194:197], v192 offset:18432
	ds_read_b128 v[198:201], v192 offset:19456
	ds_read_b128 v[206:209], v192 offset:20480
	ds_read_b128 v[210:213], v192 offset:21504
	ds_read_b128 v[214:217], v192 offset:22528
	ds_read_b128 v[218:221], v192 offset:23552
	global_load_lds_dwordx4 v[186:187], off
	s_add_i32 m0, s63, 0x2000
	s_add_u32 vcc_lo, s78, 0x40000
	v_lshl_add_u64 v[202:203], s[78:79], 0, v[176:177]
	s_addc_u32 vcc_hi, s79, 0
	s_add_i32 s63, s25, s86
	global_load_lds_dwordx4 v[202:203], off
	v_lshl_add_u64 v[222:223], vcc, 0, v[172:173]
	s_mov_b32 m0, s63
	v_lshl_add_u64 v[224:225], s[80:81], 0, v[174:175]
	global_load_lds_dwordx4 v[222:223], off
	s_add_i32 m0, s63, 0x2000
	v_lshl_add_u64 v[222:223], vcc, 0, v[176:177]
	global_load_lds_dwordx4 v[222:223], off
	s_mov_b32 m0, s87
	v_lshl_add_u64 v[222:223], s[80:81], 0, v[170:171]
	global_load_lds_dwordx4 v[222:223], off
	s_mov_b32 m0, s88
	s_nop 0
	global_load_lds_dwordx4 v[224:225], off
	s_nop 0
	s_waitcnt vmcnt(8) lgkmcnt(0)
	s_setprio 1
	s_barrier
	v_mfma_f32_16x16x32_bf16 v[62:65], v[114:117], v[162:165], 0
	v_mfma_f32_16x16x32_bf16 v[58:61], v[122:125], v[162:165], 0
	v_mfma_f32_16x16x32_bf16 v[50:53], v[114:117], v[194:197], 0
	v_mfma_f32_16x16x32_bf16 v[42:45], v[122:125], v[194:197], 0
	v_mfma_f32_16x16x32_bf16 v[34:37], v[114:117], v[206:209], 0
	v_mfma_f32_16x16x32_bf16 v[26:29], v[122:125], v[206:209], 0
	v_mfma_f32_16x16x32_bf16 v[18:21], v[114:117], v[214:217], 0
	v_mfma_f32_16x16x32_bf16 v[10:13], v[122:125], v[214:217], 0
	v_mfma_f32_16x16x32_bf16 v[62:65], v[118:121], v[166:169], v[62:65]
	v_mfma_f32_16x16x32_bf16 v[58:61], v[126:129], v[166:169], v[58:61]
	v_mfma_f32_16x16x32_bf16 v[50:53], v[118:121], v[198:201], v[50:53]
	v_mfma_f32_16x16x32_bf16 v[42:45], v[126:129], v[198:201], v[42:45]
	v_mfma_f32_16x16x32_bf16 v[34:37], v[118:121], v[210:213], v[34:37]
	v_mfma_f32_16x16x32_bf16 v[26:29], v[126:129], v[210:213], v[26:29]
	v_mfma_f32_16x16x32_bf16 v[18:21], v[118:121], v[218:221], v[18:21]
	v_mfma_f32_16x16x32_bf16 v[10:13], v[126:129], v[218:221], v[10:13]
	v_mfma_f32_16x16x32_bf16 v[54:57], v[146:149], v[162:165], 0
	v_mfma_f32_16x16x32_bf16 v[46:49], v[154:157], v[162:165], 0
	v_mfma_f32_16x16x32_bf16 v[38:41], v[146:149], v[194:197], 0
	v_mfma_f32_16x16x32_bf16 v[30:33], v[154:157], v[194:197], 0
	v_mfma_f32_16x16x32_bf16 v[22:25], v[146:149], v[206:209], 0
	v_mfma_f32_16x16x32_bf16 v[14:17], v[154:157], v[206:209], 0
	v_mfma_f32_16x16x32_bf16 v[6:9], v[146:149], v[214:217], 0
	v_mfma_f32_16x16x32_bf16 v[2:5], v[154:157], v[214:217], 0
	v_mfma_f32_16x16x32_bf16 v[54:57], v[150:153], v[166:169], v[54:57]
	v_mfma_f32_16x16x32_bf16 v[46:49], v[158:161], v[166:169], v[46:49]
	v_mfma_f32_16x16x32_bf16 v[38:41], v[150:153], v[198:201], v[38:41]
	v_mfma_f32_16x16x32_bf16 v[30:33], v[158:161], v[198:201], v[30:33]
	v_mfma_f32_16x16x32_bf16 v[22:25], v[150:153], v[210:213], v[22:25]
	v_mfma_f32_16x16x32_bf16 v[14:17], v[158:161], v[210:213], v[14:17]
	v_mfma_f32_16x16x32_bf16 v[6:9], v[150:153], v[218:221], v[6:9]
	v_mfma_f32_16x16x32_bf16 v[2:5], v[158:161], v[218:221], v[2:5]
	s_setprio 0
	s_barrier
	s_add_i32 s63, 0, 0x18000
	s_add_i32 s83, 0, 0x1c000
	v_add_u32_e32 v126, s63, v189
	v_add_u32_e32 v158, s83, v189
	ds_read_b128 v[114:117], v126
	ds_read_b128 v[118:121], v126 offset:1024
	ds_read_b128 v[122:125], v126 offset:2048
	ds_read_b128 v[126:129], v126 offset:3072
	ds_read_b128 v[146:149], v158
	ds_read_b128 v[150:153], v158 offset:1024
	ds_read_b128 v[154:157], v158 offset:2048
	ds_read_b128 v[158:161], v158 offset:3072
	s_add_u32 s80, s80, 0x40000
	s_addc_u32 s81, s81, 0
	s_mov_b32 m0, s89
	v_lshl_add_u64 v[226:227], s[80:81], 0, v[170:171]
	ds_read_b128 v[162:165], v192 offset:32768
	ds_read_b128 v[166:169], v192 offset:33792
	ds_read_b128 v[194:197], v192 offset:34816
	ds_read_b128 v[198:201], v192 offset:35840
	ds_read_b128 v[206:209], v192 offset:36864
	ds_read_b128 v[210:213], v192 offset:37888
	ds_read_b128 v[214:217], v192 offset:38912
	ds_read_b128 v[218:221], v192 offset:39936
	global_load_lds_dwordx4 v[226:227], off
	s_mov_b32 m0, s90
	v_lshl_add_u64 v[226:227], s[80:81], 0, v[174:175]
	global_load_lds_dwordx4 v[226:227], off
	s_waitcnt vmcnt(8) lgkmcnt(0)
	s_setprio 1
	s_barrier
	v_mfma_f32_16x16x32_bf16 v[142:145], v[114:117], v[162:165], v[142:145]
	v_mfma_f32_16x16x32_bf16 v[138:141], v[122:125], v[162:165], v[138:141]
	v_mfma_f32_16x16x32_bf16 v[110:113], v[114:117], v[194:197], v[110:113]
	v_mfma_f32_16x16x32_bf16 v[106:109], v[122:125], v[194:197], v[106:109]
	v_mfma_f32_16x16x32_bf16 v[98:101], v[114:117], v[206:209], v[98:101]
	v_mfma_f32_16x16x32_bf16 v[90:93], v[122:125], v[206:209], v[90:93]
	v_mfma_f32_16x16x32_bf16 v[82:85], v[114:117], v[214:217], v[82:85]
	v_mfma_f32_16x16x32_bf16 v[74:77], v[122:125], v[214:217], v[74:77]
	v_mfma_f32_16x16x32_bf16 v[142:145], v[118:121], v[166:169], v[142:145]
	v_mfma_f32_16x16x32_bf16 v[138:141], v[126:129], v[166:169], v[138:141]
	v_mfma_f32_16x16x32_bf16 v[110:113], v[118:121], v[198:201], v[110:113]
	v_mfma_f32_16x16x32_bf16 v[106:109], v[126:129], v[198:201], v[106:109]
	v_mfma_f32_16x16x32_bf16 v[98:101], v[118:121], v[210:213], v[98:101]
	v_mfma_f32_16x16x32_bf16 v[90:93], v[126:129], v[210:213], v[90:93]
	v_mfma_f32_16x16x32_bf16 v[82:85], v[118:121], v[218:221], v[82:85]
	v_mfma_f32_16x16x32_bf16 v[74:77], v[126:129], v[218:221], v[74:77]
	v_mfma_f32_16x16x32_bf16 v[134:137], v[146:149], v[162:165], v[134:137]
	v_mfma_f32_16x16x32_bf16 v[130:133], v[154:157], v[162:165], v[130:133]
	v_mfma_f32_16x16x32_bf16 v[102:105], v[146:149], v[194:197], v[102:105]
	v_mfma_f32_16x16x32_bf16 v[94:97], v[154:157], v[194:197], v[94:97]
	v_mfma_f32_16x16x32_bf16 v[86:89], v[146:149], v[206:209], v[86:89]
	v_mfma_f32_16x16x32_bf16 v[78:81], v[154:157], v[206:209], v[78:81]
	v_mfma_f32_16x16x32_bf16 v[70:73], v[146:149], v[214:217], v[70:73]
	v_mfma_f32_16x16x32_bf16 v[66:69], v[154:157], v[214:217], v[66:69]
	v_mfma_f32_16x16x32_bf16 v[134:137], v[150:153], v[166:169], v[134:137]
	v_mfma_f32_16x16x32_bf16 v[130:133], v[158:161], v[166:169], v[130:133]
	v_mfma_f32_16x16x32_bf16 v[102:105], v[150:153], v[198:201], v[102:105]
	v_mfma_f32_16x16x32_bf16 v[94:97], v[158:161], v[198:201], v[94:97]
	v_mfma_f32_16x16x32_bf16 v[86:89], v[150:153], v[210:213], v[86:89]
	v_mfma_f32_16x16x32_bf16 v[78:81], v[158:161], v[210:213], v[78:81]
	v_mfma_f32_16x16x32_bf16 v[70:73], v[150:153], v[218:221], v[70:73]
	v_mfma_f32_16x16x32_bf16 v[66:69], v[158:161], v[218:221], v[66:69]
	s_setprio 0
	s_barrier
	s_add_i32 s63, s63, s86
	v_lshl_add_u64 v[186:187], v[186:187], 0, s[22:23]
	s_mov_b32 m0, s63
	ds_read_b128 v[162:165], v192 offset:49152
	ds_read_b128 v[166:169], v192 offset:50176
	ds_read_b128 v[194:197], v192 offset:51200
	ds_read_b128 v[198:201], v192 offset:52224
	ds_read_b128 v[206:209], v192 offset:53248
	ds_read_b128 v[210:213], v192 offset:54272
	ds_read_b128 v[214:217], v192 offset:55296
	ds_read_b128 v[218:221], v192 offset:56320
	global_load_lds_dwordx4 v[186:187], off
	s_add_i32 m0, s63, 0x2000
	s_add_u32 s78, s78, 0x40080
	v_lshl_add_u64 v[186:187], v[202:203], 0, s[22:23]
	s_addc_u32 s79, s79, 0
	s_add_i32 s63, s83, s86
	global_load_lds_dwordx4 v[186:187], off
	s_mov_b32 m0, s63
	v_lshl_add_u64 v[186:187], s[78:79], 0, v[172:173]
	global_load_lds_dwordx4 v[186:187], off
	s_add_i32 m0, s63, 0x2000
	v_lshl_add_u64 v[186:187], s[78:79], 0, v[176:177]
	global_load_lds_dwordx4 v[186:187], off
	s_mov_b32 m0, s95
	v_lshl_add_u64 v[186:187], v[222:223], 0, s[22:23]
	global_load_lds_dwordx4 v[186:187], off
	s_mov_b32 m0, s96
	v_lshl_add_u64 v[186:187], v[224:225], 0, s[22:23]
	global_load_lds_dwordx4 v[186:187], off
	s_waitcnt vmcnt(8) lgkmcnt(0)
	s_setprio 1
	s_barrier
	v_mfma_f32_16x16x32_bf16 v[62:65], v[114:117], v[162:165], v[62:65]
	v_mfma_f32_16x16x32_bf16 v[58:61], v[122:125], v[162:165], v[58:61]
	v_mfma_f32_16x16x32_bf16 v[50:53], v[114:117], v[194:197], v[50:53]
	v_mfma_f32_16x16x32_bf16 v[42:45], v[122:125], v[194:197], v[42:45]
	v_mfma_f32_16x16x32_bf16 v[34:37], v[114:117], v[206:209], v[34:37]
	v_mfma_f32_16x16x32_bf16 v[26:29], v[122:125], v[206:209], v[26:29]
	v_mfma_f32_16x16x32_bf16 v[18:21], v[114:117], v[214:217], v[18:21]
	v_mfma_f32_16x16x32_bf16 v[10:13], v[122:125], v[214:217], v[10:13]
	v_mfma_f32_16x16x32_bf16 v[62:65], v[118:121], v[166:169], v[62:65]
	v_mfma_f32_16x16x32_bf16 v[58:61], v[126:129], v[166:169], v[58:61]
	v_mfma_f32_16x16x32_bf16 v[50:53], v[118:121], v[198:201], v[50:53]
	v_mfma_f32_16x16x32_bf16 v[42:45], v[126:129], v[198:201], v[42:45]
	v_mfma_f32_16x16x32_bf16 v[34:37], v[118:121], v[210:213], v[34:37]
	v_mfma_f32_16x16x32_bf16 v[26:29], v[126:129], v[210:213], v[26:29]
	v_mfma_f32_16x16x32_bf16 v[18:21], v[118:121], v[218:221], v[18:21]
	v_mfma_f32_16x16x32_bf16 v[10:13], v[126:129], v[218:221], v[10:13]
	v_mfma_f32_16x16x32_bf16 v[54:57], v[146:149], v[162:165], v[54:57]
	v_mfma_f32_16x16x32_bf16 v[46:49], v[154:157], v[162:165], v[46:49]
	v_mfma_f32_16x16x32_bf16 v[38:41], v[146:149], v[194:197], v[38:41]
	v_mfma_f32_16x16x32_bf16 v[30:33], v[154:157], v[194:197], v[30:33]
	v_mfma_f32_16x16x32_bf16 v[22:25], v[146:149], v[206:209], v[22:25]
	v_mfma_f32_16x16x32_bf16 v[14:17], v[154:157], v[206:209], v[14:17]
	v_mfma_f32_16x16x32_bf16 v[6:9], v[146:149], v[214:217], v[6:9]
	v_mfma_f32_16x16x32_bf16 v[2:5], v[154:157], v[214:217], v[2:5]
	v_mfma_f32_16x16x32_bf16 v[54:57], v[150:153], v[166:169], v[54:57]
	v_mfma_f32_16x16x32_bf16 v[46:49], v[158:161], v[166:169], v[46:49]
	v_mfma_f32_16x16x32_bf16 v[38:41], v[150:153], v[198:201], v[38:41]
	v_mfma_f32_16x16x32_bf16 v[30:33], v[158:161], v[198:201], v[30:33]
	v_mfma_f32_16x16x32_bf16 v[22:25], v[150:153], v[210:213], v[22:25]
	v_mfma_f32_16x16x32_bf16 v[14:17], v[158:161], v[210:213], v[14:17]
	v_mfma_f32_16x16x32_bf16 v[6:9], v[150:153], v[218:221], v[6:9]
	v_mfma_f32_16x16x32_bf16 v[2:5], v[158:161], v[218:221], v[2:5]
	s_setprio 0
	s_barrier
	s_add_u32 s76, s76, 0x100
	s_addc_u32 s77, s77, 0
	s_add_u32 s47, s47, 0x100
	s_addc_u32 s62, s62, 0
	s_cmp_ge_i32 s82, s7
	s_mov_b32 s63, s82
.LBB0_566:
	s_waitcnt vmcnt(0)
	ds_read_b128 v[114:117], v190
	ds_read_b128 v[118:121], v190 offset:1024
	ds_read_b128 v[122:125], v190 offset:2048
	ds_read_b128 v[126:129], v190 offset:3072
	ds_read_b128 v[146:149], v191
	ds_read_b128 v[150:153], v191 offset:1024
	ds_read_b128 v[154:157], v191 offset:2048
	ds_read_b128 v[158:161], v191 offset:3072
	s_add_i32 s82, s63, 2
	s_add_u32 s78, s76, 0xfffc0080
	s_addc_u32 s79, s77, -1
	s_cmp_eq_u32 s45, s63
	s_cselect_b32 s81, s31, s79
	s_cselect_b32 s80, s33, s78
	s_cselect_b32 s79, s34, s62
	s_cselect_b32 s78, s39, s47
	v_lshl_add_u64 v[186:187], s[76:77], 0, v[180:181]
	s_add_i32 m0, s87, 0xc000
	ds_read_b128 v[162:165], v192
	ds_read_b128 v[166:169], v192 offset:1024
	ds_read_b128 v[194:197], v192 offset:2048
	ds_read_b128 v[198:201], v192 offset:3072
	ds_read_b128 v[206:209], v192 offset:4096
	ds_read_b128 v[210:213], v192 offset:5120
	ds_read_b128 v[214:217], v192 offset:6144
	ds_read_b128 v[218:221], v192 offset:7168
	global_load_lds_dwordx4 v[186:187], off
	s_add_i32 m0, s87, 0xe000
	v_lshl_add_u64 v[186:187], s[76:77], 0, v[182:183]
	global_load_lds_dwordx4 v[186:187], off
	s_waitcnt vmcnt(8)
	s_waitcnt lgkmcnt(0)
	s_setprio 1
	s_barrier
	v_mfma_f32_16x16x32_bf16 v[142:145], v[114:117], v[162:165], v[142:145]
	v_mfma_f32_16x16x32_bf16 v[138:141], v[122:125], v[162:165], v[138:141]
	v_mfma_f32_16x16x32_bf16 v[110:113], v[114:117], v[194:197], v[110:113]
	v_mfma_f32_16x16x32_bf16 v[106:109], v[122:125], v[194:197], v[106:109]
	v_mfma_f32_16x16x32_bf16 v[98:101], v[114:117], v[206:209], v[98:101]
	v_mfma_f32_16x16x32_bf16 v[90:93], v[122:125], v[206:209], v[90:93]
	v_mfma_f32_16x16x32_bf16 v[82:85], v[114:117], v[214:217], v[82:85]
	v_mfma_f32_16x16x32_bf16 v[74:77], v[122:125], v[214:217], v[74:77]
	v_mfma_f32_16x16x32_bf16 v[142:145], v[118:121], v[166:169], v[142:145]
	v_mfma_f32_16x16x32_bf16 v[138:141], v[126:129], v[166:169], v[138:141]
	v_mfma_f32_16x16x32_bf16 v[110:113], v[118:121], v[198:201], v[110:113]
	v_mfma_f32_16x16x32_bf16 v[106:109], v[126:129], v[198:201], v[106:109]
	v_mfma_f32_16x16x32_bf16 v[98:101], v[118:121], v[210:213], v[98:101]
	v_mfma_f32_16x16x32_bf16 v[90:93], v[126:129], v[210:213], v[90:93]
	v_mfma_f32_16x16x32_bf16 v[82:85], v[118:121], v[218:221], v[82:85]
	v_mfma_f32_16x16x32_bf16 v[74:77], v[126:129], v[218:221], v[74:77]
	v_mfma_f32_16x16x32_bf16 v[134:137], v[146:149], v[162:165], v[134:137]
	v_mfma_f32_16x16x32_bf16 v[130:133], v[154:157], v[162:165], v[130:133]
	v_mfma_f32_16x16x32_bf16 v[102:105], v[146:149], v[194:197], v[102:105]
	v_mfma_f32_16x16x32_bf16 v[94:97], v[154:157], v[194:197], v[94:97]
	v_mfma_f32_16x16x32_bf16 v[86:89], v[146:149], v[206:209], v[86:89]
	v_mfma_f32_16x16x32_bf16 v[78:81], v[154:157], v[206:209], v[78:81]
	v_mfma_f32_16x16x32_bf16 v[70:73], v[146:149], v[214:217], v[70:73]
	v_mfma_f32_16x16x32_bf16 v[66:69], v[154:157], v[214:217], v[66:69]
	v_mfma_f32_16x16x32_bf16 v[134:137], v[150:153], v[166:169], v[134:137]
	v_mfma_f32_16x16x32_bf16 v[130:133], v[158:161], v[166:169], v[130:133]
	v_mfma_f32_16x16x32_bf16 v[102:105], v[150:153], v[198:201], v[102:105]
	v_mfma_f32_16x16x32_bf16 v[94:97], v[158:161], v[198:201], v[94:97]
	v_mfma_f32_16x16x32_bf16 v[86:89], v[150:153], v[210:213], v[86:89]
	v_mfma_f32_16x16x32_bf16 v[78:81], v[158:161], v[210:213], v[78:81]
	v_mfma_f32_16x16x32_bf16 v[70:73], v[150:153], v[218:221], v[70:73]
	v_mfma_f32_16x16x32_bf16 v[66:69], v[158:161], v[218:221], v[66:69]
	s_setprio 0
	s_barrier
	s_add_i32 s63, s24, s86
	v_lshl_add_u64 v[186:187], s[78:79], 0, v[172:173]
	s_mov_b32 m0, s63
	ds_read_b128 v[162:165], v192 offset:16384
	ds_read_b128 v[166:169], v192 offset:17408
	ds_read_b128 v[194:197], v192 offset:18432
	ds_read_b128 v[198:201], v192 offset:19456
	ds_read_b128 v[206:209], v192 offset:20480
	ds_read_b128 v[210:213], v192 offset:21504
	ds_read_b128 v[214:217], v192 offset:22528
	ds_read_b128 v[218:221], v192 offset:23552
	global_load_lds_dwordx4 v[186:187], off
	s_add_i32 m0, s63, 0x2000
	s_add_u32 vcc_lo, s78, 0x40000
	v_lshl_add_u64 v[202:203], s[78:79], 0, v[176:177]
	s_addc_u32 vcc_hi, s79, 0
	s_add_i32 s63, s25, s86
	global_load_lds_dwordx4 v[202:203], off
	v_lshl_add_u64 v[222:223], vcc, 0, v[172:173]
	s_mov_b32 m0, s63
	v_lshl_add_u64 v[224:225], s[80:81], 0, v[174:175]
	global_load_lds_dwordx4 v[222:223], off
	s_add_i32 m0, s63, 0x2000
	v_lshl_add_u64 v[222:223], vcc, 0, v[176:177]
	global_load_lds_dwordx4 v[222:223], off
	s_mov_b32 m0, s87
	v_lshl_add_u64 v[222:223], s[80:81], 0, v[170:171]
	global_load_lds_dwordx4 v[222:223], off
	s_mov_b32 m0, s88
	s_nop 0
	global_load_lds_dwordx4 v[224:225], off
	s_nop 0
	s_waitcnt vmcnt(8) lgkmcnt(0)
	s_setprio 1
	s_barrier
	v_mfma_f32_16x16x32_bf16 v[62:65], v[114:117], v[162:165], v[62:65]
	v_mfma_f32_16x16x32_bf16 v[58:61], v[122:125], v[162:165], v[58:61]
	v_mfma_f32_16x16x32_bf16 v[50:53], v[114:117], v[194:197], v[50:53]
	v_mfma_f32_16x16x32_bf16 v[42:45], v[122:125], v[194:197], v[42:45]
	v_mfma_f32_16x16x32_bf16 v[34:37], v[114:117], v[206:209], v[34:37]
	v_mfma_f32_16x16x32_bf16 v[26:29], v[122:125], v[206:209], v[26:29]
	v_mfma_f32_16x16x32_bf16 v[18:21], v[114:117], v[214:217], v[18:21]
	v_mfma_f32_16x16x32_bf16 v[10:13], v[122:125], v[214:217], v[10:13]
	v_mfma_f32_16x16x32_bf16 v[62:65], v[118:121], v[166:169], v[62:65]
	v_mfma_f32_16x16x32_bf16 v[58:61], v[126:129], v[166:169], v[58:61]
	v_mfma_f32_16x16x32_bf16 v[50:53], v[118:121], v[198:201], v[50:53]
	v_mfma_f32_16x16x32_bf16 v[42:45], v[126:129], v[198:201], v[42:45]
	v_mfma_f32_16x16x32_bf16 v[34:37], v[118:121], v[210:213], v[34:37]
	v_mfma_f32_16x16x32_bf16 v[26:29], v[126:129], v[210:213], v[26:29]
	v_mfma_f32_16x16x32_bf16 v[18:21], v[118:121], v[218:221], v[18:21]
	v_mfma_f32_16x16x32_bf16 v[10:13], v[126:129], v[218:221], v[10:13]
	v_mfma_f32_16x16x32_bf16 v[54:57], v[146:149], v[162:165], v[54:57]
	v_mfma_f32_16x16x32_bf16 v[46:49], v[154:157], v[162:165], v[46:49]
	v_mfma_f32_16x16x32_bf16 v[38:41], v[146:149], v[194:197], v[38:41]
	v_mfma_f32_16x16x32_bf16 v[30:33], v[154:157], v[194:197], v[30:33]
	v_mfma_f32_16x16x32_bf16 v[22:25], v[146:149], v[206:209], v[22:25]
	v_mfma_f32_16x16x32_bf16 v[14:17], v[154:157], v[206:209], v[14:17]
	v_mfma_f32_16x16x32_bf16 v[6:9], v[146:149], v[214:217], v[6:9]
	v_mfma_f32_16x16x32_bf16 v[2:5], v[154:157], v[214:217], v[2:5]
	v_mfma_f32_16x16x32_bf16 v[54:57], v[150:153], v[166:169], v[54:57]
	v_mfma_f32_16x16x32_bf16 v[46:49], v[158:161], v[166:169], v[46:49]
	v_mfma_f32_16x16x32_bf16 v[38:41], v[150:153], v[198:201], v[38:41]
	v_mfma_f32_16x16x32_bf16 v[30:33], v[158:161], v[198:201], v[30:33]
	v_mfma_f32_16x16x32_bf16 v[22:25], v[150:153], v[210:213], v[22:25]
	v_mfma_f32_16x16x32_bf16 v[14:17], v[158:161], v[210:213], v[14:17]
	v_mfma_f32_16x16x32_bf16 v[6:9], v[150:153], v[218:221], v[6:9]
	v_mfma_f32_16x16x32_bf16 v[2:5], v[158:161], v[218:221], v[2:5]
	s_setprio 0
	s_barrier
	s_add_i32 s63, 0, 0x18000
	s_add_i32 s83, 0, 0x1c000
	v_add_u32_e32 v126, s63, v189
	v_add_u32_e32 v158, s83, v189
	ds_read_b128 v[114:117], v126
	ds_read_b128 v[118:121], v126 offset:1024
	ds_read_b128 v[122:125], v126 offset:2048
	ds_read_b128 v[126:129], v126 offset:3072
	ds_read_b128 v[146:149], v158
	ds_read_b128 v[150:153], v158 offset:1024
	ds_read_b128 v[154:157], v158 offset:2048
	ds_read_b128 v[158:161], v158 offset:3072
	s_add_u32 s80, s80, 0x40000
	s_addc_u32 s81, s81, 0
	s_mov_b32 m0, s89
	v_lshl_add_u64 v[226:227], s[80:81], 0, v[170:171]
	ds_read_b128 v[162:165], v192 offset:32768
	ds_read_b128 v[166:169], v192 offset:33792
	ds_read_b128 v[194:197], v192 offset:34816
	ds_read_b128 v[198:201], v192 offset:35840
	ds_read_b128 v[206:209], v192 offset:36864
	ds_read_b128 v[210:213], v192 offset:37888
	ds_read_b128 v[214:217], v192 offset:38912
	ds_read_b128 v[218:221], v192 offset:39936
	global_load_lds_dwordx4 v[226:227], off
	s_mov_b32 m0, s90
	v_lshl_add_u64 v[226:227], s[80:81], 0, v[174:175]
	global_load_lds_dwordx4 v[226:227], off
	s_waitcnt vmcnt(8) lgkmcnt(0)
	s_setprio 1
	s_barrier
	v_mfma_f32_16x16x32_bf16 v[142:145], v[114:117], v[162:165], v[142:145]
	v_mfma_f32_16x16x32_bf16 v[138:141], v[122:125], v[162:165], v[138:141]
	v_mfma_f32_16x16x32_bf16 v[110:113], v[114:117], v[194:197], v[110:113]
	v_mfma_f32_16x16x32_bf16 v[106:109], v[122:125], v[194:197], v[106:109]
	v_mfma_f32_16x16x32_bf16 v[98:101], v[114:117], v[206:209], v[98:101]
	v_mfma_f32_16x16x32_bf16 v[90:93], v[122:125], v[206:209], v[90:93]
	v_mfma_f32_16x16x32_bf16 v[82:85], v[114:117], v[214:217], v[82:85]
	v_mfma_f32_16x16x32_bf16 v[74:77], v[122:125], v[214:217], v[74:77]
	v_mfma_f32_16x16x32_bf16 v[142:145], v[118:121], v[166:169], v[142:145]
	v_mfma_f32_16x16x32_bf16 v[138:141], v[126:129], v[166:169], v[138:141]
	v_mfma_f32_16x16x32_bf16 v[110:113], v[118:121], v[198:201], v[110:113]
	v_mfma_f32_16x16x32_bf16 v[106:109], v[126:129], v[198:201], v[106:109]
	v_mfma_f32_16x16x32_bf16 v[98:101], v[118:121], v[210:213], v[98:101]
	v_mfma_f32_16x16x32_bf16 v[90:93], v[126:129], v[210:213], v[90:93]
	v_mfma_f32_16x16x32_bf16 v[82:85], v[118:121], v[218:221], v[82:85]
	v_mfma_f32_16x16x32_bf16 v[74:77], v[126:129], v[218:221], v[74:77]
	v_mfma_f32_16x16x32_bf16 v[134:137], v[146:149], v[162:165], v[134:137]
	v_mfma_f32_16x16x32_bf16 v[130:133], v[154:157], v[162:165], v[130:133]
	v_mfma_f32_16x16x32_bf16 v[102:105], v[146:149], v[194:197], v[102:105]
	v_mfma_f32_16x16x32_bf16 v[94:97], v[154:157], v[194:197], v[94:97]
	v_mfma_f32_16x16x32_bf16 v[86:89], v[146:149], v[206:209], v[86:89]
	v_mfma_f32_16x16x32_bf16 v[78:81], v[154:157], v[206:209], v[78:81]
	v_mfma_f32_16x16x32_bf16 v[70:73], v[146:149], v[214:217], v[70:73]
	v_mfma_f32_16x16x32_bf16 v[66:69], v[154:157], v[214:217], v[66:69]
	v_mfma_f32_16x16x32_bf16 v[134:137], v[150:153], v[166:169], v[134:137]
	v_mfma_f32_16x16x32_bf16 v[130:133], v[158:161], v[166:169], v[130:133]
	v_mfma_f32_16x16x32_bf16 v[102:105], v[150:153], v[198:201], v[102:105]
	v_mfma_f32_16x16x32_bf16 v[94:97], v[158:161], v[198:201], v[94:97]
	v_mfma_f32_16x16x32_bf16 v[86:89], v[150:153], v[210:213], v[86:89]
	v_mfma_f32_16x16x32_bf16 v[78:81], v[158:161], v[210:213], v[78:81]
	v_mfma_f32_16x16x32_bf16 v[70:73], v[150:153], v[218:221], v[70:73]
	v_mfma_f32_16x16x32_bf16 v[66:69], v[158:161], v[218:221], v[66:69]
	s_setprio 0
	s_barrier
	s_add_i32 s63, s63, s86
	v_lshl_add_u64 v[186:187], v[186:187], 0, s[22:23]
	s_mov_b32 m0, s63
	ds_read_b128 v[162:165], v192 offset:49152
	ds_read_b128 v[166:169], v192 offset:50176
	ds_read_b128 v[194:197], v192 offset:51200
	ds_read_b128 v[198:201], v192 offset:52224
	ds_read_b128 v[206:209], v192 offset:53248
	ds_read_b128 v[210:213], v192 offset:54272
	ds_read_b128 v[214:217], v192 offset:55296
	ds_read_b128 v[218:221], v192 offset:56320
	global_load_lds_dwordx4 v[186:187], off
	s_add_i32 m0, s63, 0x2000
	s_add_u32 s78, s78, 0x40080
	v_lshl_add_u64 v[186:187], v[202:203], 0, s[22:23]
	s_addc_u32 s79, s79, 0
	s_add_i32 s63, s83, s86
	global_load_lds_dwordx4 v[186:187], off
	s_mov_b32 m0, s63
	v_lshl_add_u64 v[186:187], s[78:79], 0, v[172:173]
	global_load_lds_dwordx4 v[186:187], off
	s_add_i32 m0, s63, 0x2000
	v_lshl_add_u64 v[186:187], s[78:79], 0, v[176:177]
	global_load_lds_dwordx4 v[186:187], off
	s_mov_b32 m0, s95
	v_lshl_add_u64 v[186:187], v[222:223], 0, s[22:23]
	global_load_lds_dwordx4 v[186:187], off
	s_mov_b32 m0, s96
	v_lshl_add_u64 v[186:187], v[224:225], 0, s[22:23]
	global_load_lds_dwordx4 v[186:187], off
	s_waitcnt vmcnt(8) lgkmcnt(0)
	s_setprio 1
	s_barrier
	v_mfma_f32_16x16x32_bf16 v[62:65], v[114:117], v[162:165], v[62:65]
	v_mfma_f32_16x16x32_bf16 v[58:61], v[122:125], v[162:165], v[58:61]
	v_mfma_f32_16x16x32_bf16 v[50:53], v[114:117], v[194:197], v[50:53]
	v_mfma_f32_16x16x32_bf16 v[42:45], v[122:125], v[194:197], v[42:45]
	v_mfma_f32_16x16x32_bf16 v[34:37], v[114:117], v[206:209], v[34:37]
	v_mfma_f32_16x16x32_bf16 v[26:29], v[122:125], v[206:209], v[26:29]
	v_mfma_f32_16x16x32_bf16 v[18:21], v[114:117], v[214:217], v[18:21]
	v_mfma_f32_16x16x32_bf16 v[10:13], v[122:125], v[214:217], v[10:13]
	v_mfma_f32_16x16x32_bf16 v[62:65], v[118:121], v[166:169], v[62:65]
	v_mfma_f32_16x16x32_bf16 v[58:61], v[126:129], v[166:169], v[58:61]
	v_mfma_f32_16x16x32_bf16 v[50:53], v[118:121], v[198:201], v[50:53]
	v_mfma_f32_16x16x32_bf16 v[42:45], v[126:129], v[198:201], v[42:45]
	v_mfma_f32_16x16x32_bf16 v[34:37], v[118:121], v[210:213], v[34:37]
	v_mfma_f32_16x16x32_bf16 v[26:29], v[126:129], v[210:213], v[26:29]
	v_mfma_f32_16x16x32_bf16 v[18:21], v[118:121], v[218:221], v[18:21]
	v_mfma_f32_16x16x32_bf16 v[10:13], v[126:129], v[218:221], v[10:13]
	v_mfma_f32_16x16x32_bf16 v[54:57], v[146:149], v[162:165], v[54:57]
	v_mfma_f32_16x16x32_bf16 v[46:49], v[154:157], v[162:165], v[46:49]
	v_mfma_f32_16x16x32_bf16 v[38:41], v[146:149], v[194:197], v[38:41]
	v_mfma_f32_16x16x32_bf16 v[30:33], v[154:157], v[194:197], v[30:33]
	v_mfma_f32_16x16x32_bf16 v[22:25], v[146:149], v[206:209], v[22:25]
	v_mfma_f32_16x16x32_bf16 v[14:17], v[154:157], v[206:209], v[14:17]
	v_mfma_f32_16x16x32_bf16 v[6:9], v[146:149], v[214:217], v[6:9]
	v_mfma_f32_16x16x32_bf16 v[2:5], v[154:157], v[214:217], v[2:5]
	v_mfma_f32_16x16x32_bf16 v[54:57], v[150:153], v[166:169], v[54:57]
	v_mfma_f32_16x16x32_bf16 v[46:49], v[158:161], v[166:169], v[46:49]
	v_mfma_f32_16x16x32_bf16 v[38:41], v[150:153], v[198:201], v[38:41]
	v_mfma_f32_16x16x32_bf16 v[30:33], v[158:161], v[198:201], v[30:33]
	v_mfma_f32_16x16x32_bf16 v[22:25], v[150:153], v[210:213], v[22:25]
	v_mfma_f32_16x16x32_bf16 v[14:17], v[158:161], v[210:213], v[14:17]
	v_mfma_f32_16x16x32_bf16 v[6:9], v[150:153], v[218:221], v[6:9]
	v_mfma_f32_16x16x32_bf16 v[2:5], v[158:161], v[218:221], v[2:5]
	s_setprio 0
	s_barrier
	s_add_u32 s76, s76, 0x100
	s_addc_u32 s77, s77, 0
	s_add_u32 s47, s47, 0x100
	s_addc_u32 s62, s62, 0
	s_cmp_ge_i32 s82, s7
	s_mov_b32 s63, s82
	s_cbranch_scc0 .LBB0_566
	s_and_b64 vcc, exec, s[26:27]
	s_cbranch_vccz .LBB0_569
	s_barrier

.LBB0_744:
	s_add_u32 s36, s96, s22
	s_addc_u32 s37, s97, s23
	s_and_b64 s[14:15], s[4:5], exec
	s_cselect_b32 s14, s37, s43
	s_cselect_b32 s15, s36, s42
	s_add_u32 s38, s2, s26
	s_addc_u32 s39, s3, s27
	s_and_b64 s[46:47], s[4:5], exec
	s_cselect_b32 s21, s39, s45
	s_cselect_b32 s65, s38, s44
	s_add_u32 s42, s42, 0x40080
	s_addc_u32 s43, s43, 0
	s_add_u32 s66, s44, 0x100
	s_addc_u32 s67, s45, 0
	s_mov_b32 s68, -2
	ds_read_b128 v[154:157], v150
	ds_read_b128 v[158:161], v150 offset:1024
	ds_read_b128 v[162:165], v150 offset:2048
	ds_read_b128 v[166:169], v150 offset:3072
	ds_read_b128 v[170:173], v151
	ds_read_b128 v[174:177], v151 offset:1024
	ds_read_b128 v[178:181], v151 offset:2048
	ds_read_b128 v[182:185], v151 offset:3072
	s_add_u32 s44, s42, 0xfffc0080
	s_addc_u32 s45, s43, -1
	s_cmp_eq_u32 s68, 12
	s_cselect_b32 s47, s14, s45
	s_cselect_b32 s46, s15, s44
	s_cselect_b32 s45, s21, s67
	s_cselect_b32 s44, s65, s66
	v_lshl_add_u64 v[146:147], s[42:43], 0, v[138:139]
	s_add_i32 m0, s19, 0xc000
	ds_read_b128 v[186:189], v152
	ds_read_b128 v[190:193], v152 offset:1024
	ds_read_b128 v[194:197], v152 offset:2048
	ds_read_b128 v[198:201], v152 offset:3072
	ds_read_b128 v[206:209], v152 offset:4096
	ds_read_b128 v[210:213], v152 offset:5120
	ds_read_b128 v[214:217], v152 offset:6144
	ds_read_b128 v[218:221], v152 offset:7168
	global_load_lds_dwordx4 v[146:147], off
	s_add_i32 m0, s19, 0xe000
	v_lshl_add_u64 v[146:147], s[42:43], 0, v[140:141]
	global_load_lds_dwordx4 v[146:147], off
	s_nop 0
	s_waitcnt vmcnt(8) lgkmcnt(0)
	s_setprio 1
	s_barrier
	v_mfma_f32_16x16x32_bf16 v[126:129], v[154:157], v[186:189], 0
	v_mfma_f32_16x16x32_bf16 v[122:125], v[162:165], v[186:189], 0
	v_mfma_f32_16x16x32_bf16 v[110:113], v[154:157], v[194:197], 0
	v_mfma_f32_16x16x32_bf16 v[106:109], v[162:165], v[194:197], 0
	v_mfma_f32_16x16x32_bf16 v[94:97], v[154:157], v[206:209], 0
	v_mfma_f32_16x16x32_bf16 v[90:93], v[162:165], v[206:209], 0
	v_mfma_f32_16x16x32_bf16 v[78:81], v[154:157], v[214:217], 0
	v_mfma_f32_16x16x32_bf16 v[74:77], v[162:165], v[214:217], 0
	v_mfma_f32_16x16x32_bf16 v[126:129], v[158:161], v[190:193], v[126:129]
	v_mfma_f32_16x16x32_bf16 v[122:125], v[166:169], v[190:193], v[122:125]
	v_mfma_f32_16x16x32_bf16 v[110:113], v[158:161], v[198:201], v[110:113]
	v_mfma_f32_16x16x32_bf16 v[106:109], v[166:169], v[198:201], v[106:109]
	v_mfma_f32_16x16x32_bf16 v[94:97], v[158:161], v[210:213], v[94:97]
	v_mfma_f32_16x16x32_bf16 v[90:93], v[166:169], v[210:213], v[90:93]
	v_mfma_f32_16x16x32_bf16 v[78:81], v[158:161], v[218:221], v[78:81]
	v_mfma_f32_16x16x32_bf16 v[74:77], v[166:169], v[218:221], v[74:77]
	v_mfma_f32_16x16x32_bf16 v[118:121], v[170:173], v[186:189], 0
	v_mfma_f32_16x16x32_bf16 v[114:117], v[178:181], v[186:189], 0
	v_mfma_f32_16x16x32_bf16 v[102:105], v[170:173], v[194:197], 0
	v_mfma_f32_16x16x32_bf16 v[98:101], v[178:181], v[194:197], 0
	v_mfma_f32_16x16x32_bf16 v[86:89], v[170:173], v[206:209], 0
	v_mfma_f32_16x16x32_bf16 v[82:85], v[178:181], v[206:209], 0
	v_mfma_f32_16x16x32_bf16 v[70:73], v[170:173], v[214:217], 0
	v_mfma_f32_16x16x32_bf16 v[66:69], v[178:181], v[214:217], 0
	v_mfma_f32_16x16x32_bf16 v[118:121], v[174:177], v[190:193], v[118:121]
	v_mfma_f32_16x16x32_bf16 v[114:117], v[182:185], v[190:193], v[114:117]
	v_mfma_f32_16x16x32_bf16 v[102:105], v[174:177], v[198:201], v[102:105]
	v_mfma_f32_16x16x32_bf16 v[98:101], v[182:185], v[198:201], v[98:101]
	v_mfma_f32_16x16x32_bf16 v[86:89], v[174:177], v[210:213], v[86:89]
	v_mfma_f32_16x16x32_bf16 v[82:85], v[182:185], v[210:213], v[82:85]
	v_mfma_f32_16x16x32_bf16 v[70:73], v[174:177], v[218:221], v[70:73]
	v_mfma_f32_16x16x32_bf16 v[66:69], v[182:185], v[218:221], v[66:69]
	s_setprio 0
	s_barrier
	s_add_i32 s69, s49, s16
	v_lshl_add_u64 v[146:147], s[44:45], 0, v[134:135]
	s_mov_b32 m0, s69
	ds_read_b128 v[186:189], v152 offset:16384
	ds_read_b128 v[190:193], v152 offset:17408
	ds_read_b128 v[194:197], v152 offset:18432
	ds_read_b128 v[198:201], v152 offset:19456
	ds_read_b128 v[206:209], v152 offset:20480
	ds_read_b128 v[210:213], v152 offset:21504
	ds_read_b128 v[214:217], v152 offset:22528
	ds_read_b128 v[218:221], v152 offset:23552
	global_load_lds_dwordx4 v[146:147], off
	s_add_i32 m0, s69, 0x2000
	s_add_u32 s70, s44, 0x40000
	v_lshl_add_u64 v[202:203], s[44:45], 0, v[130:131]
	s_addc_u32 s71, s45, 0
	s_add_i32 s69, s62, s16
	global_load_lds_dwordx4 v[202:203], off
	v_lshl_add_u64 v[222:223], s[70:71], 0, v[134:135]
	s_mov_b32 m0, s69
	v_lshl_add_u64 v[224:225], s[46:47], 0, v[132:133]
	global_load_lds_dwordx4 v[222:223], off
	s_add_i32 m0, s69, 0x2000
	v_lshl_add_u64 v[222:223], s[70:71], 0, v[130:131]
	global_load_lds_dwordx4 v[222:223], off
	s_mov_b32 m0, s19
	v_lshl_add_u64 v[222:223], s[46:47], 0, v[136:137]
	global_load_lds_dwordx4 v[222:223], off
	s_mov_b32 m0, s24
	s_nop 0
	global_load_lds_dwordx4 v[224:225], off
	s_nop 0
	s_waitcnt vmcnt(8) lgkmcnt(0)
	s_setprio 1
	s_barrier
	v_mfma_f32_16x16x32_bf16 v[62:65], v[154:157], v[186:189], 0
	v_mfma_f32_16x16x32_bf16 v[58:61], v[162:165], v[186:189], 0
	v_mfma_f32_16x16x32_bf16 v[46:49], v[154:157], v[194:197], 0
	v_mfma_f32_16x16x32_bf16 v[42:45], v[162:165], v[194:197], 0
	v_mfma_f32_16x16x32_bf16 v[30:33], v[154:157], v[206:209], 0
	v_mfma_f32_16x16x32_bf16 v[26:29], v[162:165], v[206:209], 0
	v_mfma_f32_16x16x32_bf16 v[14:17], v[154:157], v[214:217], 0
	v_mfma_f32_16x16x32_bf16 v[10:13], v[162:165], v[214:217], 0
	v_mfma_f32_16x16x32_bf16 v[62:65], v[158:161], v[190:193], v[62:65]
	v_mfma_f32_16x16x32_bf16 v[58:61], v[166:169], v[190:193], v[58:61]
	v_mfma_f32_16x16x32_bf16 v[46:49], v[158:161], v[198:201], v[46:49]
	v_mfma_f32_16x16x32_bf16 v[42:45], v[166:169], v[198:201], v[42:45]
	v_mfma_f32_16x16x32_bf16 v[30:33], v[158:161], v[210:213], v[30:33]
	v_mfma_f32_16x16x32_bf16 v[26:29], v[166:169], v[210:213], v[26:29]
	v_mfma_f32_16x16x32_bf16 v[14:17], v[158:161], v[218:221], v[14:17]
	v_mfma_f32_16x16x32_bf16 v[10:13], v[166:169], v[218:221], v[10:13]
	v_mfma_f32_16x16x32_bf16 v[54:57], v[170:173], v[186:189], 0
	v_mfma_f32_16x16x32_bf16 v[50:53], v[178:181], v[186:189], 0
	v_mfma_f32_16x16x32_bf16 v[38:41], v[170:173], v[194:197], 0
	v_mfma_f32_16x16x32_bf16 v[34:37], v[178:181], v[194:197], 0
	v_mfma_f32_16x16x32_bf16 v[22:25], v[170:173], v[206:209], 0
	v_mfma_f32_16x16x32_bf16 v[18:21], v[178:181], v[206:209], 0
	v_mfma_f32_16x16x32_bf16 v[6:9], v[170:173], v[214:217], 0
	v_mfma_f32_16x16x32_bf16 v[2:5], v[178:181], v[214:217], 0
	v_mfma_f32_16x16x32_bf16 v[54:57], v[174:177], v[190:193], v[54:57]
	v_mfma_f32_16x16x32_bf16 v[50:53], v[182:185], v[190:193], v[50:53]
	v_mfma_f32_16x16x32_bf16 v[38:41], v[174:177], v[198:201], v[38:41]
	v_mfma_f32_16x16x32_bf16 v[34:37], v[182:185], v[198:201], v[34:37]
	v_mfma_f32_16x16x32_bf16 v[22:25], v[174:177], v[210:213], v[22:25]
	v_mfma_f32_16x16x32_bf16 v[18:21], v[182:185], v[210:213], v[18:21]
	v_mfma_f32_16x16x32_bf16 v[6:9], v[174:177], v[218:221], v[6:9]
	v_mfma_f32_16x16x32_bf16 v[2:5], v[182:185], v[218:221], v[2:5]
	s_setprio 0
	s_barrier
	s_add_i32 s69, 0, 0x18000
	v_add_u32_e32 v153, s69, v149
	s_add_i32 s70, 0, 0x1c000
	ds_read_b128 v[154:157], v153
	ds_read_b128 v[158:161], v153 offset:1024
	ds_read_b128 v[162:165], v153 offset:2048
	ds_read_b128 v[166:169], v153 offset:3072
	v_add_u32_e32 v153, s70, v149
	ds_read_b128 v[170:173], v153
	ds_read_b128 v[174:177], v153 offset:1024
	ds_read_b128 v[178:181], v153 offset:2048
	ds_read_b128 v[182:185], v153 offset:3072
	s_add_u32 s46, s46, 0x40000
	s_addc_u32 s47, s47, 0
	s_mov_b32 m0, s25
	v_lshl_add_u64 v[226:227], s[46:47], 0, v[136:137]
	ds_read_b128 v[186:189], v152 offset:32768
	ds_read_b128 v[190:193], v152 offset:33792
	ds_read_b128 v[194:197], v152 offset:34816
	ds_read_b128 v[198:201], v152 offset:35840
	ds_read_b128 v[206:209], v152 offset:36864
	ds_read_b128 v[210:213], v152 offset:37888
	ds_read_b128 v[214:217], v152 offset:38912
	ds_read_b128 v[218:221], v152 offset:39936
	global_load_lds_dwordx4 v[226:227], off
	s_mov_b32 m0, s28
	v_lshl_add_u64 v[226:227], s[46:47], 0, v[132:133]
	global_load_lds_dwordx4 v[226:227], off
	s_waitcnt vmcnt(8) lgkmcnt(0)
	s_setprio 1
	s_barrier
	v_mfma_f32_16x16x32_bf16 v[126:129], v[154:157], v[186:189], v[126:129]
	v_mfma_f32_16x16x32_bf16 v[122:125], v[162:165], v[186:189], v[122:125]
	v_mfma_f32_16x16x32_bf16 v[110:113], v[154:157], v[194:197], v[110:113]
	v_mfma_f32_16x16x32_bf16 v[106:109], v[162:165], v[194:197], v[106:109]
	v_mfma_f32_16x16x32_bf16 v[94:97], v[154:157], v[206:209], v[94:97]
	v_mfma_f32_16x16x32_bf16 v[90:93], v[162:165], v[206:209], v[90:93]
	v_mfma_f32_16x16x32_bf16 v[78:81], v[154:157], v[214:217], v[78:81]
	v_mfma_f32_16x16x32_bf16 v[74:77], v[162:165], v[214:217], v[74:77]
	v_mfma_f32_16x16x32_bf16 v[126:129], v[158:161], v[190:193], v[126:129]
	v_mfma_f32_16x16x32_bf16 v[122:125], v[166:169], v[190:193], v[122:125]
	v_mfma_f32_16x16x32_bf16 v[110:113], v[158:161], v[198:201], v[110:113]
	v_mfma_f32_16x16x32_bf16 v[106:109], v[166:169], v[198:201], v[106:109]
	v_mfma_f32_16x16x32_bf16 v[94:97], v[158:161], v[210:213], v[94:97]
	v_mfma_f32_16x16x32_bf16 v[90:93], v[166:169], v[210:213], v[90:93]
	v_mfma_f32_16x16x32_bf16 v[78:81], v[158:161], v[218:221], v[78:81]
	v_mfma_f32_16x16x32_bf16 v[74:77], v[166:169], v[218:221], v[74:77]
	v_mfma_f32_16x16x32_bf16 v[118:121], v[170:173], v[186:189], v[118:121]
	v_mfma_f32_16x16x32_bf16 v[114:117], v[178:181], v[186:189], v[114:117]
	v_mfma_f32_16x16x32_bf16 v[102:105], v[170:173], v[194:197], v[102:105]
	v_mfma_f32_16x16x32_bf16 v[98:101], v[178:181], v[194:197], v[98:101]
	v_mfma_f32_16x16x32_bf16 v[86:89], v[170:173], v[206:209], v[86:89]
	v_mfma_f32_16x16x32_bf16 v[82:85], v[178:181], v[206:209], v[82:85]
	v_mfma_f32_16x16x32_bf16 v[70:73], v[170:173], v[214:217], v[70:73]
	v_mfma_f32_16x16x32_bf16 v[66:69], v[178:181], v[214:217], v[66:69]
	v_mfma_f32_16x16x32_bf16 v[118:121], v[174:177], v[190:193], v[118:121]
	v_mfma_f32_16x16x32_bf16 v[114:117], v[182:185], v[190:193], v[114:117]
	v_mfma_f32_16x16x32_bf16 v[102:105], v[174:177], v[198:201], v[102:105]
	v_mfma_f32_16x16x32_bf16 v[98:101], v[182:185], v[198:201], v[98:101]
	v_mfma_f32_16x16x32_bf16 v[86:89], v[174:177], v[210:213], v[86:89]
	v_mfma_f32_16x16x32_bf16 v[82:85], v[182:185], v[210:213], v[82:85]
	v_mfma_f32_16x16x32_bf16 v[70:73], v[174:177], v[218:221], v[70:73]
	v_mfma_f32_16x16x32_bf16 v[66:69], v[182:185], v[218:221], v[66:69]
	s_setprio 0
	s_barrier
	s_add_i32 s46, s69, s16
	v_lshl_add_u64 v[146:147], v[146:147], 0, s[10:11]
	s_mov_b32 m0, s46
	ds_read_b128 v[186:189], v152 offset:49152
	ds_read_b128 v[190:193], v152 offset:50176
	ds_read_b128 v[194:197], v152 offset:51200
	ds_read_b128 v[198:201], v152 offset:52224
	ds_read_b128 v[206:209], v152 offset:53248
	ds_read_b128 v[210:213], v152 offset:54272
	ds_read_b128 v[214:217], v152 offset:55296
	ds_read_b128 v[218:221], v152 offset:56320
	global_load_lds_dwordx4 v[146:147], off
	s_add_i32 m0, s46, 0x2000
	s_add_u32 s44, s44, 0x40080
	v_lshl_add_u64 v[146:147], v[202:203], 0, s[10:11]
	s_addc_u32 s45, s45, 0
	s_add_i32 s46, s70, s16
	global_load_lds_dwordx4 v[146:147], off
	s_mov_b32 m0, s46
	v_lshl_add_u64 v[146:147], s[44:45], 0, v[134:135]
	global_load_lds_dwordx4 v[146:147], off
	s_add_i32 m0, s46, 0x2000
	v_lshl_add_u64 v[146:147], s[44:45], 0, v[130:131]
	global_load_lds_dwordx4 v[146:147], off
	s_mov_b32 m0, s33
	v_lshl_add_u64 v[146:147], v[222:223], 0, s[10:11]
	global_load_lds_dwordx4 v[146:147], off
	s_mov_b32 m0, s35
	v_lshl_add_u64 v[146:147], v[224:225], 0, s[10:11]
	global_load_lds_dwordx4 v[146:147], off
	s_waitcnt vmcnt(8) lgkmcnt(0)
	s_setprio 1
	s_barrier
	v_mfma_f32_16x16x32_bf16 v[62:65], v[154:157], v[186:189], v[62:65]
	v_mfma_f32_16x16x32_bf16 v[58:61], v[162:165], v[186:189], v[58:61]
	v_mfma_f32_16x16x32_bf16 v[46:49], v[154:157], v[194:197], v[46:49]
	v_mfma_f32_16x16x32_bf16 v[42:45], v[162:165], v[194:197], v[42:45]
	v_mfma_f32_16x16x32_bf16 v[30:33], v[154:157], v[206:209], v[30:33]
	v_mfma_f32_16x16x32_bf16 v[26:29], v[162:165], v[206:209], v[26:29]
	v_mfma_f32_16x16x32_bf16 v[14:17], v[154:157], v[214:217], v[14:17]
	v_mfma_f32_16x16x32_bf16 v[10:13], v[162:165], v[214:217], v[10:13]
	v_mfma_f32_16x16x32_bf16 v[62:65], v[158:161], v[190:193], v[62:65]
	v_mfma_f32_16x16x32_bf16 v[58:61], v[166:169], v[190:193], v[58:61]
	v_mfma_f32_16x16x32_bf16 v[46:49], v[158:161], v[198:201], v[46:49]
	v_mfma_f32_16x16x32_bf16 v[42:45], v[166:169], v[198:201], v[42:45]
	v_mfma_f32_16x16x32_bf16 v[30:33], v[158:161], v[210:213], v[30:33]
	v_mfma_f32_16x16x32_bf16 v[26:29], v[166:169], v[210:213], v[26:29]
	v_mfma_f32_16x16x32_bf16 v[14:17], v[158:161], v[218:221], v[14:17]
	v_mfma_f32_16x16x32_bf16 v[10:13], v[166:169], v[218:221], v[10:13]
	v_mfma_f32_16x16x32_bf16 v[54:57], v[170:173], v[186:189], v[54:57]
	v_mfma_f32_16x16x32_bf16 v[50:53], v[178:181], v[186:189], v[50:53]
	v_mfma_f32_16x16x32_bf16 v[38:41], v[170:173], v[194:197], v[38:41]
	v_mfma_f32_16x16x32_bf16 v[34:37], v[178:181], v[194:197], v[34:37]
	v_mfma_f32_16x16x32_bf16 v[22:25], v[170:173], v[206:209], v[22:25]
	v_mfma_f32_16x16x32_bf16 v[18:21], v[178:181], v[206:209], v[18:21]
	v_mfma_f32_16x16x32_bf16 v[6:9], v[170:173], v[214:217], v[6:9]
	v_mfma_f32_16x16x32_bf16 v[2:5], v[178:181], v[214:217], v[2:5]
	v_mfma_f32_16x16x32_bf16 v[54:57], v[174:177], v[190:193], v[54:57]
	v_mfma_f32_16x16x32_bf16 v[50:53], v[182:185], v[190:193], v[50:53]
	v_mfma_f32_16x16x32_bf16 v[38:41], v[174:177], v[198:201], v[38:41]
	v_mfma_f32_16x16x32_bf16 v[34:37], v[182:185], v[198:201], v[34:37]
	v_mfma_f32_16x16x32_bf16 v[22:25], v[174:177], v[210:213], v[22:25]
	v_mfma_f32_16x16x32_bf16 v[18:21], v[182:185], v[210:213], v[18:21]
	v_mfma_f32_16x16x32_bf16 v[6:9], v[174:177], v[218:221], v[6:9]
	v_mfma_f32_16x16x32_bf16 v[2:5], v[182:185], v[218:221], v[2:5]
	s_setprio 0
	s_barrier
	s_add_i32 s68, s68, 2
	s_add_u32 s42, s42, 0x100
	s_addc_u32 s43, s43, 0
	s_add_u32 s66, s66, 0x100
	s_addc_u32 s67, s67, 0
	s_cmp_gt_u32 s68, 13
.LBB0_745:
	ds_read_b128 v[154:157], v150
	ds_read_b128 v[158:161], v150 offset:1024
	ds_read_b128 v[162:165], v150 offset:2048
	ds_read_b128 v[166:169], v150 offset:3072
	ds_read_b128 v[170:173], v151
	ds_read_b128 v[174:177], v151 offset:1024
	ds_read_b128 v[178:181], v151 offset:2048
	ds_read_b128 v[182:185], v151 offset:3072
	s_add_u32 s44, s42, 0xfffc0080
	s_addc_u32 s45, s43, -1
	s_cmp_eq_u32 s68, 12
	s_cselect_b32 s47, s14, s45
	s_cselect_b32 s46, s15, s44
	s_cselect_b32 s45, s21, s67
	s_cselect_b32 s44, s65, s66
	v_lshl_add_u64 v[146:147], s[42:43], 0, v[138:139]
	s_add_i32 m0, s19, 0xc000
	ds_read_b128 v[186:189], v152
	ds_read_b128 v[190:193], v152 offset:1024
	ds_read_b128 v[194:197], v152 offset:2048
	ds_read_b128 v[198:201], v152 offset:3072
	ds_read_b128 v[206:209], v152 offset:4096
	ds_read_b128 v[210:213], v152 offset:5120
	ds_read_b128 v[214:217], v152 offset:6144
	ds_read_b128 v[218:221], v152 offset:7168
	global_load_lds_dwordx4 v[146:147], off
	s_add_i32 m0, s19, 0xe000
	v_lshl_add_u64 v[146:147], s[42:43], 0, v[140:141]
	global_load_lds_dwordx4 v[146:147], off
	s_nop 0
	s_waitcnt vmcnt(8) lgkmcnt(0)
	s_setprio 1
	s_barrier
	v_mfma_f32_16x16x32_bf16 v[126:129], v[154:157], v[186:189], v[126:129]
	v_mfma_f32_16x16x32_bf16 v[122:125], v[162:165], v[186:189], v[122:125]
	v_mfma_f32_16x16x32_bf16 v[110:113], v[154:157], v[194:197], v[110:113]
	v_mfma_f32_16x16x32_bf16 v[106:109], v[162:165], v[194:197], v[106:109]
	v_mfma_f32_16x16x32_bf16 v[94:97], v[154:157], v[206:209], v[94:97]
	v_mfma_f32_16x16x32_bf16 v[90:93], v[162:165], v[206:209], v[90:93]
	v_mfma_f32_16x16x32_bf16 v[78:81], v[154:157], v[214:217], v[78:81]
	v_mfma_f32_16x16x32_bf16 v[74:77], v[162:165], v[214:217], v[74:77]
	v_mfma_f32_16x16x32_bf16 v[126:129], v[158:161], v[190:193], v[126:129]
	v_mfma_f32_16x16x32_bf16 v[122:125], v[166:169], v[190:193], v[122:125]
	v_mfma_f32_16x16x32_bf16 v[110:113], v[158:161], v[198:201], v[110:113]
	v_mfma_f32_16x16x32_bf16 v[106:109], v[166:169], v[198:201], v[106:109]
	v_mfma_f32_16x16x32_bf16 v[94:97], v[158:161], v[210:213], v[94:97]
	v_mfma_f32_16x16x32_bf16 v[90:93], v[166:169], v[210:213], v[90:93]
	v_mfma_f32_16x16x32_bf16 v[78:81], v[158:161], v[218:221], v[78:81]
	v_mfma_f32_16x16x32_bf16 v[74:77], v[166:169], v[218:221], v[74:77]
	v_mfma_f32_16x16x32_bf16 v[118:121], v[170:173], v[186:189], v[118:121]
	v_mfma_f32_16x16x32_bf16 v[114:117], v[178:181], v[186:189], v[114:117]
	v_mfma_f32_16x16x32_bf16 v[102:105], v[170:173], v[194:197], v[102:105]
	v_mfma_f32_16x16x32_bf16 v[98:101], v[178:181], v[194:197], v[98:101]
	v_mfma_f32_16x16x32_bf16 v[86:89], v[170:173], v[206:209], v[86:89]
	v_mfma_f32_16x16x32_bf16 v[82:85], v[178:181], v[206:209], v[82:85]
	v_mfma_f32_16x16x32_bf16 v[70:73], v[170:173], v[214:217], v[70:73]
	v_mfma_f32_16x16x32_bf16 v[66:69], v[178:181], v[214:217], v[66:69]
	v_mfma_f32_16x16x32_bf16 v[118:121], v[174:177], v[190:193], v[118:121]
	v_mfma_f32_16x16x32_bf16 v[114:117], v[182:185], v[190:193], v[114:117]
	v_mfma_f32_16x16x32_bf16 v[102:105], v[174:177], v[198:201], v[102:105]
	v_mfma_f32_16x16x32_bf16 v[98:101], v[182:185], v[198:201], v[98:101]
	v_mfma_f32_16x16x32_bf16 v[86:89], v[174:177], v[210:213], v[86:89]
	v_mfma_f32_16x16x32_bf16 v[82:85], v[182:185], v[210:213], v[82:85]
	v_mfma_f32_16x16x32_bf16 v[70:73], v[174:177], v[218:221], v[70:73]
	v_mfma_f32_16x16x32_bf16 v[66:69], v[182:185], v[218:221], v[66:69]
	s_setprio 0
	s_barrier
	s_add_i32 s69, s49, s16
	v_lshl_add_u64 v[146:147], s[44:45], 0, v[134:135]
	s_mov_b32 m0, s69
	ds_read_b128 v[186:189], v152 offset:16384
	ds_read_b128 v[190:193], v152 offset:17408
	ds_read_b128 v[194:197], v152 offset:18432
	ds_read_b128 v[198:201], v152 offset:19456
	ds_read_b128 v[206:209], v152 offset:20480
	ds_read_b128 v[210:213], v152 offset:21504
	ds_read_b128 v[214:217], v152 offset:22528
	ds_read_b128 v[218:221], v152 offset:23552
	global_load_lds_dwordx4 v[146:147], off
	s_add_i32 m0, s69, 0x2000
	s_add_u32 s70, s44, 0x40000
	v_lshl_add_u64 v[202:203], s[44:45], 0, v[130:131]
	s_addc_u32 s71, s45, 0
	s_add_i32 s69, s62, s16
	global_load_lds_dwordx4 v[202:203], off
	v_lshl_add_u64 v[222:223], s[70:71], 0, v[134:135]
	s_mov_b32 m0, s69
	v_lshl_add_u64 v[224:225], s[46:47], 0, v[132:133]
	global_load_lds_dwordx4 v[222:223], off
	s_add_i32 m0, s69, 0x2000
	v_lshl_add_u64 v[222:223], s[70:71], 0, v[130:131]
	global_load_lds_dwordx4 v[222:223], off
	s_mov_b32 m0, s19
	v_lshl_add_u64 v[222:223], s[46:47], 0, v[136:137]
	global_load_lds_dwordx4 v[222:223], off
	s_mov_b32 m0, s24
	s_nop 0
	global_load_lds_dwordx4 v[224:225], off
	s_nop 0
	s_waitcnt vmcnt(8) lgkmcnt(0)
	s_setprio 1
	s_barrier
	v_mfma_f32_16x16x32_bf16 v[62:65], v[154:157], v[186:189], v[62:65]
	v_mfma_f32_16x16x32_bf16 v[58:61], v[162:165], v[186:189], v[58:61]
	v_mfma_f32_16x16x32_bf16 v[46:49], v[154:157], v[194:197], v[46:49]
	v_mfma_f32_16x16x32_bf16 v[42:45], v[162:165], v[194:197], v[42:45]
	v_mfma_f32_16x16x32_bf16 v[30:33], v[154:157], v[206:209], v[30:33]
	v_mfma_f32_16x16x32_bf16 v[26:29], v[162:165], v[206:209], v[26:29]
	v_mfma_f32_16x16x32_bf16 v[14:17], v[154:157], v[214:217], v[14:17]
	v_mfma_f32_16x16x32_bf16 v[10:13], v[162:165], v[214:217], v[10:13]
	v_mfma_f32_16x16x32_bf16 v[62:65], v[158:161], v[190:193], v[62:65]
	v_mfma_f32_16x16x32_bf16 v[58:61], v[166:169], v[190:193], v[58:61]
	v_mfma_f32_16x16x32_bf16 v[46:49], v[158:161], v[198:201], v[46:49]
	v_mfma_f32_16x16x32_bf16 v[42:45], v[166:169], v[198:201], v[42:45]
	v_mfma_f32_16x16x32_bf16 v[30:33], v[158:161], v[210:213], v[30:33]
	v_mfma_f32_16x16x32_bf16 v[26:29], v[166:169], v[210:213], v[26:29]
	v_mfma_f32_16x16x32_bf16 v[14:17], v[158:161], v[218:221], v[14:17]
	v_mfma_f32_16x16x32_bf16 v[10:13], v[166:169], v[218:221], v[10:13]
	v_mfma_f32_16x16x32_bf16 v[54:57], v[170:173], v[186:189], v[54:57]
	v_mfma_f32_16x16x32_bf16 v[50:53], v[178:181], v[186:189], v[50:53]
	v_mfma_f32_16x16x32_bf16 v[38:41], v[170:173], v[194:197], v[38:41]
	v_mfma_f32_16x16x32_bf16 v[34:37], v[178:181], v[194:197], v[34:37]
	v_mfma_f32_16x16x32_bf16 v[22:25], v[170:173], v[206:209], v[22:25]
	v_mfma_f32_16x16x32_bf16 v[18:21], v[178:181], v[206:209], v[18:21]
	v_mfma_f32_16x16x32_bf16 v[6:9], v[170:173], v[214:217], v[6:9]
	v_mfma_f32_16x16x32_bf16 v[2:5], v[178:181], v[214:217], v[2:5]
	v_mfma_f32_16x16x32_bf16 v[54:57], v[174:177], v[190:193], v[54:57]
	v_mfma_f32_16x16x32_bf16 v[50:53], v[182:185], v[190:193], v[50:53]
	v_mfma_f32_16x16x32_bf16 v[38:41], v[174:177], v[198:201], v[38:41]
	v_mfma_f32_16x16x32_bf16 v[34:37], v[182:185], v[198:201], v[34:37]
	v_mfma_f32_16x16x32_bf16 v[22:25], v[174:177], v[210:213], v[22:25]
	v_mfma_f32_16x16x32_bf16 v[18:21], v[182:185], v[210:213], v[18:21]
	v_mfma_f32_16x16x32_bf16 v[6:9], v[174:177], v[218:221], v[6:9]
	v_mfma_f32_16x16x32_bf16 v[2:5], v[182:185], v[218:221], v[2:5]
	s_setprio 0
	s_barrier
	s_add_i32 s69, 0, 0x18000
	v_add_u32_e32 v153, s69, v149
	s_add_i32 s70, 0, 0x1c000
	ds_read_b128 v[154:157], v153
	ds_read_b128 v[158:161], v153 offset:1024
	ds_read_b128 v[162:165], v153 offset:2048
	ds_read_b128 v[166:169], v153 offset:3072
	v_add_u32_e32 v153, s70, v149
	ds_read_b128 v[170:173], v153
	ds_read_b128 v[174:177], v153 offset:1024
	ds_read_b128 v[178:181], v153 offset:2048
	ds_read_b128 v[182:185], v153 offset:3072
	s_add_u32 s46, s46, 0x40000
	s_addc_u32 s47, s47, 0
	s_mov_b32 m0, s25
	v_lshl_add_u64 v[226:227], s[46:47], 0, v[136:137]
	ds_read_b128 v[186:189], v152 offset:32768
	ds_read_b128 v[190:193], v152 offset:33792
	ds_read_b128 v[194:197], v152 offset:34816
	ds_read_b128 v[198:201], v152 offset:35840
	ds_read_b128 v[206:209], v152 offset:36864
	ds_read_b128 v[210:213], v152 offset:37888
	ds_read_b128 v[214:217], v152 offset:38912
	ds_read_b128 v[218:221], v152 offset:39936
	global_load_lds_dwordx4 v[226:227], off
	s_mov_b32 m0, s28
	v_lshl_add_u64 v[226:227], s[46:47], 0, v[132:133]
	global_load_lds_dwordx4 v[226:227], off
	s_waitcnt vmcnt(8) lgkmcnt(0)
	s_setprio 1
	s_barrier
	v_mfma_f32_16x16x32_bf16 v[126:129], v[154:157], v[186:189], v[126:129]
	v_mfma_f32_16x16x32_bf16 v[122:125], v[162:165], v[186:189], v[122:125]
	v_mfma_f32_16x16x32_bf16 v[110:113], v[154:157], v[194:197], v[110:113]
	v_mfma_f32_16x16x32_bf16 v[106:109], v[162:165], v[194:197], v[106:109]
	v_mfma_f32_16x16x32_bf16 v[94:97], v[154:157], v[206:209], v[94:97]
	v_mfma_f32_16x16x32_bf16 v[90:93], v[162:165], v[206:209], v[90:93]
	v_mfma_f32_16x16x32_bf16 v[78:81], v[154:157], v[214:217], v[78:81]
	v_mfma_f32_16x16x32_bf16 v[74:77], v[162:165], v[214:217], v[74:77]
	v_mfma_f32_16x16x32_bf16 v[126:129], v[158:161], v[190:193], v[126:129]
	v_mfma_f32_16x16x32_bf16 v[122:125], v[166:169], v[190:193], v[122:125]
	v_mfma_f32_16x16x32_bf16 v[110:113], v[158:161], v[198:201], v[110:113]
	v_mfma_f32_16x16x32_bf16 v[106:109], v[166:169], v[198:201], v[106:109]
	v_mfma_f32_16x16x32_bf16 v[94:97], v[158:161], v[210:213], v[94:97]
	v_mfma_f32_16x16x32_bf16 v[90:93], v[166:169], v[210:213], v[90:93]
	v_mfma_f32_16x16x32_bf16 v[78:81], v[158:161], v[218:221], v[78:81]
	v_mfma_f32_16x16x32_bf16 v[74:77], v[166:169], v[218:221], v[74:77]
	v_mfma_f32_16x16x32_bf16 v[118:121], v[170:173], v[186:189], v[118:121]
	v_mfma_f32_16x16x32_bf16 v[114:117], v[178:181], v[186:189], v[114:117]
	v_mfma_f32_16x16x32_bf16 v[102:105], v[170:173], v[194:197], v[102:105]
	v_mfma_f32_16x16x32_bf16 v[98:101], v[178:181], v[194:197], v[98:101]
	v_mfma_f32_16x16x32_bf16 v[86:89], v[170:173], v[206:209], v[86:89]
	v_mfma_f32_16x16x32_bf16 v[82:85], v[178:181], v[206:209], v[82:85]
	v_mfma_f32_16x16x32_bf16 v[70:73], v[170:173], v[214:217], v[70:73]
	v_mfma_f32_16x16x32_bf16 v[66:69], v[178:181], v[214:217], v[66:69]
	v_mfma_f32_16x16x32_bf16 v[118:121], v[174:177], v[190:193], v[118:121]
	v_mfma_f32_16x16x32_bf16 v[114:117], v[182:185], v[190:193], v[114:117]
	v_mfma_f32_16x16x32_bf16 v[102:105], v[174:177], v[198:201], v[102:105]
	v_mfma_f32_16x16x32_bf16 v[98:101], v[182:185], v[198:201], v[98:101]
	v_mfma_f32_16x16x32_bf16 v[86:89], v[174:177], v[210:213], v[86:89]
	v_mfma_f32_16x16x32_bf16 v[82:85], v[182:185], v[210:213], v[82:85]
	v_mfma_f32_16x16x32_bf16 v[70:73], v[174:177], v[218:221], v[70:73]
	v_mfma_f32_16x16x32_bf16 v[66:69], v[182:185], v[218:221], v[66:69]
	s_setprio 0
	s_barrier
	s_add_i32 s46, s69, s16
	v_lshl_add_u64 v[146:147], v[146:147], 0, s[10:11]
	s_mov_b32 m0, s46
	ds_read_b128 v[186:189], v152 offset:49152
	ds_read_b128 v[190:193], v152 offset:50176
	ds_read_b128 v[194:197], v152 offset:51200
	ds_read_b128 v[198:201], v152 offset:52224
	ds_read_b128 v[206:209], v152 offset:53248
	ds_read_b128 v[210:213], v152 offset:54272
	ds_read_b128 v[214:217], v152 offset:55296
	ds_read_b128 v[218:221], v152 offset:56320
	global_load_lds_dwordx4 v[146:147], off
	s_add_i32 m0, s46, 0x2000
	s_add_u32 s44, s44, 0x40080
	v_lshl_add_u64 v[146:147], v[202:203], 0, s[10:11]
	s_addc_u32 s45, s45, 0
	s_add_i32 s46, s70, s16
	global_load_lds_dwordx4 v[146:147], off
	s_mov_b32 m0, s46
	v_lshl_add_u64 v[146:147], s[44:45], 0, v[134:135]
	global_load_lds_dwordx4 v[146:147], off
	s_add_i32 m0, s46, 0x2000
	v_lshl_add_u64 v[146:147], s[44:45], 0, v[130:131]
	global_load_lds_dwordx4 v[146:147], off
	s_mov_b32 m0, s33
	v_lshl_add_u64 v[146:147], v[222:223], 0, s[10:11]
	global_load_lds_dwordx4 v[146:147], off
	s_mov_b32 m0, s35
	v_lshl_add_u64 v[146:147], v[224:225], 0, s[10:11]
	global_load_lds_dwordx4 v[146:147], off
	s_waitcnt vmcnt(8) lgkmcnt(0)
	s_setprio 1
	s_barrier
	v_mfma_f32_16x16x32_bf16 v[62:65], v[154:157], v[186:189], v[62:65]
	v_mfma_f32_16x16x32_bf16 v[58:61], v[162:165], v[186:189], v[58:61]
	v_mfma_f32_16x16x32_bf16 v[46:49], v[154:157], v[194:197], v[46:49]
	v_mfma_f32_16x16x32_bf16 v[42:45], v[162:165], v[194:197], v[42:45]
	v_mfma_f32_16x16x32_bf16 v[30:33], v[154:157], v[206:209], v[30:33]
	v_mfma_f32_16x16x32_bf16 v[26:29], v[162:165], v[206:209], v[26:29]
	v_mfma_f32_16x16x32_bf16 v[14:17], v[154:157], v[214:217], v[14:17]
	v_mfma_f32_16x16x32_bf16 v[10:13], v[162:165], v[214:217], v[10:13]
	v_mfma_f32_16x16x32_bf16 v[62:65], v[158:161], v[190:193], v[62:65]
	v_mfma_f32_16x16x32_bf16 v[58:61], v[166:169], v[190:193], v[58:61]
	v_mfma_f32_16x16x32_bf16 v[46:49], v[158:161], v[198:201], v[46:49]
	v_mfma_f32_16x16x32_bf16 v[42:45], v[166:169], v[198:201], v[42:45]
	v_mfma_f32_16x16x32_bf16 v[30:33], v[158:161], v[210:213], v[30:33]
	v_mfma_f32_16x16x32_bf16 v[26:29], v[166:169], v[210:213], v[26:29]
	v_mfma_f32_16x16x32_bf16 v[14:17], v[158:161], v[218:221], v[14:17]
	v_mfma_f32_16x16x32_bf16 v[10:13], v[166:169], v[218:221], v[10:13]
	v_mfma_f32_16x16x32_bf16 v[54:57], v[170:173], v[186:189], v[54:57]
	v_mfma_f32_16x16x32_bf16 v[50:53], v[178:181], v[186:189], v[50:53]
	v_mfma_f32_16x16x32_bf16 v[38:41], v[170:173], v[194:197], v[38:41]
	v_mfma_f32_16x16x32_bf16 v[34:37], v[178:181], v[194:197], v[34:37]
	v_mfma_f32_16x16x32_bf16 v[22:25], v[170:173], v[206:209], v[22:25]
	v_mfma_f32_16x16x32_bf16 v[18:21], v[178:181], v[206:209], v[18:21]
	v_mfma_f32_16x16x32_bf16 v[6:9], v[170:173], v[214:217], v[6:9]
	v_mfma_f32_16x16x32_bf16 v[2:5], v[178:181], v[214:217], v[2:5]
	v_mfma_f32_16x16x32_bf16 v[54:57], v[174:177], v[190:193], v[54:57]
	v_mfma_f32_16x16x32_bf16 v[50:53], v[182:185], v[190:193], v[50:53]
	v_mfma_f32_16x16x32_bf16 v[38:41], v[174:177], v[198:201], v[38:41]
	v_mfma_f32_16x16x32_bf16 v[34:37], v[182:185], v[198:201], v[34:37]
	v_mfma_f32_16x16x32_bf16 v[22:25], v[174:177], v[210:213], v[22:25]
	v_mfma_f32_16x16x32_bf16 v[18:21], v[182:185], v[210:213], v[18:21]
	v_mfma_f32_16x16x32_bf16 v[6:9], v[174:177], v[218:221], v[6:9]
	v_mfma_f32_16x16x32_bf16 v[2:5], v[182:185], v[218:221], v[2:5]
	s_setprio 0
	s_barrier
	s_add_i32 s68, s68, 2
	s_add_u32 s42, s42, 0x100
	s_addc_u32 s43, s43, 0
	s_add_u32 s66, s66, 0x100
	s_addc_u32 s67, s67, 0
	s_cmp_gt_u32 s68, 13
	s_cbranch_scc0 .LBB0_745
	s_and_b64 vcc, exec, s[12:13]
	s_cbranch_vccz .LBB0_748
	s_barrier

.LBB0_833:
	s_add_u32 s72, s0, s68
	s_addc_u32 s73, s1, s69
	s_and_b64 s[62:63], s[70:71], exec
	s_cselect_b32 s15, s73, s77
	s_cselect_b32 s33, s72, s76
	s_add_u32 s74, s35, s66
	s_addc_u32 s75, s85, s67
	s_and_b64 s[62:63], s[70:71], exec
	s_cselect_b32 s34, s75, s79
	s_cselect_b32 s39, s74, s78
	s_add_i32 s45, s7, -2
	s_add_u32 s76, s76, 0x100080
	s_addc_u32 s77, s77, 0
	s_add_u32 s47, s78, 0x100
	s_addc_u32 s62, s79, 0
	s_mov_b32 s63, 0
	s_waitcnt vmcnt(0)
	ds_read_b128 v[114:117], v190
	ds_read_b128 v[118:121], v190 offset:1024
	ds_read_b128 v[122:125], v190 offset:2048
	ds_read_b128 v[126:129], v190 offset:3072
	ds_read_b128 v[146:149], v191
	ds_read_b128 v[150:153], v191 offset:1024
	ds_read_b128 v[154:157], v191 offset:2048
	ds_read_b128 v[158:161], v191 offset:3072
	s_add_i32 s82, s63, 2
	s_add_u32 s78, s76, 0xfff00080
	s_addc_u32 s79, s77, -1
	s_cmp_eq_u32 s45, s63
	s_cselect_b32 s81, s15, s79
	s_cselect_b32 s80, s33, s78
	s_cselect_b32 s79, s34, s62
	s_cselect_b32 s78, s39, s47
	v_lshl_add_u64 v[186:187], s[76:77], 0, v[180:181]
	s_add_i32 m0, s87, 0xc000
	ds_read_b128 v[162:165], v192
	ds_read_b128 v[166:169], v192 offset:1024
	ds_read_b128 v[194:197], v192 offset:2048
	ds_read_b128 v[198:201], v192 offset:3072
	ds_read_b128 v[206:209], v192 offset:4096
	ds_read_b128 v[210:213], v192 offset:5120
	ds_read_b128 v[214:217], v192 offset:6144
	ds_read_b128 v[218:221], v192 offset:7168
	global_load_lds_dwordx4 v[186:187], off
	s_add_i32 m0, s87, 0xe000
	v_lshl_add_u64 v[186:187], s[76:77], 0, v[182:183]
	global_load_lds_dwordx4 v[186:187], off
	s_nop 0
	s_waitcnt vmcnt(8) lgkmcnt(0)
	s_setprio 1
	s_barrier
	v_mfma_f32_16x16x32_bf16 v[142:145], v[114:117], v[162:165], 0
	v_mfma_f32_16x16x32_bf16 v[138:141], v[122:125], v[162:165], 0
	v_mfma_f32_16x16x32_bf16 v[110:113], v[114:117], v[194:197], 0
	v_mfma_f32_16x16x32_bf16 v[106:109], v[122:125], v[194:197], 0
	v_mfma_f32_16x16x32_bf16 v[98:101], v[114:117], v[206:209], 0
	v_mfma_f32_16x16x32_bf16 v[90:93], v[122:125], v[206:209], 0
	v_mfma_f32_16x16x32_bf16 v[82:85], v[114:117], v[214:217], 0
	v_mfma_f32_16x16x32_bf16 v[74:77], v[122:125], v[214:217], 0
	v_mfma_f32_16x16x32_bf16 v[142:145], v[118:121], v[166:169], v[142:145]
	v_mfma_f32_16x16x32_bf16 v[138:141], v[126:129], v[166:169], v[138:141]
	v_mfma_f32_16x16x32_bf16 v[110:113], v[118:121], v[198:201], v[110:113]
	v_mfma_f32_16x16x32_bf16 v[106:109], v[126:129], v[198:201], v[106:109]
	v_mfma_f32_16x16x32_bf16 v[98:101], v[118:121], v[210:213], v[98:101]
	v_mfma_f32_16x16x32_bf16 v[90:93], v[126:129], v[210:213], v[90:93]
	v_mfma_f32_16x16x32_bf16 v[82:85], v[118:121], v[218:221], v[82:85]
	v_mfma_f32_16x16x32_bf16 v[74:77], v[126:129], v[218:221], v[74:77]
	v_mfma_f32_16x16x32_bf16 v[134:137], v[146:149], v[162:165], 0
	v_mfma_f32_16x16x32_bf16 v[130:133], v[154:157], v[162:165], 0
	v_mfma_f32_16x16x32_bf16 v[102:105], v[146:149], v[194:197], 0
	v_mfma_f32_16x16x32_bf16 v[94:97], v[154:157], v[194:197], 0
	v_mfma_f32_16x16x32_bf16 v[86:89], v[146:149], v[206:209], 0
	v_mfma_f32_16x16x32_bf16 v[78:81], v[154:157], v[206:209], 0
	v_mfma_f32_16x16x32_bf16 v[70:73], v[146:149], v[214:217], 0
	v_mfma_f32_16x16x32_bf16 v[66:69], v[154:157], v[214:217], 0
	v_mfma_f32_16x16x32_bf16 v[134:137], v[150:153], v[166:169], v[134:137]
	v_mfma_f32_16x16x32_bf16 v[130:133], v[158:161], v[166:169], v[130:133]
	v_mfma_f32_16x16x32_bf16 v[102:105], v[150:153], v[198:201], v[102:105]
	v_mfma_f32_16x16x32_bf16 v[94:97], v[158:161], v[198:201], v[94:97]
	v_mfma_f32_16x16x32_bf16 v[86:89], v[150:153], v[210:213], v[86:89]
	v_mfma_f32_16x16x32_bf16 v[78:81], v[158:161], v[210:213], v[78:81]
	v_mfma_f32_16x16x32_bf16 v[70:73], v[150:153], v[218:221], v[70:73]
	v_mfma_f32_16x16x32_bf16 v[66:69], v[158:161], v[218:221], v[66:69]
	s_setprio 0
	s_barrier
	s_add_i32 s63, s24, s86
	v_lshl_add_u64 v[186:187], s[78:79], 0, v[172:173]
	s_mov_b32 m0, s63
	ds_read_b128 v[162:165], v192 offset:16384
	ds_read_b128 v[166:169], v192 offset:17408
	ds_read_b128 v[194:197], v192 offset:18432
	ds_read_b128 v[198:201], v192 offset:19456
	ds_read_b128 v[206:209], v192 offset:20480
	ds_read_b128 v[210:213], v192 offset:21504
	ds_read_b128 v[214:217], v192 offset:22528
	ds_read_b128 v[218:221], v192 offset:23552
	global_load_lds_dwordx4 v[186:187], off
	s_add_i32 m0, s63, 0x2000
	s_add_u32 vcc_lo, s78, 0x100000
	v_lshl_add_u64 v[202:203], s[78:79], 0, v[176:177]
	s_addc_u32 vcc_hi, s79, 0
	s_add_i32 s63, s25, s86
	global_load_lds_dwordx4 v[202:203], off
	v_lshl_add_u64 v[222:223], vcc, 0, v[172:173]
	s_mov_b32 m0, s63
	v_lshl_add_u64 v[224:225], s[80:81], 0, v[174:175]
	global_load_lds_dwordx4 v[222:223], off
	s_add_i32 m0, s63, 0x2000
	v_lshl_add_u64 v[222:223], vcc, 0, v[176:177]
	global_load_lds_dwordx4 v[222:223], off
	s_mov_b32 m0, s87
	v_lshl_add_u64 v[222:223], s[80:81], 0, v[170:171]
	global_load_lds_dwordx4 v[222:223], off
	s_mov_b32 m0, s88
	s_nop 0
	global_load_lds_dwordx4 v[224:225], off
	s_nop 0
	s_waitcnt vmcnt(8) lgkmcnt(0)
	s_setprio 1
	s_barrier
	v_mfma_f32_16x16x32_bf16 v[62:65], v[114:117], v[162:165], 0
	v_mfma_f32_16x16x32_bf16 v[58:61], v[122:125], v[162:165], 0
	v_mfma_f32_16x16x32_bf16 v[50:53], v[114:117], v[194:197], 0
	v_mfma_f32_16x16x32_bf16 v[42:45], v[122:125], v[194:197], 0
	v_mfma_f32_16x16x32_bf16 v[34:37], v[114:117], v[206:209], 0
	v_mfma_f32_16x16x32_bf16 v[26:29], v[122:125], v[206:209], 0
	v_mfma_f32_16x16x32_bf16 v[18:21], v[114:117], v[214:217], 0
	v_mfma_f32_16x16x32_bf16 v[10:13], v[122:125], v[214:217], 0
	v_mfma_f32_16x16x32_bf16 v[62:65], v[118:121], v[166:169], v[62:65]
	v_mfma_f32_16x16x32_bf16 v[58:61], v[126:129], v[166:169], v[58:61]
	v_mfma_f32_16x16x32_bf16 v[50:53], v[118:121], v[198:201], v[50:53]
	v_mfma_f32_16x16x32_bf16 v[42:45], v[126:129], v[198:201], v[42:45]
	v_mfma_f32_16x16x32_bf16 v[34:37], v[118:121], v[210:213], v[34:37]
	v_mfma_f32_16x16x32_bf16 v[26:29], v[126:129], v[210:213], v[26:29]
	v_mfma_f32_16x16x32_bf16 v[18:21], v[118:121], v[218:221], v[18:21]
	v_mfma_f32_16x16x32_bf16 v[10:13], v[126:129], v[218:221], v[10:13]
	v_mfma_f32_16x16x32_bf16 v[54:57], v[146:149], v[162:165], 0
	v_mfma_f32_16x16x32_bf16 v[46:49], v[154:157], v[162:165], 0
	v_mfma_f32_16x16x32_bf16 v[38:41], v[146:149], v[194:197], 0
	v_mfma_f32_16x16x32_bf16 v[30:33], v[154:157], v[194:197], 0
	v_mfma_f32_16x16x32_bf16 v[22:25], v[146:149], v[206:209], 0
	v_mfma_f32_16x16x32_bf16 v[14:17], v[154:157], v[206:209], 0
	v_mfma_f32_16x16x32_bf16 v[6:9], v[146:149], v[214:217], 0
	v_mfma_f32_16x16x32_bf16 v[2:5], v[154:157], v[214:217], 0
	v_mfma_f32_16x16x32_bf16 v[54:57], v[150:153], v[166:169], v[54:57]
	v_mfma_f32_16x16x32_bf16 v[46:49], v[158:161], v[166:169], v[46:49]
	v_mfma_f32_16x16x32_bf16 v[38:41], v[150:153], v[198:201], v[38:41]
	v_mfma_f32_16x16x32_bf16 v[30:33], v[158:161], v[198:201], v[30:33]
	v_mfma_f32_16x16x32_bf16 v[22:25], v[150:153], v[210:213], v[22:25]
	v_mfma_f32_16x16x32_bf16 v[14:17], v[158:161], v[210:213], v[14:17]
	v_mfma_f32_16x16x32_bf16 v[6:9], v[150:153], v[218:221], v[6:9]
	v_mfma_f32_16x16x32_bf16 v[2:5], v[158:161], v[218:221], v[2:5]
	s_setprio 0
	s_barrier
	s_add_i32 s63, 0, 0x18000
	s_add_i32 s83, 0, 0x1c000
	v_add_u32_e32 v126, s63, v189
	v_add_u32_e32 v158, s83, v189
	ds_read_b128 v[114:117], v126
	ds_read_b128 v[118:121], v126 offset:1024
	ds_read_b128 v[122:125], v126 offset:2048
	ds_read_b128 v[126:129], v126 offset:3072
	ds_read_b128 v[146:149], v158
	ds_read_b128 v[150:153], v158 offset:1024
	ds_read_b128 v[154:157], v158 offset:2048
	ds_read_b128 v[158:161], v158 offset:3072
	s_add_u32 s80, s80, 0x100000
	s_addc_u32 s81, s81, 0
	s_mov_b32 m0, s89
	v_lshl_add_u64 v[226:227], s[80:81], 0, v[170:171]
	ds_read_b128 v[162:165], v192 offset:32768
	ds_read_b128 v[166:169], v192 offset:33792
	ds_read_b128 v[194:197], v192 offset:34816
	ds_read_b128 v[198:201], v192 offset:35840
	ds_read_b128 v[206:209], v192 offset:36864
	ds_read_b128 v[210:213], v192 offset:37888
	ds_read_b128 v[214:217], v192 offset:38912
	ds_read_b128 v[218:221], v192 offset:39936
	global_load_lds_dwordx4 v[226:227], off
	s_mov_b32 m0, s90
	v_lshl_add_u64 v[226:227], s[80:81], 0, v[174:175]
	global_load_lds_dwordx4 v[226:227], off
	s_waitcnt vmcnt(8) lgkmcnt(0)
	s_setprio 1
	s_barrier
	v_mfma_f32_16x16x32_bf16 v[142:145], v[114:117], v[162:165], v[142:145]
	v_mfma_f32_16x16x32_bf16 v[138:141], v[122:125], v[162:165], v[138:141]
	v_mfma_f32_16x16x32_bf16 v[110:113], v[114:117], v[194:197], v[110:113]
	v_mfma_f32_16x16x32_bf16 v[106:109], v[122:125], v[194:197], v[106:109]
	v_mfma_f32_16x16x32_bf16 v[98:101], v[114:117], v[206:209], v[98:101]
	v_mfma_f32_16x16x32_bf16 v[90:93], v[122:125], v[206:209], v[90:93]
	v_mfma_f32_16x16x32_bf16 v[82:85], v[114:117], v[214:217], v[82:85]
	v_mfma_f32_16x16x32_bf16 v[74:77], v[122:125], v[214:217], v[74:77]
	v_mfma_f32_16x16x32_bf16 v[142:145], v[118:121], v[166:169], v[142:145]
	v_mfma_f32_16x16x32_bf16 v[138:141], v[126:129], v[166:169], v[138:141]
	v_mfma_f32_16x16x32_bf16 v[110:113], v[118:121], v[198:201], v[110:113]
	v_mfma_f32_16x16x32_bf16 v[106:109], v[126:129], v[198:201], v[106:109]
	v_mfma_f32_16x16x32_bf16 v[98:101], v[118:121], v[210:213], v[98:101]
	v_mfma_f32_16x16x32_bf16 v[90:93], v[126:129], v[210:213], v[90:93]
	v_mfma_f32_16x16x32_bf16 v[82:85], v[118:121], v[218:221], v[82:85]
	v_mfma_f32_16x16x32_bf16 v[74:77], v[126:129], v[218:221], v[74:77]
	v_mfma_f32_16x16x32_bf16 v[134:137], v[146:149], v[162:165], v[134:137]
	v_mfma_f32_16x16x32_bf16 v[130:133], v[154:157], v[162:165], v[130:133]
	v_mfma_f32_16x16x32_bf16 v[102:105], v[146:149], v[194:197], v[102:105]
	v_mfma_f32_16x16x32_bf16 v[94:97], v[154:157], v[194:197], v[94:97]
	v_mfma_f32_16x16x32_bf16 v[86:89], v[146:149], v[206:209], v[86:89]
	v_mfma_f32_16x16x32_bf16 v[78:81], v[154:157], v[206:209], v[78:81]
	v_mfma_f32_16x16x32_bf16 v[70:73], v[146:149], v[214:217], v[70:73]
	v_mfma_f32_16x16x32_bf16 v[66:69], v[154:157], v[214:217], v[66:69]
	v_mfma_f32_16x16x32_bf16 v[134:137], v[150:153], v[166:169], v[134:137]
	v_mfma_f32_16x16x32_bf16 v[130:133], v[158:161], v[166:169], v[130:133]
	v_mfma_f32_16x16x32_bf16 v[102:105], v[150:153], v[198:201], v[102:105]
	v_mfma_f32_16x16x32_bf16 v[94:97], v[158:161], v[198:201], v[94:97]
	v_mfma_f32_16x16x32_bf16 v[86:89], v[150:153], v[210:213], v[86:89]
	v_mfma_f32_16x16x32_bf16 v[78:81], v[158:161], v[210:213], v[78:81]
	v_mfma_f32_16x16x32_bf16 v[70:73], v[150:153], v[218:221], v[70:73]
	v_mfma_f32_16x16x32_bf16 v[66:69], v[158:161], v[218:221], v[66:69]
	s_setprio 0
	s_barrier
	s_add_i32 s63, s63, s86
	v_lshl_add_u64 v[186:187], v[186:187], 0, s[22:23]
	s_mov_b32 m0, s63
	ds_read_b128 v[162:165], v192 offset:49152
	ds_read_b128 v[166:169], v192 offset:50176
	ds_read_b128 v[194:197], v192 offset:51200
	ds_read_b128 v[198:201], v192 offset:52224
	ds_read_b128 v[206:209], v192 offset:53248
	ds_read_b128 v[210:213], v192 offset:54272
	ds_read_b128 v[214:217], v192 offset:55296
	ds_read_b128 v[218:221], v192 offset:56320
	global_load_lds_dwordx4 v[186:187], off
	s_add_i32 m0, s63, 0x2000
	s_add_u32 s78, s78, 0x100080
	v_lshl_add_u64 v[186:187], v[202:203], 0, s[22:23]
	s_addc_u32 s79, s79, 0
	s_add_i32 s63, s83, s86
	global_load_lds_dwordx4 v[186:187], off
	s_mov_b32 m0, s63
	v_lshl_add_u64 v[186:187], s[78:79], 0, v[172:173]
	global_load_lds_dwordx4 v[186:187], off
	s_add_i32 m0, s63, 0x2000
	v_lshl_add_u64 v[186:187], s[78:79], 0, v[176:177]
	global_load_lds_dwordx4 v[186:187], off
	s_mov_b32 m0, s95
	v_lshl_add_u64 v[186:187], v[222:223], 0, s[22:23]
	global_load_lds_dwordx4 v[186:187], off
	s_mov_b32 m0, s96
	v_lshl_add_u64 v[186:187], v[224:225], 0, s[22:23]
	global_load_lds_dwordx4 v[186:187], off
	s_waitcnt vmcnt(8) lgkmcnt(0)
	s_setprio 1
	s_barrier
	v_mfma_f32_16x16x32_bf16 v[62:65], v[114:117], v[162:165], v[62:65]
	v_mfma_f32_16x16x32_bf16 v[58:61], v[122:125], v[162:165], v[58:61]
	v_mfma_f32_16x16x32_bf16 v[50:53], v[114:117], v[194:197], v[50:53]
	v_mfma_f32_16x16x32_bf16 v[42:45], v[122:125], v[194:197], v[42:45]
	v_mfma_f32_16x16x32_bf16 v[34:37], v[114:117], v[206:209], v[34:37]
	v_mfma_f32_16x16x32_bf16 v[26:29], v[122:125], v[206:209], v[26:29]
	v_mfma_f32_16x16x32_bf16 v[18:21], v[114:117], v[214:217], v[18:21]
	v_mfma_f32_16x16x32_bf16 v[10:13], v[122:125], v[214:217], v[10:13]
	v_mfma_f32_16x16x32_bf16 v[62:65], v[118:121], v[166:169], v[62:65]
	v_mfma_f32_16x16x32_bf16 v[58:61], v[126:129], v[166:169], v[58:61]
	v_mfma_f32_16x16x32_bf16 v[50:53], v[118:121], v[198:201], v[50:53]
	v_mfma_f32_16x16x32_bf16 v[42:45], v[126:129], v[198:201], v[42:45]
	v_mfma_f32_16x16x32_bf16 v[34:37], v[118:121], v[210:213], v[34:37]
	v_mfma_f32_16x16x32_bf16 v[26:29], v[126:129], v[210:213], v[26:29]
	v_mfma_f32_16x16x32_bf16 v[18:21], v[118:121], v[218:221], v[18:21]
	v_mfma_f32_16x16x32_bf16 v[10:13], v[126:129], v[218:221], v[10:13]
	v_mfma_f32_16x16x32_bf16 v[54:57], v[146:149], v[162:165], v[54:57]
	v_mfma_f32_16x16x32_bf16 v[46:49], v[154:157], v[162:165], v[46:49]
	v_mfma_f32_16x16x32_bf16 v[38:41], v[146:149], v[194:197], v[38:41]
	v_mfma_f32_16x16x32_bf16 v[30:33], v[154:157], v[194:197], v[30:33]
	v_mfma_f32_16x16x32_bf16 v[22:25], v[146:149], v[206:209], v[22:25]
	v_mfma_f32_16x16x32_bf16 v[14:17], v[154:157], v[206:209], v[14:17]
	v_mfma_f32_16x16x32_bf16 v[6:9], v[146:149], v[214:217], v[6:9]
	v_mfma_f32_16x16x32_bf16 v[2:5], v[154:157], v[214:217], v[2:5]
	v_mfma_f32_16x16x32_bf16 v[54:57], v[150:153], v[166:169], v[54:57]
	v_mfma_f32_16x16x32_bf16 v[46:49], v[158:161], v[166:169], v[46:49]
	v_mfma_f32_16x16x32_bf16 v[38:41], v[150:153], v[198:201], v[38:41]
	v_mfma_f32_16x16x32_bf16 v[30:33], v[158:161], v[198:201], v[30:33]
	v_mfma_f32_16x16x32_bf16 v[22:25], v[150:153], v[210:213], v[22:25]
	v_mfma_f32_16x16x32_bf16 v[14:17], v[158:161], v[210:213], v[14:17]
	v_mfma_f32_16x16x32_bf16 v[6:9], v[150:153], v[218:221], v[6:9]
	v_mfma_f32_16x16x32_bf16 v[2:5], v[158:161], v[218:221], v[2:5]
	s_setprio 0
	s_barrier
	s_add_u32 s76, s76, 0x100
	s_addc_u32 s77, s77, 0
	s_add_u32 s47, s47, 0x100
	s_addc_u32 s62, s62, 0
	s_cmp_ge_i32 s82, s7
	s_mov_b32 s63, s82
.LBB0_834:
	ds_read_b128 v[114:117], v190
	ds_read_b128 v[118:121], v190 offset:1024
	ds_read_b128 v[122:125], v190 offset:2048
	ds_read_b128 v[126:129], v190 offset:3072
	ds_read_b128 v[146:149], v191
	ds_read_b128 v[150:153], v191 offset:1024
	ds_read_b128 v[154:157], v191 offset:2048
	ds_read_b128 v[158:161], v191 offset:3072
	s_add_i32 s82, s63, 2
	s_add_u32 s78, s76, 0xfff00080
	s_addc_u32 s79, s77, -1
	s_cmp_eq_u32 s45, s63
	s_cselect_b32 s81, s15, s79
	s_cselect_b32 s80, s33, s78
	s_cselect_b32 s79, s34, s62
	s_cselect_b32 s78, s39, s47
	v_lshl_add_u64 v[186:187], s[76:77], 0, v[180:181]
	s_add_i32 m0, s87, 0xc000
	ds_read_b128 v[162:165], v192
	ds_read_b128 v[166:169], v192 offset:1024
	ds_read_b128 v[194:197], v192 offset:2048
	ds_read_b128 v[198:201], v192 offset:3072
	ds_read_b128 v[206:209], v192 offset:4096
	ds_read_b128 v[210:213], v192 offset:5120
	ds_read_b128 v[214:217], v192 offset:6144
	ds_read_b128 v[218:221], v192 offset:7168
	global_load_lds_dwordx4 v[186:187], off
	s_add_i32 m0, s87, 0xe000
	v_lshl_add_u64 v[186:187], s[76:77], 0, v[182:183]
	global_load_lds_dwordx4 v[186:187], off
	s_waitcnt vmcnt(8) lgkmcnt(0)
	s_setprio 1
	s_barrier
	v_mfma_f32_16x16x32_bf16 v[142:145], v[114:117], v[162:165], v[142:145]
	v_mfma_f32_16x16x32_bf16 v[138:141], v[122:125], v[162:165], v[138:141]
	v_mfma_f32_16x16x32_bf16 v[110:113], v[114:117], v[194:197], v[110:113]
	v_mfma_f32_16x16x32_bf16 v[106:109], v[122:125], v[194:197], v[106:109]
	v_mfma_f32_16x16x32_bf16 v[98:101], v[114:117], v[206:209], v[98:101]
	v_mfma_f32_16x16x32_bf16 v[90:93], v[122:125], v[206:209], v[90:93]
	v_mfma_f32_16x16x32_bf16 v[82:85], v[114:117], v[214:217], v[82:85]
	v_mfma_f32_16x16x32_bf16 v[74:77], v[122:125], v[214:217], v[74:77]
	v_mfma_f32_16x16x32_bf16 v[142:145], v[118:121], v[166:169], v[142:145]
	v_mfma_f32_16x16x32_bf16 v[138:141], v[126:129], v[166:169], v[138:141]
	v_mfma_f32_16x16x32_bf16 v[110:113], v[118:121], v[198:201], v[110:113]
	v_mfma_f32_16x16x32_bf16 v[106:109], v[126:129], v[198:201], v[106:109]
	v_mfma_f32_16x16x32_bf16 v[98:101], v[118:121], v[210:213], v[98:101]
	v_mfma_f32_16x16x32_bf16 v[90:93], v[126:129], v[210:213], v[90:93]
	v_mfma_f32_16x16x32_bf16 v[82:85], v[118:121], v[218:221], v[82:85]
	v_mfma_f32_16x16x32_bf16 v[74:77], v[126:129], v[218:221], v[74:77]
	v_mfma_f32_16x16x32_bf16 v[134:137], v[146:149], v[162:165], v[134:137]
	v_mfma_f32_16x16x32_bf16 v[130:133], v[154:157], v[162:165], v[130:133]
	v_mfma_f32_16x16x32_bf16 v[102:105], v[146:149], v[194:197], v[102:105]
	v_mfma_f32_16x16x32_bf16 v[94:97], v[154:157], v[194:197], v[94:97]
	v_mfma_f32_16x16x32_bf16 v[86:89], v[146:149], v[206:209], v[86:89]
	v_mfma_f32_16x16x32_bf16 v[78:81], v[154:157], v[206:209], v[78:81]
	v_mfma_f32_16x16x32_bf16 v[70:73], v[146:149], v[214:217], v[70:73]
	v_mfma_f32_16x16x32_bf16 v[66:69], v[154:157], v[214:217], v[66:69]
	v_mfma_f32_16x16x32_bf16 v[134:137], v[150:153], v[166:169], v[134:137]
	v_mfma_f32_16x16x32_bf16 v[130:133], v[158:161], v[166:169], v[130:133]
	v_mfma_f32_16x16x32_bf16 v[102:105], v[150:153], v[198:201], v[102:105]
	v_mfma_f32_16x16x32_bf16 v[94:97], v[158:161], v[198:201], v[94:97]
	v_mfma_f32_16x16x32_bf16 v[86:89], v[150:153], v[210:213], v[86:89]
	v_mfma_f32_16x16x32_bf16 v[78:81], v[158:161], v[210:213], v[78:81]
	v_mfma_f32_16x16x32_bf16 v[70:73], v[150:153], v[218:221], v[70:73]
	v_mfma_f32_16x16x32_bf16 v[66:69], v[158:161], v[218:221], v[66:69]
	s_setprio 0
	s_barrier
	s_add_i32 s63, s24, s86
	v_lshl_add_u64 v[186:187], s[78:79], 0, v[172:173]
	s_mov_b32 m0, s63
	ds_read_b128 v[162:165], v192 offset:16384
	ds_read_b128 v[166:169], v192 offset:17408
	ds_read_b128 v[194:197], v192 offset:18432
	ds_read_b128 v[198:201], v192 offset:19456
	ds_read_b128 v[206:209], v192 offset:20480
	ds_read_b128 v[210:213], v192 offset:21504
	ds_read_b128 v[214:217], v192 offset:22528
	ds_read_b128 v[218:221], v192 offset:23552
	global_load_lds_dwordx4 v[186:187], off
	s_add_i32 m0, s63, 0x2000
	s_add_u32 vcc_lo, s78, 0x100000
	v_lshl_add_u64 v[202:203], s[78:79], 0, v[176:177]
	s_addc_u32 vcc_hi, s79, 0
	s_add_i32 s63, s25, s86
	global_load_lds_dwordx4 v[202:203], off
	v_lshl_add_u64 v[222:223], vcc, 0, v[172:173]
	s_mov_b32 m0, s63
	v_lshl_add_u64 v[224:225], s[80:81], 0, v[174:175]
	global_load_lds_dwordx4 v[222:223], off
	s_add_i32 m0, s63, 0x2000
	v_lshl_add_u64 v[222:223], vcc, 0, v[176:177]
	global_load_lds_dwordx4 v[222:223], off
	s_mov_b32 m0, s87
	v_lshl_add_u64 v[222:223], s[80:81], 0, v[170:171]
	global_load_lds_dwordx4 v[222:223], off
	s_mov_b32 m0, s88
	s_nop 0
	global_load_lds_dwordx4 v[224:225], off
	s_nop 0
	s_waitcnt vmcnt(8) lgkmcnt(0)
	s_setprio 1
	s_barrier
	v_mfma_f32_16x16x32_bf16 v[62:65], v[114:117], v[162:165], v[62:65]
	v_mfma_f32_16x16x32_bf16 v[58:61], v[122:125], v[162:165], v[58:61]
	v_mfma_f32_16x16x32_bf16 v[50:53], v[114:117], v[194:197], v[50:53]
	v_mfma_f32_16x16x32_bf16 v[42:45], v[122:125], v[194:197], v[42:45]
	v_mfma_f32_16x16x32_bf16 v[34:37], v[114:117], v[206:209], v[34:37]
	v_mfma_f32_16x16x32_bf16 v[26:29], v[122:125], v[206:209], v[26:29]
	v_mfma_f32_16x16x32_bf16 v[18:21], v[114:117], v[214:217], v[18:21]
	v_mfma_f32_16x16x32_bf16 v[10:13], v[122:125], v[214:217], v[10:13]
	v_mfma_f32_16x16x32_bf16 v[62:65], v[118:121], v[166:169], v[62:65]
	v_mfma_f32_16x16x32_bf16 v[58:61], v[126:129], v[166:169], v[58:61]
	v_mfma_f32_16x16x32_bf16 v[50:53], v[118:121], v[198:201], v[50:53]
	v_mfma_f32_16x16x32_bf16 v[42:45], v[126:129], v[198:201], v[42:45]
	v_mfma_f32_16x16x32_bf16 v[34:37], v[118:121], v[210:213], v[34:37]
	v_mfma_f32_16x16x32_bf16 v[26:29], v[126:129], v[210:213], v[26:29]
	v_mfma_f32_16x16x32_bf16 v[18:21], v[118:121], v[218:221], v[18:21]
	v_mfma_f32_16x16x32_bf16 v[10:13], v[126:129], v[218:221], v[10:13]
	v_mfma_f32_16x16x32_bf16 v[54:57], v[146:149], v[162:165], v[54:57]
	v_mfma_f32_16x16x32_bf16 v[46:49], v[154:157], v[162:165], v[46:49]
	v_mfma_f32_16x16x32_bf16 v[38:41], v[146:149], v[194:197], v[38:41]
	v_mfma_f32_16x16x32_bf16 v[30:33], v[154:157], v[194:197], v[30:33]
	v_mfma_f32_16x16x32_bf16 v[22:25], v[146:149], v[206:209], v[22:25]
	v_mfma_f32_16x16x32_bf16 v[14:17], v[154:157], v[206:209], v[14:17]
	v_mfma_f32_16x16x32_bf16 v[6:9], v[146:149], v[214:217], v[6:9]
	v_mfma_f32_16x16x32_bf16 v[2:5], v[154:157], v[214:217], v[2:5]
	v_mfma_f32_16x16x32_bf16 v[54:57], v[150:153], v[166:169], v[54:57]
	v_mfma_f32_16x16x32_bf16 v[46:49], v[158:161], v[166:169], v[46:49]
	v_mfma_f32_16x16x32_bf16 v[38:41], v[150:153], v[198:201], v[38:41]
	v_mfma_f32_16x16x32_bf16 v[30:33], v[158:161], v[198:201], v[30:33]
	v_mfma_f32_16x16x32_bf16 v[22:25], v[150:153], v[210:213], v[22:25]
	v_mfma_f32_16x16x32_bf16 v[14:17], v[158:161], v[210:213], v[14:17]
	v_mfma_f32_16x16x32_bf16 v[6:9], v[150:153], v[218:221], v[6:9]
	v_mfma_f32_16x16x32_bf16 v[2:5], v[158:161], v[218:221], v[2:5]
	s_setprio 0
	s_barrier
	s_add_i32 s63, 0, 0x18000
	s_add_i32 s83, 0, 0x1c000
	v_add_u32_e32 v126, s63, v189
	v_add_u32_e32 v158, s83, v189
	ds_read_b128 v[114:117], v126
	ds_read_b128 v[118:121], v126 offset:1024
	ds_read_b128 v[122:125], v126 offset:2048
	ds_read_b128 v[126:129], v126 offset:3072
	ds_read_b128 v[146:149], v158
	ds_read_b128 v[150:153], v158 offset:1024
	ds_read_b128 v[154:157], v158 offset:2048
	ds_read_b128 v[158:161], v158 offset:3072
	s_add_u32 s80, s80, 0x100000
	s_addc_u32 s81, s81, 0
	s_mov_b32 m0, s89
	v_lshl_add_u64 v[226:227], s[80:81], 0, v[170:171]
	ds_read_b128 v[162:165], v192 offset:32768
	ds_read_b128 v[166:169], v192 offset:33792
	ds_read_b128 v[194:197], v192 offset:34816
	ds_read_b128 v[198:201], v192 offset:35840
	ds_read_b128 v[206:209], v192 offset:36864
	ds_read_b128 v[210:213], v192 offset:37888
	ds_read_b128 v[214:217], v192 offset:38912
	ds_read_b128 v[218:221], v192 offset:39936
	global_load_lds_dwordx4 v[226:227], off
	s_mov_b32 m0, s90
	v_lshl_add_u64 v[226:227], s[80:81], 0, v[174:175]
	global_load_lds_dwordx4 v[226:227], off
	s_waitcnt vmcnt(8) lgkmcnt(0)
	s_setprio 1
	s_barrier
	v_mfma_f32_16x16x32_bf16 v[142:145], v[114:117], v[162:165], v[142:145]
	v_mfma_f32_16x16x32_bf16 v[138:141], v[122:125], v[162:165], v[138:141]
	v_mfma_f32_16x16x32_bf16 v[110:113], v[114:117], v[194:197], v[110:113]
	v_mfma_f32_16x16x32_bf16 v[106:109], v[122:125], v[194:197], v[106:109]
	v_mfma_f32_16x16x32_bf16 v[98:101], v[114:117], v[206:209], v[98:101]
	v_mfma_f32_16x16x32_bf16 v[90:93], v[122:125], v[206:209], v[90:93]
	v_mfma_f32_16x16x32_bf16 v[82:85], v[114:117], v[214:217], v[82:85]
	v_mfma_f32_16x16x32_bf16 v[74:77], v[122:125], v[214:217], v[74:77]
	v_mfma_f32_16x16x32_bf16 v[142:145], v[118:121], v[166:169], v[142:145]
	v_mfma_f32_16x16x32_bf16 v[138:141], v[126:129], v[166:169], v[138:141]
	v_mfma_f32_16x16x32_bf16 v[110:113], v[118:121], v[198:201], v[110:113]
	v_mfma_f32_16x16x32_bf16 v[106:109], v[126:129], v[198:201], v[106:109]
	v_mfma_f32_16x16x32_bf16 v[98:101], v[118:121], v[210:213], v[98:101]
	v_mfma_f32_16x16x32_bf16 v[90:93], v[126:129], v[210:213], v[90:93]
	v_mfma_f32_16x16x32_bf16 v[82:85], v[118:121], v[218:221], v[82:85]
	v_mfma_f32_16x16x32_bf16 v[74:77], v[126:129], v[218:221], v[74:77]
	v_mfma_f32_16x16x32_bf16 v[134:137], v[146:149], v[162:165], v[134:137]
	v_mfma_f32_16x16x32_bf16 v[130:133], v[154:157], v[162:165], v[130:133]
	v_mfma_f32_16x16x32_bf16 v[102:105], v[146:149], v[194:197], v[102:105]
	v_mfma_f32_16x16x32_bf16 v[94:97], v[154:157], v[194:197], v[94:97]
	v_mfma_f32_16x16x32_bf16 v[86:89], v[146:149], v[206:209], v[86:89]
	v_mfma_f32_16x16x32_bf16 v[78:81], v[154:157], v[206:209], v[78:81]
	v_mfma_f32_16x16x32_bf16 v[70:73], v[146:149], v[214:217], v[70:73]
	v_mfma_f32_16x16x32_bf16 v[66:69], v[154:157], v[214:217], v[66:69]
	v_mfma_f32_16x16x32_bf16 v[134:137], v[150:153], v[166:169], v[134:137]
	v_mfma_f32_16x16x32_bf16 v[130:133], v[158:161], v[166:169], v[130:133]
	v_mfma_f32_16x16x32_bf16 v[102:105], v[150:153], v[198:201], v[102:105]
	v_mfma_f32_16x16x32_bf16 v[94:97], v[158:161], v[198:201], v[94:97]
	v_mfma_f32_16x16x32_bf16 v[86:89], v[150:153], v[210:213], v[86:89]
	v_mfma_f32_16x16x32_bf16 v[78:81], v[158:161], v[210:213], v[78:81]
	v_mfma_f32_16x16x32_bf16 v[70:73], v[150:153], v[218:221], v[70:73]
	v_mfma_f32_16x16x32_bf16 v[66:69], v[158:161], v[218:221], v[66:69]
	s_setprio 0
	s_barrier
	s_add_i32 s63, s63, s86
	v_lshl_add_u64 v[186:187], v[186:187], 0, s[22:23]
	s_mov_b32 m0, s63
	ds_read_b128 v[162:165], v192 offset:49152
	ds_read_b128 v[166:169], v192 offset:50176
	ds_read_b128 v[194:197], v192 offset:51200
	ds_read_b128 v[198:201], v192 offset:52224
	ds_read_b128 v[206:209], v192 offset:53248
	ds_read_b128 v[210:213], v192 offset:54272
	ds_read_b128 v[214:217], v192 offset:55296
	ds_read_b128 v[218:221], v192 offset:56320
	global_load_lds_dwordx4 v[186:187], off
	s_add_i32 m0, s63, 0x2000
	s_add_u32 s78, s78, 0x100080
	v_lshl_add_u64 v[186:187], v[202:203], 0, s[22:23]
	s_addc_u32 s79, s79, 0
	s_add_i32 s63, s83, s86
	global_load_lds_dwordx4 v[186:187], off
	s_mov_b32 m0, s63
	v_lshl_add_u64 v[186:187], s[78:79], 0, v[172:173]
	global_load_lds_dwordx4 v[186:187], off
	s_add_i32 m0, s63, 0x2000
	v_lshl_add_u64 v[186:187], s[78:79], 0, v[176:177]
	global_load_lds_dwordx4 v[186:187], off
	s_mov_b32 m0, s95
	v_lshl_add_u64 v[186:187], v[222:223], 0, s[22:23]
	global_load_lds_dwordx4 v[186:187], off
	s_mov_b32 m0, s96
	v_lshl_add_u64 v[186:187], v[224:225], 0, s[22:23]
	global_load_lds_dwordx4 v[186:187], off
	s_waitcnt vmcnt(8) lgkmcnt(0)
	s_setprio 1
	s_barrier
	v_mfma_f32_16x16x32_bf16 v[62:65], v[114:117], v[162:165], v[62:65]
	v_mfma_f32_16x16x32_bf16 v[58:61], v[122:125], v[162:165], v[58:61]
	v_mfma_f32_16x16x32_bf16 v[50:53], v[114:117], v[194:197], v[50:53]
	v_mfma_f32_16x16x32_bf16 v[42:45], v[122:125], v[194:197], v[42:45]
	v_mfma_f32_16x16x32_bf16 v[34:37], v[114:117], v[206:209], v[34:37]
	v_mfma_f32_16x16x32_bf16 v[26:29], v[122:125], v[206:209], v[26:29]
	v_mfma_f32_16x16x32_bf16 v[18:21], v[114:117], v[214:217], v[18:21]
	v_mfma_f32_16x16x32_bf16 v[10:13], v[122:125], v[214:217], v[10:13]
	v_mfma_f32_16x16x32_bf16 v[62:65], v[118:121], v[166:169], v[62:65]
	v_mfma_f32_16x16x32_bf16 v[58:61], v[126:129], v[166:169], v[58:61]
	v_mfma_f32_16x16x32_bf16 v[50:53], v[118:121], v[198:201], v[50:53]
	v_mfma_f32_16x16x32_bf16 v[42:45], v[126:129], v[198:201], v[42:45]
	v_mfma_f32_16x16x32_bf16 v[34:37], v[118:121], v[210:213], v[34:37]
	v_mfma_f32_16x16x32_bf16 v[26:29], v[126:129], v[210:213], v[26:29]
	v_mfma_f32_16x16x32_bf16 v[18:21], v[118:121], v[218:221], v[18:21]
	v_mfma_f32_16x16x32_bf16 v[10:13], v[126:129], v[218:221], v[10:13]
	v_mfma_f32_16x16x32_bf16 v[54:57], v[146:149], v[162:165], v[54:57]
	v_mfma_f32_16x16x32_bf16 v[46:49], v[154:157], v[162:165], v[46:49]
	v_mfma_f32_16x16x32_bf16 v[38:41], v[146:149], v[194:197], v[38:41]
	v_mfma_f32_16x16x32_bf16 v[30:33], v[154:157], v[194:197], v[30:33]
	v_mfma_f32_16x16x32_bf16 v[22:25], v[146:149], v[206:209], v[22:25]
	v_mfma_f32_16x16x32_bf16 v[14:17], v[154:157], v[206:209], v[14:17]
	v_mfma_f32_16x16x32_bf16 v[6:9], v[146:149], v[214:217], v[6:9]
	v_mfma_f32_16x16x32_bf16 v[2:5], v[154:157], v[214:217], v[2:5]
	v_mfma_f32_16x16x32_bf16 v[54:57], v[150:153], v[166:169], v[54:57]
	v_mfma_f32_16x16x32_bf16 v[46:49], v[158:161], v[166:169], v[46:49]
	v_mfma_f32_16x16x32_bf16 v[38:41], v[150:153], v[198:201], v[38:41]
	v_mfma_f32_16x16x32_bf16 v[30:33], v[158:161], v[198:201], v[30:33]
	v_mfma_f32_16x16x32_bf16 v[22:25], v[150:153], v[210:213], v[22:25]
	v_mfma_f32_16x16x32_bf16 v[14:17], v[158:161], v[210:213], v[14:17]
	v_mfma_f32_16x16x32_bf16 v[6:9], v[150:153], v[218:221], v[6:9]
	v_mfma_f32_16x16x32_bf16 v[2:5], v[158:161], v[218:221], v[2:5]
	s_setprio 0
	s_barrier
	s_add_u32 s76, s76, 0x100
	s_addc_u32 s77, s77, 0
	s_add_u32 s47, s47, 0x100
	s_addc_u32 s62, s62, 0
	s_cmp_ge_i32 s82, s7
	s_mov_b32 s63, s82
	s_cbranch_scc0 .LBB0_834
	s_and_b64 vcc, exec, s[26:27]
	s_cbranch_vccz .LBB0_837
	s_barrier

.LBB0_1012:
	s_add_u32 s48, s96, s44
	s_addc_u32 s49, s97, s45
	s_and_b64 s[14:15], s[4:5], exec
	s_cselect_b32 s6, s49, s65
	s_cselect_b32 s14, s48, s64
	s_add_u32 s50, s3, s46
	s_addc_u32 s51, s35, s47
	s_and_b64 s[18:19], s[4:5], exec
	s_cselect_b32 s15, s51, s67
	s_cselect_b32 s17, s50, s66
	s_add_u32 s64, s64, 0x40080
	s_addc_u32 s65, s65, 0
	s_add_u32 s18, s66, 0x100
	s_addc_u32 s19, s67, 0
	s_mov_b32 s24, -2
	s_waitcnt vmcnt(0)
	ds_read_b128 v[130:133], v172
	ds_read_b128 v[134:137], v172 offset:1024
	ds_read_b128 v[138:141], v172 offset:2048
	ds_read_b128 v[142:145], v172 offset:3072
	ds_read_b128 v[164:167], v173
	ds_read_b128 v[176:179], v173 offset:1024
	ds_read_b128 v[180:183], v173 offset:2048
	ds_read_b128 v[184:187], v173 offset:3072
	s_add_u32 s25, s64, 0xfffc0080
	s_addc_u32 s28, s65, -1
	s_cmp_eq_u32 s24, 12
	s_cselect_b32 s69, s6, s28
	s_cselect_b32 s68, s14, s25
	s_cselect_b32 s67, s15, s19
	s_cselect_b32 s66, s17, s18
	v_lshl_add_u64 v[168:169], s[64:65], 0, v[156:157]
	s_add_i32 m0, s73, 0xc000
	ds_read_b128 v[188:191], v174
	ds_read_b128 v[192:195], v174 offset:1024
	ds_read_b128 v[196:199], v174 offset:2048
	ds_read_b128 v[200:203], v174 offset:3072
	ds_read_b128 v[206:209], v174 offset:4096
	ds_read_b128 v[210:213], v174 offset:5120
	ds_read_b128 v[214:217], v174 offset:6144
	ds_read_b128 v[218:221], v174 offset:7168
	global_load_lds_dwordx4 v[168:169], off
	s_add_i32 m0, s73, 0xe000
	v_lshl_add_u64 v[168:169], s[64:65], 0, v[158:159]
	global_load_lds_dwordx4 v[168:169], off
	s_nop 0
	s_waitcnt vmcnt(8) lgkmcnt(0)
	s_setprio 1
	s_barrier
	v_mfma_f32_16x16x32_bf16 v[126:129], v[130:133], v[188:191], 0
	v_mfma_f32_16x16x32_bf16 v[122:125], v[138:141], v[188:191], 0
	v_mfma_f32_16x16x32_bf16 v[110:113], v[130:133], v[196:199], 0
	v_mfma_f32_16x16x32_bf16 v[106:109], v[138:141], v[196:199], 0
	v_mfma_f32_16x16x32_bf16 v[94:97], v[130:133], v[206:209], 0
	v_mfma_f32_16x16x32_bf16 v[90:93], v[138:141], v[206:209], 0
	v_mfma_f32_16x16x32_bf16 v[78:81], v[130:133], v[214:217], 0
	v_mfma_f32_16x16x32_bf16 v[74:77], v[138:141], v[214:217], 0
	v_mfma_f32_16x16x32_bf16 v[126:129], v[134:137], v[192:195], v[126:129]
	v_mfma_f32_16x16x32_bf16 v[122:125], v[142:145], v[192:195], v[122:125]
	v_mfma_f32_16x16x32_bf16 v[110:113], v[134:137], v[200:203], v[110:113]
	v_mfma_f32_16x16x32_bf16 v[106:109], v[142:145], v[200:203], v[106:109]
	v_mfma_f32_16x16x32_bf16 v[94:97], v[134:137], v[210:213], v[94:97]
	v_mfma_f32_16x16x32_bf16 v[90:93], v[142:145], v[210:213], v[90:93]
	v_mfma_f32_16x16x32_bf16 v[78:81], v[134:137], v[218:221], v[78:81]
	v_mfma_f32_16x16x32_bf16 v[74:77], v[142:145], v[218:221], v[74:77]
	v_mfma_f32_16x16x32_bf16 v[118:121], v[164:167], v[188:191], 0
	v_mfma_f32_16x16x32_bf16 v[114:117], v[180:183], v[188:191], 0
	v_mfma_f32_16x16x32_bf16 v[102:105], v[164:167], v[196:199], 0
	v_mfma_f32_16x16x32_bf16 v[98:101], v[180:183], v[196:199], 0
	v_mfma_f32_16x16x32_bf16 v[86:89], v[164:167], v[206:209], 0
	v_mfma_f32_16x16x32_bf16 v[82:85], v[180:183], v[206:209], 0
	v_mfma_f32_16x16x32_bf16 v[70:73], v[164:167], v[214:217], 0
	v_mfma_f32_16x16x32_bf16 v[66:69], v[180:183], v[214:217], 0
	v_mfma_f32_16x16x32_bf16 v[118:121], v[176:179], v[192:195], v[118:121]
	v_mfma_f32_16x16x32_bf16 v[114:117], v[184:187], v[192:195], v[114:117]
	v_mfma_f32_16x16x32_bf16 v[102:105], v[176:179], v[200:203], v[102:105]
	v_mfma_f32_16x16x32_bf16 v[98:101], v[184:187], v[200:203], v[98:101]
	v_mfma_f32_16x16x32_bf16 v[86:89], v[176:179], v[210:213], v[86:89]
	v_mfma_f32_16x16x32_bf16 v[82:85], v[184:187], v[210:213], v[82:85]
	v_mfma_f32_16x16x32_bf16 v[70:73], v[176:179], v[218:221], v[70:73]
	v_mfma_f32_16x16x32_bf16 v[66:69], v[184:187], v[218:221], v[66:69]
	s_setprio 0
	s_barrier
	s_add_i32 s25, s82, s70
	v_lshl_add_u64 v[168:169], s[66:67], 0, v[150:151]
	s_mov_b32 m0, s25
	ds_read_b128 v[188:191], v174 offset:16384
	ds_read_b128 v[192:195], v174 offset:17408
	ds_read_b128 v[196:199], v174 offset:18432
	ds_read_b128 v[200:203], v174 offset:19456
	ds_read_b128 v[206:209], v174 offset:20480
	ds_read_b128 v[210:213], v174 offset:21504
	ds_read_b128 v[214:217], v174 offset:22528
	ds_read_b128 v[218:221], v174 offset:23552
	global_load_lds_dwordx4 v[168:169], off
	s_add_i32 m0, s25, 0x2000
	s_add_u32 s28, s66, 0x40000
	v_lshl_add_u64 v[222:223], s[66:67], 0, v[146:147]
	s_addc_u32 s29, s67, 0
	s_add_i32 s25, s83, s70
	global_load_lds_dwordx4 v[222:223], off
	v_lshl_add_u64 v[224:225], s[28:29], 0, v[150:151]
	s_mov_b32 m0, s25
	v_lshl_add_u64 v[226:227], s[68:69], 0, v[148:149]
	global_load_lds_dwordx4 v[224:225], off
	s_add_i32 m0, s25, 0x2000
	v_lshl_add_u64 v[224:225], s[28:29], 0, v[146:147]
	global_load_lds_dwordx4 v[224:225], off
	s_mov_b32 m0, s73
	v_lshl_add_u64 v[224:225], s[68:69], 0, v[152:153]
	global_load_lds_dwordx4 v[224:225], off
	s_mov_b32 m0, s74
	s_nop 0
	global_load_lds_dwordx4 v[226:227], off
	s_nop 0
	s_waitcnt vmcnt(8) lgkmcnt(0)
	s_setprio 1
	s_barrier
	v_mfma_f32_16x16x32_bf16 v[62:65], v[130:133], v[188:191], 0
	v_mfma_f32_16x16x32_bf16 v[58:61], v[138:141], v[188:191], 0
	v_mfma_f32_16x16x32_bf16 v[46:49], v[130:133], v[196:199], 0
	v_mfma_f32_16x16x32_bf16 v[42:45], v[138:141], v[196:199], 0
	v_mfma_f32_16x16x32_bf16 v[30:33], v[130:133], v[206:209], 0
	v_mfma_f32_16x16x32_bf16 v[26:29], v[138:141], v[206:209], 0
	v_mfma_f32_16x16x32_bf16 v[14:17], v[130:133], v[214:217], 0
	v_mfma_f32_16x16x32_bf16 v[10:13], v[138:141], v[214:217], 0
	v_mfma_f32_16x16x32_bf16 v[62:65], v[134:137], v[192:195], v[62:65]
	v_mfma_f32_16x16x32_bf16 v[58:61], v[142:145], v[192:195], v[58:61]
	v_mfma_f32_16x16x32_bf16 v[46:49], v[134:137], v[200:203], v[46:49]
	v_mfma_f32_16x16x32_bf16 v[42:45], v[142:145], v[200:203], v[42:45]
	v_mfma_f32_16x16x32_bf16 v[30:33], v[134:137], v[210:213], v[30:33]
	v_mfma_f32_16x16x32_bf16 v[26:29], v[142:145], v[210:213], v[26:29]
	v_mfma_f32_16x16x32_bf16 v[14:17], v[134:137], v[218:221], v[14:17]
	v_mfma_f32_16x16x32_bf16 v[10:13], v[142:145], v[218:221], v[10:13]
	v_mfma_f32_16x16x32_bf16 v[54:57], v[164:167], v[188:191], 0
	v_mfma_f32_16x16x32_bf16 v[50:53], v[180:183], v[188:191], 0
	v_mfma_f32_16x16x32_bf16 v[38:41], v[164:167], v[196:199], 0
	v_mfma_f32_16x16x32_bf16 v[34:37], v[180:183], v[196:199], 0
	v_mfma_f32_16x16x32_bf16 v[22:25], v[164:167], v[206:209], 0
	v_mfma_f32_16x16x32_bf16 v[18:21], v[180:183], v[206:209], 0
	v_mfma_f32_16x16x32_bf16 v[6:9], v[164:167], v[214:217], 0
	v_mfma_f32_16x16x32_bf16 v[2:5], v[180:183], v[214:217], 0
	v_mfma_f32_16x16x32_bf16 v[54:57], v[176:179], v[192:195], v[54:57]
	v_mfma_f32_16x16x32_bf16 v[50:53], v[184:187], v[192:195], v[50:53]
	v_mfma_f32_16x16x32_bf16 v[38:41], v[176:179], v[200:203], v[38:41]
	v_mfma_f32_16x16x32_bf16 v[34:37], v[184:187], v[200:203], v[34:37]
	v_mfma_f32_16x16x32_bf16 v[22:25], v[176:179], v[210:213], v[22:25]
	v_mfma_f32_16x16x32_bf16 v[18:21], v[184:187], v[210:213], v[18:21]
	v_mfma_f32_16x16x32_bf16 v[6:9], v[176:179], v[218:221], v[6:9]
	v_mfma_f32_16x16x32_bf16 v[2:5], v[184:187], v[218:221], v[2:5]
	s_setprio 0
	s_barrier
	s_add_i32 s25, 0, 0x18000
	s_add_i32 s30, 0, 0x1c000
	v_add_u32_e32 v142, s25, v171
	v_add_u32_e32 v175, s30, v171
	ds_read_b128 v[130:133], v142
	ds_read_b128 v[134:137], v142 offset:1024
	ds_read_b128 v[138:141], v142 offset:2048
	ds_read_b128 v[142:145], v142 offset:3072
	ds_read_b128 v[164:167], v175
	ds_read_b128 v[176:179], v175 offset:1024
	ds_read_b128 v[180:183], v175 offset:2048
	ds_read_b128 v[184:187], v175 offset:3072
	s_add_u32 s28, s68, 0x40000
	s_addc_u32 s29, s69, 0
	s_mov_b32 m0, s75
	v_lshl_add_u64 v[228:229], s[28:29], 0, v[152:153]
	ds_read_b128 v[188:191], v174 offset:32768
	ds_read_b128 v[192:195], v174 offset:33792
	ds_read_b128 v[196:199], v174 offset:34816
	ds_read_b128 v[200:203], v174 offset:35840
	ds_read_b128 v[206:209], v174 offset:36864
	ds_read_b128 v[210:213], v174 offset:37888
	ds_read_b128 v[214:217], v174 offset:38912
	ds_read_b128 v[218:221], v174 offset:39936
	global_load_lds_dwordx4 v[228:229], off
	s_mov_b32 m0, s76
	v_lshl_add_u64 v[228:229], s[28:29], 0, v[148:149]
	global_load_lds_dwordx4 v[228:229], off
	s_waitcnt vmcnt(8) lgkmcnt(0)
	s_setprio 1
	s_barrier
	v_mfma_f32_16x16x32_bf16 v[126:129], v[130:133], v[188:191], v[126:129]
	v_mfma_f32_16x16x32_bf16 v[122:125], v[138:141], v[188:191], v[122:125]
	v_mfma_f32_16x16x32_bf16 v[110:113], v[130:133], v[196:199], v[110:113]
	v_mfma_f32_16x16x32_bf16 v[106:109], v[138:141], v[196:199], v[106:109]
	v_mfma_f32_16x16x32_bf16 v[94:97], v[130:133], v[206:209], v[94:97]
	v_mfma_f32_16x16x32_bf16 v[90:93], v[138:141], v[206:209], v[90:93]
	v_mfma_f32_16x16x32_bf16 v[78:81], v[130:133], v[214:217], v[78:81]
	v_mfma_f32_16x16x32_bf16 v[74:77], v[138:141], v[214:217], v[74:77]
	v_mfma_f32_16x16x32_bf16 v[126:129], v[134:137], v[192:195], v[126:129]
	v_mfma_f32_16x16x32_bf16 v[122:125], v[142:145], v[192:195], v[122:125]
	v_mfma_f32_16x16x32_bf16 v[110:113], v[134:137], v[200:203], v[110:113]
	v_mfma_f32_16x16x32_bf16 v[106:109], v[142:145], v[200:203], v[106:109]
	v_mfma_f32_16x16x32_bf16 v[94:97], v[134:137], v[210:213], v[94:97]
	v_mfma_f32_16x16x32_bf16 v[90:93], v[142:145], v[210:213], v[90:93]
	v_mfma_f32_16x16x32_bf16 v[78:81], v[134:137], v[218:221], v[78:81]
	v_mfma_f32_16x16x32_bf16 v[74:77], v[142:145], v[218:221], v[74:77]
	v_mfma_f32_16x16x32_bf16 v[118:121], v[164:167], v[188:191], v[118:121]
	v_mfma_f32_16x16x32_bf16 v[114:117], v[180:183], v[188:191], v[114:117]
	v_mfma_f32_16x16x32_bf16 v[102:105], v[164:167], v[196:199], v[102:105]
	v_mfma_f32_16x16x32_bf16 v[98:101], v[180:183], v[196:199], v[98:101]
	v_mfma_f32_16x16x32_bf16 v[86:89], v[164:167], v[206:209], v[86:89]
	v_mfma_f32_16x16x32_bf16 v[82:85], v[180:183], v[206:209], v[82:85]
	v_mfma_f32_16x16x32_bf16 v[70:73], v[164:167], v[214:217], v[70:73]
	v_mfma_f32_16x16x32_bf16 v[66:69], v[180:183], v[214:217], v[66:69]
	v_mfma_f32_16x16x32_bf16 v[118:121], v[176:179], v[192:195], v[118:121]
	v_mfma_f32_16x16x32_bf16 v[114:117], v[184:187], v[192:195], v[114:117]
	v_mfma_f32_16x16x32_bf16 v[102:105], v[176:179], v[200:203], v[102:105]
	v_mfma_f32_16x16x32_bf16 v[98:101], v[184:187], v[200:203], v[98:101]
	v_mfma_f32_16x16x32_bf16 v[86:89], v[176:179], v[210:213], v[86:89]
	v_mfma_f32_16x16x32_bf16 v[82:85], v[184:187], v[210:213], v[82:85]
	v_mfma_f32_16x16x32_bf16 v[70:73], v[176:179], v[218:221], v[70:73]
	v_mfma_f32_16x16x32_bf16 v[66:69], v[184:187], v[218:221], v[66:69]
	s_setprio 0
	s_barrier
	s_add_i32 s25, s25, s70
	v_lshl_add_u64 v[168:169], v[168:169], 0, s[36:37]
	s_mov_b32 m0, s25
	ds_read_b128 v[188:191], v174 offset:49152
	ds_read_b128 v[192:195], v174 offset:50176
	ds_read_b128 v[196:199], v174 offset:51200
	ds_read_b128 v[200:203], v174 offset:52224
	ds_read_b128 v[206:209], v174 offset:53248
	ds_read_b128 v[210:213], v174 offset:54272
	ds_read_b128 v[214:217], v174 offset:55296
	ds_read_b128 v[218:221], v174 offset:56320
	global_load_lds_dwordx4 v[168:169], off
	s_add_i32 m0, s25, 0x2000
	s_add_u32 s28, s66, 0x40080
	v_lshl_add_u64 v[168:169], v[222:223], 0, s[36:37]
	s_addc_u32 s29, s67, 0
	s_add_i32 s25, s30, s70
	global_load_lds_dwordx4 v[168:169], off
	s_mov_b32 m0, s25
	v_lshl_add_u64 v[168:169], s[28:29], 0, v[150:151]
	global_load_lds_dwordx4 v[168:169], off
	s_add_i32 m0, s25, 0x2000
	v_lshl_add_u64 v[168:169], s[28:29], 0, v[146:147]
	global_load_lds_dwordx4 v[168:169], off
	s_mov_b32 m0, s79
	v_lshl_add_u64 v[168:169], v[224:225], 0, s[36:37]
	global_load_lds_dwordx4 v[168:169], off
	s_mov_b32 m0, s80
	v_lshl_add_u64 v[168:169], v[226:227], 0, s[36:37]
	global_load_lds_dwordx4 v[168:169], off
	s_waitcnt vmcnt(8) lgkmcnt(0)
	s_setprio 1
	s_barrier
	v_mfma_f32_16x16x32_bf16 v[62:65], v[130:133], v[188:191], v[62:65]
	v_mfma_f32_16x16x32_bf16 v[58:61], v[138:141], v[188:191], v[58:61]
	v_mfma_f32_16x16x32_bf16 v[46:49], v[130:133], v[196:199], v[46:49]
	v_mfma_f32_16x16x32_bf16 v[42:45], v[138:141], v[196:199], v[42:45]
	v_mfma_f32_16x16x32_bf16 v[30:33], v[130:133], v[206:209], v[30:33]
	v_mfma_f32_16x16x32_bf16 v[26:29], v[138:141], v[206:209], v[26:29]
	v_mfma_f32_16x16x32_bf16 v[14:17], v[130:133], v[214:217], v[14:17]
	v_mfma_f32_16x16x32_bf16 v[10:13], v[138:141], v[214:217], v[10:13]
	v_mfma_f32_16x16x32_bf16 v[62:65], v[134:137], v[192:195], v[62:65]
	v_mfma_f32_16x16x32_bf16 v[58:61], v[142:145], v[192:195], v[58:61]
	v_mfma_f32_16x16x32_bf16 v[46:49], v[134:137], v[200:203], v[46:49]
	v_mfma_f32_16x16x32_bf16 v[42:45], v[142:145], v[200:203], v[42:45]
	v_mfma_f32_16x16x32_bf16 v[30:33], v[134:137], v[210:213], v[30:33]
	v_mfma_f32_16x16x32_bf16 v[26:29], v[142:145], v[210:213], v[26:29]
	v_mfma_f32_16x16x32_bf16 v[14:17], v[134:137], v[218:221], v[14:17]
	v_mfma_f32_16x16x32_bf16 v[10:13], v[142:145], v[218:221], v[10:13]
	v_mfma_f32_16x16x32_bf16 v[54:57], v[164:167], v[188:191], v[54:57]
	v_mfma_f32_16x16x32_bf16 v[50:53], v[180:183], v[188:191], v[50:53]
	v_mfma_f32_16x16x32_bf16 v[38:41], v[164:167], v[196:199], v[38:41]
	v_mfma_f32_16x16x32_bf16 v[34:37], v[180:183], v[196:199], v[34:37]
	v_mfma_f32_16x16x32_bf16 v[22:25], v[164:167], v[206:209], v[22:25]
	v_mfma_f32_16x16x32_bf16 v[18:21], v[180:183], v[206:209], v[18:21]
	v_mfma_f32_16x16x32_bf16 v[6:9], v[164:167], v[214:217], v[6:9]
	v_mfma_f32_16x16x32_bf16 v[2:5], v[180:183], v[214:217], v[2:5]
	v_mfma_f32_16x16x32_bf16 v[54:57], v[176:179], v[192:195], v[54:57]
	v_mfma_f32_16x16x32_bf16 v[50:53], v[184:187], v[192:195], v[50:53]
	v_mfma_f32_16x16x32_bf16 v[38:41], v[176:179], v[200:203], v[38:41]
	v_mfma_f32_16x16x32_bf16 v[34:37], v[184:187], v[200:203], v[34:37]
	v_mfma_f32_16x16x32_bf16 v[22:25], v[176:179], v[210:213], v[22:25]
	v_mfma_f32_16x16x32_bf16 v[18:21], v[184:187], v[210:213], v[18:21]
	v_mfma_f32_16x16x32_bf16 v[6:9], v[176:179], v[218:221], v[6:9]
	v_mfma_f32_16x16x32_bf16 v[2:5], v[184:187], v[218:221], v[2:5]
	s_setprio 0
	s_barrier
	s_add_i32 s24, s24, 2
	s_add_u32 s64, s64, 0x100
	s_addc_u32 s65, s65, 0
	s_add_u32 s18, s18, 0x100
	s_addc_u32 s19, s19, 0
	s_cmp_gt_u32 s24, 13
.LBB0_1013:
	ds_read_b128 v[130:133], v172
	ds_read_b128 v[134:137], v172 offset:1024
	ds_read_b128 v[138:141], v172 offset:2048
	ds_read_b128 v[142:145], v172 offset:3072
	ds_read_b128 v[164:167], v173
	ds_read_b128 v[176:179], v173 offset:1024
	ds_read_b128 v[180:183], v173 offset:2048
	ds_read_b128 v[184:187], v173 offset:3072
	s_add_u32 s25, s64, 0xfffc0080
	s_addc_u32 s28, s65, -1
	s_cmp_eq_u32 s24, 12
	s_cselect_b32 s69, s6, s28
	s_cselect_b32 s68, s14, s25
	s_cselect_b32 s67, s15, s19
	s_cselect_b32 s66, s17, s18
	v_lshl_add_u64 v[168:169], s[64:65], 0, v[156:157]
	s_add_i32 m0, s73, 0xc000
	ds_read_b128 v[188:191], v174
	ds_read_b128 v[192:195], v174 offset:1024
	ds_read_b128 v[196:199], v174 offset:2048
	ds_read_b128 v[200:203], v174 offset:3072
	ds_read_b128 v[206:209], v174 offset:4096
	ds_read_b128 v[210:213], v174 offset:5120
	ds_read_b128 v[214:217], v174 offset:6144
	ds_read_b128 v[218:221], v174 offset:7168
	global_load_lds_dwordx4 v[168:169], off
	s_add_i32 m0, s73, 0xe000
	v_lshl_add_u64 v[168:169], s[64:65], 0, v[158:159]
	global_load_lds_dwordx4 v[168:169], off
	s_nop 0
	s_waitcnt vmcnt(8) lgkmcnt(0)
	s_setprio 1
	s_barrier
	v_mfma_f32_16x16x32_bf16 v[126:129], v[130:133], v[188:191], v[126:129]
	v_mfma_f32_16x16x32_bf16 v[122:125], v[138:141], v[188:191], v[122:125]
	v_mfma_f32_16x16x32_bf16 v[110:113], v[130:133], v[196:199], v[110:113]
	v_mfma_f32_16x16x32_bf16 v[106:109], v[138:141], v[196:199], v[106:109]
	v_mfma_f32_16x16x32_bf16 v[94:97], v[130:133], v[206:209], v[94:97]
	v_mfma_f32_16x16x32_bf16 v[90:93], v[138:141], v[206:209], v[90:93]
	v_mfma_f32_16x16x32_bf16 v[78:81], v[130:133], v[214:217], v[78:81]
	v_mfma_f32_16x16x32_bf16 v[74:77], v[138:141], v[214:217], v[74:77]
	v_mfma_f32_16x16x32_bf16 v[126:129], v[134:137], v[192:195], v[126:129]
	v_mfma_f32_16x16x32_bf16 v[122:125], v[142:145], v[192:195], v[122:125]
	v_mfma_f32_16x16x32_bf16 v[110:113], v[134:137], v[200:203], v[110:113]
	v_mfma_f32_16x16x32_bf16 v[106:109], v[142:145], v[200:203], v[106:109]
	v_mfma_f32_16x16x32_bf16 v[94:97], v[134:137], v[210:213], v[94:97]
	v_mfma_f32_16x16x32_bf16 v[90:93], v[142:145], v[210:213], v[90:93]
	v_mfma_f32_16x16x32_bf16 v[78:81], v[134:137], v[218:221], v[78:81]
	v_mfma_f32_16x16x32_bf16 v[74:77], v[142:145], v[218:221], v[74:77]
	v_mfma_f32_16x16x32_bf16 v[118:121], v[164:167], v[188:191], v[118:121]
	v_mfma_f32_16x16x32_bf16 v[114:117], v[180:183], v[188:191], v[114:117]
	v_mfma_f32_16x16x32_bf16 v[102:105], v[164:167], v[196:199], v[102:105]
	v_mfma_f32_16x16x32_bf16 v[98:101], v[180:183], v[196:199], v[98:101]
	v_mfma_f32_16x16x32_bf16 v[86:89], v[164:167], v[206:209], v[86:89]
	v_mfma_f32_16x16x32_bf16 v[82:85], v[180:183], v[206:209], v[82:85]
	v_mfma_f32_16x16x32_bf16 v[70:73], v[164:167], v[214:217], v[70:73]
	v_mfma_f32_16x16x32_bf16 v[66:69], v[180:183], v[214:217], v[66:69]
	v_mfma_f32_16x16x32_bf16 v[118:121], v[176:179], v[192:195], v[118:121]
	v_mfma_f32_16x16x32_bf16 v[114:117], v[184:187], v[192:195], v[114:117]
	v_mfma_f32_16x16x32_bf16 v[102:105], v[176:179], v[200:203], v[102:105]
	v_mfma_f32_16x16x32_bf16 v[98:101], v[184:187], v[200:203], v[98:101]
	v_mfma_f32_16x16x32_bf16 v[86:89], v[176:179], v[210:213], v[86:89]
	v_mfma_f32_16x16x32_bf16 v[82:85], v[184:187], v[210:213], v[82:85]
	v_mfma_f32_16x16x32_bf16 v[70:73], v[176:179], v[218:221], v[70:73]
	v_mfma_f32_16x16x32_bf16 v[66:69], v[184:187], v[218:221], v[66:69]
	s_setprio 0
	s_barrier
	s_add_i32 s25, s82, s70
	v_lshl_add_u64 v[168:169], s[66:67], 0, v[150:151]
	s_mov_b32 m0, s25
	ds_read_b128 v[188:191], v174 offset:16384
	ds_read_b128 v[192:195], v174 offset:17408
	ds_read_b128 v[196:199], v174 offset:18432
	ds_read_b128 v[200:203], v174 offset:19456
	ds_read_b128 v[206:209], v174 offset:20480
	ds_read_b128 v[210:213], v174 offset:21504
	ds_read_b128 v[214:217], v174 offset:22528
	ds_read_b128 v[218:221], v174 offset:23552
	global_load_lds_dwordx4 v[168:169], off
	s_add_i32 m0, s25, 0x2000
	s_add_u32 s28, s66, 0x40000
	v_lshl_add_u64 v[222:223], s[66:67], 0, v[146:147]
	s_addc_u32 s29, s67, 0
	s_add_i32 s25, s83, s70
	global_load_lds_dwordx4 v[222:223], off
	v_lshl_add_u64 v[224:225], s[28:29], 0, v[150:151]
	s_mov_b32 m0, s25
	v_lshl_add_u64 v[226:227], s[68:69], 0, v[148:149]
	global_load_lds_dwordx4 v[224:225], off
	s_add_i32 m0, s25, 0x2000
	v_lshl_add_u64 v[224:225], s[28:29], 0, v[146:147]
	global_load_lds_dwordx4 v[224:225], off
	s_mov_b32 m0, s73
	v_lshl_add_u64 v[224:225], s[68:69], 0, v[152:153]
	global_load_lds_dwordx4 v[224:225], off
	s_mov_b32 m0, s74
	s_nop 0
	global_load_lds_dwordx4 v[226:227], off
	s_nop 0
	s_waitcnt vmcnt(8) lgkmcnt(0)
	s_setprio 1
	s_barrier
	v_mfma_f32_16x16x32_bf16 v[62:65], v[130:133], v[188:191], v[62:65]
	v_mfma_f32_16x16x32_bf16 v[58:61], v[138:141], v[188:191], v[58:61]
	v_mfma_f32_16x16x32_bf16 v[46:49], v[130:133], v[196:199], v[46:49]
	v_mfma_f32_16x16x32_bf16 v[42:45], v[138:141], v[196:199], v[42:45]
	v_mfma_f32_16x16x32_bf16 v[30:33], v[130:133], v[206:209], v[30:33]
	v_mfma_f32_16x16x32_bf16 v[26:29], v[138:141], v[206:209], v[26:29]
	v_mfma_f32_16x16x32_bf16 v[14:17], v[130:133], v[214:217], v[14:17]
	v_mfma_f32_16x16x32_bf16 v[10:13], v[138:141], v[214:217], v[10:13]
	v_mfma_f32_16x16x32_bf16 v[62:65], v[134:137], v[192:195], v[62:65]
	v_mfma_f32_16x16x32_bf16 v[58:61], v[142:145], v[192:195], v[58:61]
	v_mfma_f32_16x16x32_bf16 v[46:49], v[134:137], v[200:203], v[46:49]
	v_mfma_f32_16x16x32_bf16 v[42:45], v[142:145], v[200:203], v[42:45]
	v_mfma_f32_16x16x32_bf16 v[30:33], v[134:137], v[210:213], v[30:33]
	v_mfma_f32_16x16x32_bf16 v[26:29], v[142:145], v[210:213], v[26:29]
	v_mfma_f32_16x16x32_bf16 v[14:17], v[134:137], v[218:221], v[14:17]
	v_mfma_f32_16x16x32_bf16 v[10:13], v[142:145], v[218:221], v[10:13]
	v_mfma_f32_16x16x32_bf16 v[54:57], v[164:167], v[188:191], v[54:57]
	v_mfma_f32_16x16x32_bf16 v[50:53], v[180:183], v[188:191], v[50:53]
	v_mfma_f32_16x16x32_bf16 v[38:41], v[164:167], v[196:199], v[38:41]
	v_mfma_f32_16x16x32_bf16 v[34:37], v[180:183], v[196:199], v[34:37]
	v_mfma_f32_16x16x32_bf16 v[22:25], v[164:167], v[206:209], v[22:25]
	v_mfma_f32_16x16x32_bf16 v[18:21], v[180:183], v[206:209], v[18:21]
	v_mfma_f32_16x16x32_bf16 v[6:9], v[164:167], v[214:217], v[6:9]
	v_mfma_f32_16x16x32_bf16 v[2:5], v[180:183], v[214:217], v[2:5]
	v_mfma_f32_16x16x32_bf16 v[54:57], v[176:179], v[192:195], v[54:57]
	v_mfma_f32_16x16x32_bf16 v[50:53], v[184:187], v[192:195], v[50:53]
	v_mfma_f32_16x16x32_bf16 v[38:41], v[176:179], v[200:203], v[38:41]
	v_mfma_f32_16x16x32_bf16 v[34:37], v[184:187], v[200:203], v[34:37]
	v_mfma_f32_16x16x32_bf16 v[22:25], v[176:179], v[210:213], v[22:25]
	v_mfma_f32_16x16x32_bf16 v[18:21], v[184:187], v[210:213], v[18:21]
	v_mfma_f32_16x16x32_bf16 v[6:9], v[176:179], v[218:221], v[6:9]
	v_mfma_f32_16x16x32_bf16 v[2:5], v[184:187], v[218:221], v[2:5]
	s_setprio 0
	s_barrier
	s_add_i32 s25, 0, 0x18000
	s_add_i32 s30, 0, 0x1c000
	v_add_u32_e32 v142, s25, v171
	v_add_u32_e32 v175, s30, v171
	ds_read_b128 v[130:133], v142
	ds_read_b128 v[134:137], v142 offset:1024
	ds_read_b128 v[138:141], v142 offset:2048
	ds_read_b128 v[142:145], v142 offset:3072
	ds_read_b128 v[164:167], v175
	ds_read_b128 v[176:179], v175 offset:1024
	ds_read_b128 v[180:183], v175 offset:2048
	ds_read_b128 v[184:187], v175 offset:3072
	s_add_u32 s28, s68, 0x40000
	s_addc_u32 s29, s69, 0
	s_mov_b32 m0, s75
	v_lshl_add_u64 v[228:229], s[28:29], 0, v[152:153]
	ds_read_b128 v[188:191], v174 offset:32768
	ds_read_b128 v[192:195], v174 offset:33792
	ds_read_b128 v[196:199], v174 offset:34816
	ds_read_b128 v[200:203], v174 offset:35840
	ds_read_b128 v[206:209], v174 offset:36864
	ds_read_b128 v[210:213], v174 offset:37888
	ds_read_b128 v[214:217], v174 offset:38912
	ds_read_b128 v[218:221], v174 offset:39936
	global_load_lds_dwordx4 v[228:229], off
	s_mov_b32 m0, s76
	v_lshl_add_u64 v[228:229], s[28:29], 0, v[148:149]
	global_load_lds_dwordx4 v[228:229], off
	s_waitcnt vmcnt(8) lgkmcnt(0)
	s_setprio 1
	s_barrier
	v_mfma_f32_16x16x32_bf16 v[126:129], v[130:133], v[188:191], v[126:129]
	v_mfma_f32_16x16x32_bf16 v[122:125], v[138:141], v[188:191], v[122:125]
	v_mfma_f32_16x16x32_bf16 v[110:113], v[130:133], v[196:199], v[110:113]
	v_mfma_f32_16x16x32_bf16 v[106:109], v[138:141], v[196:199], v[106:109]
	v_mfma_f32_16x16x32_bf16 v[94:97], v[130:133], v[206:209], v[94:97]
	v_mfma_f32_16x16x32_bf16 v[90:93], v[138:141], v[206:209], v[90:93]
	v_mfma_f32_16x16x32_bf16 v[78:81], v[130:133], v[214:217], v[78:81]
	v_mfma_f32_16x16x32_bf16 v[74:77], v[138:141], v[214:217], v[74:77]
	v_mfma_f32_16x16x32_bf16 v[126:129], v[134:137], v[192:195], v[126:129]
	v_mfma_f32_16x16x32_bf16 v[122:125], v[142:145], v[192:195], v[122:125]
	v_mfma_f32_16x16x32_bf16 v[110:113], v[134:137], v[200:203], v[110:113]
	v_mfma_f32_16x16x32_bf16 v[106:109], v[142:145], v[200:203], v[106:109]
	v_mfma_f32_16x16x32_bf16 v[94:97], v[134:137], v[210:213], v[94:97]
	v_mfma_f32_16x16x32_bf16 v[90:93], v[142:145], v[210:213], v[90:93]
	v_mfma_f32_16x16x32_bf16 v[78:81], v[134:137], v[218:221], v[78:81]
	v_mfma_f32_16x16x32_bf16 v[74:77], v[142:145], v[218:221], v[74:77]
	v_mfma_f32_16x16x32_bf16 v[118:121], v[164:167], v[188:191], v[118:121]
	v_mfma_f32_16x16x32_bf16 v[114:117], v[180:183], v[188:191], v[114:117]
	v_mfma_f32_16x16x32_bf16 v[102:105], v[164:167], v[196:199], v[102:105]
	v_mfma_f32_16x16x32_bf16 v[98:101], v[180:183], v[196:199], v[98:101]
	v_mfma_f32_16x16x32_bf16 v[86:89], v[164:167], v[206:209], v[86:89]
	v_mfma_f32_16x16x32_bf16 v[82:85], v[180:183], v[206:209], v[82:85]
	v_mfma_f32_16x16x32_bf16 v[70:73], v[164:167], v[214:217], v[70:73]
	v_mfma_f32_16x16x32_bf16 v[66:69], v[180:183], v[214:217], v[66:69]
	v_mfma_f32_16x16x32_bf16 v[118:121], v[176:179], v[192:195], v[118:121]
	v_mfma_f32_16x16x32_bf16 v[114:117], v[184:187], v[192:195], v[114:117]
	v_mfma_f32_16x16x32_bf16 v[102:105], v[176:179], v[200:203], v[102:105]
	v_mfma_f32_16x16x32_bf16 v[98:101], v[184:187], v[200:203], v[98:101]
	v_mfma_f32_16x16x32_bf16 v[86:89], v[176:179], v[210:213], v[86:89]
	v_mfma_f32_16x16x32_bf16 v[82:85], v[184:187], v[210:213], v[82:85]
	v_mfma_f32_16x16x32_bf16 v[70:73], v[176:179], v[218:221], v[70:73]
	v_mfma_f32_16x16x32_bf16 v[66:69], v[184:187], v[218:221], v[66:69]
	s_setprio 0
	s_barrier
	s_add_i32 s25, s25, s70
	v_lshl_add_u64 v[168:169], v[168:169], 0, s[36:37]
	s_mov_b32 m0, s25
	ds_read_b128 v[188:191], v174 offset:49152
	ds_read_b128 v[192:195], v174 offset:50176
	ds_read_b128 v[196:199], v174 offset:51200
	ds_read_b128 v[200:203], v174 offset:52224
	ds_read_b128 v[206:209], v174 offset:53248
	ds_read_b128 v[210:213], v174 offset:54272
	ds_read_b128 v[214:217], v174 offset:55296
	ds_read_b128 v[218:221], v174 offset:56320
	global_load_lds_dwordx4 v[168:169], off
	s_add_i32 m0, s25, 0x2000
	s_add_u32 s28, s66, 0x40080
	v_lshl_add_u64 v[168:169], v[222:223], 0, s[36:37]
	s_addc_u32 s29, s67, 0
	s_add_i32 s25, s30, s70
	global_load_lds_dwordx4 v[168:169], off
	s_mov_b32 m0, s25
	v_lshl_add_u64 v[168:169], s[28:29], 0, v[150:151]
	global_load_lds_dwordx4 v[168:169], off
	s_add_i32 m0, s25, 0x2000
	v_lshl_add_u64 v[168:169], s[28:29], 0, v[146:147]
	global_load_lds_dwordx4 v[168:169], off
	s_mov_b32 m0, s79
	v_lshl_add_u64 v[168:169], v[224:225], 0, s[36:37]
	global_load_lds_dwordx4 v[168:169], off
	s_mov_b32 m0, s80
	v_lshl_add_u64 v[168:169], v[226:227], 0, s[36:37]
	global_load_lds_dwordx4 v[168:169], off
	s_waitcnt vmcnt(8) lgkmcnt(0)
	s_setprio 1
	s_barrier
	v_mfma_f32_16x16x32_bf16 v[62:65], v[130:133], v[188:191], v[62:65]
	v_mfma_f32_16x16x32_bf16 v[58:61], v[138:141], v[188:191], v[58:61]
	v_mfma_f32_16x16x32_bf16 v[46:49], v[130:133], v[196:199], v[46:49]
	v_mfma_f32_16x16x32_bf16 v[42:45], v[138:141], v[196:199], v[42:45]
	v_mfma_f32_16x16x32_bf16 v[30:33], v[130:133], v[206:209], v[30:33]
	v_mfma_f32_16x16x32_bf16 v[26:29], v[138:141], v[206:209], v[26:29]
	v_mfma_f32_16x16x32_bf16 v[14:17], v[130:133], v[214:217], v[14:17]
	v_mfma_f32_16x16x32_bf16 v[10:13], v[138:141], v[214:217], v[10:13]
	v_mfma_f32_16x16x32_bf16 v[62:65], v[134:137], v[192:195], v[62:65]
	v_mfma_f32_16x16x32_bf16 v[58:61], v[142:145], v[192:195], v[58:61]
	v_mfma_f32_16x16x32_bf16 v[46:49], v[134:137], v[200:203], v[46:49]
	v_mfma_f32_16x16x32_bf16 v[42:45], v[142:145], v[200:203], v[42:45]
	v_mfma_f32_16x16x32_bf16 v[30:33], v[134:137], v[210:213], v[30:33]
	v_mfma_f32_16x16x32_bf16 v[26:29], v[142:145], v[210:213], v[26:29]
	v_mfma_f32_16x16x32_bf16 v[14:17], v[134:137], v[218:221], v[14:17]
	v_mfma_f32_16x16x32_bf16 v[10:13], v[142:145], v[218:221], v[10:13]
	v_mfma_f32_16x16x32_bf16 v[54:57], v[164:167], v[188:191], v[54:57]
	v_mfma_f32_16x16x32_bf16 v[50:53], v[180:183], v[188:191], v[50:53]
	v_mfma_f32_16x16x32_bf16 v[38:41], v[164:167], v[196:199], v[38:41]
	v_mfma_f32_16x16x32_bf16 v[34:37], v[180:183], v[196:199], v[34:37]
	v_mfma_f32_16x16x32_bf16 v[22:25], v[164:167], v[206:209], v[22:25]
	v_mfma_f32_16x16x32_bf16 v[18:21], v[180:183], v[206:209], v[18:21]
	v_mfma_f32_16x16x32_bf16 v[6:9], v[164:167], v[214:217], v[6:9]
	v_mfma_f32_16x16x32_bf16 v[2:5], v[180:183], v[214:217], v[2:5]
	v_mfma_f32_16x16x32_bf16 v[54:57], v[176:179], v[192:195], v[54:57]
	v_mfma_f32_16x16x32_bf16 v[50:53], v[184:187], v[192:195], v[50:53]
	v_mfma_f32_16x16x32_bf16 v[38:41], v[176:179], v[200:203], v[38:41]
	v_mfma_f32_16x16x32_bf16 v[34:37], v[184:187], v[200:203], v[34:37]
	v_mfma_f32_16x16x32_bf16 v[22:25], v[176:179], v[210:213], v[22:25]
	v_mfma_f32_16x16x32_bf16 v[18:21], v[184:187], v[210:213], v[18:21]
	v_mfma_f32_16x16x32_bf16 v[6:9], v[176:179], v[218:221], v[6:9]
	v_mfma_f32_16x16x32_bf16 v[2:5], v[184:187], v[218:221], v[2:5]
	s_setprio 0
	s_barrier
	s_add_i32 s24, s24, 2
	s_add_u32 s64, s64, 0x100
	s_addc_u32 s65, s65, 0
	s_add_u32 s18, s18, 0x100
	s_addc_u32 s19, s19, 0
	s_cmp_gt_u32 s24, 13
	s_cbranch_scc0 .LBB0_1013
	s_and_b64 vcc, exec, s[38:39]
	s_cbranch_vccz .LBB0_1016
	s_barrier

.LBB0_1427:
	s_add_u32 s90, s35, s86
	s_addc_u32 s91, s64, s87
	s_and_b64 s[14:15], s[88:89], exec
	s_cselect_b32 s14, s91, s11
	s_cselect_b32 s15, s90, s10
	s_add_u32 s92, s65, s74
	s_addc_u32 s93, s68, s75
	s_and_b64 s[66:67], s[88:89], exec
	s_cselect_b32 s51, s93, s95
	s_cselect_b32 s84, s92, s94
	s_add_i32 s85, s18, -2
	s_add_u32 s10, s10, 0x40080
	s_addc_u32 s11, s11, 0
	s_add_u32 vcc_lo, s94, 0x100
	s_addc_u32 vcc_hi, s95, 0
	s_mov_b32 s94, 0
	s_waitcnt vmcnt(0)
	s_add_i32 s66, s94, 2
	s_add_u32 s67, s10, 0xfffc0080
	s_addc_u32 s72, s11, -1
	s_cmp_eq_u32 s85, s94
	s_cselect_b32 s97, s14, s72
	s_cselect_b32 s96, s15, s67
	s_cselect_b32 s95, s51, vcc_hi
	s_cselect_b32 s94, s84, vcc_lo
	s_add_i32 s67, 0, 0x10000
	s_add_i32 s62, 0, 0x14000
	v_add_u32_e32 v126, s67, v199
	v_add_u32_e32 v158, s62, v199
	ds_read_b128 v[114:117], v126
	ds_read_b128 v[118:121], v126 offset:1024
	ds_read_b128 v[122:125], v126 offset:2048
	ds_read_b128 v[126:129], v126 offset:3072
	ds_read_b128 v[146:149], v158
	ds_read_b128 v[150:153], v158 offset:1024
	ds_read_b128 v[154:157], v158 offset:2048
	ds_read_b128 v[158:161], v158 offset:3072
	v_lshl_add_u64 v[202:203], s[10:11], 0, v[196:197]
	s_add_i32 m0, s28, 0xc000
	ds_read_b128 v[162:165], v214
	ds_read_b128 v[166:169], v214 offset:1024
	ds_read_b128 v[216:219], v214 offset:2048
	ds_read_b128 v[220:223], v214 offset:3072
	ds_read_b128 v[224:227], v214 offset:4096
	ds_read_b128 v[228:231], v214 offset:5120
	ds_read_b128 v[232:235], v214 offset:6144
	ds_read_b128 v[236:239], v214 offset:7168
	global_load_lds_dwordx4 v[202:203], off
	s_add_i32 m0, s28, 0xe000
	v_lshl_add_u64 v[202:203], s[10:11], 0, v[176:177]
	global_load_lds_dwordx4 v[202:203], off
	s_waitcnt vmcnt(8) lgkmcnt(0)
	s_setprio 1
	s_barrier
	v_mfma_f32_16x16x32_bf16 v[142:145], v[114:117], v[162:165], 0
	v_mfma_f32_16x16x32_bf16 v[138:141], v[122:125], v[162:165], 0
	v_mfma_f32_16x16x32_bf16 v[110:113], v[114:117], v[216:219], 0
	v_mfma_f32_16x16x32_bf16 v[106:109], v[122:125], v[216:219], 0
	v_mfma_f32_16x16x32_bf16 v[98:101], v[114:117], v[224:227], 0
	v_mfma_f32_16x16x32_bf16 v[90:93], v[122:125], v[224:227], 0
	v_mfma_f32_16x16x32_bf16 v[82:85], v[114:117], v[232:235], 0
	v_mfma_f32_16x16x32_bf16 v[74:77], v[122:125], v[232:235], 0
	v_mfma_f32_16x16x32_bf16 v[142:145], v[118:121], v[166:169], v[142:145]
	v_mfma_f32_16x16x32_bf16 v[138:141], v[126:129], v[166:169], v[138:141]
	v_mfma_f32_16x16x32_bf16 v[110:113], v[118:121], v[220:223], v[110:113]
	v_mfma_f32_16x16x32_bf16 v[106:109], v[126:129], v[220:223], v[106:109]
	v_mfma_f32_16x16x32_bf16 v[98:101], v[118:121], v[228:231], v[98:101]
	v_mfma_f32_16x16x32_bf16 v[90:93], v[126:129], v[228:231], v[90:93]
	v_mfma_f32_16x16x32_bf16 v[82:85], v[118:121], v[236:239], v[82:85]
	v_mfma_f32_16x16x32_bf16 v[74:77], v[126:129], v[236:239], v[74:77]
	v_mfma_f32_16x16x32_bf16 v[134:137], v[146:149], v[162:165], 0
	v_mfma_f32_16x16x32_bf16 v[130:133], v[154:157], v[162:165], 0
	v_mfma_f32_16x16x32_bf16 v[102:105], v[146:149], v[216:219], 0
	v_mfma_f32_16x16x32_bf16 v[94:97], v[154:157], v[216:219], 0
	v_mfma_f32_16x16x32_bf16 v[86:89], v[146:149], v[224:227], 0
	v_mfma_f32_16x16x32_bf16 v[78:81], v[154:157], v[224:227], 0
	v_mfma_f32_16x16x32_bf16 v[70:73], v[146:149], v[232:235], 0
	v_mfma_f32_16x16x32_bf16 v[66:69], v[154:157], v[232:235], 0
	v_mfma_f32_16x16x32_bf16 v[134:137], v[150:153], v[166:169], v[134:137]
	v_mfma_f32_16x16x32_bf16 v[130:133], v[158:161], v[166:169], v[130:133]
	v_mfma_f32_16x16x32_bf16 v[102:105], v[150:153], v[220:223], v[102:105]
	v_mfma_f32_16x16x32_bf16 v[94:97], v[158:161], v[220:223], v[94:97]
	v_mfma_f32_16x16x32_bf16 v[86:89], v[150:153], v[228:231], v[86:89]
	v_mfma_f32_16x16x32_bf16 v[78:81], v[158:161], v[228:231], v[78:81]
	v_mfma_f32_16x16x32_bf16 v[70:73], v[150:153], v[236:239], v[70:73]
	v_mfma_f32_16x16x32_bf16 v[66:69], v[158:161], v[236:239], v[66:69]
	s_setprio 0
	s_barrier
	s_add_i32 s63, s67, s17
	v_lshl_add_u64 v[202:203], s[94:95], 0, v[174:175]
	s_mov_b32 m0, s63
	ds_read_b128 v[162:165], v214 offset:16384
	ds_read_b128 v[166:169], v214 offset:17408
	ds_read_b128 v[216:219], v214 offset:18432
	ds_read_b128 v[220:223], v214 offset:19456
	ds_read_b128 v[224:227], v214 offset:20480
	ds_read_b128 v[228:231], v214 offset:21504
	ds_read_b128 v[232:235], v214 offset:22528
	ds_read_b128 v[236:239], v214 offset:23552
	global_load_lds_dwordx4 v[202:203], off
	s_add_i32 m0, s63, 0x2000
	s_add_u32 s72, s94, 0x40000
	v_lshl_add_u64 v[240:241], s[94:95], 0, v[178:179]
	s_addc_u32 s73, s95, 0
	s_add_i32 s62, s62, s17
	global_load_lds_dwordx4 v[240:241], off
	v_lshl_add_u64 v[242:243], s[72:73], 0, v[174:175]
	s_mov_b32 m0, s62
	v_lshl_add_u64 v[244:245], s[96:97], 0, v[176:177]
	global_load_lds_dwordx4 v[242:243], off
	s_add_i32 m0, s62, 0x2000
	v_lshl_add_u64 v[242:243], s[72:73], 0, v[178:179]
	global_load_lds_dwordx4 v[242:243], off
	s_mov_b32 m0, s28
	v_lshl_add_u64 v[242:243], s[96:97], 0, v[172:173]
	global_load_lds_dwordx4 v[242:243], off
	s_mov_b32 m0, s29
	s_nop 0
	global_load_lds_dwordx4 v[244:245], off
	s_nop 0
	s_waitcnt vmcnt(8) lgkmcnt(0)
	s_setprio 1
	s_barrier
	v_mfma_f32_16x16x32_bf16 v[62:65], v[114:117], v[162:165], 0
	v_mfma_f32_16x16x32_bf16 v[58:61], v[122:125], v[162:165], 0
	v_mfma_f32_16x16x32_bf16 v[50:53], v[114:117], v[216:219], 0
	v_mfma_f32_16x16x32_bf16 v[42:45], v[122:125], v[216:219], 0
	v_mfma_f32_16x16x32_bf16 v[34:37], v[114:117], v[224:227], 0
	v_mfma_f32_16x16x32_bf16 v[26:29], v[122:125], v[224:227], 0
	v_mfma_f32_16x16x32_bf16 v[18:21], v[114:117], v[232:235], 0
	v_mfma_f32_16x16x32_bf16 v[10:13], v[122:125], v[232:235], 0
	v_mfma_f32_16x16x32_bf16 v[62:65], v[118:121], v[166:169], v[62:65]
	v_mfma_f32_16x16x32_bf16 v[58:61], v[126:129], v[166:169], v[58:61]
	v_mfma_f32_16x16x32_bf16 v[50:53], v[118:121], v[220:223], v[50:53]
	v_mfma_f32_16x16x32_bf16 v[42:45], v[126:129], v[220:223], v[42:45]
	v_mfma_f32_16x16x32_bf16 v[34:37], v[118:121], v[228:231], v[34:37]
	v_mfma_f32_16x16x32_bf16 v[26:29], v[126:129], v[228:231], v[26:29]
	v_mfma_f32_16x16x32_bf16 v[18:21], v[118:121], v[236:239], v[18:21]
	v_mfma_f32_16x16x32_bf16 v[10:13], v[126:129], v[236:239], v[10:13]
	v_mfma_f32_16x16x32_bf16 v[54:57], v[146:149], v[162:165], 0
	v_mfma_f32_16x16x32_bf16 v[46:49], v[154:157], v[162:165], 0
	v_mfma_f32_16x16x32_bf16 v[38:41], v[146:149], v[216:219], 0
	v_mfma_f32_16x16x32_bf16 v[30:33], v[154:157], v[216:219], 0
	v_mfma_f32_16x16x32_bf16 v[22:25], v[146:149], v[224:227], 0
	v_mfma_f32_16x16x32_bf16 v[14:17], v[154:157], v[224:227], 0
	v_mfma_f32_16x16x32_bf16 v[6:9], v[146:149], v[232:235], 0
	v_mfma_f32_16x16x32_bf16 v[2:5], v[154:157], v[232:235], 0
	v_mfma_f32_16x16x32_bf16 v[54:57], v[150:153], v[166:169], v[54:57]
	v_mfma_f32_16x16x32_bf16 v[46:49], v[158:161], v[166:169], v[46:49]
	v_mfma_f32_16x16x32_bf16 v[38:41], v[150:153], v[220:223], v[38:41]
	v_mfma_f32_16x16x32_bf16 v[30:33], v[158:161], v[220:223], v[30:33]
	v_mfma_f32_16x16x32_bf16 v[22:25], v[150:153], v[228:231], v[22:25]
	v_mfma_f32_16x16x32_bf16 v[14:17], v[158:161], v[228:231], v[14:17]
	v_mfma_f32_16x16x32_bf16 v[6:9], v[150:153], v[236:239], v[6:9]
	v_mfma_f32_16x16x32_bf16 v[2:5], v[158:161], v[236:239], v[2:5]
	s_setprio 0
	s_barrier
	s_add_i32 s62, 0, 0x18000
	s_add_i32 s63, 0, 0x1c000
	v_add_u32_e32 v126, s62, v199
	v_add_u32_e32 v158, s63, v199
	ds_read_b128 v[114:117], v126
	ds_read_b128 v[118:121], v126 offset:1024
	ds_read_b128 v[122:125], v126 offset:2048
	ds_read_b128 v[126:129], v126 offset:3072
	ds_read_b128 v[146:149], v158
	ds_read_b128 v[150:153], v158 offset:1024
	ds_read_b128 v[154:157], v158 offset:2048
	ds_read_b128 v[158:161], v158 offset:3072
	s_add_u32 s72, s96, 0x40000
	s_addc_u32 s73, s97, 0
	s_mov_b32 m0, s30
	v_lshl_add_u64 v[246:247], s[72:73], 0, v[172:173]
	ds_read_b128 v[162:165], v214 offset:32768
	ds_read_b128 v[166:169], v214 offset:33792
	ds_read_b128 v[216:219], v214 offset:34816
	ds_read_b128 v[220:223], v214 offset:35840
	ds_read_b128 v[224:227], v214 offset:36864
	ds_read_b128 v[228:231], v214 offset:37888
	ds_read_b128 v[232:235], v214 offset:38912
	ds_read_b128 v[236:239], v214 offset:39936
	global_load_lds_dwordx4 v[246:247], off
	s_mov_b32 m0, s31
	v_lshl_add_u64 v[246:247], s[72:73], 0, v[176:177]
	global_load_lds_dwordx4 v[246:247], off
	s_waitcnt vmcnt(8) lgkmcnt(0)
	s_setprio 1
	s_barrier
	v_mfma_f32_16x16x32_bf16 v[142:145], v[114:117], v[162:165], v[142:145]
	v_mfma_f32_16x16x32_bf16 v[138:141], v[122:125], v[162:165], v[138:141]
	v_mfma_f32_16x16x32_bf16 v[110:113], v[114:117], v[216:219], v[110:113]
	v_mfma_f32_16x16x32_bf16 v[106:109], v[122:125], v[216:219], v[106:109]
	v_mfma_f32_16x16x32_bf16 v[98:101], v[114:117], v[224:227], v[98:101]
	v_mfma_f32_16x16x32_bf16 v[90:93], v[122:125], v[224:227], v[90:93]
	v_mfma_f32_16x16x32_bf16 v[82:85], v[114:117], v[232:235], v[82:85]
	v_mfma_f32_16x16x32_bf16 v[74:77], v[122:125], v[232:235], v[74:77]
	v_mfma_f32_16x16x32_bf16 v[142:145], v[118:121], v[166:169], v[142:145]
	v_mfma_f32_16x16x32_bf16 v[138:141], v[126:129], v[166:169], v[138:141]
	v_mfma_f32_16x16x32_bf16 v[110:113], v[118:121], v[220:223], v[110:113]
	v_mfma_f32_16x16x32_bf16 v[106:109], v[126:129], v[220:223], v[106:109]
	v_mfma_f32_16x16x32_bf16 v[98:101], v[118:121], v[228:231], v[98:101]
	v_mfma_f32_16x16x32_bf16 v[90:93], v[126:129], v[228:231], v[90:93]
	v_mfma_f32_16x16x32_bf16 v[82:85], v[118:121], v[236:239], v[82:85]
	v_mfma_f32_16x16x32_bf16 v[74:77], v[126:129], v[236:239], v[74:77]
	v_mfma_f32_16x16x32_bf16 v[134:137], v[146:149], v[162:165], v[134:137]
	v_mfma_f32_16x16x32_bf16 v[130:133], v[154:157], v[162:165], v[130:133]
	v_mfma_f32_16x16x32_bf16 v[102:105], v[146:149], v[216:219], v[102:105]
	v_mfma_f32_16x16x32_bf16 v[94:97], v[154:157], v[216:219], v[94:97]
	v_mfma_f32_16x16x32_bf16 v[86:89], v[146:149], v[224:227], v[86:89]
	v_mfma_f32_16x16x32_bf16 v[78:81], v[154:157], v[224:227], v[78:81]
	v_mfma_f32_16x16x32_bf16 v[70:73], v[146:149], v[232:235], v[70:73]
	v_mfma_f32_16x16x32_bf16 v[66:69], v[154:157], v[232:235], v[66:69]
	v_mfma_f32_16x16x32_bf16 v[134:137], v[150:153], v[166:169], v[134:137]
	v_mfma_f32_16x16x32_bf16 v[130:133], v[158:161], v[166:169], v[130:133]
	v_mfma_f32_16x16x32_bf16 v[102:105], v[150:153], v[220:223], v[102:105]
	v_mfma_f32_16x16x32_bf16 v[94:97], v[158:161], v[220:223], v[94:97]
	v_mfma_f32_16x16x32_bf16 v[86:89], v[150:153], v[228:231], v[86:89]
	v_mfma_f32_16x16x32_bf16 v[78:81], v[158:161], v[228:231], v[78:81]
	v_mfma_f32_16x16x32_bf16 v[70:73], v[150:153], v[236:239], v[70:73]
	v_mfma_f32_16x16x32_bf16 v[66:69], v[158:161], v[236:239], v[66:69]
	s_setprio 0
	s_barrier
	s_add_i32 s62, s62, s17
	v_lshl_add_u64 v[202:203], v[202:203], 0, s[76:77]
	s_mov_b32 m0, s62
	ds_read_b128 v[162:165], v214 offset:49152
	ds_read_b128 v[166:169], v214 offset:50176
	ds_read_b128 v[216:219], v214 offset:51200
	ds_read_b128 v[220:223], v214 offset:52224
	ds_read_b128 v[224:227], v214 offset:53248
	ds_read_b128 v[228:231], v214 offset:54272
	ds_read_b128 v[232:235], v214 offset:55296
	ds_read_b128 v[236:239], v214 offset:56320
	global_load_lds_dwordx4 v[202:203], off
	s_add_i32 m0, s62, 0x2000
	s_add_u32 s72, s94, 0x40080
	v_lshl_add_u64 v[202:203], v[240:241], 0, s[76:77]
	s_addc_u32 s73, s95, 0
	s_add_i32 s62, s63, s17
	global_load_lds_dwordx4 v[202:203], off
	s_mov_b32 m0, s62
	v_lshl_add_u64 v[202:203], s[72:73], 0, v[174:175]
	global_load_lds_dwordx4 v[202:203], off
	s_add_i32 m0, s62, 0x2000
	v_lshl_add_u64 v[202:203], s[72:73], 0, v[178:179]
	global_load_lds_dwordx4 v[202:203], off
	s_mov_b32 m0, s44
	v_lshl_add_u64 v[202:203], v[242:243], 0, s[76:77]
	global_load_lds_dwordx4 v[202:203], off
	s_mov_b32 m0, s36
	v_lshl_add_u64 v[202:203], v[244:245], 0, s[76:77]
	global_load_lds_dwordx4 v[202:203], off
	s_waitcnt vmcnt(8) lgkmcnt(0)
	s_setprio 1
	s_barrier
	v_mfma_f32_16x16x32_bf16 v[62:65], v[114:117], v[162:165], v[62:65]
	v_mfma_f32_16x16x32_bf16 v[58:61], v[122:125], v[162:165], v[58:61]
	v_mfma_f32_16x16x32_bf16 v[50:53], v[114:117], v[216:219], v[50:53]
	v_mfma_f32_16x16x32_bf16 v[42:45], v[122:125], v[216:219], v[42:45]
	v_mfma_f32_16x16x32_bf16 v[34:37], v[114:117], v[224:227], v[34:37]
	v_mfma_f32_16x16x32_bf16 v[26:29], v[122:125], v[224:227], v[26:29]
	v_mfma_f32_16x16x32_bf16 v[18:21], v[114:117], v[232:235], v[18:21]
	v_mfma_f32_16x16x32_bf16 v[10:13], v[122:125], v[232:235], v[10:13]
	v_mfma_f32_16x16x32_bf16 v[62:65], v[118:121], v[166:169], v[62:65]
	v_mfma_f32_16x16x32_bf16 v[58:61], v[126:129], v[166:169], v[58:61]
	v_mfma_f32_16x16x32_bf16 v[50:53], v[118:121], v[220:223], v[50:53]
	v_mfma_f32_16x16x32_bf16 v[42:45], v[126:129], v[220:223], v[42:45]
	v_mfma_f32_16x16x32_bf16 v[34:37], v[118:121], v[228:231], v[34:37]
	v_mfma_f32_16x16x32_bf16 v[26:29], v[126:129], v[228:231], v[26:29]
	v_mfma_f32_16x16x32_bf16 v[18:21], v[118:121], v[236:239], v[18:21]
	v_mfma_f32_16x16x32_bf16 v[10:13], v[126:129], v[236:239], v[10:13]
	v_mfma_f32_16x16x32_bf16 v[54:57], v[146:149], v[162:165], v[54:57]
	v_mfma_f32_16x16x32_bf16 v[46:49], v[154:157], v[162:165], v[46:49]
	v_mfma_f32_16x16x32_bf16 v[38:41], v[146:149], v[216:219], v[38:41]
	v_mfma_f32_16x16x32_bf16 v[30:33], v[154:157], v[216:219], v[30:33]
	v_mfma_f32_16x16x32_bf16 v[22:25], v[146:149], v[224:227], v[22:25]
	v_mfma_f32_16x16x32_bf16 v[14:17], v[154:157], v[224:227], v[14:17]
	v_mfma_f32_16x16x32_bf16 v[6:9], v[146:149], v[232:235], v[6:9]
	v_mfma_f32_16x16x32_bf16 v[2:5], v[154:157], v[232:235], v[2:5]
	v_mfma_f32_16x16x32_bf16 v[54:57], v[150:153], v[166:169], v[54:57]
	v_mfma_f32_16x16x32_bf16 v[46:49], v[158:161], v[166:169], v[46:49]
	v_mfma_f32_16x16x32_bf16 v[38:41], v[150:153], v[220:223], v[38:41]
	v_mfma_f32_16x16x32_bf16 v[30:33], v[158:161], v[220:223], v[30:33]
	v_mfma_f32_16x16x32_bf16 v[22:25], v[150:153], v[228:231], v[22:25]
	v_mfma_f32_16x16x32_bf16 v[14:17], v[158:161], v[228:231], v[14:17]
	v_mfma_f32_16x16x32_bf16 v[6:9], v[150:153], v[236:239], v[6:9]
	v_mfma_f32_16x16x32_bf16 v[2:5], v[158:161], v[236:239], v[2:5]
	s_setprio 0
	s_barrier
	s_add_u32 s10, s10, 0x100
	s_addc_u32 s11, s11, 0
	s_add_u32 vcc_lo, vcc_lo, 0x100
	s_addc_u32 vcc_hi, vcc_hi, 0
	s_cmp_ge_i32 s66, s18
	s_mov_b32 s94, s66
.LBB0_1428:
	s_add_i32 s66, s94, 2
	s_add_u32 s67, s10, 0xfffc0080
	s_addc_u32 s72, s11, -1
	s_cmp_eq_u32 s85, s94
	s_cselect_b32 s97, s14, s72
	s_cselect_b32 s96, s15, s67
	s_cselect_b32 s95, s51, vcc_hi
	s_cselect_b32 s94, s84, vcc_lo
	s_add_i32 s67, 0, 0x10000
	s_add_i32 s62, 0, 0x14000
	v_add_u32_e32 v126, s67, v199
	v_add_u32_e32 v158, s62, v199
	ds_read_b128 v[114:117], v126
	ds_read_b128 v[118:121], v126 offset:1024
	ds_read_b128 v[122:125], v126 offset:2048
	ds_read_b128 v[126:129], v126 offset:3072
	ds_read_b128 v[146:149], v158
	ds_read_b128 v[150:153], v158 offset:1024
	ds_read_b128 v[154:157], v158 offset:2048
	ds_read_b128 v[158:161], v158 offset:3072
	v_lshl_add_u64 v[202:203], s[10:11], 0, v[196:197]
	s_add_i32 m0, s28, 0xc000
	ds_read_b128 v[162:165], v214
	ds_read_b128 v[166:169], v214 offset:1024
	ds_read_b128 v[216:219], v214 offset:2048
	ds_read_b128 v[220:223], v214 offset:3072
	ds_read_b128 v[224:227], v214 offset:4096
	ds_read_b128 v[228:231], v214 offset:5120
	ds_read_b128 v[232:235], v214 offset:6144
	ds_read_b128 v[236:239], v214 offset:7168
	global_load_lds_dwordx4 v[202:203], off
	s_add_i32 m0, s28, 0xe000
	v_lshl_add_u64 v[202:203], s[10:11], 0, v[176:177]
	global_load_lds_dwordx4 v[202:203], off
	s_waitcnt vmcnt(8) lgkmcnt(0)
	s_setprio 1
	s_barrier
	v_mfma_f32_16x16x32_bf16 v[142:145], v[114:117], v[162:165], v[142:145]
	v_mfma_f32_16x16x32_bf16 v[138:141], v[122:125], v[162:165], v[138:141]
	v_mfma_f32_16x16x32_bf16 v[110:113], v[114:117], v[216:219], v[110:113]
	v_mfma_f32_16x16x32_bf16 v[106:109], v[122:125], v[216:219], v[106:109]
	v_mfma_f32_16x16x32_bf16 v[98:101], v[114:117], v[224:227], v[98:101]
	v_mfma_f32_16x16x32_bf16 v[90:93], v[122:125], v[224:227], v[90:93]
	v_mfma_f32_16x16x32_bf16 v[82:85], v[114:117], v[232:235], v[82:85]
	v_mfma_f32_16x16x32_bf16 v[74:77], v[122:125], v[232:235], v[74:77]
	v_mfma_f32_16x16x32_bf16 v[142:145], v[118:121], v[166:169], v[142:145]
	v_mfma_f32_16x16x32_bf16 v[138:141], v[126:129], v[166:169], v[138:141]
	v_mfma_f32_16x16x32_bf16 v[110:113], v[118:121], v[220:223], v[110:113]
	v_mfma_f32_16x16x32_bf16 v[106:109], v[126:129], v[220:223], v[106:109]
	v_mfma_f32_16x16x32_bf16 v[98:101], v[118:121], v[228:231], v[98:101]
	v_mfma_f32_16x16x32_bf16 v[90:93], v[126:129], v[228:231], v[90:93]
	v_mfma_f32_16x16x32_bf16 v[82:85], v[118:121], v[236:239], v[82:85]
	v_mfma_f32_16x16x32_bf16 v[74:77], v[126:129], v[236:239], v[74:77]
	v_mfma_f32_16x16x32_bf16 v[134:137], v[146:149], v[162:165], v[134:137]
	v_mfma_f32_16x16x32_bf16 v[130:133], v[154:157], v[162:165], v[130:133]
	v_mfma_f32_16x16x32_bf16 v[102:105], v[146:149], v[216:219], v[102:105]
	v_mfma_f32_16x16x32_bf16 v[94:97], v[154:157], v[216:219], v[94:97]
	v_mfma_f32_16x16x32_bf16 v[86:89], v[146:149], v[224:227], v[86:89]
	v_mfma_f32_16x16x32_bf16 v[78:81], v[154:157], v[224:227], v[78:81]
	v_mfma_f32_16x16x32_bf16 v[70:73], v[146:149], v[232:235], v[70:73]
	v_mfma_f32_16x16x32_bf16 v[66:69], v[154:157], v[232:235], v[66:69]
	v_mfma_f32_16x16x32_bf16 v[134:137], v[150:153], v[166:169], v[134:137]
	v_mfma_f32_16x16x32_bf16 v[130:133], v[158:161], v[166:169], v[130:133]
	v_mfma_f32_16x16x32_bf16 v[102:105], v[150:153], v[220:223], v[102:105]
	v_mfma_f32_16x16x32_bf16 v[94:97], v[158:161], v[220:223], v[94:97]
	v_mfma_f32_16x16x32_bf16 v[86:89], v[150:153], v[228:231], v[86:89]
	v_mfma_f32_16x16x32_bf16 v[78:81], v[158:161], v[228:231], v[78:81]
	v_mfma_f32_16x16x32_bf16 v[70:73], v[150:153], v[236:239], v[70:73]
	v_mfma_f32_16x16x32_bf16 v[66:69], v[158:161], v[236:239], v[66:69]
	s_setprio 0
	s_barrier
	s_add_i32 s63, s67, s17
	v_lshl_add_u64 v[202:203], s[94:95], 0, v[174:175]
	s_mov_b32 m0, s63
	ds_read_b128 v[162:165], v214 offset:16384
	ds_read_b128 v[166:169], v214 offset:17408
	ds_read_b128 v[216:219], v214 offset:18432
	ds_read_b128 v[220:223], v214 offset:19456
	ds_read_b128 v[224:227], v214 offset:20480
	ds_read_b128 v[228:231], v214 offset:21504
	ds_read_b128 v[232:235], v214 offset:22528
	ds_read_b128 v[236:239], v214 offset:23552
	global_load_lds_dwordx4 v[202:203], off
	s_add_i32 m0, s63, 0x2000
	s_add_u32 s72, s94, 0x40000
	v_lshl_add_u64 v[240:241], s[94:95], 0, v[178:179]
	s_addc_u32 s73, s95, 0
	s_add_i32 s62, s62, s17
	global_load_lds_dwordx4 v[240:241], off
	v_lshl_add_u64 v[242:243], s[72:73], 0, v[174:175]
	s_mov_b32 m0, s62
	v_lshl_add_u64 v[244:245], s[96:97], 0, v[176:177]
	global_load_lds_dwordx4 v[242:243], off
	s_add_i32 m0, s62, 0x2000
	v_lshl_add_u64 v[242:243], s[72:73], 0, v[178:179]
	global_load_lds_dwordx4 v[242:243], off
	s_mov_b32 m0, s28
	v_lshl_add_u64 v[242:243], s[96:97], 0, v[172:173]
	global_load_lds_dwordx4 v[242:243], off
	s_mov_b32 m0, s29
	s_nop 0
	global_load_lds_dwordx4 v[244:245], off
	s_nop 0
	s_waitcnt vmcnt(8) lgkmcnt(0)
	s_setprio 1
	s_barrier
	v_mfma_f32_16x16x32_bf16 v[62:65], v[114:117], v[162:165], v[62:65]
	v_mfma_f32_16x16x32_bf16 v[58:61], v[122:125], v[162:165], v[58:61]
	v_mfma_f32_16x16x32_bf16 v[50:53], v[114:117], v[216:219], v[50:53]
	v_mfma_f32_16x16x32_bf16 v[42:45], v[122:125], v[216:219], v[42:45]
	v_mfma_f32_16x16x32_bf16 v[34:37], v[114:117], v[224:227], v[34:37]
	v_mfma_f32_16x16x32_bf16 v[26:29], v[122:125], v[224:227], v[26:29]
	v_mfma_f32_16x16x32_bf16 v[18:21], v[114:117], v[232:235], v[18:21]
	v_mfma_f32_16x16x32_bf16 v[10:13], v[122:125], v[232:235], v[10:13]
	v_mfma_f32_16x16x32_bf16 v[62:65], v[118:121], v[166:169], v[62:65]
	v_mfma_f32_16x16x32_bf16 v[58:61], v[126:129], v[166:169], v[58:61]
	v_mfma_f32_16x16x32_bf16 v[50:53], v[118:121], v[220:223], v[50:53]
	v_mfma_f32_16x16x32_bf16 v[42:45], v[126:129], v[220:223], v[42:45]
	v_mfma_f32_16x16x32_bf16 v[34:37], v[118:121], v[228:231], v[34:37]
	v_mfma_f32_16x16x32_bf16 v[26:29], v[126:129], v[228:231], v[26:29]
	v_mfma_f32_16x16x32_bf16 v[18:21], v[118:121], v[236:239], v[18:21]
	v_mfma_f32_16x16x32_bf16 v[10:13], v[126:129], v[236:239], v[10:13]
	v_mfma_f32_16x16x32_bf16 v[54:57], v[146:149], v[162:165], v[54:57]
	v_mfma_f32_16x16x32_bf16 v[46:49], v[154:157], v[162:165], v[46:49]
	v_mfma_f32_16x16x32_bf16 v[38:41], v[146:149], v[216:219], v[38:41]
	v_mfma_f32_16x16x32_bf16 v[30:33], v[154:157], v[216:219], v[30:33]
	v_mfma_f32_16x16x32_bf16 v[22:25], v[146:149], v[224:227], v[22:25]
	v_mfma_f32_16x16x32_bf16 v[14:17], v[154:157], v[224:227], v[14:17]
	v_mfma_f32_16x16x32_bf16 v[6:9], v[146:149], v[232:235], v[6:9]
	v_mfma_f32_16x16x32_bf16 v[2:5], v[154:157], v[232:235], v[2:5]
	v_mfma_f32_16x16x32_bf16 v[54:57], v[150:153], v[166:169], v[54:57]
	v_mfma_f32_16x16x32_bf16 v[46:49], v[158:161], v[166:169], v[46:49]
	v_mfma_f32_16x16x32_bf16 v[38:41], v[150:153], v[220:223], v[38:41]
	v_mfma_f32_16x16x32_bf16 v[30:33], v[158:161], v[220:223], v[30:33]
	v_mfma_f32_16x16x32_bf16 v[22:25], v[150:153], v[228:231], v[22:25]
	v_mfma_f32_16x16x32_bf16 v[14:17], v[158:161], v[228:231], v[14:17]
	v_mfma_f32_16x16x32_bf16 v[6:9], v[150:153], v[236:239], v[6:9]
	v_mfma_f32_16x16x32_bf16 v[2:5], v[158:161], v[236:239], v[2:5]
	s_setprio 0
	s_barrier
	s_add_i32 s62, 0, 0x18000
	s_add_i32 s63, 0, 0x1c000
	v_add_u32_e32 v126, s62, v199
	v_add_u32_e32 v158, s63, v199
	ds_read_b128 v[114:117], v126
	ds_read_b128 v[118:121], v126 offset:1024
	ds_read_b128 v[122:125], v126 offset:2048
	ds_read_b128 v[126:129], v126 offset:3072
	ds_read_b128 v[146:149], v158
	ds_read_b128 v[150:153], v158 offset:1024
	ds_read_b128 v[154:157], v158 offset:2048
	ds_read_b128 v[158:161], v158 offset:3072
	s_add_u32 s72, s96, 0x40000
	s_addc_u32 s73, s97, 0
	s_mov_b32 m0, s30
	v_lshl_add_u64 v[246:247], s[72:73], 0, v[172:173]
	ds_read_b128 v[162:165], v214 offset:32768
	ds_read_b128 v[166:169], v214 offset:33792
	ds_read_b128 v[216:219], v214 offset:34816
	ds_read_b128 v[220:223], v214 offset:35840
	ds_read_b128 v[224:227], v214 offset:36864
	ds_read_b128 v[228:231], v214 offset:37888
	ds_read_b128 v[232:235], v214 offset:38912
	ds_read_b128 v[236:239], v214 offset:39936
	global_load_lds_dwordx4 v[246:247], off
	s_mov_b32 m0, s31
	v_lshl_add_u64 v[246:247], s[72:73], 0, v[176:177]
	global_load_lds_dwordx4 v[246:247], off
	s_waitcnt vmcnt(8) lgkmcnt(0)
	s_setprio 1
	s_barrier
	v_mfma_f32_16x16x32_bf16 v[142:145], v[114:117], v[162:165], v[142:145]
	v_mfma_f32_16x16x32_bf16 v[138:141], v[122:125], v[162:165], v[138:141]
	v_mfma_f32_16x16x32_bf16 v[110:113], v[114:117], v[216:219], v[110:113]
	v_mfma_f32_16x16x32_bf16 v[106:109], v[122:125], v[216:219], v[106:109]
	v_mfma_f32_16x16x32_bf16 v[98:101], v[114:117], v[224:227], v[98:101]
	v_mfma_f32_16x16x32_bf16 v[90:93], v[122:125], v[224:227], v[90:93]
	v_mfma_f32_16x16x32_bf16 v[82:85], v[114:117], v[232:235], v[82:85]
	v_mfma_f32_16x16x32_bf16 v[74:77], v[122:125], v[232:235], v[74:77]
	v_mfma_f32_16x16x32_bf16 v[142:145], v[118:121], v[166:169], v[142:145]
	v_mfma_f32_16x16x32_bf16 v[138:141], v[126:129], v[166:169], v[138:141]
	v_mfma_f32_16x16x32_bf16 v[110:113], v[118:121], v[220:223], v[110:113]
	v_mfma_f32_16x16x32_bf16 v[106:109], v[126:129], v[220:223], v[106:109]
	v_mfma_f32_16x16x32_bf16 v[98:101], v[118:121], v[228:231], v[98:101]
	v_mfma_f32_16x16x32_bf16 v[90:93], v[126:129], v[228:231], v[90:93]
	v_mfma_f32_16x16x32_bf16 v[82:85], v[118:121], v[236:239], v[82:85]
	v_mfma_f32_16x16x32_bf16 v[74:77], v[126:129], v[236:239], v[74:77]
	v_mfma_f32_16x16x32_bf16 v[134:137], v[146:149], v[162:165], v[134:137]
	v_mfma_f32_16x16x32_bf16 v[130:133], v[154:157], v[162:165], v[130:133]
	v_mfma_f32_16x16x32_bf16 v[102:105], v[146:149], v[216:219], v[102:105]
	v_mfma_f32_16x16x32_bf16 v[94:97], v[154:157], v[216:219], v[94:97]
	v_mfma_f32_16x16x32_bf16 v[86:89], v[146:149], v[224:227], v[86:89]
	v_mfma_f32_16x16x32_bf16 v[78:81], v[154:157], v[224:227], v[78:81]
	v_mfma_f32_16x16x32_bf16 v[70:73], v[146:149], v[232:235], v[70:73]
	v_mfma_f32_16x16x32_bf16 v[66:69], v[154:157], v[232:235], v[66:69]
	v_mfma_f32_16x16x32_bf16 v[134:137], v[150:153], v[166:169], v[134:137]
	v_mfma_f32_16x16x32_bf16 v[130:133], v[158:161], v[166:169], v[130:133]
	v_mfma_f32_16x16x32_bf16 v[102:105], v[150:153], v[220:223], v[102:105]
	v_mfma_f32_16x16x32_bf16 v[94:97], v[158:161], v[220:223], v[94:97]
	v_mfma_f32_16x16x32_bf16 v[86:89], v[150:153], v[228:231], v[86:89]
	v_mfma_f32_16x16x32_bf16 v[78:81], v[158:161], v[228:231], v[78:81]
	v_mfma_f32_16x16x32_bf16 v[70:73], v[150:153], v[236:239], v[70:73]
	v_mfma_f32_16x16x32_bf16 v[66:69], v[158:161], v[236:239], v[66:69]
	s_setprio 0
	s_barrier
	s_add_i32 s62, s62, s17
	v_lshl_add_u64 v[202:203], v[202:203], 0, s[76:77]
	s_mov_b32 m0, s62
	ds_read_b128 v[162:165], v214 offset:49152
	ds_read_b128 v[166:169], v214 offset:50176
	ds_read_b128 v[216:219], v214 offset:51200
	ds_read_b128 v[220:223], v214 offset:52224
	ds_read_b128 v[224:227], v214 offset:53248
	ds_read_b128 v[228:231], v214 offset:54272
	ds_read_b128 v[232:235], v214 offset:55296
	ds_read_b128 v[236:239], v214 offset:56320
	global_load_lds_dwordx4 v[202:203], off
	s_add_i32 m0, s62, 0x2000
	s_add_u32 s72, s94, 0x40080
	v_lshl_add_u64 v[202:203], v[240:241], 0, s[76:77]
	s_addc_u32 s73, s95, 0
	s_add_i32 s62, s63, s17
	global_load_lds_dwordx4 v[202:203], off
	s_mov_b32 m0, s62
	v_lshl_add_u64 v[202:203], s[72:73], 0, v[174:175]
	global_load_lds_dwordx4 v[202:203], off
	s_add_i32 m0, s62, 0x2000
	v_lshl_add_u64 v[202:203], s[72:73], 0, v[178:179]
	global_load_lds_dwordx4 v[202:203], off
	s_mov_b32 m0, s44
	v_lshl_add_u64 v[202:203], v[242:243], 0, s[76:77]
	global_load_lds_dwordx4 v[202:203], off
	s_mov_b32 m0, s36
	v_lshl_add_u64 v[202:203], v[244:245], 0, s[76:77]
	global_load_lds_dwordx4 v[202:203], off
	s_waitcnt vmcnt(8) lgkmcnt(0)
	s_setprio 1
	s_barrier
	v_mfma_f32_16x16x32_bf16 v[62:65], v[114:117], v[162:165], v[62:65]
	v_mfma_f32_16x16x32_bf16 v[58:61], v[122:125], v[162:165], v[58:61]
	v_mfma_f32_16x16x32_bf16 v[50:53], v[114:117], v[216:219], v[50:53]
	v_mfma_f32_16x16x32_bf16 v[42:45], v[122:125], v[216:219], v[42:45]
	v_mfma_f32_16x16x32_bf16 v[34:37], v[114:117], v[224:227], v[34:37]
	v_mfma_f32_16x16x32_bf16 v[26:29], v[122:125], v[224:227], v[26:29]
	v_mfma_f32_16x16x32_bf16 v[18:21], v[114:117], v[232:235], v[18:21]
	v_mfma_f32_16x16x32_bf16 v[10:13], v[122:125], v[232:235], v[10:13]
	v_mfma_f32_16x16x32_bf16 v[62:65], v[118:121], v[166:169], v[62:65]
	v_mfma_f32_16x16x32_bf16 v[58:61], v[126:129], v[166:169], v[58:61]
	v_mfma_f32_16x16x32_bf16 v[50:53], v[118:121], v[220:223], v[50:53]
	v_mfma_f32_16x16x32_bf16 v[42:45], v[126:129], v[220:223], v[42:45]
	v_mfma_f32_16x16x32_bf16 v[34:37], v[118:121], v[228:231], v[34:37]
	v_mfma_f32_16x16x32_bf16 v[26:29], v[126:129], v[228:231], v[26:29]
	v_mfma_f32_16x16x32_bf16 v[18:21], v[118:121], v[236:239], v[18:21]
	v_mfma_f32_16x16x32_bf16 v[10:13], v[126:129], v[236:239], v[10:13]
	v_mfma_f32_16x16x32_bf16 v[54:57], v[146:149], v[162:165], v[54:57]
	v_mfma_f32_16x16x32_bf16 v[46:49], v[154:157], v[162:165], v[46:49]
	v_mfma_f32_16x16x32_bf16 v[38:41], v[146:149], v[216:219], v[38:41]
	v_mfma_f32_16x16x32_bf16 v[30:33], v[154:157], v[216:219], v[30:33]
	v_mfma_f32_16x16x32_bf16 v[22:25], v[146:149], v[224:227], v[22:25]
	v_mfma_f32_16x16x32_bf16 v[14:17], v[154:157], v[224:227], v[14:17]
	v_mfma_f32_16x16x32_bf16 v[6:9], v[146:149], v[232:235], v[6:9]
	v_mfma_f32_16x16x32_bf16 v[2:5], v[154:157], v[232:235], v[2:5]
	v_mfma_f32_16x16x32_bf16 v[54:57], v[150:153], v[166:169], v[54:57]
	v_mfma_f32_16x16x32_bf16 v[46:49], v[158:161], v[166:169], v[46:49]
	v_mfma_f32_16x16x32_bf16 v[38:41], v[150:153], v[220:223], v[38:41]
	v_mfma_f32_16x16x32_bf16 v[30:33], v[158:161], v[220:223], v[30:33]
	v_mfma_f32_16x16x32_bf16 v[22:25], v[150:153], v[228:231], v[22:25]
	v_mfma_f32_16x16x32_bf16 v[14:17], v[158:161], v[228:231], v[14:17]
	v_mfma_f32_16x16x32_bf16 v[6:9], v[150:153], v[236:239], v[6:9]
	v_mfma_f32_16x16x32_bf16 v[2:5], v[158:161], v[236:239], v[2:5]
	s_setprio 0
	s_barrier
	s_add_u32 s10, s10, 0x100
	s_addc_u32 s11, s11, 0
	s_add_u32 vcc_lo, vcc_lo, 0x100
	s_addc_u32 vcc_hi, vcc_hi, 0
	s_cmp_ge_i32 s66, s18
	s_mov_b32 s94, s66
	s_cbranch_scc0 .LBB0_1428
	s_and_b64 vcc, exec, s[82:83]
	s_cbranch_vccz .LBB0_1431
	s_barrier

.LBB0_1618:
	s_add_u32 s24, s96, s20
	s_addc_u32 s25, s97, s21
	s_and_b64 s[14:15], s[4:5], exec
	s_cselect_b32 s14, s25, s29
	s_cselect_b32 s15, s24, s28
	s_add_u32 s26, s2, s22
	s_addc_u32 s27, s3, s23
	s_and_b64 s[36:37], s[4:5], exec
	s_cselect_b32 s17, s27, s31
	s_cselect_b32 s49, s26, s30
	s_add_u32 s28, s28, 0x40080
	s_addc_u32 s29, s29, 0
	s_add_u32 s50, s30, 0x100
	s_addc_u32 s51, s31, 0
	s_mov_b32 s62, -2
	ds_read_b128 v[154:157], v150
	ds_read_b128 v[158:161], v150 offset:1024
	ds_read_b128 v[162:165], v150 offset:2048
	ds_read_b128 v[166:169], v150 offset:3072
	ds_read_b128 v[170:173], v151
	ds_read_b128 v[174:177], v151 offset:1024
	ds_read_b128 v[178:181], v151 offset:2048
	ds_read_b128 v[182:185], v151 offset:3072
	s_add_u32 s30, s28, 0xfffc0080
	s_addc_u32 s31, s29, -1
	s_cmp_eq_u32 s62, 12
	s_cselect_b32 s37, s14, s31
	s_cselect_b32 s36, s15, s30
	s_cselect_b32 s31, s17, s51
	s_cselect_b32 s30, s49, s50
	v_lshl_add_u64 v[146:147], s[28:29], 0, v[138:139]
	s_add_i32 m0, s19, 0xc000
	ds_read_b128 v[186:189], v152
	ds_read_b128 v[190:193], v152 offset:1024
	ds_read_b128 v[194:197], v152 offset:2048
	ds_read_b128 v[198:201], v152 offset:3072
	ds_read_b128 v[206:209], v152 offset:4096
	ds_read_b128 v[210:213], v152 offset:5120
	ds_read_b128 v[214:217], v152 offset:6144
	ds_read_b128 v[218:221], v152 offset:7168
	global_load_lds_dwordx4 v[146:147], off
	s_add_i32 m0, s19, 0xe000
	v_lshl_add_u64 v[146:147], s[28:29], 0, v[140:141]
	global_load_lds_dwordx4 v[146:147], off
	s_nop 0
	s_waitcnt vmcnt(8) lgkmcnt(0)
	s_setprio 1
	s_barrier
	v_mfma_f32_16x16x32_bf16 v[126:129], v[154:157], v[186:189], 0
	v_mfma_f32_16x16x32_bf16 v[122:125], v[162:165], v[186:189], 0
	v_mfma_f32_16x16x32_bf16 v[110:113], v[154:157], v[194:197], 0
	v_mfma_f32_16x16x32_bf16 v[106:109], v[162:165], v[194:197], 0
	v_mfma_f32_16x16x32_bf16 v[94:97], v[154:157], v[206:209], 0
	v_mfma_f32_16x16x32_bf16 v[90:93], v[162:165], v[206:209], 0
	v_mfma_f32_16x16x32_bf16 v[78:81], v[154:157], v[214:217], 0
	v_mfma_f32_16x16x32_bf16 v[74:77], v[162:165], v[214:217], 0
	v_mfma_f32_16x16x32_bf16 v[126:129], v[158:161], v[190:193], v[126:129]
	v_mfma_f32_16x16x32_bf16 v[122:125], v[166:169], v[190:193], v[122:125]
	v_mfma_f32_16x16x32_bf16 v[110:113], v[158:161], v[198:201], v[110:113]
	v_mfma_f32_16x16x32_bf16 v[106:109], v[166:169], v[198:201], v[106:109]
	v_mfma_f32_16x16x32_bf16 v[94:97], v[158:161], v[210:213], v[94:97]
	v_mfma_f32_16x16x32_bf16 v[90:93], v[166:169], v[210:213], v[90:93]
	v_mfma_f32_16x16x32_bf16 v[78:81], v[158:161], v[218:221], v[78:81]
	v_mfma_f32_16x16x32_bf16 v[74:77], v[166:169], v[218:221], v[74:77]
	v_mfma_f32_16x16x32_bf16 v[118:121], v[170:173], v[186:189], 0
	v_mfma_f32_16x16x32_bf16 v[114:117], v[178:181], v[186:189], 0
	v_mfma_f32_16x16x32_bf16 v[102:105], v[170:173], v[194:197], 0
	v_mfma_f32_16x16x32_bf16 v[98:101], v[178:181], v[194:197], 0
	v_mfma_f32_16x16x32_bf16 v[86:89], v[170:173], v[206:209], 0
	v_mfma_f32_16x16x32_bf16 v[82:85], v[178:181], v[206:209], 0
	v_mfma_f32_16x16x32_bf16 v[70:73], v[170:173], v[214:217], 0
	v_mfma_f32_16x16x32_bf16 v[66:69], v[178:181], v[214:217], 0
	v_mfma_f32_16x16x32_bf16 v[118:121], v[174:177], v[190:193], v[118:121]
	v_mfma_f32_16x16x32_bf16 v[114:117], v[182:185], v[190:193], v[114:117]
	v_mfma_f32_16x16x32_bf16 v[102:105], v[174:177], v[198:201], v[102:105]
	v_mfma_f32_16x16x32_bf16 v[98:101], v[182:185], v[198:201], v[98:101]
	v_mfma_f32_16x16x32_bf16 v[86:89], v[174:177], v[210:213], v[86:89]
	v_mfma_f32_16x16x32_bf16 v[82:85], v[182:185], v[210:213], v[82:85]
	v_mfma_f32_16x16x32_bf16 v[70:73], v[174:177], v[218:221], v[70:73]
	v_mfma_f32_16x16x32_bf16 v[66:69], v[182:185], v[218:221], v[66:69]
	s_setprio 0
	s_barrier
	s_add_i32 s63, s45, s12
	v_lshl_add_u64 v[146:147], s[30:31], 0, v[134:135]
	s_mov_b32 m0, s63
	ds_read_b128 v[186:189], v152 offset:16384
	ds_read_b128 v[190:193], v152 offset:17408
	ds_read_b128 v[194:197], v152 offset:18432
	ds_read_b128 v[198:201], v152 offset:19456
	ds_read_b128 v[206:209], v152 offset:20480
	ds_read_b128 v[210:213], v152 offset:21504
	ds_read_b128 v[214:217], v152 offset:22528
	ds_read_b128 v[218:221], v152 offset:23552
	global_load_lds_dwordx4 v[146:147], off
	s_add_i32 m0, s63, 0x2000
	s_add_u32 s64, s30, 0x40000
	v_lshl_add_u64 v[202:203], s[30:31], 0, v[130:131]
	s_addc_u32 s65, s31, 0
	s_add_i32 s63, s46, s12
	global_load_lds_dwordx4 v[202:203], off
	v_lshl_add_u64 v[222:223], s[64:65], 0, v[134:135]
	s_mov_b32 m0, s63
	v_lshl_add_u64 v[224:225], s[36:37], 0, v[132:133]
	global_load_lds_dwordx4 v[222:223], off
	s_add_i32 m0, s63, 0x2000
	v_lshl_add_u64 v[222:223], s[64:65], 0, v[130:131]
	global_load_lds_dwordx4 v[222:223], off
	s_mov_b32 m0, s19
	v_lshl_add_u64 v[222:223], s[36:37], 0, v[136:137]
	global_load_lds_dwordx4 v[222:223], off
	s_mov_b32 m0, s33
	s_nop 0
	global_load_lds_dwordx4 v[224:225], off
	s_nop 0
	s_waitcnt vmcnt(8) lgkmcnt(0)
	s_setprio 1
	s_barrier
	v_mfma_f32_16x16x32_bf16 v[62:65], v[154:157], v[186:189], 0
	v_mfma_f32_16x16x32_bf16 v[58:61], v[162:165], v[186:189], 0
	v_mfma_f32_16x16x32_bf16 v[46:49], v[154:157], v[194:197], 0
	v_mfma_f32_16x16x32_bf16 v[42:45], v[162:165], v[194:197], 0
	v_mfma_f32_16x16x32_bf16 v[30:33], v[154:157], v[206:209], 0
	v_mfma_f32_16x16x32_bf16 v[26:29], v[162:165], v[206:209], 0
	v_mfma_f32_16x16x32_bf16 v[14:17], v[154:157], v[214:217], 0
	v_mfma_f32_16x16x32_bf16 v[10:13], v[162:165], v[214:217], 0
	v_mfma_f32_16x16x32_bf16 v[62:65], v[158:161], v[190:193], v[62:65]
	v_mfma_f32_16x16x32_bf16 v[58:61], v[166:169], v[190:193], v[58:61]
	v_mfma_f32_16x16x32_bf16 v[46:49], v[158:161], v[198:201], v[46:49]
	v_mfma_f32_16x16x32_bf16 v[42:45], v[166:169], v[198:201], v[42:45]
	v_mfma_f32_16x16x32_bf16 v[30:33], v[158:161], v[210:213], v[30:33]
	v_mfma_f32_16x16x32_bf16 v[26:29], v[166:169], v[210:213], v[26:29]
	v_mfma_f32_16x16x32_bf16 v[14:17], v[158:161], v[218:221], v[14:17]
	v_mfma_f32_16x16x32_bf16 v[10:13], v[166:169], v[218:221], v[10:13]
	v_mfma_f32_16x16x32_bf16 v[54:57], v[170:173], v[186:189], 0
	v_mfma_f32_16x16x32_bf16 v[50:53], v[178:181], v[186:189], 0
	v_mfma_f32_16x16x32_bf16 v[38:41], v[170:173], v[194:197], 0
	v_mfma_f32_16x16x32_bf16 v[34:37], v[178:181], v[194:197], 0
	v_mfma_f32_16x16x32_bf16 v[22:25], v[170:173], v[206:209], 0
	v_mfma_f32_16x16x32_bf16 v[18:21], v[178:181], v[206:209], 0
	v_mfma_f32_16x16x32_bf16 v[6:9], v[170:173], v[214:217], 0
	v_mfma_f32_16x16x32_bf16 v[2:5], v[178:181], v[214:217], 0
	v_mfma_f32_16x16x32_bf16 v[54:57], v[174:177], v[190:193], v[54:57]
	v_mfma_f32_16x16x32_bf16 v[50:53], v[182:185], v[190:193], v[50:53]
	v_mfma_f32_16x16x32_bf16 v[38:41], v[174:177], v[198:201], v[38:41]
	v_mfma_f32_16x16x32_bf16 v[34:37], v[182:185], v[198:201], v[34:37]
	v_mfma_f32_16x16x32_bf16 v[22:25], v[174:177], v[210:213], v[22:25]
	v_mfma_f32_16x16x32_bf16 v[18:21], v[182:185], v[210:213], v[18:21]
	v_mfma_f32_16x16x32_bf16 v[6:9], v[174:177], v[218:221], v[6:9]
	v_mfma_f32_16x16x32_bf16 v[2:5], v[182:185], v[218:221], v[2:5]
	s_setprio 0
	s_barrier
	s_add_i32 s63, 0, 0x18000
	v_add_u32_e32 v153, s63, v149
	s_add_i32 s64, 0, 0x1c000
	ds_read_b128 v[154:157], v153
	ds_read_b128 v[158:161], v153 offset:1024
	ds_read_b128 v[162:165], v153 offset:2048
	ds_read_b128 v[166:169], v153 offset:3072
	v_add_u32_e32 v153, s64, v149
	ds_read_b128 v[170:173], v153
	ds_read_b128 v[174:177], v153 offset:1024
	ds_read_b128 v[178:181], v153 offset:2048
	ds_read_b128 v[182:185], v153 offset:3072
	s_add_u32 s36, s36, 0x40000
	s_addc_u32 s37, s37, 0
	s_mov_b32 m0, s35
	v_lshl_add_u64 v[226:227], s[36:37], 0, v[136:137]
	ds_read_b128 v[186:189], v152 offset:32768
	ds_read_b128 v[190:193], v152 offset:33792
	ds_read_b128 v[194:197], v152 offset:34816
	ds_read_b128 v[198:201], v152 offset:35840
	ds_read_b128 v[206:209], v152 offset:36864
	ds_read_b128 v[210:213], v152 offset:37888
	ds_read_b128 v[214:217], v152 offset:38912
	ds_read_b128 v[218:221], v152 offset:39936
	global_load_lds_dwordx4 v[226:227], off
	s_mov_b32 m0, s38
	v_lshl_add_u64 v[226:227], s[36:37], 0, v[132:133]
	global_load_lds_dwordx4 v[226:227], off
	s_waitcnt vmcnt(8) lgkmcnt(0)
	s_setprio 1
	s_barrier
	v_mfma_f32_16x16x32_bf16 v[126:129], v[154:157], v[186:189], v[126:129]
	v_mfma_f32_16x16x32_bf16 v[122:125], v[162:165], v[186:189], v[122:125]
	v_mfma_f32_16x16x32_bf16 v[110:113], v[154:157], v[194:197], v[110:113]
	v_mfma_f32_16x16x32_bf16 v[106:109], v[162:165], v[194:197], v[106:109]
	v_mfma_f32_16x16x32_bf16 v[94:97], v[154:157], v[206:209], v[94:97]
	v_mfma_f32_16x16x32_bf16 v[90:93], v[162:165], v[206:209], v[90:93]
	v_mfma_f32_16x16x32_bf16 v[78:81], v[154:157], v[214:217], v[78:81]
	v_mfma_f32_16x16x32_bf16 v[74:77], v[162:165], v[214:217], v[74:77]
	v_mfma_f32_16x16x32_bf16 v[126:129], v[158:161], v[190:193], v[126:129]
	v_mfma_f32_16x16x32_bf16 v[122:125], v[166:169], v[190:193], v[122:125]
	v_mfma_f32_16x16x32_bf16 v[110:113], v[158:161], v[198:201], v[110:113]
	v_mfma_f32_16x16x32_bf16 v[106:109], v[166:169], v[198:201], v[106:109]
	v_mfma_f32_16x16x32_bf16 v[94:97], v[158:161], v[210:213], v[94:97]
	v_mfma_f32_16x16x32_bf16 v[90:93], v[166:169], v[210:213], v[90:93]
	v_mfma_f32_16x16x32_bf16 v[78:81], v[158:161], v[218:221], v[78:81]
	v_mfma_f32_16x16x32_bf16 v[74:77], v[166:169], v[218:221], v[74:77]
	v_mfma_f32_16x16x32_bf16 v[118:121], v[170:173], v[186:189], v[118:121]
	v_mfma_f32_16x16x32_bf16 v[114:117], v[178:181], v[186:189], v[114:117]
	v_mfma_f32_16x16x32_bf16 v[102:105], v[170:173], v[194:197], v[102:105]
	v_mfma_f32_16x16x32_bf16 v[98:101], v[178:181], v[194:197], v[98:101]
	v_mfma_f32_16x16x32_bf16 v[86:89], v[170:173], v[206:209], v[86:89]
	v_mfma_f32_16x16x32_bf16 v[82:85], v[178:181], v[206:209], v[82:85]
	v_mfma_f32_16x16x32_bf16 v[70:73], v[170:173], v[214:217], v[70:73]
	v_mfma_f32_16x16x32_bf16 v[66:69], v[178:181], v[214:217], v[66:69]
	v_mfma_f32_16x16x32_bf16 v[118:121], v[174:177], v[190:193], v[118:121]
	v_mfma_f32_16x16x32_bf16 v[114:117], v[182:185], v[190:193], v[114:117]
	v_mfma_f32_16x16x32_bf16 v[102:105], v[174:177], v[198:201], v[102:105]
	v_mfma_f32_16x16x32_bf16 v[98:101], v[182:185], v[198:201], v[98:101]
	v_mfma_f32_16x16x32_bf16 v[86:89], v[174:177], v[210:213], v[86:89]
	v_mfma_f32_16x16x32_bf16 v[82:85], v[182:185], v[210:213], v[82:85]
	v_mfma_f32_16x16x32_bf16 v[70:73], v[174:177], v[218:221], v[70:73]
	v_mfma_f32_16x16x32_bf16 v[66:69], v[182:185], v[218:221], v[66:69]
	s_setprio 0
	s_barrier
	s_add_i32 s36, s63, s12
	v_lshl_add_u64 v[146:147], v[146:147], 0, s[8:9]
	s_mov_b32 m0, s36
	ds_read_b128 v[186:189], v152 offset:49152
	ds_read_b128 v[190:193], v152 offset:50176
	ds_read_b128 v[194:197], v152 offset:51200
	ds_read_b128 v[198:201], v152 offset:52224
	ds_read_b128 v[206:209], v152 offset:53248
	ds_read_b128 v[210:213], v152 offset:54272
	ds_read_b128 v[214:217], v152 offset:55296
	ds_read_b128 v[218:221], v152 offset:56320
	global_load_lds_dwordx4 v[146:147], off
	s_add_i32 m0, s36, 0x2000
	s_add_u32 s30, s30, 0x40080
	v_lshl_add_u64 v[146:147], v[202:203], 0, s[8:9]
	s_addc_u32 s31, s31, 0
	s_add_i32 s36, s64, s12
	global_load_lds_dwordx4 v[146:147], off
	s_mov_b32 m0, s36
	v_lshl_add_u64 v[146:147], s[30:31], 0, v[134:135]
	global_load_lds_dwordx4 v[146:147], off
	s_add_i32 m0, s36, 0x2000
	v_lshl_add_u64 v[146:147], s[30:31], 0, v[130:131]
	global_load_lds_dwordx4 v[146:147], off
	s_mov_b32 m0, s42
	v_lshl_add_u64 v[146:147], v[222:223], 0, s[8:9]
	global_load_lds_dwordx4 v[146:147], off
	s_mov_b32 m0, s43
	v_lshl_add_u64 v[146:147], v[224:225], 0, s[8:9]
	global_load_lds_dwordx4 v[146:147], off
	s_waitcnt vmcnt(8) lgkmcnt(0)
	s_setprio 1
	s_barrier
	v_mfma_f32_16x16x32_bf16 v[62:65], v[154:157], v[186:189], v[62:65]
	v_mfma_f32_16x16x32_bf16 v[58:61], v[162:165], v[186:189], v[58:61]
	v_mfma_f32_16x16x32_bf16 v[46:49], v[154:157], v[194:197], v[46:49]
	v_mfma_f32_16x16x32_bf16 v[42:45], v[162:165], v[194:197], v[42:45]
	v_mfma_f32_16x16x32_bf16 v[30:33], v[154:157], v[206:209], v[30:33]
	v_mfma_f32_16x16x32_bf16 v[26:29], v[162:165], v[206:209], v[26:29]
	v_mfma_f32_16x16x32_bf16 v[14:17], v[154:157], v[214:217], v[14:17]
	v_mfma_f32_16x16x32_bf16 v[10:13], v[162:165], v[214:217], v[10:13]
	v_mfma_f32_16x16x32_bf16 v[62:65], v[158:161], v[190:193], v[62:65]
	v_mfma_f32_16x16x32_bf16 v[58:61], v[166:169], v[190:193], v[58:61]
	v_mfma_f32_16x16x32_bf16 v[46:49], v[158:161], v[198:201], v[46:49]
	v_mfma_f32_16x16x32_bf16 v[42:45], v[166:169], v[198:201], v[42:45]
	v_mfma_f32_16x16x32_bf16 v[30:33], v[158:161], v[210:213], v[30:33]
	v_mfma_f32_16x16x32_bf16 v[26:29], v[166:169], v[210:213], v[26:29]
	v_mfma_f32_16x16x32_bf16 v[14:17], v[158:161], v[218:221], v[14:17]
	v_mfma_f32_16x16x32_bf16 v[10:13], v[166:169], v[218:221], v[10:13]
	v_mfma_f32_16x16x32_bf16 v[54:57], v[170:173], v[186:189], v[54:57]
	v_mfma_f32_16x16x32_bf16 v[50:53], v[178:181], v[186:189], v[50:53]
	v_mfma_f32_16x16x32_bf16 v[38:41], v[170:173], v[194:197], v[38:41]
	v_mfma_f32_16x16x32_bf16 v[34:37], v[178:181], v[194:197], v[34:37]
	v_mfma_f32_16x16x32_bf16 v[22:25], v[170:173], v[206:209], v[22:25]
	v_mfma_f32_16x16x32_bf16 v[18:21], v[178:181], v[206:209], v[18:21]
	v_mfma_f32_16x16x32_bf16 v[6:9], v[170:173], v[214:217], v[6:9]
	v_mfma_f32_16x16x32_bf16 v[2:5], v[178:181], v[214:217], v[2:5]
	v_mfma_f32_16x16x32_bf16 v[54:57], v[174:177], v[190:193], v[54:57]
	v_mfma_f32_16x16x32_bf16 v[50:53], v[182:185], v[190:193], v[50:53]
	v_mfma_f32_16x16x32_bf16 v[38:41], v[174:177], v[198:201], v[38:41]
	v_mfma_f32_16x16x32_bf16 v[34:37], v[182:185], v[198:201], v[34:37]
	v_mfma_f32_16x16x32_bf16 v[22:25], v[174:177], v[210:213], v[22:25]
	v_mfma_f32_16x16x32_bf16 v[18:21], v[182:185], v[210:213], v[18:21]
	v_mfma_f32_16x16x32_bf16 v[6:9], v[174:177], v[218:221], v[6:9]
	v_mfma_f32_16x16x32_bf16 v[2:5], v[182:185], v[218:221], v[2:5]
	s_setprio 0
	s_barrier
	s_add_i32 s62, s62, 2
	s_add_u32 s28, s28, 0x100
	s_addc_u32 s29, s29, 0
	s_add_u32 s50, s50, 0x100
	s_addc_u32 s51, s51, 0
	s_cmp_gt_u32 s62, 13
.LBB0_1619:
	ds_read_b128 v[154:157], v150
	ds_read_b128 v[158:161], v150 offset:1024
	ds_read_b128 v[162:165], v150 offset:2048
	ds_read_b128 v[166:169], v150 offset:3072
	ds_read_b128 v[170:173], v151
	ds_read_b128 v[174:177], v151 offset:1024
	ds_read_b128 v[178:181], v151 offset:2048
	ds_read_b128 v[182:185], v151 offset:3072
	s_add_u32 s30, s28, 0xfffc0080
	s_addc_u32 s31, s29, -1
	s_cmp_eq_u32 s62, 12
	s_cselect_b32 s37, s14, s31
	s_cselect_b32 s36, s15, s30
	s_cselect_b32 s31, s17, s51
	s_cselect_b32 s30, s49, s50
	v_lshl_add_u64 v[146:147], s[28:29], 0, v[138:139]
	s_add_i32 m0, s19, 0xc000
	ds_read_b128 v[186:189], v152
	ds_read_b128 v[190:193], v152 offset:1024
	ds_read_b128 v[194:197], v152 offset:2048
	ds_read_b128 v[198:201], v152 offset:3072
	ds_read_b128 v[206:209], v152 offset:4096
	ds_read_b128 v[210:213], v152 offset:5120
	ds_read_b128 v[214:217], v152 offset:6144
	ds_read_b128 v[218:221], v152 offset:7168
	global_load_lds_dwordx4 v[146:147], off
	s_add_i32 m0, s19, 0xe000
	v_lshl_add_u64 v[146:147], s[28:29], 0, v[140:141]
	global_load_lds_dwordx4 v[146:147], off
	s_nop 0
	s_waitcnt vmcnt(8) lgkmcnt(0)
	s_setprio 1
	s_barrier
	v_mfma_f32_16x16x32_bf16 v[126:129], v[154:157], v[186:189], v[126:129]
	v_mfma_f32_16x16x32_bf16 v[122:125], v[162:165], v[186:189], v[122:125]
	v_mfma_f32_16x16x32_bf16 v[110:113], v[154:157], v[194:197], v[110:113]
	v_mfma_f32_16x16x32_bf16 v[106:109], v[162:165], v[194:197], v[106:109]
	v_mfma_f32_16x16x32_bf16 v[94:97], v[154:157], v[206:209], v[94:97]
	v_mfma_f32_16x16x32_bf16 v[90:93], v[162:165], v[206:209], v[90:93]
	v_mfma_f32_16x16x32_bf16 v[78:81], v[154:157], v[214:217], v[78:81]
	v_mfma_f32_16x16x32_bf16 v[74:77], v[162:165], v[214:217], v[74:77]
	v_mfma_f32_16x16x32_bf16 v[126:129], v[158:161], v[190:193], v[126:129]
	v_mfma_f32_16x16x32_bf16 v[122:125], v[166:169], v[190:193], v[122:125]
	v_mfma_f32_16x16x32_bf16 v[110:113], v[158:161], v[198:201], v[110:113]
	v_mfma_f32_16x16x32_bf16 v[106:109], v[166:169], v[198:201], v[106:109]
	v_mfma_f32_16x16x32_bf16 v[94:97], v[158:161], v[210:213], v[94:97]
	v_mfma_f32_16x16x32_bf16 v[90:93], v[166:169], v[210:213], v[90:93]
	v_mfma_f32_16x16x32_bf16 v[78:81], v[158:161], v[218:221], v[78:81]
	v_mfma_f32_16x16x32_bf16 v[74:77], v[166:169], v[218:221], v[74:77]
	v_mfma_f32_16x16x32_bf16 v[118:121], v[170:173], v[186:189], v[118:121]
	v_mfma_f32_16x16x32_bf16 v[114:117], v[178:181], v[186:189], v[114:117]
	v_mfma_f32_16x16x32_bf16 v[102:105], v[170:173], v[194:197], v[102:105]
	v_mfma_f32_16x16x32_bf16 v[98:101], v[178:181], v[194:197], v[98:101]
	v_mfma_f32_16x16x32_bf16 v[86:89], v[170:173], v[206:209], v[86:89]
	v_mfma_f32_16x16x32_bf16 v[82:85], v[178:181], v[206:209], v[82:85]
	v_mfma_f32_16x16x32_bf16 v[70:73], v[170:173], v[214:217], v[70:73]
	v_mfma_f32_16x16x32_bf16 v[66:69], v[178:181], v[214:217], v[66:69]
	v_mfma_f32_16x16x32_bf16 v[118:121], v[174:177], v[190:193], v[118:121]
	v_mfma_f32_16x16x32_bf16 v[114:117], v[182:185], v[190:193], v[114:117]
	v_mfma_f32_16x16x32_bf16 v[102:105], v[174:177], v[198:201], v[102:105]
	v_mfma_f32_16x16x32_bf16 v[98:101], v[182:185], v[198:201], v[98:101]
	v_mfma_f32_16x16x32_bf16 v[86:89], v[174:177], v[210:213], v[86:89]
	v_mfma_f32_16x16x32_bf16 v[82:85], v[182:185], v[210:213], v[82:85]
	v_mfma_f32_16x16x32_bf16 v[70:73], v[174:177], v[218:221], v[70:73]
	v_mfma_f32_16x16x32_bf16 v[66:69], v[182:185], v[218:221], v[66:69]
	s_setprio 0
	s_barrier
	s_add_i32 s63, s45, s12
	v_lshl_add_u64 v[146:147], s[30:31], 0, v[134:135]
	s_mov_b32 m0, s63
	ds_read_b128 v[186:189], v152 offset:16384
	ds_read_b128 v[190:193], v152 offset:17408
	ds_read_b128 v[194:197], v152 offset:18432
	ds_read_b128 v[198:201], v152 offset:19456
	ds_read_b128 v[206:209], v152 offset:20480
	ds_read_b128 v[210:213], v152 offset:21504
	ds_read_b128 v[214:217], v152 offset:22528
	ds_read_b128 v[218:221], v152 offset:23552
	global_load_lds_dwordx4 v[146:147], off
	s_add_i32 m0, s63, 0x2000
	s_add_u32 s64, s30, 0x40000
	v_lshl_add_u64 v[202:203], s[30:31], 0, v[130:131]
	s_addc_u32 s65, s31, 0
	s_add_i32 s63, s46, s12
	global_load_lds_dwordx4 v[202:203], off
	v_lshl_add_u64 v[222:223], s[64:65], 0, v[134:135]
	s_mov_b32 m0, s63
	v_lshl_add_u64 v[224:225], s[36:37], 0, v[132:133]
	global_load_lds_dwordx4 v[222:223], off
	s_add_i32 m0, s63, 0x2000
	v_lshl_add_u64 v[222:223], s[64:65], 0, v[130:131]
	global_load_lds_dwordx4 v[222:223], off
	s_mov_b32 m0, s19
	v_lshl_add_u64 v[222:223], s[36:37], 0, v[136:137]
	global_load_lds_dwordx4 v[222:223], off
	s_mov_b32 m0, s33
	s_nop 0
	global_load_lds_dwordx4 v[224:225], off
	s_nop 0
	s_waitcnt vmcnt(8) lgkmcnt(0)
	s_setprio 1
	s_barrier
	v_mfma_f32_16x16x32_bf16 v[62:65], v[154:157], v[186:189], v[62:65]
	v_mfma_f32_16x16x32_bf16 v[58:61], v[162:165], v[186:189], v[58:61]
	v_mfma_f32_16x16x32_bf16 v[46:49], v[154:157], v[194:197], v[46:49]
	v_mfma_f32_16x16x32_bf16 v[42:45], v[162:165], v[194:197], v[42:45]
	v_mfma_f32_16x16x32_bf16 v[30:33], v[154:157], v[206:209], v[30:33]
	v_mfma_f32_16x16x32_bf16 v[26:29], v[162:165], v[206:209], v[26:29]
	v_mfma_f32_16x16x32_bf16 v[14:17], v[154:157], v[214:217], v[14:17]
	v_mfma_f32_16x16x32_bf16 v[10:13], v[162:165], v[214:217], v[10:13]
	v_mfma_f32_16x16x32_bf16 v[62:65], v[158:161], v[190:193], v[62:65]
	v_mfma_f32_16x16x32_bf16 v[58:61], v[166:169], v[190:193], v[58:61]
	v_mfma_f32_16x16x32_bf16 v[46:49], v[158:161], v[198:201], v[46:49]
	v_mfma_f32_16x16x32_bf16 v[42:45], v[166:169], v[198:201], v[42:45]
	v_mfma_f32_16x16x32_bf16 v[30:33], v[158:161], v[210:213], v[30:33]
	v_mfma_f32_16x16x32_bf16 v[26:29], v[166:169], v[210:213], v[26:29]
	v_mfma_f32_16x16x32_bf16 v[14:17], v[158:161], v[218:221], v[14:17]
	v_mfma_f32_16x16x32_bf16 v[10:13], v[166:169], v[218:221], v[10:13]
	v_mfma_f32_16x16x32_bf16 v[54:57], v[170:173], v[186:189], v[54:57]
	v_mfma_f32_16x16x32_bf16 v[50:53], v[178:181], v[186:189], v[50:53]
	v_mfma_f32_16x16x32_bf16 v[38:41], v[170:173], v[194:197], v[38:41]
	v_mfma_f32_16x16x32_bf16 v[34:37], v[178:181], v[194:197], v[34:37]
	v_mfma_f32_16x16x32_bf16 v[22:25], v[170:173], v[206:209], v[22:25]
	v_mfma_f32_16x16x32_bf16 v[18:21], v[178:181], v[206:209], v[18:21]
	v_mfma_f32_16x16x32_bf16 v[6:9], v[170:173], v[214:217], v[6:9]
	v_mfma_f32_16x16x32_bf16 v[2:5], v[178:181], v[214:217], v[2:5]
	v_mfma_f32_16x16x32_bf16 v[54:57], v[174:177], v[190:193], v[54:57]
	v_mfma_f32_16x16x32_bf16 v[50:53], v[182:185], v[190:193], v[50:53]
	v_mfma_f32_16x16x32_bf16 v[38:41], v[174:177], v[198:201], v[38:41]
	v_mfma_f32_16x16x32_bf16 v[34:37], v[182:185], v[198:201], v[34:37]
	v_mfma_f32_16x16x32_bf16 v[22:25], v[174:177], v[210:213], v[22:25]
	v_mfma_f32_16x16x32_bf16 v[18:21], v[182:185], v[210:213], v[18:21]
	v_mfma_f32_16x16x32_bf16 v[6:9], v[174:177], v[218:221], v[6:9]
	v_mfma_f32_16x16x32_bf16 v[2:5], v[182:185], v[218:221], v[2:5]
	s_setprio 0
	s_barrier
	s_add_i32 s63, 0, 0x18000
	v_add_u32_e32 v153, s63, v149
	s_add_i32 s64, 0, 0x1c000
	ds_read_b128 v[154:157], v153
	ds_read_b128 v[158:161], v153 offset:1024
	ds_read_b128 v[162:165], v153 offset:2048
	ds_read_b128 v[166:169], v153 offset:3072
	v_add_u32_e32 v153, s64, v149
	ds_read_b128 v[170:173], v153
	ds_read_b128 v[174:177], v153 offset:1024
	ds_read_b128 v[178:181], v153 offset:2048
	ds_read_b128 v[182:185], v153 offset:3072
	s_add_u32 s36, s36, 0x40000
	s_addc_u32 s37, s37, 0
	s_mov_b32 m0, s35
	v_lshl_add_u64 v[226:227], s[36:37], 0, v[136:137]
	ds_read_b128 v[186:189], v152 offset:32768
	ds_read_b128 v[190:193], v152 offset:33792
	ds_read_b128 v[194:197], v152 offset:34816
	ds_read_b128 v[198:201], v152 offset:35840
	ds_read_b128 v[206:209], v152 offset:36864
	ds_read_b128 v[210:213], v152 offset:37888
	ds_read_b128 v[214:217], v152 offset:38912
	ds_read_b128 v[218:221], v152 offset:39936
	global_load_lds_dwordx4 v[226:227], off
	s_mov_b32 m0, s38
	v_lshl_add_u64 v[226:227], s[36:37], 0, v[132:133]
	global_load_lds_dwordx4 v[226:227], off
	s_waitcnt vmcnt(8) lgkmcnt(0)
	s_setprio 1
	s_barrier
	v_mfma_f32_16x16x32_bf16 v[126:129], v[154:157], v[186:189], v[126:129]
	v_mfma_f32_16x16x32_bf16 v[122:125], v[162:165], v[186:189], v[122:125]
	v_mfma_f32_16x16x32_bf16 v[110:113], v[154:157], v[194:197], v[110:113]
	v_mfma_f32_16x16x32_bf16 v[106:109], v[162:165], v[194:197], v[106:109]
	v_mfma_f32_16x16x32_bf16 v[94:97], v[154:157], v[206:209], v[94:97]
	v_mfma_f32_16x16x32_bf16 v[90:93], v[162:165], v[206:209], v[90:93]
	v_mfma_f32_16x16x32_bf16 v[78:81], v[154:157], v[214:217], v[78:81]
	v_mfma_f32_16x16x32_bf16 v[74:77], v[162:165], v[214:217], v[74:77]
	v_mfma_f32_16x16x32_bf16 v[126:129], v[158:161], v[190:193], v[126:129]
	v_mfma_f32_16x16x32_bf16 v[122:125], v[166:169], v[190:193], v[122:125]
	v_mfma_f32_16x16x32_bf16 v[110:113], v[158:161], v[198:201], v[110:113]
	v_mfma_f32_16x16x32_bf16 v[106:109], v[166:169], v[198:201], v[106:109]
	v_mfma_f32_16x16x32_bf16 v[94:97], v[158:161], v[210:213], v[94:97]
	v_mfma_f32_16x16x32_bf16 v[90:93], v[166:169], v[210:213], v[90:93]
	v_mfma_f32_16x16x32_bf16 v[78:81], v[158:161], v[218:221], v[78:81]
	v_mfma_f32_16x16x32_bf16 v[74:77], v[166:169], v[218:221], v[74:77]
	v_mfma_f32_16x16x32_bf16 v[118:121], v[170:173], v[186:189], v[118:121]
	v_mfma_f32_16x16x32_bf16 v[114:117], v[178:181], v[186:189], v[114:117]
	v_mfma_f32_16x16x32_bf16 v[102:105], v[170:173], v[194:197], v[102:105]
	v_mfma_f32_16x16x32_bf16 v[98:101], v[178:181], v[194:197], v[98:101]
	v_mfma_f32_16x16x32_bf16 v[86:89], v[170:173], v[206:209], v[86:89]
	v_mfma_f32_16x16x32_bf16 v[82:85], v[178:181], v[206:209], v[82:85]
	v_mfma_f32_16x16x32_bf16 v[70:73], v[170:173], v[214:217], v[70:73]
	v_mfma_f32_16x16x32_bf16 v[66:69], v[178:181], v[214:217], v[66:69]
	v_mfma_f32_16x16x32_bf16 v[118:121], v[174:177], v[190:193], v[118:121]
	v_mfma_f32_16x16x32_bf16 v[114:117], v[182:185], v[190:193], v[114:117]
	v_mfma_f32_16x16x32_bf16 v[102:105], v[174:177], v[198:201], v[102:105]
	v_mfma_f32_16x16x32_bf16 v[98:101], v[182:185], v[198:201], v[98:101]
	v_mfma_f32_16x16x32_bf16 v[86:89], v[174:177], v[210:213], v[86:89]
	v_mfma_f32_16x16x32_bf16 v[82:85], v[182:185], v[210:213], v[82:85]
	v_mfma_f32_16x16x32_bf16 v[70:73], v[174:177], v[218:221], v[70:73]
	v_mfma_f32_16x16x32_bf16 v[66:69], v[182:185], v[218:221], v[66:69]
	s_setprio 0
	s_barrier
	s_add_i32 s36, s63, s12
	v_lshl_add_u64 v[146:147], v[146:147], 0, s[8:9]
	s_mov_b32 m0, s36
	ds_read_b128 v[186:189], v152 offset:49152
	ds_read_b128 v[190:193], v152 offset:50176
	ds_read_b128 v[194:197], v152 offset:51200
	ds_read_b128 v[198:201], v152 offset:52224
	ds_read_b128 v[206:209], v152 offset:53248
	ds_read_b128 v[210:213], v152 offset:54272
	ds_read_b128 v[214:217], v152 offset:55296
	ds_read_b128 v[218:221], v152 offset:56320
	global_load_lds_dwordx4 v[146:147], off
	s_add_i32 m0, s36, 0x2000
	s_add_u32 s30, s30, 0x40080
	v_lshl_add_u64 v[146:147], v[202:203], 0, s[8:9]
	s_addc_u32 s31, s31, 0
	s_add_i32 s36, s64, s12
	global_load_lds_dwordx4 v[146:147], off
	s_mov_b32 m0, s36
	v_lshl_add_u64 v[146:147], s[30:31], 0, v[134:135]
	global_load_lds_dwordx4 v[146:147], off
	s_add_i32 m0, s36, 0x2000
	v_lshl_add_u64 v[146:147], s[30:31], 0, v[130:131]
	global_load_lds_dwordx4 v[146:147], off
	s_mov_b32 m0, s42
	v_lshl_add_u64 v[146:147], v[222:223], 0, s[8:9]
	global_load_lds_dwordx4 v[146:147], off
	s_mov_b32 m0, s43
	v_lshl_add_u64 v[146:147], v[224:225], 0, s[8:9]
	global_load_lds_dwordx4 v[146:147], off
	s_waitcnt vmcnt(8) lgkmcnt(0)
	s_setprio 1
	s_barrier
	v_mfma_f32_16x16x32_bf16 v[62:65], v[154:157], v[186:189], v[62:65]
	v_mfma_f32_16x16x32_bf16 v[58:61], v[162:165], v[186:189], v[58:61]
	v_mfma_f32_16x16x32_bf16 v[46:49], v[154:157], v[194:197], v[46:49]
	v_mfma_f32_16x16x32_bf16 v[42:45], v[162:165], v[194:197], v[42:45]
	v_mfma_f32_16x16x32_bf16 v[30:33], v[154:157], v[206:209], v[30:33]
	v_mfma_f32_16x16x32_bf16 v[26:29], v[162:165], v[206:209], v[26:29]
	v_mfma_f32_16x16x32_bf16 v[14:17], v[154:157], v[214:217], v[14:17]
	v_mfma_f32_16x16x32_bf16 v[10:13], v[162:165], v[214:217], v[10:13]
	v_mfma_f32_16x16x32_bf16 v[62:65], v[158:161], v[190:193], v[62:65]
	v_mfma_f32_16x16x32_bf16 v[58:61], v[166:169], v[190:193], v[58:61]
	v_mfma_f32_16x16x32_bf16 v[46:49], v[158:161], v[198:201], v[46:49]
	v_mfma_f32_16x16x32_bf16 v[42:45], v[166:169], v[198:201], v[42:45]
	v_mfma_f32_16x16x32_bf16 v[30:33], v[158:161], v[210:213], v[30:33]
	v_mfma_f32_16x16x32_bf16 v[26:29], v[166:169], v[210:213], v[26:29]
	v_mfma_f32_16x16x32_bf16 v[14:17], v[158:161], v[218:221], v[14:17]
	v_mfma_f32_16x16x32_bf16 v[10:13], v[166:169], v[218:221], v[10:13]
	v_mfma_f32_16x16x32_bf16 v[54:57], v[170:173], v[186:189], v[54:57]
	v_mfma_f32_16x16x32_bf16 v[50:53], v[178:181], v[186:189], v[50:53]
	v_mfma_f32_16x16x32_bf16 v[38:41], v[170:173], v[194:197], v[38:41]
	v_mfma_f32_16x16x32_bf16 v[34:37], v[178:181], v[194:197], v[34:37]
	v_mfma_f32_16x16x32_bf16 v[22:25], v[170:173], v[206:209], v[22:25]
	v_mfma_f32_16x16x32_bf16 v[18:21], v[178:181], v[206:209], v[18:21]
	v_mfma_f32_16x16x32_bf16 v[6:9], v[170:173], v[214:217], v[6:9]
	v_mfma_f32_16x16x32_bf16 v[2:5], v[178:181], v[214:217], v[2:5]
	v_mfma_f32_16x16x32_bf16 v[54:57], v[174:177], v[190:193], v[54:57]
	v_mfma_f32_16x16x32_bf16 v[50:53], v[182:185], v[190:193], v[50:53]
	v_mfma_f32_16x16x32_bf16 v[38:41], v[174:177], v[198:201], v[38:41]
	v_mfma_f32_16x16x32_bf16 v[34:37], v[182:185], v[198:201], v[34:37]
	v_mfma_f32_16x16x32_bf16 v[22:25], v[174:177], v[210:213], v[22:25]
	v_mfma_f32_16x16x32_bf16 v[18:21], v[182:185], v[210:213], v[18:21]
	v_mfma_f32_16x16x32_bf16 v[6:9], v[174:177], v[218:221], v[6:9]
	v_mfma_f32_16x16x32_bf16 v[2:5], v[182:185], v[218:221], v[2:5]
	s_setprio 0
	s_barrier
	s_add_i32 s62, s62, 2
	s_add_u32 s28, s28, 0x100
	s_addc_u32 s29, s29, 0
	s_add_u32 s50, s50, 0x100
	s_addc_u32 s51, s51, 0
	s_cmp_gt_u32 s62, 13
	s_cbranch_scc0 .LBB0_1619
	s_and_b64 vcc, exec, s[10:11]
	s_cbranch_vccz .LBB0_1622
	s_barrier

.LBB0_1707:
	v_readlane_b32 s46, v249, 32
	v_readlane_b32 s47, v249, 33
	s_add_u32 s46, s46, s42
	s_addc_u32 s47, s47, s43
	s_and_b64 s[48:49], s[44:45], exec
	s_cselect_b32 s34, s47, s51
	s_cselect_b32 s66, s46, s50
	s_add_u32 s48, s35, s40
	s_addc_u32 s49, s70, s41
	s_and_b64 s[64:65], s[44:45], exec
	s_cselect_b32 s67, s49, s63
	s_cselect_b32 s68, s48, s62
	s_add_i32 s69, s7, -2
	s_add_u32 s50, s50, 0x100080
	s_addc_u32 s51, s51, 0
	s_add_u32 s91, s62, 0x100
	s_addc_u32 s92, s63, 0
	s_mov_b32 s62, 0
	s_waitcnt vmcnt(0)
	ds_read_b128 v[130:133], v168
	ds_read_b128 v[134:137], v168 offset:1024
	ds_read_b128 v[138:141], v168 offset:2048
	ds_read_b128 v[142:145], v168 offset:3072
	ds_read_b128 v[162:165], v169
	ds_read_b128 v[172:175], v169 offset:1024
	ds_read_b128 v[176:179], v169 offset:2048
	ds_read_b128 v[180:183], v169 offset:3072
	s_add_i32 s93, s62, 2
	s_add_u32 s63, s50, 0xfff00080
	s_addc_u32 s64, s51, -1
	s_cmp_eq_u32 s69, s62
	s_cselect_b32 s62, s68, s91
	s_cselect_b32 s65, s34, s64
	s_cselect_b32 s64, s66, s63
	s_cselect_b32 s63, s67, s92
	v_lshl_add_u64 v[218:219], s[50:51], 0, v[156:157]
	s_add_i32 m0, s12, 0xc000
	ds_read_b128 v[184:187], v170
	ds_read_b128 v[188:191], v170 offset:1024
	ds_read_b128 v[192:195], v170 offset:2048
	ds_read_b128 v[196:199], v170 offset:3072
	ds_read_b128 v[200:203], v170 offset:4096
	ds_read_b128 v[206:209], v170 offset:5120
	ds_read_b128 v[210:213], v170 offset:6144
	ds_read_b128 v[214:217], v170 offset:7168
	global_load_lds_dwordx4 v[218:219], off
	s_add_i32 m0, s12, 0xe000
	v_lshl_add_u64 v[218:219], s[50:51], 0, v[158:159]
	global_load_lds_dwordx4 v[218:219], off
	s_nop 0
	s_waitcnt vmcnt(8) lgkmcnt(0)
	s_setprio 1
	s_barrier
	v_mfma_f32_16x16x32_bf16 v[126:129], v[130:133], v[184:187], 0
	v_mfma_f32_16x16x32_bf16 v[122:125], v[138:141], v[184:187], 0
	v_mfma_f32_16x16x32_bf16 v[110:113], v[130:133], v[192:195], 0
	v_mfma_f32_16x16x32_bf16 v[106:109], v[138:141], v[192:195], 0
	v_mfma_f32_16x16x32_bf16 v[98:101], v[130:133], v[200:203], 0
	v_mfma_f32_16x16x32_bf16 v[90:93], v[138:141], v[200:203], 0
	v_mfma_f32_16x16x32_bf16 v[82:85], v[130:133], v[210:213], 0
	v_mfma_f32_16x16x32_bf16 v[74:77], v[138:141], v[210:213], 0
	v_mfma_f32_16x16x32_bf16 v[126:129], v[134:137], v[188:191], v[126:129]
	v_mfma_f32_16x16x32_bf16 v[122:125], v[142:145], v[188:191], v[122:125]
	v_mfma_f32_16x16x32_bf16 v[110:113], v[134:137], v[196:199], v[110:113]
	v_mfma_f32_16x16x32_bf16 v[106:109], v[142:145], v[196:199], v[106:109]
	v_mfma_f32_16x16x32_bf16 v[98:101], v[134:137], v[206:209], v[98:101]
	v_mfma_f32_16x16x32_bf16 v[90:93], v[142:145], v[206:209], v[90:93]
	v_mfma_f32_16x16x32_bf16 v[82:85], v[134:137], v[214:217], v[82:85]
	v_mfma_f32_16x16x32_bf16 v[74:77], v[142:145], v[214:217], v[74:77]
	v_mfma_f32_16x16x32_bf16 v[118:121], v[162:165], v[184:187], 0
	v_mfma_f32_16x16x32_bf16 v[114:117], v[176:179], v[184:187], 0
	v_mfma_f32_16x16x32_bf16 v[102:105], v[162:165], v[192:195], 0
	v_mfma_f32_16x16x32_bf16 v[94:97], v[176:179], v[192:195], 0
	v_mfma_f32_16x16x32_bf16 v[86:89], v[162:165], v[200:203], 0
	v_mfma_f32_16x16x32_bf16 v[78:81], v[176:179], v[200:203], 0
	v_mfma_f32_16x16x32_bf16 v[70:73], v[162:165], v[210:213], 0
	v_mfma_f32_16x16x32_bf16 v[66:69], v[176:179], v[210:213], 0
	v_mfma_f32_16x16x32_bf16 v[118:121], v[172:175], v[188:191], v[118:121]
	v_mfma_f32_16x16x32_bf16 v[114:117], v[180:183], v[188:191], v[114:117]
	v_mfma_f32_16x16x32_bf16 v[102:105], v[172:175], v[196:199], v[102:105]
	v_mfma_f32_16x16x32_bf16 v[94:97], v[180:183], v[196:199], v[94:97]
	v_mfma_f32_16x16x32_bf16 v[86:89], v[172:175], v[206:209], v[86:89]
	v_mfma_f32_16x16x32_bf16 v[78:81], v[180:183], v[206:209], v[78:81]
	v_mfma_f32_16x16x32_bf16 v[70:73], v[172:175], v[214:217], v[70:73]
	v_mfma_f32_16x16x32_bf16 v[66:69], v[180:183], v[214:217], v[66:69]
	s_setprio 0
	s_barrier
	s_add_i32 s94, s31, s2
	v_lshl_add_u64 v[218:219], s[62:63], 0, v[148:149]
	s_mov_b32 m0, s94
	ds_read_b128 v[184:187], v170 offset:16384
	ds_read_b128 v[188:191], v170 offset:17408
	ds_read_b128 v[192:195], v170 offset:18432
	ds_read_b128 v[196:199], v170 offset:19456
	ds_read_b128 v[200:203], v170 offset:20480
	ds_read_b128 v[206:209], v170 offset:21504
	ds_read_b128 v[210:213], v170 offset:22528
	ds_read_b128 v[214:217], v170 offset:23552
	global_load_lds_dwordx4 v[218:219], off
	s_add_i32 m0, s94, 0x2000
	s_add_u32 s94, s62, 0x100000
	v_lshl_add_u64 v[220:221], s[62:63], 0, v[152:153]
	s_addc_u32 s95, s63, 0
	s_add_i32 s96, s82, s2
	global_load_lds_dwordx4 v[220:221], off
	v_lshl_add_u64 v[222:223], s[94:95], 0, v[148:149]
	s_mov_b32 m0, s96
	v_lshl_add_u64 v[224:225], s[64:65], 0, v[150:151]
	global_load_lds_dwordx4 v[222:223], off
	s_add_i32 m0, s96, 0x2000
	v_lshl_add_u64 v[222:223], s[94:95], 0, v[152:153]
	global_load_lds_dwordx4 v[222:223], off
	s_mov_b32 m0, s12
	v_lshl_add_u64 v[222:223], s[64:65], 0, v[146:147]
	global_load_lds_dwordx4 v[222:223], off
	s_mov_b32 m0, s13
	s_nop 0
	global_load_lds_dwordx4 v[224:225], off
	s_nop 0
	s_waitcnt vmcnt(8) lgkmcnt(0)
	s_setprio 1
	s_barrier
	v_mfma_f32_16x16x32_bf16 v[62:65], v[130:133], v[184:187], 0
	v_mfma_f32_16x16x32_bf16 v[58:61], v[138:141], v[184:187], 0
	v_mfma_f32_16x16x32_bf16 v[50:53], v[130:133], v[192:195], 0
	v_mfma_f32_16x16x32_bf16 v[42:45], v[138:141], v[192:195], 0
	v_mfma_f32_16x16x32_bf16 v[34:37], v[130:133], v[200:203], 0
	v_mfma_f32_16x16x32_bf16 v[26:29], v[138:141], v[200:203], 0
	v_mfma_f32_16x16x32_bf16 v[18:21], v[130:133], v[210:213], 0
	v_mfma_f32_16x16x32_bf16 v[10:13], v[138:141], v[210:213], 0
	v_mfma_f32_16x16x32_bf16 v[62:65], v[134:137], v[188:191], v[62:65]
	v_mfma_f32_16x16x32_bf16 v[58:61], v[142:145], v[188:191], v[58:61]
	v_mfma_f32_16x16x32_bf16 v[50:53], v[134:137], v[196:199], v[50:53]
	v_mfma_f32_16x16x32_bf16 v[42:45], v[142:145], v[196:199], v[42:45]
	v_mfma_f32_16x16x32_bf16 v[34:37], v[134:137], v[206:209], v[34:37]
	v_mfma_f32_16x16x32_bf16 v[26:29], v[142:145], v[206:209], v[26:29]
	v_mfma_f32_16x16x32_bf16 v[18:21], v[134:137], v[214:217], v[18:21]
	v_mfma_f32_16x16x32_bf16 v[10:13], v[142:145], v[214:217], v[10:13]
	v_mfma_f32_16x16x32_bf16 v[54:57], v[162:165], v[184:187], 0
	v_mfma_f32_16x16x32_bf16 v[46:49], v[176:179], v[184:187], 0
	v_mfma_f32_16x16x32_bf16 v[38:41], v[162:165], v[192:195], 0
	v_mfma_f32_16x16x32_bf16 v[30:33], v[176:179], v[192:195], 0
	v_mfma_f32_16x16x32_bf16 v[22:25], v[162:165], v[200:203], 0
	v_mfma_f32_16x16x32_bf16 v[14:17], v[176:179], v[200:203], 0
	v_mfma_f32_16x16x32_bf16 v[6:9], v[162:165], v[210:213], 0
	v_mfma_f32_16x16x32_bf16 v[2:5], v[176:179], v[210:213], 0
	v_mfma_f32_16x16x32_bf16 v[54:57], v[172:175], v[188:191], v[54:57]
	v_mfma_f32_16x16x32_bf16 v[46:49], v[180:183], v[188:191], v[46:49]
	v_mfma_f32_16x16x32_bf16 v[38:41], v[172:175], v[196:199], v[38:41]
	v_mfma_f32_16x16x32_bf16 v[30:33], v[180:183], v[196:199], v[30:33]
	v_mfma_f32_16x16x32_bf16 v[22:25], v[172:175], v[206:209], v[22:25]
	v_mfma_f32_16x16x32_bf16 v[14:17], v[180:183], v[206:209], v[14:17]
	v_mfma_f32_16x16x32_bf16 v[6:9], v[172:175], v[214:217], v[6:9]
	v_mfma_f32_16x16x32_bf16 v[2:5], v[180:183], v[214:217], v[2:5]
	s_setprio 0
	s_barrier
	s_add_i32 s94, 0, 0x18000
	s_add_i32 s95, 0, 0x1c000
	v_add_u32_e32 v142, s94, v167
	v_add_u32_e32 v154, s95, v167
	ds_read_b128 v[130:133], v142
	ds_read_b128 v[134:137], v142 offset:1024
	ds_read_b128 v[138:141], v142 offset:2048
	ds_read_b128 v[142:145], v142 offset:3072
	ds_read_b128 v[162:165], v154
	ds_read_b128 v[172:175], v154 offset:1024
	ds_read_b128 v[176:179], v154 offset:2048
	ds_read_b128 v[180:183], v154 offset:3072
	s_add_u32 s64, s64, 0x100000
	s_addc_u32 s65, s65, 0
	s_mov_b32 m0, s18
	v_lshl_add_u64 v[226:227], s[64:65], 0, v[146:147]
	ds_read_b128 v[184:187], v170 offset:32768
	ds_read_b128 v[188:191], v170 offset:33792
	ds_read_b128 v[192:195], v170 offset:34816
	ds_read_b128 v[196:199], v170 offset:35840
	ds_read_b128 v[200:203], v170 offset:36864
	ds_read_b128 v[206:209], v170 offset:37888
	ds_read_b128 v[210:213], v170 offset:38912
	ds_read_b128 v[214:217], v170 offset:39936
	global_load_lds_dwordx4 v[226:227], off
	s_mov_b32 m0, s19
	v_lshl_add_u64 v[226:227], s[64:65], 0, v[150:151]
	global_load_lds_dwordx4 v[226:227], off
	s_waitcnt vmcnt(8) lgkmcnt(0)
	s_setprio 1
	s_barrier
	v_mfma_f32_16x16x32_bf16 v[126:129], v[130:133], v[184:187], v[126:129]
	v_mfma_f32_16x16x32_bf16 v[122:125], v[138:141], v[184:187], v[122:125]
	v_mfma_f32_16x16x32_bf16 v[110:113], v[130:133], v[192:195], v[110:113]
	v_mfma_f32_16x16x32_bf16 v[106:109], v[138:141], v[192:195], v[106:109]
	v_mfma_f32_16x16x32_bf16 v[98:101], v[130:133], v[200:203], v[98:101]
	v_mfma_f32_16x16x32_bf16 v[90:93], v[138:141], v[200:203], v[90:93]
	v_mfma_f32_16x16x32_bf16 v[82:85], v[130:133], v[210:213], v[82:85]
	v_mfma_f32_16x16x32_bf16 v[74:77], v[138:141], v[210:213], v[74:77]
	v_mfma_f32_16x16x32_bf16 v[126:129], v[134:137], v[188:191], v[126:129]
	v_mfma_f32_16x16x32_bf16 v[122:125], v[142:145], v[188:191], v[122:125]
	v_mfma_f32_16x16x32_bf16 v[110:113], v[134:137], v[196:199], v[110:113]
	v_mfma_f32_16x16x32_bf16 v[106:109], v[142:145], v[196:199], v[106:109]
	v_mfma_f32_16x16x32_bf16 v[98:101], v[134:137], v[206:209], v[98:101]
	v_mfma_f32_16x16x32_bf16 v[90:93], v[142:145], v[206:209], v[90:93]
	v_mfma_f32_16x16x32_bf16 v[82:85], v[134:137], v[214:217], v[82:85]
	v_mfma_f32_16x16x32_bf16 v[74:77], v[142:145], v[214:217], v[74:77]
	v_mfma_f32_16x16x32_bf16 v[118:121], v[162:165], v[184:187], v[118:121]
	v_mfma_f32_16x16x32_bf16 v[114:117], v[176:179], v[184:187], v[114:117]
	v_mfma_f32_16x16x32_bf16 v[102:105], v[162:165], v[192:195], v[102:105]
	v_mfma_f32_16x16x32_bf16 v[94:97], v[176:179], v[192:195], v[94:97]
	v_mfma_f32_16x16x32_bf16 v[86:89], v[162:165], v[200:203], v[86:89]
	v_mfma_f32_16x16x32_bf16 v[78:81], v[176:179], v[200:203], v[78:81]
	v_mfma_f32_16x16x32_bf16 v[70:73], v[162:165], v[210:213], v[70:73]
	v_mfma_f32_16x16x32_bf16 v[66:69], v[176:179], v[210:213], v[66:69]
	v_mfma_f32_16x16x32_bf16 v[118:121], v[172:175], v[188:191], v[118:121]
	v_mfma_f32_16x16x32_bf16 v[114:117], v[180:183], v[188:191], v[114:117]
	v_mfma_f32_16x16x32_bf16 v[102:105], v[172:175], v[196:199], v[102:105]
	v_mfma_f32_16x16x32_bf16 v[94:97], v[180:183], v[196:199], v[94:97]
	v_mfma_f32_16x16x32_bf16 v[86:89], v[172:175], v[206:209], v[86:89]
	v_mfma_f32_16x16x32_bf16 v[78:81], v[180:183], v[206:209], v[78:81]
	v_mfma_f32_16x16x32_bf16 v[70:73], v[172:175], v[214:217], v[70:73]
	v_mfma_f32_16x16x32_bf16 v[66:69], v[180:183], v[214:217], v[66:69]
	s_setprio 0
	s_barrier
	s_add_i32 s64, s94, s2
	v_lshl_add_u64 v[218:219], v[218:219], 0, s[16:17]
	s_mov_b32 m0, s64
	ds_read_b128 v[184:187], v170 offset:49152
	ds_read_b128 v[188:191], v170 offset:50176
	ds_read_b128 v[192:195], v170 offset:51200
	ds_read_b128 v[196:199], v170 offset:52224
	ds_read_b128 v[200:203], v170 offset:53248
	ds_read_b128 v[206:209], v170 offset:54272
	ds_read_b128 v[210:213], v170 offset:55296
	ds_read_b128 v[214:217], v170 offset:56320
	global_load_lds_dwordx4 v[218:219], off
	s_add_i32 m0, s64, 0x2000
	s_add_u32 s62, s62, 0x100080
	v_lshl_add_u64 v[218:219], v[220:221], 0, s[16:17]
	s_addc_u32 s63, s63, 0
	s_add_i32 s64, s95, s2
	global_load_lds_dwordx4 v[218:219], off
	s_mov_b32 m0, s64
	v_lshl_add_u64 v[218:219], s[62:63], 0, v[148:149]
	global_load_lds_dwordx4 v[218:219], off
	s_add_i32 m0, s64, 0x2000
	v_lshl_add_u64 v[218:219], s[62:63], 0, v[152:153]
	global_load_lds_dwordx4 v[218:219], off
	s_mov_b32 m0, s74
	v_lshl_add_u64 v[218:219], v[222:223], 0, s[16:17]
	global_load_lds_dwordx4 v[218:219], off
	s_mov_b32 m0, s75
	v_lshl_add_u64 v[218:219], v[224:225], 0, s[16:17]
	global_load_lds_dwordx4 v[218:219], off
	s_waitcnt vmcnt(8) lgkmcnt(0)
	s_setprio 1
	s_barrier
	v_mfma_f32_16x16x32_bf16 v[62:65], v[130:133], v[184:187], v[62:65]
	v_mfma_f32_16x16x32_bf16 v[58:61], v[138:141], v[184:187], v[58:61]
	v_mfma_f32_16x16x32_bf16 v[50:53], v[130:133], v[192:195], v[50:53]
	v_mfma_f32_16x16x32_bf16 v[42:45], v[138:141], v[192:195], v[42:45]
	v_mfma_f32_16x16x32_bf16 v[34:37], v[130:133], v[200:203], v[34:37]
	v_mfma_f32_16x16x32_bf16 v[26:29], v[138:141], v[200:203], v[26:29]
	v_mfma_f32_16x16x32_bf16 v[18:21], v[130:133], v[210:213], v[18:21]
	v_mfma_f32_16x16x32_bf16 v[10:13], v[138:141], v[210:213], v[10:13]
	v_mfma_f32_16x16x32_bf16 v[62:65], v[134:137], v[188:191], v[62:65]
	v_mfma_f32_16x16x32_bf16 v[58:61], v[142:145], v[188:191], v[58:61]
	v_mfma_f32_16x16x32_bf16 v[50:53], v[134:137], v[196:199], v[50:53]
	v_mfma_f32_16x16x32_bf16 v[42:45], v[142:145], v[196:199], v[42:45]
	v_mfma_f32_16x16x32_bf16 v[34:37], v[134:137], v[206:209], v[34:37]
	v_mfma_f32_16x16x32_bf16 v[26:29], v[142:145], v[206:209], v[26:29]
	v_mfma_f32_16x16x32_bf16 v[18:21], v[134:137], v[214:217], v[18:21]
	v_mfma_f32_16x16x32_bf16 v[10:13], v[142:145], v[214:217], v[10:13]
	v_mfma_f32_16x16x32_bf16 v[54:57], v[162:165], v[184:187], v[54:57]
	v_mfma_f32_16x16x32_bf16 v[46:49], v[176:179], v[184:187], v[46:49]
	v_mfma_f32_16x16x32_bf16 v[38:41], v[162:165], v[192:195], v[38:41]
	v_mfma_f32_16x16x32_bf16 v[30:33], v[176:179], v[192:195], v[30:33]
	v_mfma_f32_16x16x32_bf16 v[22:25], v[162:165], v[200:203], v[22:25]
	v_mfma_f32_16x16x32_bf16 v[14:17], v[176:179], v[200:203], v[14:17]
	v_mfma_f32_16x16x32_bf16 v[6:9], v[162:165], v[210:213], v[6:9]
	v_mfma_f32_16x16x32_bf16 v[2:5], v[176:179], v[210:213], v[2:5]
	v_mfma_f32_16x16x32_bf16 v[54:57], v[172:175], v[188:191], v[54:57]
	v_mfma_f32_16x16x32_bf16 v[46:49], v[180:183], v[188:191], v[46:49]
	v_mfma_f32_16x16x32_bf16 v[38:41], v[172:175], v[196:199], v[38:41]
	v_mfma_f32_16x16x32_bf16 v[30:33], v[180:183], v[196:199], v[30:33]
	v_mfma_f32_16x16x32_bf16 v[22:25], v[172:175], v[206:209], v[22:25]
	v_mfma_f32_16x16x32_bf16 v[14:17], v[180:183], v[206:209], v[14:17]
	v_mfma_f32_16x16x32_bf16 v[6:9], v[172:175], v[214:217], v[6:9]
	v_mfma_f32_16x16x32_bf16 v[2:5], v[180:183], v[214:217], v[2:5]
	s_setprio 0
	s_barrier
	s_add_u32 s50, s50, 0x100
	s_addc_u32 s51, s51, 0
	s_add_u32 s91, s91, 0x100
	s_addc_u32 s92, s92, 0
	s_cmp_ge_i32 s93, s7
	s_mov_b32 s62, s93
.LBB0_1708:
	ds_read_b128 v[130:133], v168
	ds_read_b128 v[134:137], v168 offset:1024
	ds_read_b128 v[138:141], v168 offset:2048
	ds_read_b128 v[142:145], v168 offset:3072
	ds_read_b128 v[162:165], v169
	ds_read_b128 v[172:175], v169 offset:1024
	ds_read_b128 v[176:179], v169 offset:2048
	ds_read_b128 v[180:183], v169 offset:3072
	s_add_i32 s93, s62, 2
	s_add_u32 s63, s50, 0xfff00080
	s_addc_u32 s64, s51, -1
	s_cmp_eq_u32 s69, s62
	s_cselect_b32 s62, s68, s91
	s_cselect_b32 s65, s34, s64
	s_cselect_b32 s64, s66, s63
	s_cselect_b32 s63, s67, s92
	v_lshl_add_u64 v[218:219], s[50:51], 0, v[156:157]
	s_add_i32 m0, s12, 0xc000
	ds_read_b128 v[184:187], v170
	ds_read_b128 v[188:191], v170 offset:1024
	ds_read_b128 v[192:195], v170 offset:2048
	ds_read_b128 v[196:199], v170 offset:3072
	ds_read_b128 v[200:203], v170 offset:4096
	ds_read_b128 v[206:209], v170 offset:5120
	ds_read_b128 v[210:213], v170 offset:6144
	ds_read_b128 v[214:217], v170 offset:7168
	global_load_lds_dwordx4 v[218:219], off
	s_add_i32 m0, s12, 0xe000
	v_lshl_add_u64 v[218:219], s[50:51], 0, v[158:159]
	global_load_lds_dwordx4 v[218:219], off
	s_waitcnt vmcnt(8) lgkmcnt(0)
	s_setprio 1
	s_barrier
	v_mfma_f32_16x16x32_bf16 v[126:129], v[130:133], v[184:187], v[126:129]
	v_mfma_f32_16x16x32_bf16 v[122:125], v[138:141], v[184:187], v[122:125]
	v_mfma_f32_16x16x32_bf16 v[110:113], v[130:133], v[192:195], v[110:113]
	v_mfma_f32_16x16x32_bf16 v[106:109], v[138:141], v[192:195], v[106:109]
	v_mfma_f32_16x16x32_bf16 v[98:101], v[130:133], v[200:203], v[98:101]
	v_mfma_f32_16x16x32_bf16 v[90:93], v[138:141], v[200:203], v[90:93]
	v_mfma_f32_16x16x32_bf16 v[82:85], v[130:133], v[210:213], v[82:85]
	v_mfma_f32_16x16x32_bf16 v[74:77], v[138:141], v[210:213], v[74:77]
	v_mfma_f32_16x16x32_bf16 v[126:129], v[134:137], v[188:191], v[126:129]
	v_mfma_f32_16x16x32_bf16 v[122:125], v[142:145], v[188:191], v[122:125]
	v_mfma_f32_16x16x32_bf16 v[110:113], v[134:137], v[196:199], v[110:113]
	v_mfma_f32_16x16x32_bf16 v[106:109], v[142:145], v[196:199], v[106:109]
	v_mfma_f32_16x16x32_bf16 v[98:101], v[134:137], v[206:209], v[98:101]
	v_mfma_f32_16x16x32_bf16 v[90:93], v[142:145], v[206:209], v[90:93]
	v_mfma_f32_16x16x32_bf16 v[82:85], v[134:137], v[214:217], v[82:85]
	v_mfma_f32_16x16x32_bf16 v[74:77], v[142:145], v[214:217], v[74:77]
	v_mfma_f32_16x16x32_bf16 v[118:121], v[162:165], v[184:187], v[118:121]
	v_mfma_f32_16x16x32_bf16 v[114:117], v[176:179], v[184:187], v[114:117]
	v_mfma_f32_16x16x32_bf16 v[102:105], v[162:165], v[192:195], v[102:105]
	v_mfma_f32_16x16x32_bf16 v[94:97], v[176:179], v[192:195], v[94:97]
	v_mfma_f32_16x16x32_bf16 v[86:89], v[162:165], v[200:203], v[86:89]
	v_mfma_f32_16x16x32_bf16 v[78:81], v[176:179], v[200:203], v[78:81]
	v_mfma_f32_16x16x32_bf16 v[70:73], v[162:165], v[210:213], v[70:73]
	v_mfma_f32_16x16x32_bf16 v[66:69], v[176:179], v[210:213], v[66:69]
	v_mfma_f32_16x16x32_bf16 v[118:121], v[172:175], v[188:191], v[118:121]
	v_mfma_f32_16x16x32_bf16 v[114:117], v[180:183], v[188:191], v[114:117]
	v_mfma_f32_16x16x32_bf16 v[102:105], v[172:175], v[196:199], v[102:105]
	v_mfma_f32_16x16x32_bf16 v[94:97], v[180:183], v[196:199], v[94:97]
	v_mfma_f32_16x16x32_bf16 v[86:89], v[172:175], v[206:209], v[86:89]
	v_mfma_f32_16x16x32_bf16 v[78:81], v[180:183], v[206:209], v[78:81]
	v_mfma_f32_16x16x32_bf16 v[70:73], v[172:175], v[214:217], v[70:73]
	v_mfma_f32_16x16x32_bf16 v[66:69], v[180:183], v[214:217], v[66:69]
	s_setprio 0
	s_barrier
	s_add_i32 s94, s31, s2
	v_lshl_add_u64 v[218:219], s[62:63], 0, v[148:149]
	s_mov_b32 m0, s94
	ds_read_b128 v[184:187], v170 offset:16384
	ds_read_b128 v[188:191], v170 offset:17408
	ds_read_b128 v[192:195], v170 offset:18432
	ds_read_b128 v[196:199], v170 offset:19456
	ds_read_b128 v[200:203], v170 offset:20480
	ds_read_b128 v[206:209], v170 offset:21504
	ds_read_b128 v[210:213], v170 offset:22528
	ds_read_b128 v[214:217], v170 offset:23552
	global_load_lds_dwordx4 v[218:219], off
	s_add_i32 m0, s94, 0x2000
	s_add_u32 s94, s62, 0x100000
	v_lshl_add_u64 v[220:221], s[62:63], 0, v[152:153]
	s_addc_u32 s95, s63, 0
	s_add_i32 s96, s82, s2
	global_load_lds_dwordx4 v[220:221], off
	v_lshl_add_u64 v[222:223], s[94:95], 0, v[148:149]
	s_mov_b32 m0, s96
	v_lshl_add_u64 v[224:225], s[64:65], 0, v[150:151]
	global_load_lds_dwordx4 v[222:223], off
	s_add_i32 m0, s96, 0x2000
	v_lshl_add_u64 v[222:223], s[94:95], 0, v[152:153]
	global_load_lds_dwordx4 v[222:223], off
	s_mov_b32 m0, s12
	v_lshl_add_u64 v[222:223], s[64:65], 0, v[146:147]
	global_load_lds_dwordx4 v[222:223], off
	s_mov_b32 m0, s13
	s_nop 0
	global_load_lds_dwordx4 v[224:225], off
	s_nop 0
	s_waitcnt vmcnt(8) lgkmcnt(0)
	s_setprio 1
	s_barrier
	v_mfma_f32_16x16x32_bf16 v[62:65], v[130:133], v[184:187], v[62:65]
	v_mfma_f32_16x16x32_bf16 v[58:61], v[138:141], v[184:187], v[58:61]
	v_mfma_f32_16x16x32_bf16 v[50:53], v[130:133], v[192:195], v[50:53]
	v_mfma_f32_16x16x32_bf16 v[42:45], v[138:141], v[192:195], v[42:45]
	v_mfma_f32_16x16x32_bf16 v[34:37], v[130:133], v[200:203], v[34:37]
	v_mfma_f32_16x16x32_bf16 v[26:29], v[138:141], v[200:203], v[26:29]
	v_mfma_f32_16x16x32_bf16 v[18:21], v[130:133], v[210:213], v[18:21]
	v_mfma_f32_16x16x32_bf16 v[10:13], v[138:141], v[210:213], v[10:13]
	v_mfma_f32_16x16x32_bf16 v[62:65], v[134:137], v[188:191], v[62:65]
	v_mfma_f32_16x16x32_bf16 v[58:61], v[142:145], v[188:191], v[58:61]
	v_mfma_f32_16x16x32_bf16 v[50:53], v[134:137], v[196:199], v[50:53]
	v_mfma_f32_16x16x32_bf16 v[42:45], v[142:145], v[196:199], v[42:45]
	v_mfma_f32_16x16x32_bf16 v[34:37], v[134:137], v[206:209], v[34:37]
	v_mfma_f32_16x16x32_bf16 v[26:29], v[142:145], v[206:209], v[26:29]
	v_mfma_f32_16x16x32_bf16 v[18:21], v[134:137], v[214:217], v[18:21]
	v_mfma_f32_16x16x32_bf16 v[10:13], v[142:145], v[214:217], v[10:13]
	v_mfma_f32_16x16x32_bf16 v[54:57], v[162:165], v[184:187], v[54:57]
	v_mfma_f32_16x16x32_bf16 v[46:49], v[176:179], v[184:187], v[46:49]
	v_mfma_f32_16x16x32_bf16 v[38:41], v[162:165], v[192:195], v[38:41]
	v_mfma_f32_16x16x32_bf16 v[30:33], v[176:179], v[192:195], v[30:33]
	v_mfma_f32_16x16x32_bf16 v[22:25], v[162:165], v[200:203], v[22:25]
	v_mfma_f32_16x16x32_bf16 v[14:17], v[176:179], v[200:203], v[14:17]
	v_mfma_f32_16x16x32_bf16 v[6:9], v[162:165], v[210:213], v[6:9]
	v_mfma_f32_16x16x32_bf16 v[2:5], v[176:179], v[210:213], v[2:5]
	v_mfma_f32_16x16x32_bf16 v[54:57], v[172:175], v[188:191], v[54:57]
	v_mfma_f32_16x16x32_bf16 v[46:49], v[180:183], v[188:191], v[46:49]
	v_mfma_f32_16x16x32_bf16 v[38:41], v[172:175], v[196:199], v[38:41]
	v_mfma_f32_16x16x32_bf16 v[30:33], v[180:183], v[196:199], v[30:33]
	v_mfma_f32_16x16x32_bf16 v[22:25], v[172:175], v[206:209], v[22:25]
	v_mfma_f32_16x16x32_bf16 v[14:17], v[180:183], v[206:209], v[14:17]
	v_mfma_f32_16x16x32_bf16 v[6:9], v[172:175], v[214:217], v[6:9]
	v_mfma_f32_16x16x32_bf16 v[2:5], v[180:183], v[214:217], v[2:5]
	s_setprio 0
	s_barrier
	s_add_i32 s94, 0, 0x18000
	s_add_i32 s95, 0, 0x1c000
	v_add_u32_e32 v142, s94, v167
	v_add_u32_e32 v154, s95, v167
	ds_read_b128 v[130:133], v142
	ds_read_b128 v[134:137], v142 offset:1024
	ds_read_b128 v[138:141], v142 offset:2048
	ds_read_b128 v[142:145], v142 offset:3072
	ds_read_b128 v[162:165], v154
	ds_read_b128 v[172:175], v154 offset:1024
	ds_read_b128 v[176:179], v154 offset:2048
	ds_read_b128 v[180:183], v154 offset:3072
	s_add_u32 s64, s64, 0x100000
	s_addc_u32 s65, s65, 0
	s_mov_b32 m0, s18
	v_lshl_add_u64 v[226:227], s[64:65], 0, v[146:147]
	ds_read_b128 v[184:187], v170 offset:32768
	ds_read_b128 v[188:191], v170 offset:33792
	ds_read_b128 v[192:195], v170 offset:34816
	ds_read_b128 v[196:199], v170 offset:35840
	ds_read_b128 v[200:203], v170 offset:36864
	ds_read_b128 v[206:209], v170 offset:37888
	ds_read_b128 v[210:213], v170 offset:38912
	ds_read_b128 v[214:217], v170 offset:39936
	global_load_lds_dwordx4 v[226:227], off
	s_mov_b32 m0, s19
	v_lshl_add_u64 v[226:227], s[64:65], 0, v[150:151]
	global_load_lds_dwordx4 v[226:227], off
	s_waitcnt vmcnt(8) lgkmcnt(0)
	s_setprio 1
	s_barrier
	v_mfma_f32_16x16x32_bf16 v[126:129], v[130:133], v[184:187], v[126:129]
	v_mfma_f32_16x16x32_bf16 v[122:125], v[138:141], v[184:187], v[122:125]
	v_mfma_f32_16x16x32_bf16 v[110:113], v[130:133], v[192:195], v[110:113]
	v_mfma_f32_16x16x32_bf16 v[106:109], v[138:141], v[192:195], v[106:109]
	v_mfma_f32_16x16x32_bf16 v[98:101], v[130:133], v[200:203], v[98:101]
	v_mfma_f32_16x16x32_bf16 v[90:93], v[138:141], v[200:203], v[90:93]
	v_mfma_f32_16x16x32_bf16 v[82:85], v[130:133], v[210:213], v[82:85]
	v_mfma_f32_16x16x32_bf16 v[74:77], v[138:141], v[210:213], v[74:77]
	v_mfma_f32_16x16x32_bf16 v[126:129], v[134:137], v[188:191], v[126:129]
	v_mfma_f32_16x16x32_bf16 v[122:125], v[142:145], v[188:191], v[122:125]
	v_mfma_f32_16x16x32_bf16 v[110:113], v[134:137], v[196:199], v[110:113]
	v_mfma_f32_16x16x32_bf16 v[106:109], v[142:145], v[196:199], v[106:109]
	v_mfma_f32_16x16x32_bf16 v[98:101], v[134:137], v[206:209], v[98:101]
	v_mfma_f32_16x16x32_bf16 v[90:93], v[142:145], v[206:209], v[90:93]
	v_mfma_f32_16x16x32_bf16 v[82:85], v[134:137], v[214:217], v[82:85]
	v_mfma_f32_16x16x32_bf16 v[74:77], v[142:145], v[214:217], v[74:77]
	v_mfma_f32_16x16x32_bf16 v[118:121], v[162:165], v[184:187], v[118:121]
	v_mfma_f32_16x16x32_bf16 v[114:117], v[176:179], v[184:187], v[114:117]
	v_mfma_f32_16x16x32_bf16 v[102:105], v[162:165], v[192:195], v[102:105]
	v_mfma_f32_16x16x32_bf16 v[94:97], v[176:179], v[192:195], v[94:97]
	v_mfma_f32_16x16x32_bf16 v[86:89], v[162:165], v[200:203], v[86:89]
	v_mfma_f32_16x16x32_bf16 v[78:81], v[176:179], v[200:203], v[78:81]
	v_mfma_f32_16x16x32_bf16 v[70:73], v[162:165], v[210:213], v[70:73]
	v_mfma_f32_16x16x32_bf16 v[66:69], v[176:179], v[210:213], v[66:69]
	v_mfma_f32_16x16x32_bf16 v[118:121], v[172:175], v[188:191], v[118:121]
	v_mfma_f32_16x16x32_bf16 v[114:117], v[180:183], v[188:191], v[114:117]
	v_mfma_f32_16x16x32_bf16 v[102:105], v[172:175], v[196:199], v[102:105]
	v_mfma_f32_16x16x32_bf16 v[94:97], v[180:183], v[196:199], v[94:97]
	v_mfma_f32_16x16x32_bf16 v[86:89], v[172:175], v[206:209], v[86:89]
	v_mfma_f32_16x16x32_bf16 v[78:81], v[180:183], v[206:209], v[78:81]
	v_mfma_f32_16x16x32_bf16 v[70:73], v[172:175], v[214:217], v[70:73]
	v_mfma_f32_16x16x32_bf16 v[66:69], v[180:183], v[214:217], v[66:69]
	s_setprio 0
	s_barrier
	s_add_i32 s64, s94, s2
	v_lshl_add_u64 v[218:219], v[218:219], 0, s[16:17]
	s_mov_b32 m0, s64
	ds_read_b128 v[184:187], v170 offset:49152
	ds_read_b128 v[188:191], v170 offset:50176
	ds_read_b128 v[192:195], v170 offset:51200
	ds_read_b128 v[196:199], v170 offset:52224
	ds_read_b128 v[200:203], v170 offset:53248
	ds_read_b128 v[206:209], v170 offset:54272
	ds_read_b128 v[210:213], v170 offset:55296
	ds_read_b128 v[214:217], v170 offset:56320
	global_load_lds_dwordx4 v[218:219], off
	s_add_i32 m0, s64, 0x2000
	s_add_u32 s62, s62, 0x100080
	v_lshl_add_u64 v[218:219], v[220:221], 0, s[16:17]
	s_addc_u32 s63, s63, 0
	s_add_i32 s64, s95, s2
	global_load_lds_dwordx4 v[218:219], off
	s_mov_b32 m0, s64
	v_lshl_add_u64 v[218:219], s[62:63], 0, v[148:149]
	global_load_lds_dwordx4 v[218:219], off
	s_add_i32 m0, s64, 0x2000
	v_lshl_add_u64 v[218:219], s[62:63], 0, v[152:153]
	global_load_lds_dwordx4 v[218:219], off
	s_mov_b32 m0, s74
	v_lshl_add_u64 v[218:219], v[222:223], 0, s[16:17]
	global_load_lds_dwordx4 v[218:219], off
	s_mov_b32 m0, s75
	v_lshl_add_u64 v[218:219], v[224:225], 0, s[16:17]
	global_load_lds_dwordx4 v[218:219], off
	s_waitcnt vmcnt(8) lgkmcnt(0)
	s_setprio 1
	s_barrier
	v_mfma_f32_16x16x32_bf16 v[62:65], v[130:133], v[184:187], v[62:65]
	v_mfma_f32_16x16x32_bf16 v[58:61], v[138:141], v[184:187], v[58:61]
	v_mfma_f32_16x16x32_bf16 v[50:53], v[130:133], v[192:195], v[50:53]
	v_mfma_f32_16x16x32_bf16 v[42:45], v[138:141], v[192:195], v[42:45]
	v_mfma_f32_16x16x32_bf16 v[34:37], v[130:133], v[200:203], v[34:37]
	v_mfma_f32_16x16x32_bf16 v[26:29], v[138:141], v[200:203], v[26:29]
	v_mfma_f32_16x16x32_bf16 v[18:21], v[130:133], v[210:213], v[18:21]
	v_mfma_f32_16x16x32_bf16 v[10:13], v[138:141], v[210:213], v[10:13]
	v_mfma_f32_16x16x32_bf16 v[62:65], v[134:137], v[188:191], v[62:65]
	v_mfma_f32_16x16x32_bf16 v[58:61], v[142:145], v[188:191], v[58:61]
	v_mfma_f32_16x16x32_bf16 v[50:53], v[134:137], v[196:199], v[50:53]
	v_mfma_f32_16x16x32_bf16 v[42:45], v[142:145], v[196:199], v[42:45]
	v_mfma_f32_16x16x32_bf16 v[34:37], v[134:137], v[206:209], v[34:37]
	v_mfma_f32_16x16x32_bf16 v[26:29], v[142:145], v[206:209], v[26:29]
	v_mfma_f32_16x16x32_bf16 v[18:21], v[134:137], v[214:217], v[18:21]
	v_mfma_f32_16x16x32_bf16 v[10:13], v[142:145], v[214:217], v[10:13]
	v_mfma_f32_16x16x32_bf16 v[54:57], v[162:165], v[184:187], v[54:57]
	v_mfma_f32_16x16x32_bf16 v[46:49], v[176:179], v[184:187], v[46:49]
	v_mfma_f32_16x16x32_bf16 v[38:41], v[162:165], v[192:195], v[38:41]
	v_mfma_f32_16x16x32_bf16 v[30:33], v[176:179], v[192:195], v[30:33]
	v_mfma_f32_16x16x32_bf16 v[22:25], v[162:165], v[200:203], v[22:25]
	v_mfma_f32_16x16x32_bf16 v[14:17], v[176:179], v[200:203], v[14:17]
	v_mfma_f32_16x16x32_bf16 v[6:9], v[162:165], v[210:213], v[6:9]
	v_mfma_f32_16x16x32_bf16 v[2:5], v[176:179], v[210:213], v[2:5]
	v_mfma_f32_16x16x32_bf16 v[54:57], v[172:175], v[188:191], v[54:57]
	v_mfma_f32_16x16x32_bf16 v[46:49], v[180:183], v[188:191], v[46:49]
	v_mfma_f32_16x16x32_bf16 v[38:41], v[172:175], v[196:199], v[38:41]
	v_mfma_f32_16x16x32_bf16 v[30:33], v[180:183], v[196:199], v[30:33]
	v_mfma_f32_16x16x32_bf16 v[22:25], v[172:175], v[206:209], v[22:25]
	v_mfma_f32_16x16x32_bf16 v[14:17], v[180:183], v[206:209], v[14:17]
	v_mfma_f32_16x16x32_bf16 v[6:9], v[172:175], v[214:217], v[6:9]
	v_mfma_f32_16x16x32_bf16 v[2:5], v[180:183], v[214:217], v[2:5]
	s_setprio 0
	s_barrier
	s_add_u32 s50, s50, 0x100
	s_addc_u32 s51, s51, 0
	s_add_u32 s91, s91, 0x100
	s_addc_u32 s92, s92, 0
	s_cmp_ge_i32 s93, s7
	s_mov_b32 s62, s93
	s_cbranch_scc0 .LBB0_1708
	s_and_b64 vcc, exec, s[20:21]
	s_cbranch_vccz .LBB0_1711
	s_barrier
